# GEMM k-loops: first K iteration peeled with SrcC=0 MFMAs; per-tile accumulator zeroing (128 v_mov) removed
# speedup vs baseline: 1.0136x; 1.0100x over previous
; #define G_STAGE(bufoff, gbase, voff) do { _Pragma("unroll") for (int _i = 0; _i < 2; ++_i) \
;         __builtin_amdgcn_global_load_lds((const unsigned*)((const char*)(gbase) + voff[_i]), (LAS unsigned*)(lds + (bufoff) + ldsw + _i * 8192), 16, 0, 0); } while (0)
; #define G_LDA(dst, b, h) do { _Pragma("unroll") for (int m = 0; m < 4; ++m) _Pragma("unroll") for (int k = 0; k < 2; ++k) dst[m][k] = *(const LAS bf16x8*)(lds + G_SA(b, h) + aoff + m * 2048 + k * 1024); } while (0)
; #define G_LDB(dst, b, h) do { _Pragma("unroll") for (int n = 0; n < 2; ++n) _Pragma("unroll") for (int k = 0; k < 2; ++k) dst[n][k] = *(const LAS bf16x8*)(lds + G_SB(b, h) + boff + n * 2048 + k * 1024); } while (0)
; #define G_MMA(ai, bj, At_, Bt_) do { __builtin_amdgcn_s_setprio(1); _Pragma("unroll") for (int m = 0; m < 4; ++m) _Pragma("unroll") for (int n = 0; n < 2; ++n) _Pragma("unroll") for (int k = 0; k < 2; ++k) \
;         acc[ai][bj][m][n] = __builtin_amdgcn_mfma_f32_16x16x32_bf16(Bt_[n][k], At_[m][k], acc[ai][bj][m][n], 0, 0, 0); __builtin_amdgcn_s_setprio(0); } while (0)
; #define WAIT_V(n) asm volatile("s_waitcnt vmcnt(" #n ")" ::: "memory")
; #define BAR __builtin_amdgcn_s_barrier()
; template <class Get, class Epi>
; DI void gemm_loop(int ntiles, int ld, char* shm, const Get& get, const Epi& epi) {
;     ...
;         const int Ln = L + gridDim.x; const bool has_next = Ln < ntiles; if (has_next) nxt = get(Ln);
;         const char* nA = has_next ? (const char*)nxt.A + (size_t)nxt.brow * ld * 2 : cA; const char* nB = has_next ? (const char*)nxt.Bt + (size_t)nxt.bcol * ld * 2 : cB;
;         const int nt = cur.K / BK;
;         for (int t = 0; t < nt; t += 2) {
;             const bool last = (t == nt - 2);
;             const char* a1 = cA + (size_t)(t + 1) * kstep;
;             const char* a2 = last ? nA : cA + (size_t)(t + 2) * kstep; const char* b2 = last ? nB : cB + (size_t)(t + 2) * kstep;
;             const char* a3 = a2 + kstep; const char* b3 = b2 + kstep;
;             G_LDB(B0, 0, 0); G_LDB(B1, 0, 1); SCHED; G_LDA(At, 0, 0); G_STAGE(G_SA(1, 1), a1 + hstep, voffA);
;             WAIT_V(8); WAIT_L(0); BAR; G_MMA(0, 0, At, B0); G_MMA(0, 1, At, B1); BAR; SCHED;
;             G_LDA(At, 0, 1); G_STAGE(G_SB(0, 0), b2, voffB); G_STAGE(G_SB(0, 1), b2 + hstep, voffB); G_STAGE(G_SA(0, 0), a2, voffA);
;     ...
;         G_ZERO;
;         cur = nxt; cA = nA; cB = nB; L = Ln;
.LBB0_430:
	s_lshl_b32 s28, s57, 13
	s_add_u32 s28, s39, s28
	s_addc_u32 s29, s40, 0
	s_and_b64 s[30:31], s[12:13], exec
	s_cselect_b32 s74, s29, s35
	s_cselect_b32 s75, s28, s34
	s_lshl_b32 s30, s58, 13
	s_add_u32 s30, s41, s30
	s_addc_u32 s31, s42, 0
	s_and_b64 s[36:37], s[12:13], exec
	s_cselect_b32 s76, s31, s15
	s_cselect_b32 s78, s30, s14
	s_add_u32 s34, s34, 0x100080
	s_addc_u32 s35, s35, 0
	s_add_u32 s79, s14, 0x100
	s_addc_u32 s80, s15, 0
	s_mov_b32 s81, -2
.Lpeel_431:
	ds_read_b128 v[146:149], v141
	ds_read_b128 v[150:153], v141 offset:1024
	ds_read_b128 v[154:157], v141 offset:2048
	ds_read_b128 v[158:161], v141 offset:3072
	ds_read_b128 v[162:165], v142
	ds_read_b128 v[166:169], v142 offset:1024
	ds_read_b128 v[170:173], v142 offset:2048
	ds_read_b128 v[174:177], v142 offset:3072
	s_add_u32 s14, s34, 0xfff00080
	s_addc_u32 s15, s35, -1
	s_cmp_eq_u32 s81, 60
	s_cselect_b32 s37, s74, s15
	s_cselect_b32 s36, s75, s14
	s_cselect_b32 s15, s76, s80
	s_cselect_b32 s14, s78, s79
	s_mov_b32 m0, s56
	v_lshl_add_u64 v[182:183], s[34:35], 0, v[136:137]
	ds_read_b128 v[178:181], v143
	ds_read_b128 v[188:191], v143 offset:1024
	ds_read_b128 v[192:195], v143 offset:2048
	ds_read_b128 v[196:199], v143 offset:3072
	ds_read_b128 v[200:203], v143 offset:4096
	ds_read_b128 v[204:207], v143 offset:5120
	ds_read_b128 v[208:211], v143 offset:6144
	ds_read_b128 v[212:215], v143 offset:7168
	global_load_lds_dwordx4 v[182:183], off
	v_lshl_add_u64 v[182:183], s[34:35], 0, v[138:139]
	s_add_i32 m0, s43, 0xe000
	s_nop 0
	global_load_lds_dwordx4 v[182:183], off
	s_waitcnt vmcnt(8)
	s_waitcnt lgkmcnt(0)
	s_barrier
	s_setprio 1
	s_waitcnt lgkmcnt(0)
	v_mfma_f32_16x16x32_bf16 v[124:127], v[146:149], v[178:181], 0
	v_mfma_f32_16x16x32_bf16 v[120:123], v[154:157], v[178:181], 0
	v_mfma_f32_16x16x32_bf16 v[116:119], v[146:149], v[192:195], 0
	v_mfma_f32_16x16x32_bf16 v[112:115], v[154:157], v[192:195], 0
	v_mfma_f32_16x16x32_bf16 v[100:103], v[146:149], v[200:203], 0
	v_mfma_f32_16x16x32_bf16 v[96:99], v[154:157], v[200:203], 0
	v_mfma_f32_16x16x32_bf16 v[84:87], v[146:149], v[208:211], 0
	v_mfma_f32_16x16x32_bf16 v[80:83], v[154:157], v[208:211], 0
	v_mfma_f32_16x16x32_bf16 v[124:127], v[150:153], v[188:191], v[124:127]
	v_mfma_f32_16x16x32_bf16 v[120:123], v[158:161], v[188:191], v[120:123]
	v_mfma_f32_16x16x32_bf16 v[116:119], v[150:153], v[196:199], v[116:119]
	v_mfma_f32_16x16x32_bf16 v[112:115], v[158:161], v[196:199], v[112:115]
	v_mfma_f32_16x16x32_bf16 v[100:103], v[150:153], v[204:207], v[100:103]
	v_mfma_f32_16x16x32_bf16 v[96:99], v[158:161], v[204:207], v[96:99]
	v_mfma_f32_16x16x32_bf16 v[84:87], v[150:153], v[212:215], v[84:87]
	v_mfma_f32_16x16x32_bf16 v[80:83], v[158:161], v[212:215], v[80:83]
	s_setprio 0
	s_setprio 1
	v_mfma_f32_16x16x32_bf16 v[108:111], v[162:165], v[178:181], 0
	v_mfma_f32_16x16x32_bf16 v[104:107], v[170:173], v[178:181], 0
	v_mfma_f32_16x16x32_bf16 v[92:95], v[162:165], v[192:195], 0
	v_mfma_f32_16x16x32_bf16 v[88:91], v[170:173], v[192:195], 0
	v_mfma_f32_16x16x32_bf16 v[76:79], v[162:165], v[200:203], 0
	v_mfma_f32_16x16x32_bf16 v[72:75], v[170:173], v[200:203], 0
	v_mfma_f32_16x16x32_bf16 v[68:71], v[162:165], v[208:211], 0
	v_mfma_f32_16x16x32_bf16 v[64:67], v[170:173], v[208:211], 0
	v_mfma_f32_16x16x32_bf16 v[108:111], v[166:169], v[188:191], v[108:111]
	v_mfma_f32_16x16x32_bf16 v[104:107], v[174:177], v[188:191], v[104:107]
	v_mfma_f32_16x16x32_bf16 v[92:95], v[166:169], v[196:199], v[92:95]
	v_mfma_f32_16x16x32_bf16 v[88:91], v[174:177], v[196:199], v[88:91]
	v_mfma_f32_16x16x32_bf16 v[76:79], v[166:169], v[204:207], v[76:79]
	v_mfma_f32_16x16x32_bf16 v[72:75], v[174:177], v[204:207], v[72:75]
	v_mfma_f32_16x16x32_bf16 v[68:71], v[166:169], v[212:215], v[68:71]
	v_mfma_f32_16x16x32_bf16 v[64:67], v[174:177], v[212:215], v[64:67]
	s_setprio 0
	s_barrier
	s_add_i32 s82, s54, s38
	v_lshl_add_u64 v[182:183], s[14:15], 0, v[132:133]
	s_mov_b32 m0, s82
	ds_read_b128 v[178:181], v143 offset:16384
	ds_read_b128 v[188:191], v143 offset:17408
	ds_read_b128 v[192:195], v143 offset:18432
	ds_read_b128 v[196:199], v143 offset:19456
	ds_read_b128 v[200:203], v143 offset:20480
	ds_read_b128 v[204:207], v143 offset:21504
	ds_read_b128 v[208:211], v143 offset:22528
	ds_read_b128 v[212:215], v143 offset:23552
	global_load_lds_dwordx4 v[182:183], off
	s_add_i32 m0, s82, 0x2000
	s_add_u32 s82, s14, 0x100000
	v_lshl_add_u64 v[184:185], s[14:15], 0, v[128:129]
	s_addc_u32 s83, s15, 0
	s_add_i32 s84, s55, s38
	global_load_lds_dwordx4 v[184:185], off
	v_lshl_add_u64 v[186:187], s[82:83], 0, v[132:133]
	s_mov_b32 m0, s84
	v_lshl_add_u64 v[216:217], s[36:37], 0, v[130:131]
	global_load_lds_dwordx4 v[186:187], off
	v_lshl_add_u64 v[186:187], s[82:83], 0, v[128:129]
	s_add_i32 m0, s84, 0x2000
	s_nop 0
	global_load_lds_dwordx4 v[186:187], off
	v_lshl_add_u64 v[186:187], s[36:37], 0, v[134:135]
	s_mov_b32 m0, s43
	s_nop 0
	global_load_lds_dwordx4 v[186:187], off
	s_mov_b32 m0, s44
	s_nop 0
	global_load_lds_dwordx4 v[216:217], off
	s_waitcnt vmcnt(8)
	s_waitcnt lgkmcnt(0)
	s_barrier
; #define G_STAGE(bufoff, gbase, voff) do { _Pragma("unroll") for (int _i = 0; _i < 2; ++_i) \
;         __builtin_amdgcn_global_load_lds((const unsigned*)((const char*)(gbase) + voff[_i]), (LAS unsigned*)(lds + (bufoff) + ldsw + _i * 8192), 16, 0, 0); } while (0)
; #define G_LDA(dst, b, h) do { _Pragma("unroll") for (int m = 0; m < 4; ++m) _Pragma("unroll") for (int k = 0; k < 2; ++k) dst[m][k] = *(const LAS bf16x8*)(lds + G_SA(b, h) + aoff + m * 2048 + k * 1024); } while (0)
; #define G_LDB(dst, b, h) do { _Pragma("unroll") for (int n = 0; n < 2; ++n) _Pragma("unroll") for (int k = 0; k < 2; ++k) dst[n][k] = *(const LAS bf16x8*)(lds + G_SB(b, h) + boff + n * 2048 + k * 1024); } while (0)
; #define G_MMA(ai, bj, At_, Bt_) do { __builtin_amdgcn_s_setprio(1); _Pragma("unroll") for (int m = 0; m < 4; ++m) _Pragma("unroll") for (int n = 0; n < 2; ++n) _Pragma("unroll") for (int k = 0; k < 2; ++k) \
;         acc[ai][bj][m][n] = __builtin_amdgcn_mfma_f32_16x16x32_bf16(Bt_[n][k], At_[m][k], acc[ai][bj][m][n], 0, 0, 0); __builtin_amdgcn_s_setprio(0); } while (0)
; #define WAIT_V(n) asm volatile("s_waitcnt vmcnt(" #n ")" ::: "memory")
; #define WAIT_L(n) asm volatile("s_waitcnt lgkmcnt(" #n ")" ::: "memory")
; #define BAR __builtin_amdgcn_s_barrier()
; #define SCHED __builtin_amdgcn_sched_barrier(0)
; template <class Get, class Epi>
; DI void gemm_loop(int ntiles, int ld, char* shm, const Get& get, const Epi& epi) {
;     ...
;             WAIT_V(8); WAIT_L(0); BAR; G_MMA(0, 0, At, B0); G_MMA(0, 1, At, B1); BAR; SCHED;
;             G_LDA(At, 0, 1); G_STAGE(G_SB(0, 0), b2, voffB); G_STAGE(G_SB(0, 1), b2 + hstep, voffB); G_STAGE(G_SA(0, 0), a2, voffA);
;             WAIT_V(8); WAIT_L(0); BAR; G_MMA(1, 0, At, B0); G_MMA(1, 1, At, B1); BAR; SCHED;
;             G_LDB(B0, 1, 0); G_LDB(B1, 1, 1); SCHED; G_LDA(At, 1, 0); G_STAGE(G_SA(0, 1), a2 + hstep, voffA);
;             WAIT_V(8); WAIT_L(0); BAR; G_MMA(0, 0, At, B0); G_MMA(0, 1, At, B1); BAR; SCHED;
	s_setprio 1
	s_waitcnt lgkmcnt(0)
	v_mfma_f32_16x16x32_bf16 v[60:63], v[146:149], v[178:181], 0
	v_mfma_f32_16x16x32_bf16 v[56:59], v[154:157], v[178:181], 0
	v_mfma_f32_16x16x32_bf16 v[52:55], v[146:149], v[192:195], 0
	v_mfma_f32_16x16x32_bf16 v[48:51], v[154:157], v[192:195], 0
	v_mfma_f32_16x16x32_bf16 v[36:39], v[146:149], v[200:203], 0
	v_mfma_f32_16x16x32_bf16 v[32:35], v[154:157], v[200:203], 0
	v_mfma_f32_16x16x32_bf16 v[20:23], v[146:149], v[208:211], 0
	v_mfma_f32_16x16x32_bf16 v[16:19], v[154:157], v[208:211], 0
	v_mfma_f32_16x16x32_bf16 v[60:63], v[150:153], v[188:191], v[60:63]
	v_mfma_f32_16x16x32_bf16 v[56:59], v[158:161], v[188:191], v[56:59]
	v_mfma_f32_16x16x32_bf16 v[52:55], v[150:153], v[196:199], v[52:55]
	v_mfma_f32_16x16x32_bf16 v[48:51], v[158:161], v[196:199], v[48:51]
	v_mfma_f32_16x16x32_bf16 v[36:39], v[150:153], v[204:207], v[36:39]
	v_mfma_f32_16x16x32_bf16 v[32:35], v[158:161], v[204:207], v[32:35]
	v_mfma_f32_16x16x32_bf16 v[20:23], v[150:153], v[212:215], v[20:23]
	v_mfma_f32_16x16x32_bf16 v[16:19], v[158:161], v[212:215], v[16:19]
	s_setprio 0
	s_setprio 1
	v_mfma_f32_16x16x32_bf16 v[44:47], v[162:165], v[178:181], 0
	v_mfma_f32_16x16x32_bf16 v[40:43], v[170:173], v[178:181], 0
	v_mfma_f32_16x16x32_bf16 v[28:31], v[162:165], v[192:195], 0
	v_mfma_f32_16x16x32_bf16 v[24:27], v[170:173], v[192:195], 0
	v_mfma_f32_16x16x32_bf16 v[12:15], v[162:165], v[200:203], 0
	v_mfma_f32_16x16x32_bf16 v[8:11], v[170:173], v[200:203], 0
	v_mfma_f32_16x16x32_bf16 v[4:7], v[162:165], v[208:211], 0
	v_mfma_f32_16x16x32_bf16 v[0:3], v[170:173], v[208:211], 0
	v_mfma_f32_16x16x32_bf16 v[44:47], v[166:169], v[188:191], v[44:47]
	v_mfma_f32_16x16x32_bf16 v[40:43], v[174:177], v[188:191], v[40:43]
	v_mfma_f32_16x16x32_bf16 v[28:31], v[166:169], v[196:199], v[28:31]
	v_mfma_f32_16x16x32_bf16 v[24:27], v[174:177], v[196:199], v[24:27]
	v_mfma_f32_16x16x32_bf16 v[12:15], v[166:169], v[204:207], v[12:15]
	v_mfma_f32_16x16x32_bf16 v[8:11], v[174:177], v[204:207], v[8:11]
	v_mfma_f32_16x16x32_bf16 v[4:7], v[166:169], v[212:215], v[4:7]
	v_mfma_f32_16x16x32_bf16 v[0:3], v[174:177], v[212:215], v[0:3]
	s_setprio 0
	s_barrier
	s_add_i32 s82, 0, 0x18000
	v_add_u32_e32 v145, s82, v140
	s_add_i32 s83, 0, 0x1c000
	ds_read_b128 v[146:149], v145
	ds_read_b128 v[150:153], v145 offset:1024
	ds_read_b128 v[154:157], v145 offset:2048
	ds_read_b128 v[158:161], v145 offset:3072
	v_add_u32_e32 v145, s83, v140
	ds_read_b128 v[162:165], v145
	ds_read_b128 v[166:169], v145 offset:1024
	ds_read_b128 v[170:173], v145 offset:2048
	ds_read_b128 v[174:177], v145 offset:3072
	s_add_u32 s36, s36, 0x100000
	s_addc_u32 s37, s37, 0
	s_mov_b32 m0, s45
	v_lshl_add_u64 v[218:219], s[36:37], 0, v[134:135]
	ds_read_b128 v[178:181], v143 offset:32768
	ds_read_b128 v[188:191], v143 offset:33792
	ds_read_b128 v[192:195], v143 offset:34816
	ds_read_b128 v[196:199], v143 offset:35840
	ds_read_b128 v[200:203], v143 offset:36864
	ds_read_b128 v[204:207], v143 offset:37888
	ds_read_b128 v[208:211], v143 offset:38912
	ds_read_b128 v[212:215], v143 offset:39936
	global_load_lds_dwordx4 v[218:219], off
	v_lshl_add_u64 v[218:219], s[36:37], 0, v[130:131]
	s_mov_b32 m0, s46
	s_nop 0
	global_load_lds_dwordx4 v[218:219], off
	s_waitcnt vmcnt(8)
	s_waitcnt lgkmcnt(0)
	s_barrier
	s_setprio 1
	s_waitcnt lgkmcnt(0)
	v_mfma_f32_16x16x32_bf16 v[124:127], v[146:149], v[178:181], v[124:127]
	v_mfma_f32_16x16x32_bf16 v[120:123], v[154:157], v[178:181], v[120:123]
	v_mfma_f32_16x16x32_bf16 v[116:119], v[146:149], v[192:195], v[116:119]
	v_mfma_f32_16x16x32_bf16 v[112:115], v[154:157], v[192:195], v[112:115]
	v_mfma_f32_16x16x32_bf16 v[100:103], v[146:149], v[200:203], v[100:103]
	v_mfma_f32_16x16x32_bf16 v[96:99], v[154:157], v[200:203], v[96:99]
	v_mfma_f32_16x16x32_bf16 v[84:87], v[146:149], v[208:211], v[84:87]
	v_mfma_f32_16x16x32_bf16 v[80:83], v[154:157], v[208:211], v[80:83]
	v_mfma_f32_16x16x32_bf16 v[124:127], v[150:153], v[188:191], v[124:127]
	v_mfma_f32_16x16x32_bf16 v[120:123], v[158:161], v[188:191], v[120:123]
	v_mfma_f32_16x16x32_bf16 v[116:119], v[150:153], v[196:199], v[116:119]
	v_mfma_f32_16x16x32_bf16 v[112:115], v[158:161], v[196:199], v[112:115]
	v_mfma_f32_16x16x32_bf16 v[100:103], v[150:153], v[204:207], v[100:103]
	v_mfma_f32_16x16x32_bf16 v[96:99], v[158:161], v[204:207], v[96:99]
	v_mfma_f32_16x16x32_bf16 v[84:87], v[150:153], v[212:215], v[84:87]
	v_mfma_f32_16x16x32_bf16 v[80:83], v[158:161], v[212:215], v[80:83]
	s_setprio 0
	s_setprio 1
	v_mfma_f32_16x16x32_bf16 v[108:111], v[162:165], v[178:181], v[108:111]
	v_mfma_f32_16x16x32_bf16 v[104:107], v[170:173], v[178:181], v[104:107]
	v_mfma_f32_16x16x32_bf16 v[92:95], v[162:165], v[192:195], v[92:95]
	v_mfma_f32_16x16x32_bf16 v[88:91], v[170:173], v[192:195], v[88:91]
	v_mfma_f32_16x16x32_bf16 v[76:79], v[162:165], v[200:203], v[76:79]
	v_mfma_f32_16x16x32_bf16 v[72:75], v[170:173], v[200:203], v[72:75]
	v_mfma_f32_16x16x32_bf16 v[68:71], v[162:165], v[208:211], v[68:71]
	v_mfma_f32_16x16x32_bf16 v[64:67], v[170:173], v[208:211], v[64:67]
	v_mfma_f32_16x16x32_bf16 v[108:111], v[166:169], v[188:191], v[108:111]
	v_mfma_f32_16x16x32_bf16 v[104:107], v[174:177], v[188:191], v[104:107]
	v_mfma_f32_16x16x32_bf16 v[92:95], v[166:169], v[196:199], v[92:95]
	v_mfma_f32_16x16x32_bf16 v[88:91], v[174:177], v[196:199], v[88:91]
	v_mfma_f32_16x16x32_bf16 v[76:79], v[166:169], v[204:207], v[76:79]
	v_mfma_f32_16x16x32_bf16 v[72:75], v[174:177], v[204:207], v[72:75]
	v_mfma_f32_16x16x32_bf16 v[68:71], v[166:169], v[212:215], v[68:71]
	v_mfma_f32_16x16x32_bf16 v[64:67], v[174:177], v[212:215], v[64:67]
	s_setprio 0
	s_barrier
; #define G_STAGE(bufoff, gbase, voff) do { _Pragma("unroll") for (int _i = 0; _i < 2; ++_i) \
;         __builtin_amdgcn_global_load_lds((const unsigned*)((const char*)(gbase) + voff[_i]), (LAS unsigned*)(lds + (bufoff) + ldsw + _i * 8192), 16, 0, 0); } while (0)
; #define G_LDA(dst, b, h) do { _Pragma("unroll") for (int m = 0; m < 4; ++m) _Pragma("unroll") for (int k = 0; k < 2; ++k) dst[m][k] = *(const LAS bf16x8*)(lds + G_SA(b, h) + aoff + m * 2048 + k * 1024); } while (0)
; #define G_MMA(ai, bj, At_, Bt_) do { __builtin_amdgcn_s_setprio(1); _Pragma("unroll") for (int m = 0; m < 4; ++m) _Pragma("unroll") for (int n = 0; n < 2; ++n) _Pragma("unroll") for (int k = 0; k < 2; ++k) \
;         acc[ai][bj][m][n] = __builtin_amdgcn_mfma_f32_16x16x32_bf16(Bt_[n][k], At_[m][k], acc[ai][bj][m][n], 0, 0, 0); __builtin_amdgcn_s_setprio(0); } while (0)
; #define WAIT_V(n) asm volatile("s_waitcnt vmcnt(" #n ")" ::: "memory")
; #define WAIT_L(n) asm volatile("s_waitcnt lgkmcnt(" #n ")" ::: "memory")
; #define BAR __builtin_amdgcn_s_barrier()
; #define SCHED __builtin_amdgcn_sched_barrier(0)
; template <class Get, class Epi>
; DI void gemm_loop(int ntiles, int ld, char* shm, const Get& get, const Epi& epi) {
;     ...
;             G_LDA(At, 1, 1); G_STAGE(G_SB(1, 0), b3, voffB); G_STAGE(G_SB(1, 1), b3 + hstep, voffB); G_STAGE(G_SA(1, 0), a3, voffA);
;             WAIT_V(8); WAIT_L(0); BAR; G_MMA(1, 0, At, B0); G_MMA(1, 1, At, B1); BAR; SCHED;
;         }
	s_add_i32 s36, s82, s38
	v_lshl_add_u64 v[182:183], v[182:183], 0, s[8:9]
	s_mov_b32 m0, s36
	ds_read_b128 v[178:181], v143 offset:49152
	ds_read_b128 v[188:191], v143 offset:50176
	ds_read_b128 v[192:195], v143 offset:51200
	ds_read_b128 v[196:199], v143 offset:52224
	ds_read_b128 v[200:203], v143 offset:53248
	ds_read_b128 v[204:207], v143 offset:54272
	ds_read_b128 v[208:211], v143 offset:55296
	ds_read_b128 v[212:215], v143 offset:56320
	global_load_lds_dwordx4 v[182:183], off
	s_add_i32 m0, s36, 0x2000
	s_add_u32 s14, s14, 0x100080
	v_lshl_add_u64 v[182:183], v[184:185], 0, s[8:9]
	s_addc_u32 s15, s15, 0
	s_add_i32 s36, s83, s38
	global_load_lds_dwordx4 v[182:183], off
	v_lshl_add_u64 v[182:183], s[14:15], 0, v[132:133]
	s_mov_b32 m0, s36
	s_nop 0
	global_load_lds_dwordx4 v[182:183], off
	v_lshl_add_u64 v[182:183], s[14:15], 0, v[128:129]
	s_add_i32 m0, s36, 0x2000
	s_nop 0
	global_load_lds_dwordx4 v[182:183], off
	v_lshl_add_u64 v[182:183], v[186:187], 0, s[8:9]
	s_mov_b32 m0, s47
	s_nop 0
	global_load_lds_dwordx4 v[182:183], off
	v_lshl_add_u64 v[182:183], v[216:217], 0, s[8:9]
	s_mov_b32 m0, s50
	s_nop 0
	global_load_lds_dwordx4 v[182:183], off
	s_waitcnt vmcnt(8)
	s_waitcnt lgkmcnt(0)
	s_barrier
	s_setprio 1
	s_waitcnt lgkmcnt(0)
	v_mfma_f32_16x16x32_bf16 v[60:63], v[146:149], v[178:181], v[60:63]
	v_mfma_f32_16x16x32_bf16 v[56:59], v[154:157], v[178:181], v[56:59]
	v_mfma_f32_16x16x32_bf16 v[52:55], v[146:149], v[192:195], v[52:55]
	v_mfma_f32_16x16x32_bf16 v[48:51], v[154:157], v[192:195], v[48:51]
	v_mfma_f32_16x16x32_bf16 v[36:39], v[146:149], v[200:203], v[36:39]
	v_mfma_f32_16x16x32_bf16 v[32:35], v[154:157], v[200:203], v[32:35]
	v_mfma_f32_16x16x32_bf16 v[20:23], v[146:149], v[208:211], v[20:23]
	v_mfma_f32_16x16x32_bf16 v[16:19], v[154:157], v[208:211], v[16:19]
	v_mfma_f32_16x16x32_bf16 v[60:63], v[150:153], v[188:191], v[60:63]
	v_mfma_f32_16x16x32_bf16 v[56:59], v[158:161], v[188:191], v[56:59]
	v_mfma_f32_16x16x32_bf16 v[52:55], v[150:153], v[196:199], v[52:55]
	v_mfma_f32_16x16x32_bf16 v[48:51], v[158:161], v[196:199], v[48:51]
	v_mfma_f32_16x16x32_bf16 v[36:39], v[150:153], v[204:207], v[36:39]
	v_mfma_f32_16x16x32_bf16 v[32:35], v[158:161], v[204:207], v[32:35]
	v_mfma_f32_16x16x32_bf16 v[20:23], v[150:153], v[212:215], v[20:23]
	v_mfma_f32_16x16x32_bf16 v[16:19], v[158:161], v[212:215], v[16:19]
	s_setprio 0
	s_setprio 1
	v_mfma_f32_16x16x32_bf16 v[44:47], v[162:165], v[178:181], v[44:47]
	v_mfma_f32_16x16x32_bf16 v[40:43], v[170:173], v[178:181], v[40:43]
	v_mfma_f32_16x16x32_bf16 v[28:31], v[162:165], v[192:195], v[28:31]
	v_mfma_f32_16x16x32_bf16 v[24:27], v[170:173], v[192:195], v[24:27]
	v_mfma_f32_16x16x32_bf16 v[12:15], v[162:165], v[200:203], v[12:15]
	v_mfma_f32_16x16x32_bf16 v[8:11], v[170:173], v[200:203], v[8:11]
	v_mfma_f32_16x16x32_bf16 v[4:7], v[162:165], v[208:211], v[4:7]
	v_mfma_f32_16x16x32_bf16 v[0:3], v[170:173], v[208:211], v[0:3]
	v_mfma_f32_16x16x32_bf16 v[44:47], v[166:169], v[188:191], v[44:47]
	v_mfma_f32_16x16x32_bf16 v[40:43], v[174:177], v[188:191], v[40:43]
	v_mfma_f32_16x16x32_bf16 v[28:31], v[166:169], v[196:199], v[28:31]
	v_mfma_f32_16x16x32_bf16 v[24:27], v[174:177], v[196:199], v[24:27]
	v_mfma_f32_16x16x32_bf16 v[12:15], v[166:169], v[204:207], v[12:15]
	v_mfma_f32_16x16x32_bf16 v[8:11], v[174:177], v[204:207], v[8:11]
	v_mfma_f32_16x16x32_bf16 v[4:7], v[166:169], v[212:215], v[4:7]
	v_mfma_f32_16x16x32_bf16 v[0:3], v[174:177], v[212:215], v[0:3]
	s_setprio 0
	s_barrier
	s_add_i32 s81, s81, 2
	s_add_u32 s34, s34, 0x100
	s_addc_u32 s35, s35, 0
	s_add_u32 s79, s79, 0x100
	s_addc_u32 s80, s80, 0
	s_cmp_gt_u32 s81, 61
	s_cbranch_scc0 .LBB0_431
	s_branch .Lpost_431

; #define BAR __builtin_amdgcn_s_barrier()
; template <class Get, class Epi>
; DI void gemm_loop(int ntiles, int ld, char* shm, const Get& get, const Epi& epi) {
;     ...
;         }
;         if (wr == 0) BAR;
.Lpost_431:
	s_and_b64 vcc, exec, s[10:11]
	s_cbranch_vccz .LBB0_434
	s_barrier

; #define G_STAGE(bufoff, gbase, voff) do { _Pragma("unroll") for (int _i = 0; _i < 2; ++_i) \
;         __builtin_amdgcn_global_load_lds((const unsigned*)((const char*)(gbase) + voff[_i]), (LAS unsigned*)(lds + (bufoff) + ldsw + _i * 8192), 16, 0, 0); } while (0)
; #define G_LDA(dst, b, h) do { _Pragma("unroll") for (int m = 0; m < 4; ++m) _Pragma("unroll") for (int k = 0; k < 2; ++k) dst[m][k] = *(const LAS bf16x8*)(lds + G_SA(b, h) + aoff + m * 2048 + k * 1024); } while (0)
; #define G_LDB(dst, b, h) do { _Pragma("unroll") for (int n = 0; n < 2; ++n) _Pragma("unroll") for (int k = 0; k < 2; ++k) dst[n][k] = *(const LAS bf16x8*)(lds + G_SB(b, h) + boff + n * 2048 + k * 1024); } while (0)
; #define WAIT_V(n) asm volatile("s_waitcnt vmcnt(" #n ")" ::: "memory")
; template <class Get, class Epi>
; DI void gemm_loop(int ntiles, int ld, char* shm, const Get& get, const Epi& epi) {
;     ...
;         const int Ln = L + gridDim.x; const bool has_next = Ln < ntiles; if (has_next) nxt = get(Ln);
;         const char* nA = has_next ? (const char*)nxt.A + (size_t)nxt.brow * ld * 2 : cA; const char* nB = has_next ? (const char*)nxt.Bt + (size_t)nxt.bcol * ld * 2 : cB;
;         const int nt = cur.K / BK;
;         for (int t = 0; t < nt; t += 2) {
;             const bool last = (t == nt - 2);
;             const char* a1 = cA + (size_t)(t + 1) * kstep;
;             const char* a2 = last ? nA : cA + (size_t)(t + 2) * kstep; const char* b2 = last ? nB : cB + (size_t)(t + 2) * kstep;
;             const char* a3 = a2 + kstep; const char* b3 = b2 + kstep;
;             G_LDB(B0, 0, 0); G_LDB(B1, 0, 1); SCHED; G_LDA(At, 0, 0); G_STAGE(G_SA(1, 1), a1 + hstep, voffA);
;             WAIT_V(8); WAIT_L(0); BAR; G_MMA(0, 0, At, B0); G_MMA(0, 1, At, B1); BAR; SCHED;
;             G_LDA(At, 0, 1); G_STAGE(G_SB(0, 0), b2, voffB); G_STAGE(G_SB(0, 1), b2 + hstep, voffB); G_STAGE(G_SA(0, 0), a2, voffA);
; template <int layer>
; DI void layer_body(const Params& p, const XcdBarrier& xb, char* shm) {
;     ...
;               gemm_loop(NB * 4, 512, shm,
;                   [&](int L) { const int b = L >> 2, pn = L & 3; return Tile{wc, gtc + (size_t)b * 1024 * 512, 512, 512, 512, 0, pn * 256}; },
;                   [&](int L, const AccT& acc, int brow, int bcol, int wr, int wc_, int fr, int fq) { EpiBf16 e{Yb + ((size_t)(L >> 2) * LT) * D, (size_t)D}; e(acc, brow, bcol, wr, wc_, fr, fq); }); }
.LBB0_444:
	s_mov_b32 s75, s40
	s_add_i32 s40, s40, s70
	s_mov_b64 s[14:15], s[6:7]
	s_ashr_i32 s6, s40, 2
	s_ashr_i32 s7, s6, 31
	s_lshl_b64 s[6:7], s[6:7], 20
	s_add_u32 s6, s4, s6
	s_mov_b64 s[36:37], s[8:9]
	s_addc_u32 s7, s5, s7
	s_lshl_b32 s8, s40, 8
	s_mov_b32 s74, s42
	s_and_b32 s42, s8, 0x300
	s_cmp_lt_i32 s40, 32
	s_cselect_b64 s[8:9], -1, 0
	s_and_b64 s[8:9], s[8:9], exec
	s_cselect_b32 s8, s6, s14
	s_cselect_b32 s14, s42, s74
	s_cselect_b32 s9, s7, s15
	s_lshl_b32 s14, s14, 10
	s_add_u32 s8, s8, s14
	s_addc_u32 s9, s9, 0
	s_cmp_lt_i32 s40, 32
	s_cselect_b64 s[34:35], -1, 0
	s_and_b64 s[14:15], s[34:35], exec
	s_cselect_b32 s76, s9, s37
	s_cselect_b32 s78, s8, s36
	s_add_u32 s79, s36, 0x100
	s_addc_u32 s80, s37, 0
	s_mov_b32 s81, -2
	s_mov_b64 s[36:37], s[30:31]
.Lpeel_445:
	ds_read_b128 v[146:149], v140
	ds_read_b128 v[150:153], v140 offset:1024
	ds_read_b128 v[154:157], v140 offset:2048
	ds_read_b128 v[158:161], v140 offset:3072
	ds_read_b128 v[162:165], v141
	ds_read_b128 v[166:169], v141 offset:1024
	ds_read_b128 v[170:173], v141 offset:2048
	ds_read_b128 v[174:177], v141 offset:3072
	s_add_u32 s14, s36, 0xfffe0080
	s_addc_u32 s15, s37, -1
	s_cmp_eq_u32 s81, 4
	s_cselect_b32 s39, s3, s15
	s_cselect_b32 s38, s2, s14
	s_cselect_b32 s15, s76, s80
	s_cselect_b32 s14, s78, s79
	s_mov_b32 m0, s50
	v_lshl_add_u64 v[182:183], s[36:37], 0, v[136:137]
	ds_read_b128 v[178:181], v142
	ds_read_b128 v[188:191], v142 offset:1024
	ds_read_b128 v[192:195], v142 offset:2048
	ds_read_b128 v[196:199], v142 offset:3072
	ds_read_b128 v[200:203], v142 offset:4096
	ds_read_b128 v[204:207], v142 offset:5120
	ds_read_b128 v[208:211], v142 offset:6144
	ds_read_b128 v[212:215], v142 offset:7168
	global_load_lds_dwordx4 v[182:183], off
	v_lshl_add_u64 v[182:183], s[36:37], 0, v[138:139]
	s_mov_b32 m0, s51
	s_nop 0
	global_load_lds_dwordx4 v[182:183], off
	s_waitcnt vmcnt(8)
	s_waitcnt lgkmcnt(0)
	s_barrier
	s_setprio 1
	s_waitcnt lgkmcnt(0)
	v_mfma_f32_16x16x32_bf16 v[124:127], v[146:149], v[178:181], 0
	v_mfma_f32_16x16x32_bf16 v[120:123], v[154:157], v[178:181], 0
	v_mfma_f32_16x16x32_bf16 v[116:119], v[146:149], v[192:195], 0
	v_mfma_f32_16x16x32_bf16 v[112:115], v[154:157], v[192:195], 0
	v_mfma_f32_16x16x32_bf16 v[100:103], v[146:149], v[200:203], 0
	v_mfma_f32_16x16x32_bf16 v[96:99], v[154:157], v[200:203], 0
	v_mfma_f32_16x16x32_bf16 v[84:87], v[146:149], v[208:211], 0
	v_mfma_f32_16x16x32_bf16 v[80:83], v[154:157], v[208:211], 0
	v_mfma_f32_16x16x32_bf16 v[124:127], v[150:153], v[188:191], v[124:127]
	v_mfma_f32_16x16x32_bf16 v[120:123], v[158:161], v[188:191], v[120:123]
	v_mfma_f32_16x16x32_bf16 v[116:119], v[150:153], v[196:199], v[116:119]
	v_mfma_f32_16x16x32_bf16 v[112:115], v[158:161], v[196:199], v[112:115]
	v_mfma_f32_16x16x32_bf16 v[100:103], v[150:153], v[204:207], v[100:103]
	v_mfma_f32_16x16x32_bf16 v[96:99], v[158:161], v[204:207], v[96:99]
	v_mfma_f32_16x16x32_bf16 v[84:87], v[150:153], v[212:215], v[84:87]
	v_mfma_f32_16x16x32_bf16 v[80:83], v[158:161], v[212:215], v[80:83]
	s_setprio 0
	s_setprio 1
	v_mfma_f32_16x16x32_bf16 v[108:111], v[162:165], v[178:181], 0
	v_mfma_f32_16x16x32_bf16 v[104:107], v[170:173], v[178:181], 0
	v_mfma_f32_16x16x32_bf16 v[92:95], v[162:165], v[192:195], 0
	v_mfma_f32_16x16x32_bf16 v[88:91], v[170:173], v[192:195], 0
	v_mfma_f32_16x16x32_bf16 v[76:79], v[162:165], v[200:203], 0
	v_mfma_f32_16x16x32_bf16 v[72:75], v[170:173], v[200:203], 0
	v_mfma_f32_16x16x32_bf16 v[68:71], v[162:165], v[208:211], 0
	v_mfma_f32_16x16x32_bf16 v[64:67], v[170:173], v[208:211], 0
	v_mfma_f32_16x16x32_bf16 v[108:111], v[166:169], v[188:191], v[108:111]
	v_mfma_f32_16x16x32_bf16 v[104:107], v[174:177], v[188:191], v[104:107]
	v_mfma_f32_16x16x32_bf16 v[92:95], v[166:169], v[196:199], v[92:95]
	v_mfma_f32_16x16x32_bf16 v[88:91], v[174:177], v[196:199], v[88:91]
	v_mfma_f32_16x16x32_bf16 v[76:79], v[166:169], v[204:207], v[76:79]
	v_mfma_f32_16x16x32_bf16 v[72:75], v[174:177], v[204:207], v[72:75]
	v_mfma_f32_16x16x32_bf16 v[68:71], v[166:169], v[212:215], v[68:71]
	v_mfma_f32_16x16x32_bf16 v[64:67], v[174:177], v[212:215], v[64:67]
	s_setprio 0
	s_barrier
	s_mov_b32 m0, s54
	v_lshl_add_u64 v[182:183], s[14:15], 0, v[132:133]
	s_add_u32 s82, s14, 0x20000
	ds_read_b128 v[178:181], v142 offset:16384
	ds_read_b128 v[188:191], v142 offset:17408
	ds_read_b128 v[192:195], v142 offset:18432
	ds_read_b128 v[196:199], v142 offset:19456
	ds_read_b128 v[200:203], v142 offset:20480
	ds_read_b128 v[204:207], v142 offset:21504
	ds_read_b128 v[208:211], v142 offset:22528
	ds_read_b128 v[212:215], v142 offset:23552
	global_load_lds_dwordx4 v[182:183], off
	v_lshl_add_u64 v[184:185], s[14:15], 0, v[128:129]
	s_mov_b32 m0, s55
	s_addc_u32 s83, s15, 0
	global_load_lds_dwordx4 v[184:185], off
	v_lshl_add_u64 v[186:187], s[82:83], 0, v[132:133]
	s_mov_b32 m0, s56
	v_lshl_add_u64 v[216:217], s[38:39], 0, v[130:131]
	global_load_lds_dwordx4 v[186:187], off
	v_lshl_add_u64 v[186:187], s[82:83], 0, v[128:129]
	s_mov_b32 m0, s57
	s_nop 0
	global_load_lds_dwordx4 v[186:187], off
	v_lshl_add_u64 v[186:187], s[38:39], 0, v[134:135]
	s_mov_b32 m0, s41
	s_nop 0
	global_load_lds_dwordx4 v[186:187], off
	s_mov_b32 m0, s43
	s_nop 0
	global_load_lds_dwordx4 v[216:217], off
	s_waitcnt vmcnt(8)
	s_waitcnt lgkmcnt(0)
	s_barrier
; #define G_STAGE(bufoff, gbase, voff) do { _Pragma("unroll") for (int _i = 0; _i < 2; ++_i) \
;         __builtin_amdgcn_global_load_lds((const unsigned*)((const char*)(gbase) + voff[_i]), (LAS unsigned*)(lds + (bufoff) + ldsw + _i * 8192), 16, 0, 0); } while (0)
; #define G_LDA(dst, b, h) do { _Pragma("unroll") for (int m = 0; m < 4; ++m) _Pragma("unroll") for (int k = 0; k < 2; ++k) dst[m][k] = *(const LAS bf16x8*)(lds + G_SA(b, h) + aoff + m * 2048 + k * 1024); } while (0)
; #define G_LDB(dst, b, h) do { _Pragma("unroll") for (int n = 0; n < 2; ++n) _Pragma("unroll") for (int k = 0; k < 2; ++k) dst[n][k] = *(const LAS bf16x8*)(lds + G_SB(b, h) + boff + n * 2048 + k * 1024); } while (0)
; #define G_MMA(ai, bj, At_, Bt_) do { __builtin_amdgcn_s_setprio(1); _Pragma("unroll") for (int m = 0; m < 4; ++m) _Pragma("unroll") for (int n = 0; n < 2; ++n) _Pragma("unroll") for (int k = 0; k < 2; ++k) \
;         acc[ai][bj][m][n] = __builtin_amdgcn_mfma_f32_16x16x32_bf16(Bt_[n][k], At_[m][k], acc[ai][bj][m][n], 0, 0, 0); __builtin_amdgcn_s_setprio(0); } while (0)
; #define WAIT_V(n) asm volatile("s_waitcnt vmcnt(" #n ")" ::: "memory")
; #define WAIT_L(n) asm volatile("s_waitcnt lgkmcnt(" #n ")" ::: "memory")
; #define BAR __builtin_amdgcn_s_barrier()
; #define SCHED __builtin_amdgcn_sched_barrier(0)
; template <class Get, class Epi>
; DI void gemm_loop(int ntiles, int ld, char* shm, const Get& get, const Epi& epi) {
;     ...
;             WAIT_V(8); WAIT_L(0); BAR; G_MMA(0, 0, At, B0); G_MMA(0, 1, At, B1); BAR; SCHED;
;             G_LDA(At, 0, 1); G_STAGE(G_SB(0, 0), b2, voffB); G_STAGE(G_SB(0, 1), b2 + hstep, voffB); G_STAGE(G_SA(0, 0), a2, voffA);
;             WAIT_V(8); WAIT_L(0); BAR; G_MMA(1, 0, At, B0); G_MMA(1, 1, At, B1); BAR; SCHED;
;             G_LDB(B0, 1, 0); G_LDB(B1, 1, 1); SCHED; G_LDA(At, 1, 0); G_STAGE(G_SA(0, 1), a2 + hstep, voffA);
;             WAIT_V(8); WAIT_L(0); BAR; G_MMA(0, 0, At, B0); G_MMA(0, 1, At, B1); BAR; SCHED;
	s_setprio 1
	s_waitcnt lgkmcnt(0)
	v_mfma_f32_16x16x32_bf16 v[60:63], v[146:149], v[178:181], 0
	v_mfma_f32_16x16x32_bf16 v[56:59], v[154:157], v[178:181], 0
	v_mfma_f32_16x16x32_bf16 v[52:55], v[146:149], v[192:195], 0
	v_mfma_f32_16x16x32_bf16 v[48:51], v[154:157], v[192:195], 0
	v_mfma_f32_16x16x32_bf16 v[36:39], v[146:149], v[200:203], 0
	v_mfma_f32_16x16x32_bf16 v[32:35], v[154:157], v[200:203], 0
	v_mfma_f32_16x16x32_bf16 v[20:23], v[146:149], v[208:211], 0
	v_mfma_f32_16x16x32_bf16 v[16:19], v[154:157], v[208:211], 0
	v_mfma_f32_16x16x32_bf16 v[60:63], v[150:153], v[188:191], v[60:63]
	v_mfma_f32_16x16x32_bf16 v[56:59], v[158:161], v[188:191], v[56:59]
	v_mfma_f32_16x16x32_bf16 v[52:55], v[150:153], v[196:199], v[52:55]
	v_mfma_f32_16x16x32_bf16 v[48:51], v[158:161], v[196:199], v[48:51]
	v_mfma_f32_16x16x32_bf16 v[36:39], v[150:153], v[204:207], v[36:39]
	v_mfma_f32_16x16x32_bf16 v[32:35], v[158:161], v[204:207], v[32:35]
	v_mfma_f32_16x16x32_bf16 v[20:23], v[150:153], v[212:215], v[20:23]
	v_mfma_f32_16x16x32_bf16 v[16:19], v[158:161], v[212:215], v[16:19]
	s_setprio 0
	s_setprio 1
	v_mfma_f32_16x16x32_bf16 v[44:47], v[162:165], v[178:181], 0
	v_mfma_f32_16x16x32_bf16 v[40:43], v[170:173], v[178:181], 0
	v_mfma_f32_16x16x32_bf16 v[28:31], v[162:165], v[192:195], 0
	v_mfma_f32_16x16x32_bf16 v[24:27], v[170:173], v[192:195], 0
	v_mfma_f32_16x16x32_bf16 v[12:15], v[162:165], v[200:203], 0
	v_mfma_f32_16x16x32_bf16 v[8:11], v[170:173], v[200:203], 0
	v_mfma_f32_16x16x32_bf16 v[4:7], v[162:165], v[208:211], 0
	v_mfma_f32_16x16x32_bf16 v[0:3], v[170:173], v[208:211], 0
	v_mfma_f32_16x16x32_bf16 v[44:47], v[166:169], v[188:191], v[44:47]
	v_mfma_f32_16x16x32_bf16 v[40:43], v[174:177], v[188:191], v[40:43]
	v_mfma_f32_16x16x32_bf16 v[28:31], v[166:169], v[196:199], v[28:31]
	v_mfma_f32_16x16x32_bf16 v[24:27], v[174:177], v[196:199], v[24:27]
	v_mfma_f32_16x16x32_bf16 v[12:15], v[166:169], v[204:207], v[12:15]
	v_mfma_f32_16x16x32_bf16 v[8:11], v[174:177], v[204:207], v[8:11]
	v_mfma_f32_16x16x32_bf16 v[4:7], v[166:169], v[212:215], v[4:7]
	v_mfma_f32_16x16x32_bf16 v[0:3], v[174:177], v[212:215], v[0:3]
	s_setprio 0
	s_barrier
	ds_read_b128 v[146:149], v143
	ds_read_b128 v[150:153], v143 offset:1024
	ds_read_b128 v[154:157], v143 offset:2048
	ds_read_b128 v[158:161], v143 offset:3072
	ds_read_b128 v[162:165], v144
	ds_read_b128 v[166:169], v144 offset:1024
	ds_read_b128 v[170:173], v144 offset:2048
	ds_read_b128 v[174:177], v144 offset:3072
	s_add_u32 s38, s38, 0x20000
	s_addc_u32 s39, s39, 0
	s_mov_b32 m0, s44
	v_lshl_add_u64 v[218:219], s[38:39], 0, v[134:135]
	ds_read_b128 v[178:181], v142 offset:32768
	ds_read_b128 v[188:191], v142 offset:33792
	ds_read_b128 v[192:195], v142 offset:34816
	ds_read_b128 v[196:199], v142 offset:35840
	ds_read_b128 v[200:203], v142 offset:36864
	ds_read_b128 v[204:207], v142 offset:37888
	ds_read_b128 v[208:211], v142 offset:38912
	ds_read_b128 v[212:215], v142 offset:39936
	global_load_lds_dwordx4 v[218:219], off
	v_lshl_add_u64 v[218:219], s[38:39], 0, v[130:131]
	s_mov_b32 m0, s45
	s_nop 0
	global_load_lds_dwordx4 v[218:219], off
	s_waitcnt vmcnt(8)
	s_waitcnt lgkmcnt(0)
	s_barrier
	s_setprio 1
	s_waitcnt lgkmcnt(0)
	v_mfma_f32_16x16x32_bf16 v[124:127], v[146:149], v[178:181], v[124:127]
	v_mfma_f32_16x16x32_bf16 v[120:123], v[154:157], v[178:181], v[120:123]
	v_mfma_f32_16x16x32_bf16 v[116:119], v[146:149], v[192:195], v[116:119]
	v_mfma_f32_16x16x32_bf16 v[112:115], v[154:157], v[192:195], v[112:115]
	v_mfma_f32_16x16x32_bf16 v[100:103], v[146:149], v[200:203], v[100:103]
	v_mfma_f32_16x16x32_bf16 v[96:99], v[154:157], v[200:203], v[96:99]
	v_mfma_f32_16x16x32_bf16 v[84:87], v[146:149], v[208:211], v[84:87]
	v_mfma_f32_16x16x32_bf16 v[80:83], v[154:157], v[208:211], v[80:83]
	v_mfma_f32_16x16x32_bf16 v[124:127], v[150:153], v[188:191], v[124:127]
	v_mfma_f32_16x16x32_bf16 v[120:123], v[158:161], v[188:191], v[120:123]
	v_mfma_f32_16x16x32_bf16 v[116:119], v[150:153], v[196:199], v[116:119]
	v_mfma_f32_16x16x32_bf16 v[112:115], v[158:161], v[196:199], v[112:115]
	v_mfma_f32_16x16x32_bf16 v[100:103], v[150:153], v[204:207], v[100:103]
	v_mfma_f32_16x16x32_bf16 v[96:99], v[158:161], v[204:207], v[96:99]
	v_mfma_f32_16x16x32_bf16 v[84:87], v[150:153], v[212:215], v[84:87]
	v_mfma_f32_16x16x32_bf16 v[80:83], v[158:161], v[212:215], v[80:83]
	s_setprio 0
	s_setprio 1
	v_mfma_f32_16x16x32_bf16 v[108:111], v[162:165], v[178:181], v[108:111]
	v_mfma_f32_16x16x32_bf16 v[104:107], v[170:173], v[178:181], v[104:107]
	v_mfma_f32_16x16x32_bf16 v[92:95], v[162:165], v[192:195], v[92:95]
	v_mfma_f32_16x16x32_bf16 v[88:91], v[170:173], v[192:195], v[88:91]
	v_mfma_f32_16x16x32_bf16 v[76:79], v[162:165], v[200:203], v[76:79]
	v_mfma_f32_16x16x32_bf16 v[72:75], v[170:173], v[200:203], v[72:75]
	v_mfma_f32_16x16x32_bf16 v[68:71], v[162:165], v[208:211], v[68:71]
	v_mfma_f32_16x16x32_bf16 v[64:67], v[170:173], v[208:211], v[64:67]
	v_mfma_f32_16x16x32_bf16 v[108:111], v[166:169], v[188:191], v[108:111]
	v_mfma_f32_16x16x32_bf16 v[104:107], v[174:177], v[188:191], v[104:107]
	v_mfma_f32_16x16x32_bf16 v[92:95], v[166:169], v[196:199], v[92:95]
	v_mfma_f32_16x16x32_bf16 v[88:91], v[174:177], v[196:199], v[88:91]
	v_mfma_f32_16x16x32_bf16 v[76:79], v[166:169], v[204:207], v[76:79]
	v_mfma_f32_16x16x32_bf16 v[72:75], v[174:177], v[204:207], v[72:75]
	v_mfma_f32_16x16x32_bf16 v[68:71], v[166:169], v[212:215], v[68:71]
	v_mfma_f32_16x16x32_bf16 v[64:67], v[174:177], v[212:215], v[64:67]
	s_setprio 0
	s_barrier
; #define G_STAGE(bufoff, gbase, voff) do { _Pragma("unroll") for (int _i = 0; _i < 2; ++_i) \
;         __builtin_amdgcn_global_load_lds((const unsigned*)((const char*)(gbase) + voff[_i]), (LAS unsigned*)(lds + (bufoff) + ldsw + _i * 8192), 16, 0, 0); } while (0)
; #define G_LDA(dst, b, h) do { _Pragma("unroll") for (int m = 0; m < 4; ++m) _Pragma("unroll") for (int k = 0; k < 2; ++k) dst[m][k] = *(const LAS bf16x8*)(lds + G_SA(b, h) + aoff + m * 2048 + k * 1024); } while (0)
; #define G_MMA(ai, bj, At_, Bt_) do { __builtin_amdgcn_s_setprio(1); _Pragma("unroll") for (int m = 0; m < 4; ++m) _Pragma("unroll") for (int n = 0; n < 2; ++n) _Pragma("unroll") for (int k = 0; k < 2; ++k) \
;         acc[ai][bj][m][n] = __builtin_amdgcn_mfma_f32_16x16x32_bf16(Bt_[n][k], At_[m][k], acc[ai][bj][m][n], 0, 0, 0); __builtin_amdgcn_s_setprio(0); } while (0)
; #define WAIT_V(n) asm volatile("s_waitcnt vmcnt(" #n ")" ::: "memory")
; #define WAIT_L(n) asm volatile("s_waitcnt lgkmcnt(" #n ")" ::: "memory")
; #define BAR __builtin_amdgcn_s_barrier()
; #define SCHED __builtin_amdgcn_sched_barrier(0)
; template <class Get, class Epi>
; DI void gemm_loop(int ntiles, int ld, char* shm, const Get& get, const Epi& epi) {
;     ...
;             G_LDA(At, 1, 1); G_STAGE(G_SB(1, 0), b3, voffB); G_STAGE(G_SB(1, 1), b3 + hstep, voffB); G_STAGE(G_SA(1, 0), a3, voffA);
;             WAIT_V(8); WAIT_L(0); BAR; G_MMA(1, 0, At, B0); G_MMA(1, 1, At, B1); BAR; SCHED;
;         }
	s_mov_b32 m0, s58
	v_lshl_add_u64 v[182:183], v[182:183], 0, s[12:13]
	s_add_u32 s14, s14, 0x20080
	ds_read_b128 v[178:181], v142 offset:49152
	ds_read_b128 v[188:191], v142 offset:50176
	ds_read_b128 v[192:195], v142 offset:51200
	ds_read_b128 v[196:199], v142 offset:52224
	ds_read_b128 v[200:203], v142 offset:53248
	ds_read_b128 v[204:207], v142 offset:54272
	ds_read_b128 v[208:211], v142 offset:55296
	ds_read_b128 v[212:215], v142 offset:56320
	global_load_lds_dwordx4 v[182:183], off
	v_lshl_add_u64 v[182:183], v[184:185], 0, s[12:13]
	s_mov_b32 m0, s59
	s_addc_u32 s15, s15, 0
	global_load_lds_dwordx4 v[182:183], off
	v_lshl_add_u64 v[182:183], s[14:15], 0, v[132:133]
	s_mov_b32 m0, s72
	s_nop 0
	global_load_lds_dwordx4 v[182:183], off
	v_lshl_add_u64 v[182:183], s[14:15], 0, v[128:129]
	s_mov_b32 m0, s73
	s_nop 0
	global_load_lds_dwordx4 v[182:183], off
	v_lshl_add_u64 v[182:183], v[186:187], 0, s[12:13]
	s_mov_b32 m0, s46
	s_nop 0
	global_load_lds_dwordx4 v[182:183], off
	v_lshl_add_u64 v[182:183], v[216:217], 0, s[12:13]
	s_mov_b32 m0, s47
	s_nop 0
	global_load_lds_dwordx4 v[182:183], off
	s_waitcnt vmcnt(8)
	s_waitcnt lgkmcnt(0)
	s_barrier
	s_setprio 1
	s_waitcnt lgkmcnt(0)
	v_mfma_f32_16x16x32_bf16 v[60:63], v[146:149], v[178:181], v[60:63]
	v_mfma_f32_16x16x32_bf16 v[56:59], v[154:157], v[178:181], v[56:59]
	v_mfma_f32_16x16x32_bf16 v[52:55], v[146:149], v[192:195], v[52:55]
	v_mfma_f32_16x16x32_bf16 v[48:51], v[154:157], v[192:195], v[48:51]
	v_mfma_f32_16x16x32_bf16 v[36:39], v[146:149], v[200:203], v[36:39]
	v_mfma_f32_16x16x32_bf16 v[32:35], v[154:157], v[200:203], v[32:35]
	v_mfma_f32_16x16x32_bf16 v[20:23], v[146:149], v[208:211], v[20:23]
	v_mfma_f32_16x16x32_bf16 v[16:19], v[154:157], v[208:211], v[16:19]
	v_mfma_f32_16x16x32_bf16 v[60:63], v[150:153], v[188:191], v[60:63]
	v_mfma_f32_16x16x32_bf16 v[56:59], v[158:161], v[188:191], v[56:59]
	v_mfma_f32_16x16x32_bf16 v[52:55], v[150:153], v[196:199], v[52:55]
	v_mfma_f32_16x16x32_bf16 v[48:51], v[158:161], v[196:199], v[48:51]
	v_mfma_f32_16x16x32_bf16 v[36:39], v[150:153], v[204:207], v[36:39]
	v_mfma_f32_16x16x32_bf16 v[32:35], v[158:161], v[204:207], v[32:35]
	v_mfma_f32_16x16x32_bf16 v[20:23], v[150:153], v[212:215], v[20:23]
	v_mfma_f32_16x16x32_bf16 v[16:19], v[158:161], v[212:215], v[16:19]
	s_setprio 0
	s_setprio 1
	v_mfma_f32_16x16x32_bf16 v[44:47], v[162:165], v[178:181], v[44:47]
	v_mfma_f32_16x16x32_bf16 v[40:43], v[170:173], v[178:181], v[40:43]
	v_mfma_f32_16x16x32_bf16 v[28:31], v[162:165], v[192:195], v[28:31]
	v_mfma_f32_16x16x32_bf16 v[24:27], v[170:173], v[192:195], v[24:27]
	v_mfma_f32_16x16x32_bf16 v[12:15], v[162:165], v[200:203], v[12:15]
	v_mfma_f32_16x16x32_bf16 v[8:11], v[170:173], v[200:203], v[8:11]
	v_mfma_f32_16x16x32_bf16 v[4:7], v[162:165], v[208:211], v[4:7]
	v_mfma_f32_16x16x32_bf16 v[0:3], v[170:173], v[208:211], v[0:3]
	v_mfma_f32_16x16x32_bf16 v[44:47], v[166:169], v[188:191], v[44:47]
	v_mfma_f32_16x16x32_bf16 v[40:43], v[174:177], v[188:191], v[40:43]
	v_mfma_f32_16x16x32_bf16 v[28:31], v[166:169], v[196:199], v[28:31]
	v_mfma_f32_16x16x32_bf16 v[24:27], v[174:177], v[196:199], v[24:27]
	v_mfma_f32_16x16x32_bf16 v[12:15], v[166:169], v[204:207], v[12:15]
	v_mfma_f32_16x16x32_bf16 v[8:11], v[174:177], v[204:207], v[8:11]
	v_mfma_f32_16x16x32_bf16 v[4:7], v[166:169], v[212:215], v[4:7]
	v_mfma_f32_16x16x32_bf16 v[0:3], v[174:177], v[212:215], v[0:3]
	s_setprio 0
	s_barrier
	s_add_i32 s81, s81, 2
	s_add_u32 s36, s36, 0x100
	s_addc_u32 s37, s37, 0
	s_add_u32 s79, s79, 0x100
	s_addc_u32 s80, s80, 0
	s_cmp_gt_u32 s81, 5
	s_cbranch_scc0 .LBB0_445
	s_branch .Lpost_445

; #define BAR __builtin_amdgcn_s_barrier()
; template <class Get, class Epi>
; DI void gemm_loop(int ntiles, int ld, char* shm, const Get& get, const Epi& epi) {
;     ...
;         }
;         if (wr == 0) BAR;
.Lpost_445:
	s_and_b64 vcc, exec, s[28:29]
	s_cbranch_vccz .LBB0_448
	s_barrier

; #define G_STAGE(bufoff, gbase, voff) do { _Pragma("unroll") for (int _i = 0; _i < 2; ++_i) \
;         __builtin_amdgcn_global_load_lds((const unsigned*)((const char*)(gbase) + voff[_i]), (LAS unsigned*)(lds + (bufoff) + ldsw + _i * 8192), 16, 0, 0); } while (0)
; #define G_LDA(dst, b, h) do { _Pragma("unroll") for (int m = 0; m < 4; ++m) _Pragma("unroll") for (int k = 0; k < 2; ++k) dst[m][k] = *(const LAS bf16x8*)(lds + G_SA(b, h) + aoff + m * 2048 + k * 1024); } while (0)
; #define G_LDB(dst, b, h) do { _Pragma("unroll") for (int n = 0; n < 2; ++n) _Pragma("unroll") for (int k = 0; k < 2; ++k) dst[n][k] = *(const LAS bf16x8*)(lds + G_SB(b, h) + boff + n * 2048 + k * 1024); } while (0)
; #define G_MMA(ai, bj, At_, Bt_) do { __builtin_amdgcn_s_setprio(1); _Pragma("unroll") for (int m = 0; m < 4; ++m) _Pragma("unroll") for (int n = 0; n < 2; ++n) _Pragma("unroll") for (int k = 0; k < 2; ++k) \
;         acc[ai][bj][m][n] = __builtin_amdgcn_mfma_f32_16x16x32_bf16(Bt_[n][k], At_[m][k], acc[ai][bj][m][n], 0, 0, 0); __builtin_amdgcn_s_setprio(0); } while (0)
; #define WAIT_V(n) asm volatile("s_waitcnt vmcnt(" #n ")" ::: "memory")
; #define WAIT_L(n) asm volatile("s_waitcnt lgkmcnt(" #n ")" ::: "memory")
; #define BAR __builtin_amdgcn_s_barrier()
; template <class Get, class Epi>
; DI void gemm_loop(int ntiles, int ld, char* shm, const Get& get, const Epi& epi) {
;     ...
;         const int Ln = L + gridDim.x; const bool has_next = Ln < ntiles; if (has_next) nxt = get(Ln);
;         const char* nA = has_next ? (const char*)nxt.A + (size_t)nxt.brow * ld * 2 : cA; const char* nB = has_next ? (const char*)nxt.Bt + (size_t)nxt.bcol * ld * 2 : cB;
;         const int nt = cur.K / BK;
;         for (int t = 0; t < nt; t += 2) {
;             const bool last = (t == nt - 2);
;             const char* a1 = cA + (size_t)(t + 1) * kstep;
;             const char* a2 = last ? nA : cA + (size_t)(t + 2) * kstep; const char* b2 = last ? nB : cB + (size_t)(t + 2) * kstep;
;             const char* a3 = a2 + kstep; const char* b3 = b2 + kstep;
;             G_LDB(B0, 0, 0); G_LDB(B1, 0, 1); SCHED; G_LDA(At, 0, 0); G_STAGE(G_SA(1, 1), a1 + hstep, voffA);
;             WAIT_V(8); WAIT_L(0); BAR; G_MMA(0, 0, At, B0); G_MMA(0, 1, At, B1); BAR; SCHED;
;             G_LDA(At, 0, 1); G_STAGE(G_SB(0, 0), b2, voffB); G_STAGE(G_SB(0, 1), b2 + hstep, voffB); G_STAGE(G_SA(0, 0), a2, voffA);
.LBB0_527:
	s_ashr_i32 s35, s34, 31
	s_lshl_b64 s[38:39], s[34:35], 11
	s_add_u32 s38, s4, s38
	s_addc_u32 s39, s5, s39
	s_and_b64 s[40:41], s[90:91], exec
	s_cselect_b32 s3, s39, s45
	s_cselect_b32 s35, s38, s44
	s_ashr_i32 s37, s36, 31
	s_lshl_b64 s[40:41], s[36:37], 11
	s_add_u32 s40, s6, s40
	s_addc_u32 s41, s7, s41
	s_and_b64 s[54:55], s[90:91], exec
	s_cselect_b32 s37, s41, s15
	s_cselect_b32 s43, s40, s14
	s_lshr_b32 s51, s46, 6
	s_add_i32 s54, s51, -2
	s_add_u32 s44, s44, 0x40080
	s_addc_u32 s45, s45, 0
	s_add_u32 s55, s14, 0x100
	s_addc_u32 s82, s15, 0
	s_mov_b32 s14, 0
.Lpeel_528:
	ds_read_b128 v[128:131], v177
	ds_read_b128 v[132:135], v177 offset:1024
	ds_read_b128 v[136:139], v177 offset:2048
	ds_read_b128 v[140:143], v177 offset:3072
	ds_read_b128 v[144:147], v178
	ds_read_b128 v[148:151], v178 offset:1024
	ds_read_b128 v[164:167], v178 offset:2048
	ds_read_b128 v[168:171], v178 offset:3072
	s_add_i32 s83, s14, 2
	s_add_u32 s15, s44, 0xfffc0080
	s_addc_u32 s46, s45, -1
	s_cmp_eq_u32 s54, s14
	s_cselect_b32 s14, s43, s55
	s_cselect_b32 s47, s3, s46
	s_cselect_b32 s46, s35, s15
	s_cselect_b32 s15, s37, s82
	v_lshl_add_u64 v[184:185], s[44:45], 0, v[160:161]
	s_add_i32 m0, s57, 0xc000
	ds_read_b128 v[172:175], v179
	ds_read_b128 v[180:183], v179 offset:1024
	ds_read_b128 v[188:191], v179 offset:2048
	ds_read_b128 v[192:195], v179 offset:3072
	ds_read_b128 v[196:199], v179 offset:4096
	ds_read_b128 v[200:203], v179 offset:5120
	ds_read_b128 v[204:207], v179 offset:6144
	ds_read_b128 v[208:211], v179 offset:7168
	global_load_lds_dwordx4 v[184:185], off
	v_lshl_add_u64 v[184:185], s[44:45], 0, v[162:163]
	s_add_i32 m0, s57, 0xe000
	s_nop 0
	global_load_lds_dwordx4 v[184:185], off
	s_waitcnt vmcnt(8)
	s_waitcnt lgkmcnt(0)
	s_barrier
	s_setprio 1
	s_waitcnt lgkmcnt(0)
	v_mfma_f32_16x16x32_bf16 v[124:127], v[128:131], v[172:175], 0
	v_mfma_f32_16x16x32_bf16 v[120:123], v[136:139], v[172:175], 0
	v_mfma_f32_16x16x32_bf16 v[116:119], v[128:131], v[188:191], 0
	v_mfma_f32_16x16x32_bf16 v[112:115], v[136:139], v[188:191], 0
	v_mfma_f32_16x16x32_bf16 v[108:111], v[128:131], v[196:199], 0
	v_mfma_f32_16x16x32_bf16 v[104:107], v[136:139], v[196:199], 0
	v_mfma_f32_16x16x32_bf16 v[100:103], v[128:131], v[204:207], 0
	v_mfma_f32_16x16x32_bf16 v[96:99], v[136:139], v[204:207], 0
	v_mfma_f32_16x16x32_bf16 v[124:127], v[132:135], v[180:183], v[124:127]
	v_mfma_f32_16x16x32_bf16 v[120:123], v[140:143], v[180:183], v[120:123]
	v_mfma_f32_16x16x32_bf16 v[116:119], v[132:135], v[192:195], v[116:119]
	v_mfma_f32_16x16x32_bf16 v[112:115], v[140:143], v[192:195], v[112:115]
	v_mfma_f32_16x16x32_bf16 v[108:111], v[132:135], v[200:203], v[108:111]
	v_mfma_f32_16x16x32_bf16 v[104:107], v[140:143], v[200:203], v[104:107]
	v_mfma_f32_16x16x32_bf16 v[100:103], v[132:135], v[208:211], v[100:103]
	v_mfma_f32_16x16x32_bf16 v[96:99], v[140:143], v[208:211], v[96:99]
	s_setprio 0
	s_setprio 1
	v_mfma_f32_16x16x32_bf16 v[60:63], v[144:147], v[172:175], 0
	v_mfma_f32_16x16x32_bf16 v[56:59], v[164:167], v[172:175], 0
	v_mfma_f32_16x16x32_bf16 v[52:55], v[144:147], v[188:191], 0
	v_mfma_f32_16x16x32_bf16 v[48:51], v[164:167], v[188:191], 0
	v_mfma_f32_16x16x32_bf16 v[44:47], v[144:147], v[196:199], 0
	v_mfma_f32_16x16x32_bf16 v[40:43], v[164:167], v[196:199], 0
	v_mfma_f32_16x16x32_bf16 v[36:39], v[144:147], v[204:207], 0
	v_mfma_f32_16x16x32_bf16 v[32:35], v[164:167], v[204:207], 0
	v_mfma_f32_16x16x32_bf16 v[60:63], v[148:151], v[180:183], v[60:63]
	v_mfma_f32_16x16x32_bf16 v[56:59], v[168:171], v[180:183], v[56:59]
	v_mfma_f32_16x16x32_bf16 v[52:55], v[148:151], v[192:195], v[52:55]
	v_mfma_f32_16x16x32_bf16 v[48:51], v[168:171], v[192:195], v[48:51]
	v_mfma_f32_16x16x32_bf16 v[44:47], v[148:151], v[200:203], v[44:47]
	v_mfma_f32_16x16x32_bf16 v[40:43], v[168:171], v[200:203], v[40:43]
	v_mfma_f32_16x16x32_bf16 v[36:39], v[148:151], v[208:211], v[36:39]
	v_mfma_f32_16x16x32_bf16 v[32:35], v[168:171], v[208:211], v[32:35]
	s_setprio 0
	s_barrier
	s_add_i32 s84, s78, s56
	v_lshl_add_u64 v[184:185], s[14:15], 0, v[154:155]
	s_mov_b32 m0, s84
	ds_read_b128 v[172:175], v179 offset:16384
	ds_read_b128 v[180:183], v179 offset:17408
	ds_read_b128 v[188:191], v179 offset:18432
	ds_read_b128 v[192:195], v179 offset:19456
	ds_read_b128 v[196:199], v179 offset:20480
	ds_read_b128 v[200:203], v179 offset:21504
	ds_read_b128 v[204:207], v179 offset:22528
	ds_read_b128 v[208:211], v179 offset:23552
	global_load_lds_dwordx4 v[184:185], off
	s_add_i32 m0, s84, 0x2000
	s_add_u32 s84, s14, 0x40000
	v_lshl_add_u64 v[186:187], s[14:15], 0, v[158:159]
	s_addc_u32 s85, s15, 0
	s_add_i32 s86, s79, s56
	global_load_lds_dwordx4 v[186:187], off
	v_lshl_add_u64 v[212:213], s[84:85], 0, v[154:155]
	s_mov_b32 m0, s86
	v_lshl_add_u64 v[214:215], s[46:47], 0, v[156:157]
	global_load_lds_dwordx4 v[212:213], off
	v_lshl_add_u64 v[212:213], s[84:85], 0, v[158:159]
	s_add_i32 m0, s86, 0x2000
	s_nop 0
	global_load_lds_dwordx4 v[212:213], off
	v_lshl_add_u64 v[212:213], s[46:47], 0, v[152:153]
	s_mov_b32 m0, s57
	s_nop 0
	global_load_lds_dwordx4 v[212:213], off
	s_mov_b32 m0, s58
	s_nop 0
	global_load_lds_dwordx4 v[214:215], off
	s_waitcnt vmcnt(8)
	s_waitcnt lgkmcnt(0)
	s_barrier
; #define G_STAGE(bufoff, gbase, voff) do { _Pragma("unroll") for (int _i = 0; _i < 2; ++_i) \
;         __builtin_amdgcn_global_load_lds((const unsigned*)((const char*)(gbase) + voff[_i]), (LAS unsigned*)(lds + (bufoff) + ldsw + _i * 8192), 16, 0, 0); } while (0)
; #define G_LDA(dst, b, h) do { _Pragma("unroll") for (int m = 0; m < 4; ++m) _Pragma("unroll") for (int k = 0; k < 2; ++k) dst[m][k] = *(const LAS bf16x8*)(lds + G_SA(b, h) + aoff + m * 2048 + k * 1024); } while (0)
; #define G_LDB(dst, b, h) do { _Pragma("unroll") for (int n = 0; n < 2; ++n) _Pragma("unroll") for (int k = 0; k < 2; ++k) dst[n][k] = *(const LAS bf16x8*)(lds + G_SB(b, h) + boff + n * 2048 + k * 1024); } while (0)
; #define G_MMA(ai, bj, At_, Bt_) do { __builtin_amdgcn_s_setprio(1); _Pragma("unroll") for (int m = 0; m < 4; ++m) _Pragma("unroll") for (int n = 0; n < 2; ++n) _Pragma("unroll") for (int k = 0; k < 2; ++k) \
;         acc[ai][bj][m][n] = __builtin_amdgcn_mfma_f32_16x16x32_bf16(Bt_[n][k], At_[m][k], acc[ai][bj][m][n], 0, 0, 0); __builtin_amdgcn_s_setprio(0); } while (0)
; #define WAIT_V(n) asm volatile("s_waitcnt vmcnt(" #n ")" ::: "memory")
; #define WAIT_L(n) asm volatile("s_waitcnt lgkmcnt(" #n ")" ::: "memory")
; #define BAR __builtin_amdgcn_s_barrier()
; #define SCHED __builtin_amdgcn_sched_barrier(0)
; template <class Get, class Epi>
; DI void gemm_loop(int ntiles, int ld, char* shm, const Get& get, const Epi& epi) {
;     ...
;             WAIT_V(8); WAIT_L(0); BAR; G_MMA(1, 0, At, B0); G_MMA(1, 1, At, B1); BAR; SCHED;
;             G_LDB(B0, 1, 0); G_LDB(B1, 1, 1); SCHED; G_LDA(At, 1, 0); G_STAGE(G_SA(0, 1), a2 + hstep, voffA);
;             WAIT_V(8); WAIT_L(0); BAR; G_MMA(0, 0, At, B0); G_MMA(0, 1, At, B1); BAR; SCHED;
	s_setprio 1
	s_waitcnt lgkmcnt(0)
	v_mfma_f32_16x16x32_bf16 v[92:95], v[128:131], v[172:175], 0
	v_mfma_f32_16x16x32_bf16 v[88:91], v[136:139], v[172:175], 0
	v_mfma_f32_16x16x32_bf16 v[84:87], v[128:131], v[188:191], 0
	v_mfma_f32_16x16x32_bf16 v[80:83], v[136:139], v[188:191], 0
	v_mfma_f32_16x16x32_bf16 v[76:79], v[128:131], v[196:199], 0
	v_mfma_f32_16x16x32_bf16 v[72:75], v[136:139], v[196:199], 0
	v_mfma_f32_16x16x32_bf16 v[68:71], v[128:131], v[204:207], 0
	v_mfma_f32_16x16x32_bf16 v[64:67], v[136:139], v[204:207], 0
	v_mfma_f32_16x16x32_bf16 v[92:95], v[132:135], v[180:183], v[92:95]
	v_mfma_f32_16x16x32_bf16 v[88:91], v[140:143], v[180:183], v[88:91]
	v_mfma_f32_16x16x32_bf16 v[84:87], v[132:135], v[192:195], v[84:87]
	v_mfma_f32_16x16x32_bf16 v[80:83], v[140:143], v[192:195], v[80:83]
	v_mfma_f32_16x16x32_bf16 v[76:79], v[132:135], v[200:203], v[76:79]
	v_mfma_f32_16x16x32_bf16 v[72:75], v[140:143], v[200:203], v[72:75]
	v_mfma_f32_16x16x32_bf16 v[68:71], v[132:135], v[208:211], v[68:71]
	v_mfma_f32_16x16x32_bf16 v[64:67], v[140:143], v[208:211], v[64:67]
	s_setprio 0
	s_setprio 1
	v_mfma_f32_16x16x32_bf16 v[28:31], v[144:147], v[172:175], 0
	v_mfma_f32_16x16x32_bf16 v[24:27], v[164:167], v[172:175], 0
	v_mfma_f32_16x16x32_bf16 v[20:23], v[144:147], v[188:191], 0
	v_mfma_f32_16x16x32_bf16 v[16:19], v[164:167], v[188:191], 0
	v_mfma_f32_16x16x32_bf16 v[12:15], v[144:147], v[196:199], 0
	v_mfma_f32_16x16x32_bf16 v[8:11], v[164:167], v[196:199], 0
	v_mfma_f32_16x16x32_bf16 v[4:7], v[144:147], v[204:207], 0
	v_mfma_f32_16x16x32_bf16 v[0:3], v[164:167], v[204:207], 0
	v_mfma_f32_16x16x32_bf16 v[28:31], v[148:151], v[180:183], v[28:31]
	v_mfma_f32_16x16x32_bf16 v[24:27], v[168:171], v[180:183], v[24:27]
	v_mfma_f32_16x16x32_bf16 v[20:23], v[148:151], v[192:195], v[20:23]
	v_mfma_f32_16x16x32_bf16 v[16:19], v[168:171], v[192:195], v[16:19]
	v_mfma_f32_16x16x32_bf16 v[12:15], v[148:151], v[200:203], v[12:15]
	v_mfma_f32_16x16x32_bf16 v[8:11], v[168:171], v[200:203], v[8:11]
	v_mfma_f32_16x16x32_bf16 v[4:7], v[148:151], v[208:211], v[4:7]
	v_mfma_f32_16x16x32_bf16 v[0:3], v[168:171], v[208:211], v[0:3]
	s_setprio 0
	s_barrier
	s_add_i32 s84, 0, 0x18000
	s_add_i32 s85, 0, 0x1c000
	v_add_u32_e32 v140, s84, v176
	v_add_u32_e32 v168, s85, v176
	ds_read_b128 v[128:131], v140
	ds_read_b128 v[132:135], v140 offset:1024
	ds_read_b128 v[136:139], v140 offset:2048
	ds_read_b128 v[140:143], v140 offset:3072
	ds_read_b128 v[144:147], v168
	ds_read_b128 v[148:151], v168 offset:1024
	ds_read_b128 v[164:167], v168 offset:2048
	ds_read_b128 v[168:171], v168 offset:3072
	s_add_u32 s46, s46, 0x40000
	s_addc_u32 s47, s47, 0
	s_mov_b32 m0, s59
	v_lshl_add_u64 v[216:217], s[46:47], 0, v[152:153]
	ds_read_b128 v[172:175], v179 offset:32768
	ds_read_b128 v[180:183], v179 offset:33792
	ds_read_b128 v[188:191], v179 offset:34816
	ds_read_b128 v[192:195], v179 offset:35840
	ds_read_b128 v[196:199], v179 offset:36864
	ds_read_b128 v[200:203], v179 offset:37888
	ds_read_b128 v[204:207], v179 offset:38912
	ds_read_b128 v[208:211], v179 offset:39936
	global_load_lds_dwordx4 v[216:217], off
	v_lshl_add_u64 v[216:217], s[46:47], 0, v[156:157]
	s_mov_b32 m0, s72
	s_nop 0
	global_load_lds_dwordx4 v[216:217], off
	s_waitcnt vmcnt(8)
	s_waitcnt lgkmcnt(0)
	s_barrier
	s_setprio 1
	s_waitcnt lgkmcnt(0)
	v_mfma_f32_16x16x32_bf16 v[124:127], v[128:131], v[172:175], v[124:127]
	v_mfma_f32_16x16x32_bf16 v[120:123], v[136:139], v[172:175], v[120:123]
	v_mfma_f32_16x16x32_bf16 v[116:119], v[128:131], v[188:191], v[116:119]
	v_mfma_f32_16x16x32_bf16 v[112:115], v[136:139], v[188:191], v[112:115]
	v_mfma_f32_16x16x32_bf16 v[108:111], v[128:131], v[196:199], v[108:111]
	v_mfma_f32_16x16x32_bf16 v[104:107], v[136:139], v[196:199], v[104:107]
	v_mfma_f32_16x16x32_bf16 v[100:103], v[128:131], v[204:207], v[100:103]
	v_mfma_f32_16x16x32_bf16 v[96:99], v[136:139], v[204:207], v[96:99]
	v_mfma_f32_16x16x32_bf16 v[124:127], v[132:135], v[180:183], v[124:127]
	v_mfma_f32_16x16x32_bf16 v[120:123], v[140:143], v[180:183], v[120:123]
	v_mfma_f32_16x16x32_bf16 v[116:119], v[132:135], v[192:195], v[116:119]
	v_mfma_f32_16x16x32_bf16 v[112:115], v[140:143], v[192:195], v[112:115]
	v_mfma_f32_16x16x32_bf16 v[108:111], v[132:135], v[200:203], v[108:111]
	v_mfma_f32_16x16x32_bf16 v[104:107], v[140:143], v[200:203], v[104:107]
	v_mfma_f32_16x16x32_bf16 v[100:103], v[132:135], v[208:211], v[100:103]
	v_mfma_f32_16x16x32_bf16 v[96:99], v[140:143], v[208:211], v[96:99]
	s_setprio 0
	s_setprio 1
	v_mfma_f32_16x16x32_bf16 v[60:63], v[144:147], v[172:175], v[60:63]
	v_mfma_f32_16x16x32_bf16 v[56:59], v[164:167], v[172:175], v[56:59]
	v_mfma_f32_16x16x32_bf16 v[52:55], v[144:147], v[188:191], v[52:55]
	v_mfma_f32_16x16x32_bf16 v[48:51], v[164:167], v[188:191], v[48:51]
	v_mfma_f32_16x16x32_bf16 v[44:47], v[144:147], v[196:199], v[44:47]
	v_mfma_f32_16x16x32_bf16 v[40:43], v[164:167], v[196:199], v[40:43]
	v_mfma_f32_16x16x32_bf16 v[36:39], v[144:147], v[204:207], v[36:39]
	v_mfma_f32_16x16x32_bf16 v[32:35], v[164:167], v[204:207], v[32:35]
	v_mfma_f32_16x16x32_bf16 v[60:63], v[148:151], v[180:183], v[60:63]
	v_mfma_f32_16x16x32_bf16 v[56:59], v[168:171], v[180:183], v[56:59]
	v_mfma_f32_16x16x32_bf16 v[52:55], v[148:151], v[192:195], v[52:55]
	v_mfma_f32_16x16x32_bf16 v[48:51], v[168:171], v[192:195], v[48:51]
	v_mfma_f32_16x16x32_bf16 v[44:47], v[148:151], v[200:203], v[44:47]
	v_mfma_f32_16x16x32_bf16 v[40:43], v[168:171], v[200:203], v[40:43]
	v_mfma_f32_16x16x32_bf16 v[36:39], v[148:151], v[208:211], v[36:39]
	v_mfma_f32_16x16x32_bf16 v[32:35], v[168:171], v[208:211], v[32:35]
	s_setprio 0
	s_barrier
; #define G_STAGE(bufoff, gbase, voff) do { _Pragma("unroll") for (int _i = 0; _i < 2; ++_i) \
;         __builtin_amdgcn_global_load_lds((const unsigned*)((const char*)(gbase) + voff[_i]), (LAS unsigned*)(lds + (bufoff) + ldsw + _i * 8192), 16, 0, 0); } while (0)
; #define G_LDA(dst, b, h) do { _Pragma("unroll") for (int m = 0; m < 4; ++m) _Pragma("unroll") for (int k = 0; k < 2; ++k) dst[m][k] = *(const LAS bf16x8*)(lds + G_SA(b, h) + aoff + m * 2048 + k * 1024); } while (0)
; #define G_MMA(ai, bj, At_, Bt_) do { __builtin_amdgcn_s_setprio(1); _Pragma("unroll") for (int m = 0; m < 4; ++m) _Pragma("unroll") for (int n = 0; n < 2; ++n) _Pragma("unroll") for (int k = 0; k < 2; ++k) \
;         acc[ai][bj][m][n] = __builtin_amdgcn_mfma_f32_16x16x32_bf16(Bt_[n][k], At_[m][k], acc[ai][bj][m][n], 0, 0, 0); __builtin_amdgcn_s_setprio(0); } while (0)
; #define WAIT_V(n) asm volatile("s_waitcnt vmcnt(" #n ")" ::: "memory")
; #define WAIT_L(n) asm volatile("s_waitcnt lgkmcnt(" #n ")" ::: "memory")
; #define BAR __builtin_amdgcn_s_barrier()
; #define SCHED __builtin_amdgcn_sched_barrier(0)
; template <class Get, class Epi>
; DI void gemm_loop(int ntiles, int ld, char* shm, const Get& get, const Epi& epi) {
;     ...
;             G_LDA(At, 1, 1); G_STAGE(G_SB(1, 0), b3, voffB); G_STAGE(G_SB(1, 1), b3 + hstep, voffB); G_STAGE(G_SA(1, 0), a3, voffA);
;             WAIT_V(8); WAIT_L(0); BAR; G_MMA(1, 0, At, B0); G_MMA(1, 1, At, B1); BAR; SCHED;
;         }
	s_add_i32 s46, s84, s56
	v_lshl_add_u64 v[184:185], v[184:185], 0, s[10:11]
	s_mov_b32 m0, s46
	ds_read_b128 v[172:175], v179 offset:49152
	ds_read_b128 v[180:183], v179 offset:50176
	ds_read_b128 v[188:191], v179 offset:51200
	ds_read_b128 v[192:195], v179 offset:52224
	ds_read_b128 v[196:199], v179 offset:53248
	ds_read_b128 v[200:203], v179 offset:54272
	ds_read_b128 v[204:207], v179 offset:55296
	ds_read_b128 v[208:211], v179 offset:56320
	global_load_lds_dwordx4 v[184:185], off
	s_add_i32 m0, s46, 0x2000
	s_add_u32 s14, s14, 0x40080
	v_lshl_add_u64 v[184:185], v[186:187], 0, s[10:11]
	s_addc_u32 s15, s15, 0
	s_add_i32 s46, s85, s56
	global_load_lds_dwordx4 v[184:185], off
	v_lshl_add_u64 v[184:185], s[14:15], 0, v[154:155]
	s_mov_b32 m0, s46
	s_nop 0
	global_load_lds_dwordx4 v[184:185], off
	v_lshl_add_u64 v[184:185], s[14:15], 0, v[158:159]
	s_add_i32 m0, s46, 0x2000
	s_nop 0
	global_load_lds_dwordx4 v[184:185], off
	v_lshl_add_u64 v[184:185], v[212:213], 0, s[10:11]
	s_mov_b32 m0, s75
	s_nop 0
	global_load_lds_dwordx4 v[184:185], off
	v_lshl_add_u64 v[184:185], v[214:215], 0, s[10:11]
	s_mov_b32 m0, s76
	s_nop 0
	global_load_lds_dwordx4 v[184:185], off
	s_waitcnt vmcnt(8)
	s_waitcnt lgkmcnt(0)
	s_barrier
	s_setprio 1
	s_waitcnt lgkmcnt(0)
	v_mfma_f32_16x16x32_bf16 v[92:95], v[128:131], v[172:175], v[92:95]
	v_mfma_f32_16x16x32_bf16 v[88:91], v[136:139], v[172:175], v[88:91]
	v_mfma_f32_16x16x32_bf16 v[84:87], v[128:131], v[188:191], v[84:87]
	v_mfma_f32_16x16x32_bf16 v[80:83], v[136:139], v[188:191], v[80:83]
	v_mfma_f32_16x16x32_bf16 v[76:79], v[128:131], v[196:199], v[76:79]
	v_mfma_f32_16x16x32_bf16 v[72:75], v[136:139], v[196:199], v[72:75]
	v_mfma_f32_16x16x32_bf16 v[68:71], v[128:131], v[204:207], v[68:71]
	v_mfma_f32_16x16x32_bf16 v[64:67], v[136:139], v[204:207], v[64:67]
	v_mfma_f32_16x16x32_bf16 v[92:95], v[132:135], v[180:183], v[92:95]
	v_mfma_f32_16x16x32_bf16 v[88:91], v[140:143], v[180:183], v[88:91]
	v_mfma_f32_16x16x32_bf16 v[84:87], v[132:135], v[192:195], v[84:87]
	v_mfma_f32_16x16x32_bf16 v[80:83], v[140:143], v[192:195], v[80:83]
	v_mfma_f32_16x16x32_bf16 v[76:79], v[132:135], v[200:203], v[76:79]
	v_mfma_f32_16x16x32_bf16 v[72:75], v[140:143], v[200:203], v[72:75]
	v_mfma_f32_16x16x32_bf16 v[68:71], v[132:135], v[208:211], v[68:71]
	v_mfma_f32_16x16x32_bf16 v[64:67], v[140:143], v[208:211], v[64:67]
	s_setprio 0
	s_setprio 1
	v_mfma_f32_16x16x32_bf16 v[28:31], v[144:147], v[172:175], v[28:31]
	v_mfma_f32_16x16x32_bf16 v[24:27], v[164:167], v[172:175], v[24:27]
	v_mfma_f32_16x16x32_bf16 v[20:23], v[144:147], v[188:191], v[20:23]
	v_mfma_f32_16x16x32_bf16 v[16:19], v[164:167], v[188:191], v[16:19]
	v_mfma_f32_16x16x32_bf16 v[12:15], v[144:147], v[196:199], v[12:15]
	v_mfma_f32_16x16x32_bf16 v[8:11], v[164:167], v[196:199], v[8:11]
	v_mfma_f32_16x16x32_bf16 v[4:7], v[144:147], v[204:207], v[4:7]
	v_mfma_f32_16x16x32_bf16 v[0:3], v[164:167], v[204:207], v[0:3]
	v_mfma_f32_16x16x32_bf16 v[28:31], v[148:151], v[180:183], v[28:31]
	v_mfma_f32_16x16x32_bf16 v[24:27], v[168:171], v[180:183], v[24:27]
	v_mfma_f32_16x16x32_bf16 v[20:23], v[148:151], v[192:195], v[20:23]
	v_mfma_f32_16x16x32_bf16 v[16:19], v[168:171], v[192:195], v[16:19]
	v_mfma_f32_16x16x32_bf16 v[12:15], v[148:151], v[200:203], v[12:15]
	v_mfma_f32_16x16x32_bf16 v[8:11], v[168:171], v[200:203], v[8:11]
	v_mfma_f32_16x16x32_bf16 v[4:7], v[148:151], v[208:211], v[4:7]
	v_mfma_f32_16x16x32_bf16 v[0:3], v[168:171], v[208:211], v[0:3]
	s_setprio 0
	s_barrier
	s_add_u32 s44, s44, 0x100
	s_addc_u32 s45, s45, 0
	s_add_u32 s55, s55, 0x100
	s_addc_u32 s82, s82, 0
	s_cmp_ge_u32 s83, s51
	s_mov_b32 s14, s83
	s_cbranch_scc0 .LBB0_528
	s_branch .Lpost_528

; #define BAR __builtin_amdgcn_s_barrier()
; template <class Get, class Epi>
; DI void gemm_loop(int ntiles, int ld, char* shm, const Get& get, const Epi& epi) {
;     ...
;         }
;         if (wr == 0) BAR;
.Lpost_528:
	s_and_b64 vcc, exec, s[12:13]
	s_cbranch_vccz .LBB0_531
	s_barrier

; #define G_STAGE(bufoff, gbase, voff) do { _Pragma("unroll") for (int _i = 0; _i < 2; ++_i) \
;         __builtin_amdgcn_global_load_lds((const unsigned*)((const char*)(gbase) + voff[_i]), (LAS unsigned*)(lds + (bufoff) + ldsw + _i * 8192), 16, 0, 0); } while (0)
; #define G_LDA(dst, b, h) do { _Pragma("unroll") for (int m = 0; m < 4; ++m) _Pragma("unroll") for (int k = 0; k < 2; ++k) dst[m][k] = *(const LAS bf16x8*)(lds + G_SA(b, h) + aoff + m * 2048 + k * 1024); } while (0)
; #define G_LDB(dst, b, h) do { _Pragma("unroll") for (int n = 0; n < 2; ++n) _Pragma("unroll") for (int k = 0; k < 2; ++k) dst[n][k] = *(const LAS bf16x8*)(lds + G_SB(b, h) + boff + n * 2048 + k * 1024); } while (0)
; #define G_MMA(ai, bj, At_, Bt_) do { __builtin_amdgcn_s_setprio(1); _Pragma("unroll") for (int m = 0; m < 4; ++m) _Pragma("unroll") for (int n = 0; n < 2; ++n) _Pragma("unroll") for (int k = 0; k < 2; ++k) \
;         acc[ai][bj][m][n] = __builtin_amdgcn_mfma_f32_16x16x32_bf16(Bt_[n][k], At_[m][k], acc[ai][bj][m][n], 0, 0, 0); __builtin_amdgcn_s_setprio(0); } while (0)
; #define WAIT_V(n) asm volatile("s_waitcnt vmcnt(" #n ")" ::: "memory")
; #define WAIT_L(n) asm volatile("s_waitcnt lgkmcnt(" #n ")" ::: "memory")
; #define BAR __builtin_amdgcn_s_barrier()
; template <class Get, class Epi>
; DI void gemm_loop(int ntiles, int ld, char* shm, const Get& get, const Epi& epi) {
;     ...
;         const int Ln = L + gridDim.x; const bool has_next = Ln < ntiles; if (has_next) nxt = get(Ln);
;         const char* nA = has_next ? (const char*)nxt.A + (size_t)nxt.brow * ld * 2 : cA; const char* nB = has_next ? (const char*)nxt.Bt + (size_t)nxt.bcol * ld * 2 : cB;
;         const int nt = cur.K / BK;
;         for (int t = 0; t < nt; t += 2) {
;             const bool last = (t == nt - 2);
;             const char* a1 = cA + (size_t)(t + 1) * kstep;
;             const char* a2 = last ? nA : cA + (size_t)(t + 2) * kstep; const char* b2 = last ? nB : cB + (size_t)(t + 2) * kstep;
;             const char* a3 = a2 + kstep; const char* b3 = b2 + kstep;
;             G_LDB(B0, 0, 0); G_LDB(B1, 0, 1); SCHED; G_LDA(At, 0, 0); G_STAGE(G_SA(1, 1), a1 + hstep, voffA);
;             WAIT_V(8); WAIT_L(0); BAR; G_MMA(0, 0, At, B0); G_MMA(0, 1, At, B1); BAR; SCHED;
;             G_LDA(At, 0, 1); G_STAGE(G_SB(0, 0), b2, voffB); G_STAGE(G_SB(0, 1), b2 + hstep, voffB); G_STAGE(G_SA(0, 0), a2, voffA);
.LBB0_762:
	s_ashr_i32 s9, s8, 31
	s_lshl_b64 s[12:13], s[8:9], 11
	s_add_u32 s12, s16, s12
	s_addc_u32 s13, s17, s13
	s_and_b64 s[28:29], s[6:7], exec
	s_cselect_b32 s9, s13, s37
	s_cselect_b32 s50, s12, s36
	s_ashr_i32 s11, s10, 31
	s_lshl_b64 s[28:29], s[10:11], 11
	s_add_u32 s28, s90, s28
	s_addc_u32 s29, s91, s29
	s_and_b64 s[38:39], s[6:7], exec
	s_cselect_b32 s11, s29, s15
	s_cselect_b32 s51, s28, s14
	s_add_u32 s36, s36, 0x40080
	s_addc_u32 s37, s37, 0
	s_add_u32 s52, s14, 0x100
	s_addc_u32 s53, s15, 0
	s_mov_b32 s54, -2
.Lpeel_763:
	ds_read_b128 v[144:147], v141
	ds_read_b128 v[148:151], v141 offset:1024
	ds_read_b128 v[152:155], v141 offset:2048
	ds_read_b128 v[156:159], v141 offset:3072
	ds_read_b128 v[160:163], v142
	ds_read_b128 v[164:167], v142 offset:1024
	ds_read_b128 v[168:171], v142 offset:2048
	ds_read_b128 v[172:175], v142 offset:3072
	s_add_u32 s14, s36, 0xfffc0080
	s_addc_u32 s15, s37, -1
	s_cmp_eq_u32 s54, 12
	s_cselect_b32 s39, s9, s15
	s_cselect_b32 s38, s50, s14
	s_cselect_b32 s15, s11, s53
	s_cselect_b32 s14, s51, s52
	v_lshl_add_u64 v[184:185], s[36:37], 0, v[136:137]
	s_add_i32 m0, s31, 0xc000
	ds_read_b128 v[176:179], v143
	ds_read_b128 v[180:183], v143 offset:1024
	ds_read_b128 v[188:191], v143 offset:2048
	ds_read_b128 v[192:195], v143 offset:3072
	ds_read_b128 v[196:199], v143 offset:4096
	ds_read_b128 v[200:203], v143 offset:5120
	ds_read_b128 v[204:207], v143 offset:6144
	ds_read_b128 v[208:211], v143 offset:7168
	global_load_lds_dwordx4 v[184:185], off
	v_lshl_add_u64 v[184:185], s[36:37], 0, v[138:139]
	s_add_i32 m0, s31, 0xe000
	s_nop 0
	global_load_lds_dwordx4 v[184:185], off
	s_waitcnt vmcnt(8)
	s_waitcnt lgkmcnt(0)
	s_barrier
	s_setprio 1
	s_waitcnt lgkmcnt(0)
	v_mfma_f32_16x16x32_bf16 v[124:127], v[144:147], v[176:179], 0
	v_mfma_f32_16x16x32_bf16 v[120:123], v[152:155], v[176:179], 0
	v_mfma_f32_16x16x32_bf16 v[108:111], v[144:147], v[188:191], 0
	v_mfma_f32_16x16x32_bf16 v[104:107], v[152:155], v[188:191], 0
	v_mfma_f32_16x16x32_bf16 v[92:95], v[144:147], v[196:199], 0
	v_mfma_f32_16x16x32_bf16 v[88:91], v[152:155], v[196:199], 0
	v_mfma_f32_16x16x32_bf16 v[76:79], v[144:147], v[204:207], 0
	v_mfma_f32_16x16x32_bf16 v[72:75], v[152:155], v[204:207], 0
	v_mfma_f32_16x16x32_bf16 v[124:127], v[148:151], v[180:183], v[124:127]
	v_mfma_f32_16x16x32_bf16 v[120:123], v[156:159], v[180:183], v[120:123]
	v_mfma_f32_16x16x32_bf16 v[108:111], v[148:151], v[192:195], v[108:111]
	v_mfma_f32_16x16x32_bf16 v[104:107], v[156:159], v[192:195], v[104:107]
	v_mfma_f32_16x16x32_bf16 v[92:95], v[148:151], v[200:203], v[92:95]
	v_mfma_f32_16x16x32_bf16 v[88:91], v[156:159], v[200:203], v[88:91]
	v_mfma_f32_16x16x32_bf16 v[76:79], v[148:151], v[208:211], v[76:79]
	v_mfma_f32_16x16x32_bf16 v[72:75], v[156:159], v[208:211], v[72:75]
	s_setprio 0
	s_setprio 1
	v_mfma_f32_16x16x32_bf16 v[116:119], v[160:163], v[176:179], 0
	v_mfma_f32_16x16x32_bf16 v[112:115], v[168:171], v[176:179], 0
	v_mfma_f32_16x16x32_bf16 v[100:103], v[160:163], v[188:191], 0
	v_mfma_f32_16x16x32_bf16 v[96:99], v[168:171], v[188:191], 0
	v_mfma_f32_16x16x32_bf16 v[84:87], v[160:163], v[196:199], 0
	v_mfma_f32_16x16x32_bf16 v[80:83], v[168:171], v[196:199], 0
	v_mfma_f32_16x16x32_bf16 v[68:71], v[160:163], v[204:207], 0
	v_mfma_f32_16x16x32_bf16 v[64:67], v[168:171], v[204:207], 0
	v_mfma_f32_16x16x32_bf16 v[116:119], v[164:167], v[180:183], v[116:119]
	v_mfma_f32_16x16x32_bf16 v[112:115], v[172:175], v[180:183], v[112:115]
	v_mfma_f32_16x16x32_bf16 v[100:103], v[164:167], v[192:195], v[100:103]
	v_mfma_f32_16x16x32_bf16 v[96:99], v[172:175], v[192:195], v[96:99]
	v_mfma_f32_16x16x32_bf16 v[84:87], v[164:167], v[200:203], v[84:87]
	v_mfma_f32_16x16x32_bf16 v[80:83], v[172:175], v[200:203], v[80:83]
	v_mfma_f32_16x16x32_bf16 v[68:71], v[164:167], v[208:211], v[68:71]
	v_mfma_f32_16x16x32_bf16 v[64:67], v[172:175], v[208:211], v[64:67]
	s_setprio 0
	s_barrier
	s_add_i32 s55, s45, s26
	v_lshl_add_u64 v[184:185], s[14:15], 0, v[132:133]
	s_mov_b32 m0, s55
	ds_read_b128 v[176:179], v143 offset:16384
	ds_read_b128 v[180:183], v143 offset:17408
	ds_read_b128 v[188:191], v143 offset:18432
	ds_read_b128 v[192:195], v143 offset:19456
	ds_read_b128 v[196:199], v143 offset:20480
	ds_read_b128 v[200:203], v143 offset:21504
	ds_read_b128 v[204:207], v143 offset:22528
	ds_read_b128 v[208:211], v143 offset:23552
	global_load_lds_dwordx4 v[184:185], off
	s_add_i32 m0, s55, 0x2000
	s_add_u32 s56, s14, 0x40000
	v_lshl_add_u64 v[186:187], s[14:15], 0, v[128:129]
	s_addc_u32 s57, s15, 0
	s_add_i32 s55, s46, s26
	global_load_lds_dwordx4 v[186:187], off
	v_lshl_add_u64 v[212:213], s[56:57], 0, v[132:133]
	s_mov_b32 m0, s55
	v_lshl_add_u64 v[214:215], s[38:39], 0, v[130:131]
	global_load_lds_dwordx4 v[212:213], off
	v_lshl_add_u64 v[212:213], s[56:57], 0, v[128:129]
	s_add_i32 m0, s55, 0x2000
	s_nop 0
	global_load_lds_dwordx4 v[212:213], off
	v_lshl_add_u64 v[212:213], s[38:39], 0, v[134:135]
	s_mov_b32 m0, s31
	s_nop 0
	global_load_lds_dwordx4 v[212:213], off
	s_mov_b32 m0, s35
	s_nop 0
	global_load_lds_dwordx4 v[214:215], off
	s_waitcnt vmcnt(8)
	s_waitcnt lgkmcnt(0)
	s_barrier
; #define G_STAGE(bufoff, gbase, voff) do { _Pragma("unroll") for (int _i = 0; _i < 2; ++_i) \
;         __builtin_amdgcn_global_load_lds((const unsigned*)((const char*)(gbase) + voff[_i]), (LAS unsigned*)(lds + (bufoff) + ldsw + _i * 8192), 16, 0, 0); } while (0)
; #define G_LDA(dst, b, h) do { _Pragma("unroll") for (int m = 0; m < 4; ++m) _Pragma("unroll") for (int k = 0; k < 2; ++k) dst[m][k] = *(const LAS bf16x8*)(lds + G_SA(b, h) + aoff + m * 2048 + k * 1024); } while (0)
; #define G_LDB(dst, b, h) do { _Pragma("unroll") for (int n = 0; n < 2; ++n) _Pragma("unroll") for (int k = 0; k < 2; ++k) dst[n][k] = *(const LAS bf16x8*)(lds + G_SB(b, h) + boff + n * 2048 + k * 1024); } while (0)
; #define G_MMA(ai, bj, At_, Bt_) do { __builtin_amdgcn_s_setprio(1); _Pragma("unroll") for (int m = 0; m < 4; ++m) _Pragma("unroll") for (int n = 0; n < 2; ++n) _Pragma("unroll") for (int k = 0; k < 2; ++k) \
;         acc[ai][bj][m][n] = __builtin_amdgcn_mfma_f32_16x16x32_bf16(Bt_[n][k], At_[m][k], acc[ai][bj][m][n], 0, 0, 0); __builtin_amdgcn_s_setprio(0); } while (0)
; #define WAIT_V(n) asm volatile("s_waitcnt vmcnt(" #n ")" ::: "memory")
; #define WAIT_L(n) asm volatile("s_waitcnt lgkmcnt(" #n ")" ::: "memory")
; #define BAR __builtin_amdgcn_s_barrier()
; #define SCHED __builtin_amdgcn_sched_barrier(0)
; template <class Get, class Epi>
; DI void gemm_loop(int ntiles, int ld, char* shm, const Get& get, const Epi& epi) {
;     ...
;             WAIT_V(8); WAIT_L(0); BAR; G_MMA(1, 0, At, B0); G_MMA(1, 1, At, B1); BAR; SCHED;
;             G_LDB(B0, 1, 0); G_LDB(B1, 1, 1); SCHED; G_LDA(At, 1, 0); G_STAGE(G_SA(0, 1), a2 + hstep, voffA);
;             WAIT_V(8); WAIT_L(0); BAR; G_MMA(0, 0, At, B0); G_MMA(0, 1, At, B1); BAR; SCHED;
	s_setprio 1
	s_waitcnt lgkmcnt(0)
	v_mfma_f32_16x16x32_bf16 v[60:63], v[144:147], v[176:179], 0
	v_mfma_f32_16x16x32_bf16 v[56:59], v[152:155], v[176:179], 0
	v_mfma_f32_16x16x32_bf16 v[44:47], v[144:147], v[188:191], 0
	v_mfma_f32_16x16x32_bf16 v[40:43], v[152:155], v[188:191], 0
	v_mfma_f32_16x16x32_bf16 v[28:31], v[144:147], v[196:199], 0
	v_mfma_f32_16x16x32_bf16 v[24:27], v[152:155], v[196:199], 0
	v_mfma_f32_16x16x32_bf16 v[12:15], v[144:147], v[204:207], 0
	v_mfma_f32_16x16x32_bf16 v[8:11], v[152:155], v[204:207], 0
	v_mfma_f32_16x16x32_bf16 v[60:63], v[148:151], v[180:183], v[60:63]
	v_mfma_f32_16x16x32_bf16 v[56:59], v[156:159], v[180:183], v[56:59]
	v_mfma_f32_16x16x32_bf16 v[44:47], v[148:151], v[192:195], v[44:47]
	v_mfma_f32_16x16x32_bf16 v[40:43], v[156:159], v[192:195], v[40:43]
	v_mfma_f32_16x16x32_bf16 v[28:31], v[148:151], v[200:203], v[28:31]
	v_mfma_f32_16x16x32_bf16 v[24:27], v[156:159], v[200:203], v[24:27]
	v_mfma_f32_16x16x32_bf16 v[12:15], v[148:151], v[208:211], v[12:15]
	v_mfma_f32_16x16x32_bf16 v[8:11], v[156:159], v[208:211], v[8:11]
	s_setprio 0
	s_setprio 1
	v_mfma_f32_16x16x32_bf16 v[52:55], v[160:163], v[176:179], 0
	v_mfma_f32_16x16x32_bf16 v[48:51], v[168:171], v[176:179], 0
	v_mfma_f32_16x16x32_bf16 v[36:39], v[160:163], v[188:191], 0
	v_mfma_f32_16x16x32_bf16 v[32:35], v[168:171], v[188:191], 0
	v_mfma_f32_16x16x32_bf16 v[20:23], v[160:163], v[196:199], 0
	v_mfma_f32_16x16x32_bf16 v[16:19], v[168:171], v[196:199], 0
	v_mfma_f32_16x16x32_bf16 v[4:7], v[160:163], v[204:207], 0
	v_mfma_f32_16x16x32_bf16 v[0:3], v[168:171], v[204:207], 0
	v_mfma_f32_16x16x32_bf16 v[52:55], v[164:167], v[180:183], v[52:55]
	v_mfma_f32_16x16x32_bf16 v[48:51], v[172:175], v[180:183], v[48:51]
	v_mfma_f32_16x16x32_bf16 v[36:39], v[164:167], v[192:195], v[36:39]
	v_mfma_f32_16x16x32_bf16 v[32:35], v[172:175], v[192:195], v[32:35]
	v_mfma_f32_16x16x32_bf16 v[20:23], v[164:167], v[200:203], v[20:23]
	v_mfma_f32_16x16x32_bf16 v[16:19], v[172:175], v[200:203], v[16:19]
	v_mfma_f32_16x16x32_bf16 v[4:7], v[164:167], v[208:211], v[4:7]
	v_mfma_f32_16x16x32_bf16 v[0:3], v[172:175], v[208:211], v[0:3]
	s_setprio 0
	s_barrier
	s_add_i32 s55, 0, 0x18000
	s_add_i32 s56, 0, 0x1c000
	v_add_u32_e32 v156, s55, v140
	v_add_u32_e32 v172, s56, v140
	ds_read_b128 v[144:147], v156
	ds_read_b128 v[148:151], v156 offset:1024
	ds_read_b128 v[152:155], v156 offset:2048
	ds_read_b128 v[156:159], v156 offset:3072
	ds_read_b128 v[160:163], v172
	ds_read_b128 v[164:167], v172 offset:1024
	ds_read_b128 v[168:171], v172 offset:2048
	ds_read_b128 v[172:175], v172 offset:3072
	s_add_u32 s38, s38, 0x40000
	s_addc_u32 s39, s39, 0
	s_mov_b32 m0, s41
	v_lshl_add_u64 v[216:217], s[38:39], 0, v[134:135]
	ds_read_b128 v[176:179], v143 offset:32768
	ds_read_b128 v[180:183], v143 offset:33792
	ds_read_b128 v[188:191], v143 offset:34816
	ds_read_b128 v[192:195], v143 offset:35840
	ds_read_b128 v[196:199], v143 offset:36864
	ds_read_b128 v[200:203], v143 offset:37888
	ds_read_b128 v[204:207], v143 offset:38912
	ds_read_b128 v[208:211], v143 offset:39936
	global_load_lds_dwordx4 v[216:217], off
	v_lshl_add_u64 v[216:217], s[38:39], 0, v[130:131]
	s_mov_b32 m0, s42
	s_nop 0
	global_load_lds_dwordx4 v[216:217], off
	s_waitcnt vmcnt(8)
	s_waitcnt lgkmcnt(0)
	s_barrier
	s_setprio 1
	s_waitcnt lgkmcnt(0)
	v_mfma_f32_16x16x32_bf16 v[124:127], v[144:147], v[176:179], v[124:127]
	v_mfma_f32_16x16x32_bf16 v[120:123], v[152:155], v[176:179], v[120:123]
	v_mfma_f32_16x16x32_bf16 v[108:111], v[144:147], v[188:191], v[108:111]
	v_mfma_f32_16x16x32_bf16 v[104:107], v[152:155], v[188:191], v[104:107]
	v_mfma_f32_16x16x32_bf16 v[92:95], v[144:147], v[196:199], v[92:95]
	v_mfma_f32_16x16x32_bf16 v[88:91], v[152:155], v[196:199], v[88:91]
	v_mfma_f32_16x16x32_bf16 v[76:79], v[144:147], v[204:207], v[76:79]
	v_mfma_f32_16x16x32_bf16 v[72:75], v[152:155], v[204:207], v[72:75]
	v_mfma_f32_16x16x32_bf16 v[124:127], v[148:151], v[180:183], v[124:127]
	v_mfma_f32_16x16x32_bf16 v[120:123], v[156:159], v[180:183], v[120:123]
	v_mfma_f32_16x16x32_bf16 v[108:111], v[148:151], v[192:195], v[108:111]
	v_mfma_f32_16x16x32_bf16 v[104:107], v[156:159], v[192:195], v[104:107]
	v_mfma_f32_16x16x32_bf16 v[92:95], v[148:151], v[200:203], v[92:95]
	v_mfma_f32_16x16x32_bf16 v[88:91], v[156:159], v[200:203], v[88:91]
	v_mfma_f32_16x16x32_bf16 v[76:79], v[148:151], v[208:211], v[76:79]
	v_mfma_f32_16x16x32_bf16 v[72:75], v[156:159], v[208:211], v[72:75]
	s_setprio 0
	s_setprio 1
	v_mfma_f32_16x16x32_bf16 v[116:119], v[160:163], v[176:179], v[116:119]
	v_mfma_f32_16x16x32_bf16 v[112:115], v[168:171], v[176:179], v[112:115]
	v_mfma_f32_16x16x32_bf16 v[100:103], v[160:163], v[188:191], v[100:103]
	v_mfma_f32_16x16x32_bf16 v[96:99], v[168:171], v[188:191], v[96:99]
	v_mfma_f32_16x16x32_bf16 v[84:87], v[160:163], v[196:199], v[84:87]
	v_mfma_f32_16x16x32_bf16 v[80:83], v[168:171], v[196:199], v[80:83]
	v_mfma_f32_16x16x32_bf16 v[68:71], v[160:163], v[204:207], v[68:71]
	v_mfma_f32_16x16x32_bf16 v[64:67], v[168:171], v[204:207], v[64:67]
	v_mfma_f32_16x16x32_bf16 v[116:119], v[164:167], v[180:183], v[116:119]
	v_mfma_f32_16x16x32_bf16 v[112:115], v[172:175], v[180:183], v[112:115]
	v_mfma_f32_16x16x32_bf16 v[100:103], v[164:167], v[192:195], v[100:103]
	v_mfma_f32_16x16x32_bf16 v[96:99], v[172:175], v[192:195], v[96:99]
	v_mfma_f32_16x16x32_bf16 v[84:87], v[164:167], v[200:203], v[84:87]
	v_mfma_f32_16x16x32_bf16 v[80:83], v[172:175], v[200:203], v[80:83]
	v_mfma_f32_16x16x32_bf16 v[68:71], v[164:167], v[208:211], v[68:71]
	v_mfma_f32_16x16x32_bf16 v[64:67], v[172:175], v[208:211], v[64:67]
	s_setprio 0
	s_barrier
; #define G_STAGE(bufoff, gbase, voff) do { _Pragma("unroll") for (int _i = 0; _i < 2; ++_i) \
;         __builtin_amdgcn_global_load_lds((const unsigned*)((const char*)(gbase) + voff[_i]), (LAS unsigned*)(lds + (bufoff) + ldsw + _i * 8192), 16, 0, 0); } while (0)
; #define G_LDA(dst, b, h) do { _Pragma("unroll") for (int m = 0; m < 4; ++m) _Pragma("unroll") for (int k = 0; k < 2; ++k) dst[m][k] = *(const LAS bf16x8*)(lds + G_SA(b, h) + aoff + m * 2048 + k * 1024); } while (0)
; #define G_MMA(ai, bj, At_, Bt_) do { __builtin_amdgcn_s_setprio(1); _Pragma("unroll") for (int m = 0; m < 4; ++m) _Pragma("unroll") for (int n = 0; n < 2; ++n) _Pragma("unroll") for (int k = 0; k < 2; ++k) \
;         acc[ai][bj][m][n] = __builtin_amdgcn_mfma_f32_16x16x32_bf16(Bt_[n][k], At_[m][k], acc[ai][bj][m][n], 0, 0, 0); __builtin_amdgcn_s_setprio(0); } while (0)
; #define WAIT_V(n) asm volatile("s_waitcnt vmcnt(" #n ")" ::: "memory")
; #define WAIT_L(n) asm volatile("s_waitcnt lgkmcnt(" #n ")" ::: "memory")
; #define BAR __builtin_amdgcn_s_barrier()
; #define SCHED __builtin_amdgcn_sched_barrier(0)
; template <class Get, class Epi>
; DI void gemm_loop(int ntiles, int ld, char* shm, const Get& get, const Epi& epi) {
;     ...
;             G_LDA(At, 1, 1); G_STAGE(G_SB(1, 0), b3, voffB); G_STAGE(G_SB(1, 1), b3 + hstep, voffB); G_STAGE(G_SA(1, 0), a3, voffA);
;             WAIT_V(8); WAIT_L(0); BAR; G_MMA(1, 0, At, B0); G_MMA(1, 1, At, B1); BAR; SCHED;
;         }
	s_add_i32 s38, s55, s26
	v_lshl_add_u64 v[184:185], v[184:185], 0, s[2:3]
	s_mov_b32 m0, s38
	ds_read_b128 v[176:179], v143 offset:49152
	ds_read_b128 v[180:183], v143 offset:50176
	ds_read_b128 v[188:191], v143 offset:51200
	ds_read_b128 v[192:195], v143 offset:52224
	ds_read_b128 v[196:199], v143 offset:53248
	ds_read_b128 v[200:203], v143 offset:54272
	ds_read_b128 v[204:207], v143 offset:55296
	ds_read_b128 v[208:211], v143 offset:56320
	global_load_lds_dwordx4 v[184:185], off
	s_add_i32 m0, s38, 0x2000
	s_add_u32 s14, s14, 0x40080
	v_lshl_add_u64 v[184:185], v[186:187], 0, s[2:3]
	s_addc_u32 s15, s15, 0
	s_add_i32 s38, s56, s26
	global_load_lds_dwordx4 v[184:185], off
	v_lshl_add_u64 v[184:185], s[14:15], 0, v[132:133]
	s_mov_b32 m0, s38
	s_nop 0
	global_load_lds_dwordx4 v[184:185], off
	v_lshl_add_u64 v[184:185], s[14:15], 0, v[128:129]
	s_add_i32 m0, s38, 0x2000
	s_nop 0
	global_load_lds_dwordx4 v[184:185], off
	v_lshl_add_u64 v[184:185], v[212:213], 0, s[2:3]
	s_mov_b32 m0, s43
	s_nop 0
	global_load_lds_dwordx4 v[184:185], off
	v_lshl_add_u64 v[184:185], v[214:215], 0, s[2:3]
	s_mov_b32 m0, s44
	s_nop 0
	global_load_lds_dwordx4 v[184:185], off
	s_waitcnt vmcnt(8)
	s_waitcnt lgkmcnt(0)
	s_barrier
	s_setprio 1
	s_waitcnt lgkmcnt(0)
	v_mfma_f32_16x16x32_bf16 v[60:63], v[144:147], v[176:179], v[60:63]
	v_mfma_f32_16x16x32_bf16 v[56:59], v[152:155], v[176:179], v[56:59]
	v_mfma_f32_16x16x32_bf16 v[44:47], v[144:147], v[188:191], v[44:47]
	v_mfma_f32_16x16x32_bf16 v[40:43], v[152:155], v[188:191], v[40:43]
	v_mfma_f32_16x16x32_bf16 v[28:31], v[144:147], v[196:199], v[28:31]
	v_mfma_f32_16x16x32_bf16 v[24:27], v[152:155], v[196:199], v[24:27]
	v_mfma_f32_16x16x32_bf16 v[12:15], v[144:147], v[204:207], v[12:15]
	v_mfma_f32_16x16x32_bf16 v[8:11], v[152:155], v[204:207], v[8:11]
	v_mfma_f32_16x16x32_bf16 v[60:63], v[148:151], v[180:183], v[60:63]
	v_mfma_f32_16x16x32_bf16 v[56:59], v[156:159], v[180:183], v[56:59]
	v_mfma_f32_16x16x32_bf16 v[44:47], v[148:151], v[192:195], v[44:47]
	v_mfma_f32_16x16x32_bf16 v[40:43], v[156:159], v[192:195], v[40:43]
	v_mfma_f32_16x16x32_bf16 v[28:31], v[148:151], v[200:203], v[28:31]
	v_mfma_f32_16x16x32_bf16 v[24:27], v[156:159], v[200:203], v[24:27]
	v_mfma_f32_16x16x32_bf16 v[12:15], v[148:151], v[208:211], v[12:15]
	v_mfma_f32_16x16x32_bf16 v[8:11], v[156:159], v[208:211], v[8:11]
	s_setprio 0
	s_setprio 1
	v_mfma_f32_16x16x32_bf16 v[52:55], v[160:163], v[176:179], v[52:55]
	v_mfma_f32_16x16x32_bf16 v[48:51], v[168:171], v[176:179], v[48:51]
	v_mfma_f32_16x16x32_bf16 v[36:39], v[160:163], v[188:191], v[36:39]
	v_mfma_f32_16x16x32_bf16 v[32:35], v[168:171], v[188:191], v[32:35]
	v_mfma_f32_16x16x32_bf16 v[20:23], v[160:163], v[196:199], v[20:23]
	v_mfma_f32_16x16x32_bf16 v[16:19], v[168:171], v[196:199], v[16:19]
	v_mfma_f32_16x16x32_bf16 v[4:7], v[160:163], v[204:207], v[4:7]
	v_mfma_f32_16x16x32_bf16 v[0:3], v[168:171], v[204:207], v[0:3]
	v_mfma_f32_16x16x32_bf16 v[52:55], v[164:167], v[180:183], v[52:55]
	v_mfma_f32_16x16x32_bf16 v[48:51], v[172:175], v[180:183], v[48:51]
	v_mfma_f32_16x16x32_bf16 v[36:39], v[164:167], v[192:195], v[36:39]
	v_mfma_f32_16x16x32_bf16 v[32:35], v[172:175], v[192:195], v[32:35]
	v_mfma_f32_16x16x32_bf16 v[20:23], v[164:167], v[200:203], v[20:23]
	v_mfma_f32_16x16x32_bf16 v[16:19], v[172:175], v[200:203], v[16:19]
	v_mfma_f32_16x16x32_bf16 v[4:7], v[164:167], v[208:211], v[4:7]
	v_mfma_f32_16x16x32_bf16 v[0:3], v[172:175], v[208:211], v[0:3]
	s_setprio 0
	s_barrier
	s_add_i32 s54, s54, 2
	s_add_u32 s36, s36, 0x100
	s_addc_u32 s37, s37, 0
	s_add_u32 s52, s52, 0x100
	s_addc_u32 s53, s53, 0
	s_cmp_gt_u32 s54, 13
	s_cbranch_scc0 .LBB0_763
	s_branch .Lpost_763

; #define BAR __builtin_amdgcn_s_barrier()
; template <class Get, class Epi>
; DI void gemm_loop(int ntiles, int ld, char* shm, const Get& get, const Epi& epi) {
;     ...
;         }
;         if (wr == 0) BAR;
.Lpost_763:
	s_and_b64 vcc, exec, s[4:5]
	s_cbranch_vccz .LBB0_766
	s_barrier

; #define G_STAGE(bufoff, gbase, voff) do { _Pragma("unroll") for (int _i = 0; _i < 2; ++_i) \
;         __builtin_amdgcn_global_load_lds((const unsigned*)((const char*)(gbase) + voff[_i]), (LAS unsigned*)(lds + (bufoff) + ldsw + _i * 8192), 16, 0, 0); } while (0)
; #define G_LDA(dst, b, h) do { _Pragma("unroll") for (int m = 0; m < 4; ++m) _Pragma("unroll") for (int k = 0; k < 2; ++k) dst[m][k] = *(const LAS bf16x8*)(lds + G_SA(b, h) + aoff + m * 2048 + k * 1024); } while (0)
; #define G_LDB(dst, b, h) do { _Pragma("unroll") for (int n = 0; n < 2; ++n) _Pragma("unroll") for (int k = 0; k < 2; ++k) dst[n][k] = *(const LAS bf16x8*)(lds + G_SB(b, h) + boff + n * 2048 + k * 1024); } while (0)
; #define G_MMA(ai, bj, At_, Bt_) do { __builtin_amdgcn_s_setprio(1); _Pragma("unroll") for (int m = 0; m < 4; ++m) _Pragma("unroll") for (int n = 0; n < 2; ++n) _Pragma("unroll") for (int k = 0; k < 2; ++k) \
;         acc[ai][bj][m][n] = __builtin_amdgcn_mfma_f32_16x16x32_bf16(Bt_[n][k], At_[m][k], acc[ai][bj][m][n], 0, 0, 0); __builtin_amdgcn_s_setprio(0); } while (0)
; #define WAIT_V(n) asm volatile("s_waitcnt vmcnt(" #n ")" ::: "memory")
; #define WAIT_L(n) asm volatile("s_waitcnt lgkmcnt(" #n ")" ::: "memory")
; #define BAR __builtin_amdgcn_s_barrier()
; template <class Get, class Epi>
; DI void gemm_loop(int ntiles, int ld, char* shm, const Get& get, const Epi& epi) {
;     ...
;         const int Ln = L + gridDim.x; const bool has_next = Ln < ntiles; if (has_next) nxt = get(Ln);
;         const char* nA = has_next ? (const char*)nxt.A + (size_t)nxt.brow * ld * 2 : cA; const char* nB = has_next ? (const char*)nxt.Bt + (size_t)nxt.bcol * ld * 2 : cB;
;         const int nt = cur.K / BK;
;         for (int t = 0; t < nt; t += 2) {
;             const bool last = (t == nt - 2);
;             const char* a1 = cA + (size_t)(t + 1) * kstep;
;             const char* a2 = last ? nA : cA + (size_t)(t + 2) * kstep; const char* b2 = last ? nB : cB + (size_t)(t + 2) * kstep;
;             const char* a3 = a2 + kstep; const char* b3 = b2 + kstep;
;             G_LDB(B0, 0, 0); G_LDB(B1, 0, 1); SCHED; G_LDA(At, 0, 0); G_STAGE(G_SA(1, 1), a1 + hstep, voffA);
;             WAIT_V(8); WAIT_L(0); BAR; G_MMA(0, 0, At, B0); G_MMA(0, 1, At, B1); BAR; SCHED;
;             G_LDA(At, 0, 1); G_STAGE(G_SB(0, 0), b2, voffB); G_STAGE(G_SB(0, 1), b2 + hstep, voffB); G_STAGE(G_SA(0, 0), a2, voffA);
.LBB0_849:
	s_lshr_b32 s59, s38, 6
	s_add_i32 s72, s59, -2
	s_add_u32 s73, s14, 0x100
	s_addc_u32 s74, s15, 0
	s_mov_b32 s38, 0
.Lpeel_850:
	ds_read_b128 v[128:131], v169
	ds_read_b128 v[132:135], v169 offset:1024
	ds_read_b128 v[136:139], v169 offset:2048
	ds_read_b128 v[140:143], v169 offset:3072
	ds_read_b128 v[158:161], v170
	ds_read_b128 v[162:165], v170 offset:1024
	ds_read_b128 v[172:175], v170 offset:2048
	ds_read_b128 v[176:179], v170 offset:3072
	s_add_i32 s75, s38, 2
	s_add_u32 s14, s4, 0x100
	s_addc_u32 s15, s5, 0
	s_cmp_eq_u32 s72, s38
	s_cselect_b32 s38, s36, s73
	s_cselect_b32 s41, s35, s15
	s_cselect_b32 s40, s34, s14
	s_cselect_b32 s39, s37, s74
	v_lshl_add_u64 v[144:145], s[4:5], 0, v[154:155]
	s_add_i32 m0, s42, 0xc000
	ds_read_b128 v[180:183], v171
	ds_read_b128 v[188:191], v171 offset:1024
	ds_read_b128 v[192:195], v171 offset:2048
	ds_read_b128 v[196:199], v171 offset:3072
	ds_read_b128 v[200:203], v171 offset:4096
	ds_read_b128 v[204:207], v171 offset:5120
	ds_read_b128 v[208:211], v171 offset:6144
	ds_read_b128 v[212:215], v171 offset:7168
	global_load_lds_dwordx4 v[144:145], off
	v_lshl_add_u64 v[144:145], s[4:5], 0, v[156:157]
	s_add_i32 m0, s42, 0xe000
	s_nop 0
	global_load_lds_dwordx4 v[144:145], off
	s_waitcnt vmcnt(8)
	s_waitcnt lgkmcnt(0)
	s_barrier
	s_setprio 1
	s_waitcnt lgkmcnt(0)
	v_mfma_f32_16x16x32_bf16 v[124:127], v[128:131], v[180:183], 0
	v_mfma_f32_16x16x32_bf16 v[120:123], v[136:139], v[180:183], 0
	v_mfma_f32_16x16x32_bf16 v[116:119], v[128:131], v[192:195], 0
	v_mfma_f32_16x16x32_bf16 v[112:115], v[136:139], v[192:195], 0
	v_mfma_f32_16x16x32_bf16 v[108:111], v[128:131], v[200:203], 0
	v_mfma_f32_16x16x32_bf16 v[104:107], v[136:139], v[200:203], 0
	v_mfma_f32_16x16x32_bf16 v[100:103], v[128:131], v[208:211], 0
	v_mfma_f32_16x16x32_bf16 v[96:99], v[136:139], v[208:211], 0
	v_mfma_f32_16x16x32_bf16 v[124:127], v[132:135], v[188:191], v[124:127]
	v_mfma_f32_16x16x32_bf16 v[120:123], v[140:143], v[188:191], v[120:123]
	v_mfma_f32_16x16x32_bf16 v[116:119], v[132:135], v[196:199], v[116:119]
	v_mfma_f32_16x16x32_bf16 v[112:115], v[140:143], v[196:199], v[112:115]
	v_mfma_f32_16x16x32_bf16 v[108:111], v[132:135], v[204:207], v[108:111]
	v_mfma_f32_16x16x32_bf16 v[104:107], v[140:143], v[204:207], v[104:107]
	v_mfma_f32_16x16x32_bf16 v[100:103], v[132:135], v[212:215], v[100:103]
	v_mfma_f32_16x16x32_bf16 v[96:99], v[140:143], v[212:215], v[96:99]
	s_setprio 0
	s_setprio 1
	v_mfma_f32_16x16x32_bf16 v[60:63], v[158:161], v[180:183], 0
	v_mfma_f32_16x16x32_bf16 v[56:59], v[172:175], v[180:183], 0
	v_mfma_f32_16x16x32_bf16 v[52:55], v[158:161], v[192:195], 0
	v_mfma_f32_16x16x32_bf16 v[48:51], v[172:175], v[192:195], 0
	v_mfma_f32_16x16x32_bf16 v[44:47], v[158:161], v[200:203], 0
	v_mfma_f32_16x16x32_bf16 v[40:43], v[172:175], v[200:203], 0
	v_mfma_f32_16x16x32_bf16 v[36:39], v[158:161], v[208:211], 0
	v_mfma_f32_16x16x32_bf16 v[32:35], v[172:175], v[208:211], 0
	v_mfma_f32_16x16x32_bf16 v[60:63], v[162:165], v[188:191], v[60:63]
	v_mfma_f32_16x16x32_bf16 v[56:59], v[176:179], v[188:191], v[56:59]
	v_mfma_f32_16x16x32_bf16 v[52:55], v[162:165], v[196:199], v[52:55]
	v_mfma_f32_16x16x32_bf16 v[48:51], v[176:179], v[196:199], v[48:51]
	v_mfma_f32_16x16x32_bf16 v[44:47], v[162:165], v[204:207], v[44:47]
	v_mfma_f32_16x16x32_bf16 v[40:43], v[176:179], v[204:207], v[40:43]
	v_mfma_f32_16x16x32_bf16 v[36:39], v[162:165], v[212:215], v[36:39]
	v_mfma_f32_16x16x32_bf16 v[32:35], v[176:179], v[212:215], v[32:35]
	s_setprio 0
	s_barrier
	s_add_i32 s4, s50, s26
	v_lshl_add_u64 v[144:145], s[38:39], 0, v[148:149]
	s_mov_b32 m0, s4
	ds_read_b128 v[180:183], v171 offset:16384
	ds_read_b128 v[188:191], v171 offset:17408
	ds_read_b128 v[192:195], v171 offset:18432
	ds_read_b128 v[196:199], v171 offset:19456
	ds_read_b128 v[200:203], v171 offset:20480
	ds_read_b128 v[204:207], v171 offset:21504
	ds_read_b128 v[208:211], v171 offset:22528
	ds_read_b128 v[212:215], v171 offset:23552
	global_load_lds_dwordx4 v[144:145], off
	s_add_i32 m0, s4, 0x2000
	s_add_u32 s4, s38, 0xb0000
	v_lshl_add_u64 v[166:167], s[38:39], 0, v[152:153]
	s_addc_u32 s5, s39, 0
	s_add_i32 s76, s51, s26
	global_load_lds_dwordx4 v[166:167], off
	v_lshl_add_u64 v[184:185], s[4:5], 0, v[148:149]
	s_mov_b32 m0, s76
	v_lshl_add_u64 v[186:187], s[40:41], 0, v[150:151]
	global_load_lds_dwordx4 v[184:185], off
	v_lshl_add_u64 v[184:185], s[4:5], 0, v[152:153]
	s_add_i32 m0, s76, 0x2000
	s_nop 0
	global_load_lds_dwordx4 v[184:185], off
	v_lshl_add_u64 v[184:185], s[40:41], 0, v[146:147]
	s_mov_b32 m0, s42
	s_nop 0
	global_load_lds_dwordx4 v[184:185], off
	s_mov_b32 m0, s43
	s_nop 0
	global_load_lds_dwordx4 v[186:187], off
	s_waitcnt vmcnt(8)
	s_waitcnt lgkmcnt(0)
	s_barrier
; #define G_STAGE(bufoff, gbase, voff) do { _Pragma("unroll") for (int _i = 0; _i < 2; ++_i) \
;         __builtin_amdgcn_global_load_lds((const unsigned*)((const char*)(gbase) + voff[_i]), (LAS unsigned*)(lds + (bufoff) + ldsw + _i * 8192), 16, 0, 0); } while (0)
; #define G_LDA(dst, b, h) do { _Pragma("unroll") for (int m = 0; m < 4; ++m) _Pragma("unroll") for (int k = 0; k < 2; ++k) dst[m][k] = *(const LAS bf16x8*)(lds + G_SA(b, h) + aoff + m * 2048 + k * 1024); } while (0)
; #define G_LDB(dst, b, h) do { _Pragma("unroll") for (int n = 0; n < 2; ++n) _Pragma("unroll") for (int k = 0; k < 2; ++k) dst[n][k] = *(const LAS bf16x8*)(lds + G_SB(b, h) + boff + n * 2048 + k * 1024); } while (0)
; #define G_MMA(ai, bj, At_, Bt_) do { __builtin_amdgcn_s_setprio(1); _Pragma("unroll") for (int m = 0; m < 4; ++m) _Pragma("unroll") for (int n = 0; n < 2; ++n) _Pragma("unroll") for (int k = 0; k < 2; ++k) \
;         acc[ai][bj][m][n] = __builtin_amdgcn_mfma_f32_16x16x32_bf16(Bt_[n][k], At_[m][k], acc[ai][bj][m][n], 0, 0, 0); __builtin_amdgcn_s_setprio(0); } while (0)
; #define WAIT_V(n) asm volatile("s_waitcnt vmcnt(" #n ")" ::: "memory")
; #define WAIT_L(n) asm volatile("s_waitcnt lgkmcnt(" #n ")" ::: "memory")
; #define BAR __builtin_amdgcn_s_barrier()
; #define SCHED __builtin_amdgcn_sched_barrier(0)
; template <class Get, class Epi>
; DI void gemm_loop(int ntiles, int ld, char* shm, const Get& get, const Epi& epi) {
;     ...
;             WAIT_V(8); WAIT_L(0); BAR; G_MMA(1, 0, At, B0); G_MMA(1, 1, At, B1); BAR; SCHED;
;             G_LDB(B0, 1, 0); G_LDB(B1, 1, 1); SCHED; G_LDA(At, 1, 0); G_STAGE(G_SA(0, 1), a2 + hstep, voffA);
;             WAIT_V(8); WAIT_L(0); BAR; G_MMA(0, 0, At, B0); G_MMA(0, 1, At, B1); BAR; SCHED;
	s_setprio 1
	s_waitcnt lgkmcnt(0)
	v_mfma_f32_16x16x32_bf16 v[92:95], v[128:131], v[180:183], 0
	v_mfma_f32_16x16x32_bf16 v[88:91], v[136:139], v[180:183], 0
	v_mfma_f32_16x16x32_bf16 v[84:87], v[128:131], v[192:195], 0
	v_mfma_f32_16x16x32_bf16 v[80:83], v[136:139], v[192:195], 0
	v_mfma_f32_16x16x32_bf16 v[76:79], v[128:131], v[200:203], 0
	v_mfma_f32_16x16x32_bf16 v[72:75], v[136:139], v[200:203], 0
	v_mfma_f32_16x16x32_bf16 v[68:71], v[128:131], v[208:211], 0
	v_mfma_f32_16x16x32_bf16 v[64:67], v[136:139], v[208:211], 0
	v_mfma_f32_16x16x32_bf16 v[92:95], v[132:135], v[188:191], v[92:95]
	v_mfma_f32_16x16x32_bf16 v[88:91], v[140:143], v[188:191], v[88:91]
	v_mfma_f32_16x16x32_bf16 v[84:87], v[132:135], v[196:199], v[84:87]
	v_mfma_f32_16x16x32_bf16 v[80:83], v[140:143], v[196:199], v[80:83]
	v_mfma_f32_16x16x32_bf16 v[76:79], v[132:135], v[204:207], v[76:79]
	v_mfma_f32_16x16x32_bf16 v[72:75], v[140:143], v[204:207], v[72:75]
	v_mfma_f32_16x16x32_bf16 v[68:71], v[132:135], v[212:215], v[68:71]
	v_mfma_f32_16x16x32_bf16 v[64:67], v[140:143], v[212:215], v[64:67]
	s_setprio 0
	s_setprio 1
	v_mfma_f32_16x16x32_bf16 v[28:31], v[158:161], v[180:183], 0
	v_mfma_f32_16x16x32_bf16 v[24:27], v[172:175], v[180:183], 0
	v_mfma_f32_16x16x32_bf16 v[20:23], v[158:161], v[192:195], 0
	v_mfma_f32_16x16x32_bf16 v[16:19], v[172:175], v[192:195], 0
	v_mfma_f32_16x16x32_bf16 v[12:15], v[158:161], v[200:203], 0
	v_mfma_f32_16x16x32_bf16 v[8:11], v[172:175], v[200:203], 0
	v_mfma_f32_16x16x32_bf16 v[4:7], v[158:161], v[208:211], 0
	v_mfma_f32_16x16x32_bf16 v[0:3], v[172:175], v[208:211], 0
	v_mfma_f32_16x16x32_bf16 v[28:31], v[162:165], v[188:191], v[28:31]
	v_mfma_f32_16x16x32_bf16 v[24:27], v[176:179], v[188:191], v[24:27]
	v_mfma_f32_16x16x32_bf16 v[20:23], v[162:165], v[196:199], v[20:23]
	v_mfma_f32_16x16x32_bf16 v[16:19], v[176:179], v[196:199], v[16:19]
	v_mfma_f32_16x16x32_bf16 v[12:15], v[162:165], v[204:207], v[12:15]
	v_mfma_f32_16x16x32_bf16 v[8:11], v[176:179], v[204:207], v[8:11]
	v_mfma_f32_16x16x32_bf16 v[4:7], v[162:165], v[212:215], v[4:7]
	v_mfma_f32_16x16x32_bf16 v[0:3], v[176:179], v[212:215], v[0:3]
	s_setprio 0
	s_barrier
	s_add_i32 s76, 0, 0x18000
	s_add_i32 s78, 0, 0x1c000
	v_add_u32_e32 v140, s76, v168
	v_add_u32_e32 v176, s78, v168
	ds_read_b128 v[128:131], v140
	ds_read_b128 v[132:135], v140 offset:1024
	ds_read_b128 v[136:139], v140 offset:2048
	ds_read_b128 v[140:143], v140 offset:3072
	ds_read_b128 v[158:161], v176
	ds_read_b128 v[162:165], v176 offset:1024
	ds_read_b128 v[172:175], v176 offset:2048
	ds_read_b128 v[176:179], v176 offset:3072
	s_add_u32 s4, s40, 0xb0000
	s_addc_u32 s5, s41, 0
	s_mov_b32 m0, s44
	v_lshl_add_u64 v[216:217], s[4:5], 0, v[146:147]
	ds_read_b128 v[180:183], v171 offset:32768
	ds_read_b128 v[188:191], v171 offset:33792
	ds_read_b128 v[192:195], v171 offset:34816
	ds_read_b128 v[196:199], v171 offset:35840
	ds_read_b128 v[200:203], v171 offset:36864
	ds_read_b128 v[204:207], v171 offset:37888
	ds_read_b128 v[208:211], v171 offset:38912
	ds_read_b128 v[212:215], v171 offset:39936
	global_load_lds_dwordx4 v[216:217], off
	v_lshl_add_u64 v[216:217], s[4:5], 0, v[150:151]
	s_mov_b32 m0, s45
	s_nop 0
	global_load_lds_dwordx4 v[216:217], off
	s_waitcnt vmcnt(8)
	s_waitcnt lgkmcnt(0)
	s_barrier
	s_setprio 1
	s_waitcnt lgkmcnt(0)
	v_mfma_f32_16x16x32_bf16 v[124:127], v[128:131], v[180:183], v[124:127]
	v_mfma_f32_16x16x32_bf16 v[120:123], v[136:139], v[180:183], v[120:123]
	v_mfma_f32_16x16x32_bf16 v[116:119], v[128:131], v[192:195], v[116:119]
	v_mfma_f32_16x16x32_bf16 v[112:115], v[136:139], v[192:195], v[112:115]
	v_mfma_f32_16x16x32_bf16 v[108:111], v[128:131], v[200:203], v[108:111]
	v_mfma_f32_16x16x32_bf16 v[104:107], v[136:139], v[200:203], v[104:107]
	v_mfma_f32_16x16x32_bf16 v[100:103], v[128:131], v[208:211], v[100:103]
	v_mfma_f32_16x16x32_bf16 v[96:99], v[136:139], v[208:211], v[96:99]
	v_mfma_f32_16x16x32_bf16 v[124:127], v[132:135], v[188:191], v[124:127]
	v_mfma_f32_16x16x32_bf16 v[120:123], v[140:143], v[188:191], v[120:123]
	v_mfma_f32_16x16x32_bf16 v[116:119], v[132:135], v[196:199], v[116:119]
	v_mfma_f32_16x16x32_bf16 v[112:115], v[140:143], v[196:199], v[112:115]
	v_mfma_f32_16x16x32_bf16 v[108:111], v[132:135], v[204:207], v[108:111]
	v_mfma_f32_16x16x32_bf16 v[104:107], v[140:143], v[204:207], v[104:107]
	v_mfma_f32_16x16x32_bf16 v[100:103], v[132:135], v[212:215], v[100:103]
	v_mfma_f32_16x16x32_bf16 v[96:99], v[140:143], v[212:215], v[96:99]
	s_setprio 0
	s_setprio 1
	v_mfma_f32_16x16x32_bf16 v[60:63], v[158:161], v[180:183], v[60:63]
	v_mfma_f32_16x16x32_bf16 v[56:59], v[172:175], v[180:183], v[56:59]
	v_mfma_f32_16x16x32_bf16 v[52:55], v[158:161], v[192:195], v[52:55]
	v_mfma_f32_16x16x32_bf16 v[48:51], v[172:175], v[192:195], v[48:51]
	v_mfma_f32_16x16x32_bf16 v[44:47], v[158:161], v[200:203], v[44:47]
	v_mfma_f32_16x16x32_bf16 v[40:43], v[172:175], v[200:203], v[40:43]
	v_mfma_f32_16x16x32_bf16 v[36:39], v[158:161], v[208:211], v[36:39]
	v_mfma_f32_16x16x32_bf16 v[32:35], v[172:175], v[208:211], v[32:35]
	v_mfma_f32_16x16x32_bf16 v[60:63], v[162:165], v[188:191], v[60:63]
	v_mfma_f32_16x16x32_bf16 v[56:59], v[176:179], v[188:191], v[56:59]
	v_mfma_f32_16x16x32_bf16 v[52:55], v[162:165], v[196:199], v[52:55]
	v_mfma_f32_16x16x32_bf16 v[48:51], v[176:179], v[196:199], v[48:51]
	v_mfma_f32_16x16x32_bf16 v[44:47], v[162:165], v[204:207], v[44:47]
	v_mfma_f32_16x16x32_bf16 v[40:43], v[176:179], v[204:207], v[40:43]
	v_mfma_f32_16x16x32_bf16 v[36:39], v[162:165], v[212:215], v[36:39]
	v_mfma_f32_16x16x32_bf16 v[32:35], v[176:179], v[212:215], v[32:35]
	s_setprio 0
	s_barrier
; #define G_STAGE(bufoff, gbase, voff) do { _Pragma("unroll") for (int _i = 0; _i < 2; ++_i) \
;         __builtin_amdgcn_global_load_lds((const unsigned*)((const char*)(gbase) + voff[_i]), (LAS unsigned*)(lds + (bufoff) + ldsw + _i * 8192), 16, 0, 0); } while (0)
; #define G_LDA(dst, b, h) do { _Pragma("unroll") for (int m = 0; m < 4; ++m) _Pragma("unroll") for (int k = 0; k < 2; ++k) dst[m][k] = *(const LAS bf16x8*)(lds + G_SA(b, h) + aoff + m * 2048 + k * 1024); } while (0)
; #define G_MMA(ai, bj, At_, Bt_) do { __builtin_amdgcn_s_setprio(1); _Pragma("unroll") for (int m = 0; m < 4; ++m) _Pragma("unroll") for (int n = 0; n < 2; ++n) _Pragma("unroll") for (int k = 0; k < 2; ++k) \
;         acc[ai][bj][m][n] = __builtin_amdgcn_mfma_f32_16x16x32_bf16(Bt_[n][k], At_[m][k], acc[ai][bj][m][n], 0, 0, 0); __builtin_amdgcn_s_setprio(0); } while (0)
; #define WAIT_V(n) asm volatile("s_waitcnt vmcnt(" #n ")" ::: "memory")
; #define WAIT_L(n) asm volatile("s_waitcnt lgkmcnt(" #n ")" ::: "memory")
; #define BAR __builtin_amdgcn_s_barrier()
; #define SCHED __builtin_amdgcn_sched_barrier(0)
; template <class Get, class Epi>
; DI void gemm_loop(int ntiles, int ld, char* shm, const Get& get, const Epi& epi) {
;     ...
;             G_LDA(At, 1, 1); G_STAGE(G_SB(1, 0), b3, voffB); G_STAGE(G_SB(1, 1), b3 + hstep, voffB); G_STAGE(G_SA(1, 0), a3, voffA);
;             WAIT_V(8); WAIT_L(0); BAR; G_MMA(1, 0, At, B0); G_MMA(1, 1, At, B1); BAR; SCHED;
;         }
	s_add_i32 s4, s76, s26
	v_lshl_add_u64 v[144:145], v[144:145], 0, s[10:11]
	s_mov_b32 m0, s4
	ds_read_b128 v[180:183], v171 offset:49152
	ds_read_b128 v[188:191], v171 offset:50176
	ds_read_b128 v[192:195], v171 offset:51200
	ds_read_b128 v[196:199], v171 offset:52224
	ds_read_b128 v[200:203], v171 offset:53248
	ds_read_b128 v[204:207], v171 offset:54272
	ds_read_b128 v[208:211], v171 offset:55296
	ds_read_b128 v[212:215], v171 offset:56320
	global_load_lds_dwordx4 v[144:145], off
	s_add_i32 m0, s4, 0x2000
	s_add_u32 s4, s38, 0xb0080
	v_lshl_add_u64 v[144:145], v[166:167], 0, s[10:11]
	s_addc_u32 s5, s39, 0
	s_add_i32 s38, s78, s26
	global_load_lds_dwordx4 v[144:145], off
	v_lshl_add_u64 v[144:145], s[4:5], 0, v[148:149]
	s_mov_b32 m0, s38
	s_nop 0
	global_load_lds_dwordx4 v[144:145], off
	v_lshl_add_u64 v[144:145], s[4:5], 0, v[152:153]
	s_add_i32 m0, s38, 0x2000
	s_nop 0
	global_load_lds_dwordx4 v[144:145], off
	v_lshl_add_u64 v[144:145], v[184:185], 0, s[10:11]
	s_mov_b32 m0, s48
	s_nop 0
	global_load_lds_dwordx4 v[144:145], off
	v_lshl_add_u64 v[144:145], v[186:187], 0, s[10:11]
	s_mov_b32 m0, s49
	s_nop 0
	global_load_lds_dwordx4 v[144:145], off
	s_waitcnt vmcnt(8)
	s_waitcnt lgkmcnt(0)
	s_barrier
	s_setprio 1
	s_waitcnt lgkmcnt(0)
	v_mfma_f32_16x16x32_bf16 v[92:95], v[128:131], v[180:183], v[92:95]
	v_mfma_f32_16x16x32_bf16 v[88:91], v[136:139], v[180:183], v[88:91]
	v_mfma_f32_16x16x32_bf16 v[84:87], v[128:131], v[192:195], v[84:87]
	v_mfma_f32_16x16x32_bf16 v[80:83], v[136:139], v[192:195], v[80:83]
	v_mfma_f32_16x16x32_bf16 v[76:79], v[128:131], v[200:203], v[76:79]
	v_mfma_f32_16x16x32_bf16 v[72:75], v[136:139], v[200:203], v[72:75]
	v_mfma_f32_16x16x32_bf16 v[68:71], v[128:131], v[208:211], v[68:71]
	v_mfma_f32_16x16x32_bf16 v[64:67], v[136:139], v[208:211], v[64:67]
	v_mfma_f32_16x16x32_bf16 v[92:95], v[132:135], v[188:191], v[92:95]
	v_mfma_f32_16x16x32_bf16 v[88:91], v[140:143], v[188:191], v[88:91]
	v_mfma_f32_16x16x32_bf16 v[84:87], v[132:135], v[196:199], v[84:87]
	v_mfma_f32_16x16x32_bf16 v[80:83], v[140:143], v[196:199], v[80:83]
	v_mfma_f32_16x16x32_bf16 v[76:79], v[132:135], v[204:207], v[76:79]
	v_mfma_f32_16x16x32_bf16 v[72:75], v[140:143], v[204:207], v[72:75]
	v_mfma_f32_16x16x32_bf16 v[68:71], v[132:135], v[212:215], v[68:71]
	v_mfma_f32_16x16x32_bf16 v[64:67], v[140:143], v[212:215], v[64:67]
	s_setprio 0
	s_setprio 1
	v_mfma_f32_16x16x32_bf16 v[28:31], v[158:161], v[180:183], v[28:31]
	v_mfma_f32_16x16x32_bf16 v[24:27], v[172:175], v[180:183], v[24:27]
	v_mfma_f32_16x16x32_bf16 v[20:23], v[158:161], v[192:195], v[20:23]
	v_mfma_f32_16x16x32_bf16 v[16:19], v[172:175], v[192:195], v[16:19]
	v_mfma_f32_16x16x32_bf16 v[12:15], v[158:161], v[200:203], v[12:15]
	v_mfma_f32_16x16x32_bf16 v[8:11], v[172:175], v[200:203], v[8:11]
	v_mfma_f32_16x16x32_bf16 v[4:7], v[158:161], v[208:211], v[4:7]
	v_mfma_f32_16x16x32_bf16 v[0:3], v[172:175], v[208:211], v[0:3]
	v_mfma_f32_16x16x32_bf16 v[28:31], v[162:165], v[188:191], v[28:31]
	v_mfma_f32_16x16x32_bf16 v[24:27], v[176:179], v[188:191], v[24:27]
	v_mfma_f32_16x16x32_bf16 v[20:23], v[162:165], v[196:199], v[20:23]
	v_mfma_f32_16x16x32_bf16 v[16:19], v[176:179], v[196:199], v[16:19]
	v_mfma_f32_16x16x32_bf16 v[12:15], v[162:165], v[204:207], v[12:15]
	v_mfma_f32_16x16x32_bf16 v[8:11], v[176:179], v[204:207], v[8:11]
	v_mfma_f32_16x16x32_bf16 v[4:7], v[162:165], v[212:215], v[4:7]
	v_mfma_f32_16x16x32_bf16 v[0:3], v[176:179], v[212:215], v[0:3]
	s_setprio 0
	s_barrier
	s_add_u32 s73, s73, 0x100
	s_addc_u32 s74, s74, 0
	s_cmp_ge_u32 s75, s59
	s_mov_b64 s[4:5], s[14:15]
	s_mov_b32 s38, s75
	s_cbranch_scc0 .LBB0_850
	s_branch .Lpost_850

; #define G_STAGE(bufoff, gbase, voff) do { _Pragma("unroll") for (int _i = 0; _i < 2; ++_i) \
;         __builtin_amdgcn_global_load_lds((const unsigned*)((const char*)(gbase) + voff[_i]), (LAS unsigned*)(lds + (bufoff) + ldsw + _i * 8192), 16, 0, 0); } while (0)
; #define G_LDA(dst, b, h) do { _Pragma("unroll") for (int m = 0; m < 4; ++m) _Pragma("unroll") for (int k = 0; k < 2; ++k) dst[m][k] = *(const LAS bf16x8*)(lds + G_SA(b, h) + aoff + m * 2048 + k * 1024); } while (0)
; #define G_LDB(dst, b, h) do { _Pragma("unroll") for (int n = 0; n < 2; ++n) _Pragma("unroll") for (int k = 0; k < 2; ++k) dst[n][k] = *(const LAS bf16x8*)(lds + G_SB(b, h) + boff + n * 2048 + k * 1024); } while (0)
; #define G_MMA(ai, bj, At_, Bt_) do { __builtin_amdgcn_s_setprio(1); _Pragma("unroll") for (int m = 0; m < 4; ++m) _Pragma("unroll") for (int n = 0; n < 2; ++n) _Pragma("unroll") for (int k = 0; k < 2; ++k) \
;         acc[ai][bj][m][n] = __builtin_amdgcn_mfma_f32_16x16x32_bf16(Bt_[n][k], At_[m][k], acc[ai][bj][m][n], 0, 0, 0); __builtin_amdgcn_s_setprio(0); } while (0)
; #define WAIT_V(n) asm volatile("s_waitcnt vmcnt(" #n ")" ::: "memory")
; #define WAIT_L(n) asm volatile("s_waitcnt lgkmcnt(" #n ")" ::: "memory")
; #define BAR __builtin_amdgcn_s_barrier()
; template <class Get, class Epi>
; DI void gemm_loop(int ntiles, int ld, char* shm, const Get& get, const Epi& epi) {
;     ...
;         const int Ln = L + gridDim.x; const bool has_next = Ln < ntiles; if (has_next) nxt = get(Ln);
;         const char* nA = has_next ? (const char*)nxt.A + (size_t)nxt.brow * ld * 2 : cA; const char* nB = has_next ? (const char*)nxt.Bt + (size_t)nxt.bcol * ld * 2 : cB;
;         const int nt = cur.K / BK;
;         for (int t = 0; t < nt; t += 2) {
;             const bool last = (t == nt - 2);
;             const char* a1 = cA + (size_t)(t + 1) * kstep;
;             const char* a2 = last ? nA : cA + (size_t)(t + 2) * kstep; const char* b2 = last ? nB : cB + (size_t)(t + 2) * kstep;
;             const char* a3 = a2 + kstep; const char* b3 = b2 + kstep;
;             G_LDB(B0, 0, 0); G_LDB(B1, 0, 1); SCHED; G_LDA(At, 0, 0); G_STAGE(G_SA(1, 1), a1 + hstep, voffA);
;             WAIT_V(8); WAIT_L(0); BAR; G_MMA(0, 0, At, B0); G_MMA(0, 1, At, B1); BAR; SCHED;
;             G_LDA(At, 0, 1); G_STAGE(G_SB(0, 0), b2, voffB); G_STAGE(G_SB(0, 1), b2 + hstep, voffB); G_STAGE(G_SA(0, 0), a2, voffA);
.LBB0_1098:
	s_ashr_i32 s39, s38, 31
	s_lshl_b64 s[40:41], s[38:39], 11
	s_add_u32 s40, s2, s40
	s_addc_u32 s41, s3, s41
	s_and_b64 s[42:43], s[34:35], exec
	s_cselect_b32 s39, s41, s47
	s_cselect_b32 s72, s40, s46
	s_ashr_i32 s37, s36, 31
	s_lshl_b64 s[42:43], s[36:37], 11
	s_add_u32 s42, s0, s42
	s_addc_u32 s43, s1, s43
	s_and_b64 s[52:53], s[34:35], exec
	s_cselect_b32 s37, s43, s15
	s_cselect_b32 s73, s42, s14
	s_add_u32 s52, s46, 0x40080
	s_addc_u32 s53, s47, 0
	s_add_u32 s74, s14, 0x100
	s_addc_u32 s75, s15, 0
	s_mov_b32 s76, -2
.Lpeel_1099:
	ds_read_b128 v[140:143], v145
	ds_read_b128 v[148:151], v145 offset:1024
	ds_read_b128 v[152:155], v145 offset:2048
	ds_read_b128 v[156:159], v145 offset:3072
	ds_read_b128 v[160:163], v146
	ds_read_b128 v[164:167], v146 offset:1024
	ds_read_b128 v[168:171], v146 offset:2048
	ds_read_b128 v[172:175], v146 offset:3072
	s_add_u32 s14, s52, 0xfffc0080
	s_addc_u32 s15, s53, -1
	s_cmp_eq_u32 s76, 12
	s_cselect_b32 s47, s39, s15
	s_cselect_b32 s46, s72, s14
	s_cselect_b32 s15, s37, s75
	s_cselect_b32 s14, s73, s74
	v_lshl_add_u64 v[208:209], s[52:53], 0, v[136:137]
	s_add_i32 m0, s45, 0xc000
	ds_read_b128 v[176:179], v147
	ds_read_b128 v[180:183], v147 offset:1024
	ds_read_b128 v[184:187], v147 offset:2048
	ds_read_b128 v[188:191], v147 offset:3072
	ds_read_b128 v[192:195], v147 offset:4096
	ds_read_b128 v[196:199], v147 offset:5120
	ds_read_b128 v[200:203], v147 offset:6144
	ds_read_b128 v[204:207], v147 offset:7168
	global_load_lds_dwordx4 v[208:209], off
	v_lshl_add_u64 v[208:209], s[52:53], 0, v[138:139]
	s_add_i32 m0, s45, 0xe000
	s_nop 0
	global_load_lds_dwordx4 v[208:209], off
	s_waitcnt vmcnt(8)
	s_waitcnt lgkmcnt(0)
	s_barrier
	s_setprio 1
	s_waitcnt lgkmcnt(0)
	v_mfma_f32_16x16x32_bf16 v[124:127], v[140:143], v[176:179], 0
	v_mfma_f32_16x16x32_bf16 v[120:123], v[152:155], v[176:179], 0
	v_mfma_f32_16x16x32_bf16 v[116:119], v[140:143], v[184:187], 0
	v_mfma_f32_16x16x32_bf16 v[112:115], v[152:155], v[184:187], 0
	v_mfma_f32_16x16x32_bf16 v[108:111], v[140:143], v[192:195], 0
	v_mfma_f32_16x16x32_bf16 v[100:103], v[152:155], v[192:195], 0
	v_mfma_f32_16x16x32_bf16 v[92:95], v[140:143], v[200:203], 0
	v_mfma_f32_16x16x32_bf16 v[84:87], v[152:155], v[200:203], 0
	v_mfma_f32_16x16x32_bf16 v[124:127], v[148:151], v[180:183], v[124:127]
	v_mfma_f32_16x16x32_bf16 v[120:123], v[156:159], v[180:183], v[120:123]
	v_mfma_f32_16x16x32_bf16 v[116:119], v[148:151], v[188:191], v[116:119]
	v_mfma_f32_16x16x32_bf16 v[112:115], v[156:159], v[188:191], v[112:115]
	v_mfma_f32_16x16x32_bf16 v[108:111], v[148:151], v[196:199], v[108:111]
	v_mfma_f32_16x16x32_bf16 v[100:103], v[156:159], v[196:199], v[100:103]
	v_mfma_f32_16x16x32_bf16 v[92:95], v[148:151], v[204:207], v[92:95]
	v_mfma_f32_16x16x32_bf16 v[84:87], v[156:159], v[204:207], v[84:87]
	s_setprio 0
	s_setprio 1
	v_mfma_f32_16x16x32_bf16 v[104:107], v[160:163], v[176:179], 0
	v_mfma_f32_16x16x32_bf16 v[96:99], v[168:171], v[176:179], 0
	v_mfma_f32_16x16x32_bf16 v[88:91], v[160:163], v[184:187], 0
	v_mfma_f32_16x16x32_bf16 v[80:83], v[168:171], v[184:187], 0
	v_mfma_f32_16x16x32_bf16 v[76:79], v[160:163], v[192:195], 0
	v_mfma_f32_16x16x32_bf16 v[72:75], v[168:171], v[192:195], 0
	v_mfma_f32_16x16x32_bf16 v[68:71], v[160:163], v[200:203], 0
	v_mfma_f32_16x16x32_bf16 v[64:67], v[168:171], v[200:203], 0
	v_mfma_f32_16x16x32_bf16 v[104:107], v[164:167], v[180:183], v[104:107]
	v_mfma_f32_16x16x32_bf16 v[96:99], v[172:175], v[180:183], v[96:99]
	v_mfma_f32_16x16x32_bf16 v[88:91], v[164:167], v[188:191], v[88:91]
	v_mfma_f32_16x16x32_bf16 v[80:83], v[172:175], v[188:191], v[80:83]
	v_mfma_f32_16x16x32_bf16 v[76:79], v[164:167], v[196:199], v[76:79]
	v_mfma_f32_16x16x32_bf16 v[72:75], v[172:175], v[196:199], v[72:75]
	v_mfma_f32_16x16x32_bf16 v[68:71], v[164:167], v[204:207], v[68:71]
	v_mfma_f32_16x16x32_bf16 v[64:67], v[172:175], v[204:207], v[64:67]
	s_setprio 0
	s_barrier
	s_add_i32 s77, s57, s7
	v_lshl_add_u64 v[208:209], s[14:15], 0, v[130:131]
	s_mov_b32 m0, s77
	ds_read_b128 v[176:179], v147 offset:16384
	ds_read_b128 v[180:183], v147 offset:17408
	ds_read_b128 v[184:187], v147 offset:18432
	ds_read_b128 v[188:191], v147 offset:19456
	ds_read_b128 v[192:195], v147 offset:20480
	ds_read_b128 v[196:199], v147 offset:21504
	ds_read_b128 v[200:203], v147 offset:22528
	ds_read_b128 v[204:207], v147 offset:23552
	global_load_lds_dwordx4 v[208:209], off
	s_add_i32 m0, s77, 0x2000
	s_add_u32 s78, s14, 0x40000
	v_lshl_add_u64 v[210:211], s[14:15], 0, v[134:135]
	s_addc_u32 s79, s15, 0
	s_add_i32 s77, s58, s7
	global_load_lds_dwordx4 v[210:211], off
	v_lshl_add_u64 v[212:213], s[78:79], 0, v[130:131]
	s_mov_b32 m0, s77
	v_lshl_add_u64 v[214:215], s[46:47], 0, v[132:133]
	global_load_lds_dwordx4 v[212:213], off
	v_lshl_add_u64 v[212:213], s[78:79], 0, v[134:135]
	s_add_i32 m0, s77, 0x2000
	s_nop 0
	global_load_lds_dwordx4 v[212:213], off
	v_lshl_add_u64 v[212:213], s[46:47], 0, v[128:129]
	s_mov_b32 m0, s45
	s_nop 0
	global_load_lds_dwordx4 v[212:213], off
	s_mov_b32 m0, s49
	s_nop 0
	global_load_lds_dwordx4 v[214:215], off
	s_waitcnt vmcnt(8)
	s_waitcnt lgkmcnt(0)
	s_barrier
; #define G_STAGE(bufoff, gbase, voff) do { _Pragma("unroll") for (int _i = 0; _i < 2; ++_i) \
;         __builtin_amdgcn_global_load_lds((const unsigned*)((const char*)(gbase) + voff[_i]), (LAS unsigned*)(lds + (bufoff) + ldsw + _i * 8192), 16, 0, 0); } while (0)
; #define G_LDA(dst, b, h) do { _Pragma("unroll") for (int m = 0; m < 4; ++m) _Pragma("unroll") for (int k = 0; k < 2; ++k) dst[m][k] = *(const LAS bf16x8*)(lds + G_SA(b, h) + aoff + m * 2048 + k * 1024); } while (0)
; #define G_LDB(dst, b, h) do { _Pragma("unroll") for (int n = 0; n < 2; ++n) _Pragma("unroll") for (int k = 0; k < 2; ++k) dst[n][k] = *(const LAS bf16x8*)(lds + G_SB(b, h) + boff + n * 2048 + k * 1024); } while (0)
; #define G_MMA(ai, bj, At_, Bt_) do { __builtin_amdgcn_s_setprio(1); _Pragma("unroll") for (int m = 0; m < 4; ++m) _Pragma("unroll") for (int n = 0; n < 2; ++n) _Pragma("unroll") for (int k = 0; k < 2; ++k) \
;         acc[ai][bj][m][n] = __builtin_amdgcn_mfma_f32_16x16x32_bf16(Bt_[n][k], At_[m][k], acc[ai][bj][m][n], 0, 0, 0); __builtin_amdgcn_s_setprio(0); } while (0)
; #define WAIT_V(n) asm volatile("s_waitcnt vmcnt(" #n ")" ::: "memory")
; #define WAIT_L(n) asm volatile("s_waitcnt lgkmcnt(" #n ")" ::: "memory")
; #define BAR __builtin_amdgcn_s_barrier()
; #define SCHED __builtin_amdgcn_sched_barrier(0)
; template <class Get, class Epi>
; DI void gemm_loop(int ntiles, int ld, char* shm, const Get& get, const Epi& epi) {
;     ...
;             WAIT_V(8); WAIT_L(0); BAR; G_MMA(1, 0, At, B0); G_MMA(1, 1, At, B1); BAR; SCHED;
;             G_LDB(B0, 1, 0); G_LDB(B1, 1, 1); SCHED; G_LDA(At, 1, 0); G_STAGE(G_SA(0, 1), a2 + hstep, voffA);
;             WAIT_V(8); WAIT_L(0); BAR; G_MMA(0, 0, At, B0); G_MMA(0, 1, At, B1); BAR; SCHED;
	s_setprio 1
	s_waitcnt lgkmcnt(0)
	v_mfma_f32_16x16x32_bf16 v[60:63], v[140:143], v[176:179], 0
	v_mfma_f32_16x16x32_bf16 v[56:59], v[152:155], v[176:179], 0
	v_mfma_f32_16x16x32_bf16 v[52:55], v[140:143], v[184:187], 0
	v_mfma_f32_16x16x32_bf16 v[48:51], v[152:155], v[184:187], 0
	v_mfma_f32_16x16x32_bf16 v[44:47], v[140:143], v[192:195], 0
	v_mfma_f32_16x16x32_bf16 v[36:39], v[152:155], v[192:195], 0
	v_mfma_f32_16x16x32_bf16 v[28:31], v[140:143], v[200:203], 0
	v_mfma_f32_16x16x32_bf16 v[20:23], v[152:155], v[200:203], 0
	v_mfma_f32_16x16x32_bf16 v[60:63], v[148:151], v[180:183], v[60:63]
	v_mfma_f32_16x16x32_bf16 v[56:59], v[156:159], v[180:183], v[56:59]
	v_mfma_f32_16x16x32_bf16 v[52:55], v[148:151], v[188:191], v[52:55]
	v_mfma_f32_16x16x32_bf16 v[48:51], v[156:159], v[188:191], v[48:51]
	v_mfma_f32_16x16x32_bf16 v[44:47], v[148:151], v[196:199], v[44:47]
	v_mfma_f32_16x16x32_bf16 v[36:39], v[156:159], v[196:199], v[36:39]
	v_mfma_f32_16x16x32_bf16 v[28:31], v[148:151], v[204:207], v[28:31]
	v_mfma_f32_16x16x32_bf16 v[20:23], v[156:159], v[204:207], v[20:23]
	s_setprio 0
	s_setprio 1
	v_mfma_f32_16x16x32_bf16 v[40:43], v[160:163], v[176:179], 0
	v_mfma_f32_16x16x32_bf16 v[32:35], v[168:171], v[176:179], 0
	v_mfma_f32_16x16x32_bf16 v[24:27], v[160:163], v[184:187], 0
	v_mfma_f32_16x16x32_bf16 v[16:19], v[168:171], v[184:187], 0
	v_mfma_f32_16x16x32_bf16 v[12:15], v[160:163], v[192:195], 0
	v_mfma_f32_16x16x32_bf16 v[8:11], v[168:171], v[192:195], 0
	v_mfma_f32_16x16x32_bf16 v[4:7], v[160:163], v[200:203], 0
	v_mfma_f32_16x16x32_bf16 v[0:3], v[168:171], v[200:203], 0
	v_mfma_f32_16x16x32_bf16 v[40:43], v[164:167], v[180:183], v[40:43]
	v_mfma_f32_16x16x32_bf16 v[32:35], v[172:175], v[180:183], v[32:35]
	v_mfma_f32_16x16x32_bf16 v[24:27], v[164:167], v[188:191], v[24:27]
	v_mfma_f32_16x16x32_bf16 v[16:19], v[172:175], v[188:191], v[16:19]
	v_mfma_f32_16x16x32_bf16 v[12:15], v[164:167], v[196:199], v[12:15]
	v_mfma_f32_16x16x32_bf16 v[8:11], v[172:175], v[196:199], v[8:11]
	v_mfma_f32_16x16x32_bf16 v[4:7], v[164:167], v[204:207], v[4:7]
	v_mfma_f32_16x16x32_bf16 v[0:3], v[172:175], v[204:207], v[0:3]
	s_setprio 0
	s_barrier
	s_add_i32 s77, 0, 0x18000
	s_add_i32 s78, 0, 0x1c000
	v_add_u32_e32 v156, s77, v144
	v_add_u32_e32 v172, s78, v144
	ds_read_b128 v[140:143], v156
	ds_read_b128 v[148:151], v156 offset:1024
	ds_read_b128 v[152:155], v156 offset:2048
	ds_read_b128 v[156:159], v156 offset:3072
	ds_read_b128 v[160:163], v172
	ds_read_b128 v[164:167], v172 offset:1024
	ds_read_b128 v[168:171], v172 offset:2048
	ds_read_b128 v[172:175], v172 offset:3072
	s_add_u32 s46, s46, 0x40000
	s_addc_u32 s47, s47, 0
	s_mov_b32 m0, s50
	v_lshl_add_u64 v[216:217], s[46:47], 0, v[128:129]
	ds_read_b128 v[176:179], v147 offset:32768
	ds_read_b128 v[180:183], v147 offset:33792
	ds_read_b128 v[184:187], v147 offset:34816
	ds_read_b128 v[188:191], v147 offset:35840
	ds_read_b128 v[192:195], v147 offset:36864
	ds_read_b128 v[196:199], v147 offset:37888
	ds_read_b128 v[200:203], v147 offset:38912
	ds_read_b128 v[204:207], v147 offset:39936
	global_load_lds_dwordx4 v[216:217], off
	v_lshl_add_u64 v[216:217], s[46:47], 0, v[132:133]
	s_mov_b32 m0, s51
	s_nop 0
	global_load_lds_dwordx4 v[216:217], off
	s_waitcnt vmcnt(8)
	s_waitcnt lgkmcnt(0)
	s_barrier
	s_setprio 1
	s_waitcnt lgkmcnt(0)
	v_mfma_f32_16x16x32_bf16 v[124:127], v[140:143], v[176:179], v[124:127]
	v_mfma_f32_16x16x32_bf16 v[120:123], v[152:155], v[176:179], v[120:123]
	v_mfma_f32_16x16x32_bf16 v[116:119], v[140:143], v[184:187], v[116:119]
	v_mfma_f32_16x16x32_bf16 v[112:115], v[152:155], v[184:187], v[112:115]
	v_mfma_f32_16x16x32_bf16 v[108:111], v[140:143], v[192:195], v[108:111]
	v_mfma_f32_16x16x32_bf16 v[100:103], v[152:155], v[192:195], v[100:103]
	v_mfma_f32_16x16x32_bf16 v[92:95], v[140:143], v[200:203], v[92:95]
	v_mfma_f32_16x16x32_bf16 v[84:87], v[152:155], v[200:203], v[84:87]
	v_mfma_f32_16x16x32_bf16 v[124:127], v[148:151], v[180:183], v[124:127]
	v_mfma_f32_16x16x32_bf16 v[120:123], v[156:159], v[180:183], v[120:123]
	v_mfma_f32_16x16x32_bf16 v[116:119], v[148:151], v[188:191], v[116:119]
	v_mfma_f32_16x16x32_bf16 v[112:115], v[156:159], v[188:191], v[112:115]
	v_mfma_f32_16x16x32_bf16 v[108:111], v[148:151], v[196:199], v[108:111]
	v_mfma_f32_16x16x32_bf16 v[100:103], v[156:159], v[196:199], v[100:103]
	v_mfma_f32_16x16x32_bf16 v[92:95], v[148:151], v[204:207], v[92:95]
	v_mfma_f32_16x16x32_bf16 v[84:87], v[156:159], v[204:207], v[84:87]
	s_setprio 0
	s_setprio 1
	v_mfma_f32_16x16x32_bf16 v[104:107], v[160:163], v[176:179], v[104:107]
	v_mfma_f32_16x16x32_bf16 v[96:99], v[168:171], v[176:179], v[96:99]
	v_mfma_f32_16x16x32_bf16 v[88:91], v[160:163], v[184:187], v[88:91]
	v_mfma_f32_16x16x32_bf16 v[80:83], v[168:171], v[184:187], v[80:83]
	v_mfma_f32_16x16x32_bf16 v[76:79], v[160:163], v[192:195], v[76:79]
	v_mfma_f32_16x16x32_bf16 v[72:75], v[168:171], v[192:195], v[72:75]
	v_mfma_f32_16x16x32_bf16 v[68:71], v[160:163], v[200:203], v[68:71]
	v_mfma_f32_16x16x32_bf16 v[64:67], v[168:171], v[200:203], v[64:67]
	v_mfma_f32_16x16x32_bf16 v[104:107], v[164:167], v[180:183], v[104:107]
	v_mfma_f32_16x16x32_bf16 v[96:99], v[172:175], v[180:183], v[96:99]
	v_mfma_f32_16x16x32_bf16 v[88:91], v[164:167], v[188:191], v[88:91]
	v_mfma_f32_16x16x32_bf16 v[80:83], v[172:175], v[188:191], v[80:83]
	v_mfma_f32_16x16x32_bf16 v[76:79], v[164:167], v[196:199], v[76:79]
	v_mfma_f32_16x16x32_bf16 v[72:75], v[172:175], v[196:199], v[72:75]
	v_mfma_f32_16x16x32_bf16 v[68:71], v[164:167], v[204:207], v[68:71]
	v_mfma_f32_16x16x32_bf16 v[64:67], v[172:175], v[204:207], v[64:67]
	s_setprio 0
	s_barrier
; #define G_STAGE(bufoff, gbase, voff) do { _Pragma("unroll") for (int _i = 0; _i < 2; ++_i) \
;         __builtin_amdgcn_global_load_lds((const unsigned*)((const char*)(gbase) + voff[_i]), (LAS unsigned*)(lds + (bufoff) + ldsw + _i * 8192), 16, 0, 0); } while (0)
; #define G_LDA(dst, b, h) do { _Pragma("unroll") for (int m = 0; m < 4; ++m) _Pragma("unroll") for (int k = 0; k < 2; ++k) dst[m][k] = *(const LAS bf16x8*)(lds + G_SA(b, h) + aoff + m * 2048 + k * 1024); } while (0)
; #define G_MMA(ai, bj, At_, Bt_) do { __builtin_amdgcn_s_setprio(1); _Pragma("unroll") for (int m = 0; m < 4; ++m) _Pragma("unroll") for (int n = 0; n < 2; ++n) _Pragma("unroll") for (int k = 0; k < 2; ++k) \
;         acc[ai][bj][m][n] = __builtin_amdgcn_mfma_f32_16x16x32_bf16(Bt_[n][k], At_[m][k], acc[ai][bj][m][n], 0, 0, 0); __builtin_amdgcn_s_setprio(0); } while (0)
; #define WAIT_V(n) asm volatile("s_waitcnt vmcnt(" #n ")" ::: "memory")
; #define WAIT_L(n) asm volatile("s_waitcnt lgkmcnt(" #n ")" ::: "memory")
; #define BAR __builtin_amdgcn_s_barrier()
; #define SCHED __builtin_amdgcn_sched_barrier(0)
; template <class Get, class Epi>
; DI void gemm_loop(int ntiles, int ld, char* shm, const Get& get, const Epi& epi) {
;     ...
;             G_LDA(At, 1, 1); G_STAGE(G_SB(1, 0), b3, voffB); G_STAGE(G_SB(1, 1), b3 + hstep, voffB); G_STAGE(G_SA(1, 0), a3, voffA);
;             WAIT_V(8); WAIT_L(0); BAR; G_MMA(1, 0, At, B0); G_MMA(1, 1, At, B1); BAR; SCHED;
;         }
	s_add_i32 s46, s77, s7
	v_lshl_add_u64 v[208:209], v[208:209], 0, s[10:11]
	s_mov_b32 m0, s46
	ds_read_b128 v[176:179], v147 offset:49152
	ds_read_b128 v[180:183], v147 offset:50176
	ds_read_b128 v[184:187], v147 offset:51200
	ds_read_b128 v[188:191], v147 offset:52224
	ds_read_b128 v[192:195], v147 offset:53248
	ds_read_b128 v[196:199], v147 offset:54272
	ds_read_b128 v[200:203], v147 offset:55296
	ds_read_b128 v[204:207], v147 offset:56320
	global_load_lds_dwordx4 v[208:209], off
	s_add_i32 m0, s46, 0x2000
	s_add_u32 s14, s14, 0x40080
	v_lshl_add_u64 v[208:209], v[210:211], 0, s[10:11]
	s_addc_u32 s15, s15, 0
	s_add_i32 s46, s78, s7
	global_load_lds_dwordx4 v[208:209], off
	v_lshl_add_u64 v[208:209], s[14:15], 0, v[130:131]
	s_mov_b32 m0, s46
	s_nop 0
	global_load_lds_dwordx4 v[208:209], off
	v_lshl_add_u64 v[208:209], s[14:15], 0, v[134:135]
	s_add_i32 m0, s46, 0x2000
	s_nop 0
	global_load_lds_dwordx4 v[208:209], off
	v_lshl_add_u64 v[208:209], v[212:213], 0, s[10:11]
	s_mov_b32 m0, s54
	s_nop 0
	global_load_lds_dwordx4 v[208:209], off
	v_lshl_add_u64 v[208:209], v[214:215], 0, s[10:11]
	s_mov_b32 m0, s55
	s_nop 0
	global_load_lds_dwordx4 v[208:209], off
	s_waitcnt vmcnt(8)
	s_waitcnt lgkmcnt(0)
	s_barrier
	s_setprio 1
	s_waitcnt lgkmcnt(0)
	v_mfma_f32_16x16x32_bf16 v[60:63], v[140:143], v[176:179], v[60:63]
	v_mfma_f32_16x16x32_bf16 v[56:59], v[152:155], v[176:179], v[56:59]
	v_mfma_f32_16x16x32_bf16 v[52:55], v[140:143], v[184:187], v[52:55]
	v_mfma_f32_16x16x32_bf16 v[48:51], v[152:155], v[184:187], v[48:51]
	v_mfma_f32_16x16x32_bf16 v[44:47], v[140:143], v[192:195], v[44:47]
	v_mfma_f32_16x16x32_bf16 v[36:39], v[152:155], v[192:195], v[36:39]
	v_mfma_f32_16x16x32_bf16 v[28:31], v[140:143], v[200:203], v[28:31]
	v_mfma_f32_16x16x32_bf16 v[20:23], v[152:155], v[200:203], v[20:23]
	v_mfma_f32_16x16x32_bf16 v[60:63], v[148:151], v[180:183], v[60:63]
	v_mfma_f32_16x16x32_bf16 v[56:59], v[156:159], v[180:183], v[56:59]
	v_mfma_f32_16x16x32_bf16 v[52:55], v[148:151], v[188:191], v[52:55]
	v_mfma_f32_16x16x32_bf16 v[48:51], v[156:159], v[188:191], v[48:51]
	v_mfma_f32_16x16x32_bf16 v[44:47], v[148:151], v[196:199], v[44:47]
	v_mfma_f32_16x16x32_bf16 v[36:39], v[156:159], v[196:199], v[36:39]
	v_mfma_f32_16x16x32_bf16 v[28:31], v[148:151], v[204:207], v[28:31]
	v_mfma_f32_16x16x32_bf16 v[20:23], v[156:159], v[204:207], v[20:23]
	s_setprio 0
	s_setprio 1
	v_mfma_f32_16x16x32_bf16 v[40:43], v[160:163], v[176:179], v[40:43]
	v_mfma_f32_16x16x32_bf16 v[32:35], v[168:171], v[176:179], v[32:35]
	v_mfma_f32_16x16x32_bf16 v[24:27], v[160:163], v[184:187], v[24:27]
	v_mfma_f32_16x16x32_bf16 v[16:19], v[168:171], v[184:187], v[16:19]
	v_mfma_f32_16x16x32_bf16 v[12:15], v[160:163], v[192:195], v[12:15]
	v_mfma_f32_16x16x32_bf16 v[8:11], v[168:171], v[192:195], v[8:11]
	v_mfma_f32_16x16x32_bf16 v[4:7], v[160:163], v[200:203], v[4:7]
	v_mfma_f32_16x16x32_bf16 v[0:3], v[168:171], v[200:203], v[0:3]
	v_mfma_f32_16x16x32_bf16 v[40:43], v[164:167], v[180:183], v[40:43]
	v_mfma_f32_16x16x32_bf16 v[32:35], v[172:175], v[180:183], v[32:35]
	v_mfma_f32_16x16x32_bf16 v[24:27], v[164:167], v[188:191], v[24:27]
	v_mfma_f32_16x16x32_bf16 v[16:19], v[172:175], v[188:191], v[16:19]
	v_mfma_f32_16x16x32_bf16 v[12:15], v[164:167], v[196:199], v[12:15]
	v_mfma_f32_16x16x32_bf16 v[8:11], v[172:175], v[196:199], v[8:11]
	v_mfma_f32_16x16x32_bf16 v[4:7], v[164:167], v[204:207], v[4:7]
	v_mfma_f32_16x16x32_bf16 v[0:3], v[172:175], v[204:207], v[0:3]
	s_setprio 0
	s_barrier
	s_add_i32 s76, s76, 2
	s_add_u32 s52, s52, 0x100
	s_addc_u32 s53, s53, 0
	s_add_u32 s74, s74, 0x100
	s_addc_u32 s75, s75, 0
	s_cmp_gt_u32 s76, 13
	s_cbranch_scc0 .LBB0_1099
	s_branch .Lpost_1099

; #define G_STAGE(bufoff, gbase, voff) do { _Pragma("unroll") for (int _i = 0; _i < 2; ++_i) \
;         __builtin_amdgcn_global_load_lds((const unsigned*)((const char*)(gbase) + voff[_i]), (LAS unsigned*)(lds + (bufoff) + ldsw + _i * 8192), 16, 0, 0); } while (0)
; #define G_LDA(dst, b, h) do { _Pragma("unroll") for (int m = 0; m < 4; ++m) _Pragma("unroll") for (int k = 0; k < 2; ++k) dst[m][k] = *(const LAS bf16x8*)(lds + G_SA(b, h) + aoff + m * 2048 + k * 1024); } while (0)
; #define G_LDB(dst, b, h) do { _Pragma("unroll") for (int n = 0; n < 2; ++n) _Pragma("unroll") for (int k = 0; k < 2; ++k) dst[n][k] = *(const LAS bf16x8*)(lds + G_SB(b, h) + boff + n * 2048 + k * 1024); } while (0)
; #define G_MMA(ai, bj, At_, Bt_) do { __builtin_amdgcn_s_setprio(1); _Pragma("unroll") for (int m = 0; m < 4; ++m) _Pragma("unroll") for (int n = 0; n < 2; ++n) _Pragma("unroll") for (int k = 0; k < 2; ++k) \
;         acc[ai][bj][m][n] = __builtin_amdgcn_mfma_f32_16x16x32_bf16(Bt_[n][k], At_[m][k], acc[ai][bj][m][n], 0, 0, 0); __builtin_amdgcn_s_setprio(0); } while (0)
; #define WAIT_V(n) asm volatile("s_waitcnt vmcnt(" #n ")" ::: "memory")
; #define WAIT_L(n) asm volatile("s_waitcnt lgkmcnt(" #n ")" ::: "memory")
; #define BAR __builtin_amdgcn_s_barrier()
; template <class Get, class Epi>
; DI void gemm_loop(int ntiles, int ld, char* shm, const Get& get, const Epi& epi) {
;     ...
;         const int Ln = L + gridDim.x; const bool has_next = Ln < ntiles; if (has_next) nxt = get(Ln);
;         const char* nA = has_next ? (const char*)nxt.A + (size_t)nxt.brow * ld * 2 : cA; const char* nB = has_next ? (const char*)nxt.Bt + (size_t)nxt.bcol * ld * 2 : cB;
;         const int nt = cur.K / BK;
;         for (int t = 0; t < nt; t += 2) {
;             const bool last = (t == nt - 2);
;             const char* a1 = cA + (size_t)(t + 1) * kstep;
;             const char* a2 = last ? nA : cA + (size_t)(t + 2) * kstep; const char* b2 = last ? nB : cB + (size_t)(t + 2) * kstep;
;             const char* a3 = a2 + kstep; const char* b3 = b2 + kstep;
;             G_LDB(B0, 0, 0); G_LDB(B1, 0, 1); SCHED; G_LDA(At, 0, 0); G_STAGE(G_SA(1, 1), a1 + hstep, voffA);
;             WAIT_V(8); WAIT_L(0); BAR; G_MMA(0, 0, At, B0); G_MMA(0, 1, At, B1); BAR; SCHED;
;             G_LDA(At, 0, 1); G_STAGE(G_SB(0, 0), b2, voffB); G_STAGE(G_SB(0, 1), b2 + hstep, voffB); G_STAGE(G_SA(0, 0), a2, voffA);
.LBB0_1462:
	s_ashr_i32 s37, s36, 31
	s_lshl_b64 s[40:41], s[36:37], 11
	s_add_u32 s40, s0, s40
	s_addc_u32 s41, s1, s41
	s_and_b64 s[42:43], s[34:35], exec
	s_cselect_b32 s3, s41, s47
	s_cselect_b32 s37, s40, s46
	s_ashr_i32 s39, s38, 31
	s_lshl_b64 s[42:43], s[38:39], 11
	s_add_u32 s42, s4, s42
	s_addc_u32 s43, s5, s43
	s_and_b64 s[74:75], s[34:35], exec
	s_cselect_b32 s39, s43, s15
	s_cselect_b32 s73, s42, s14
	s_lshr_b32 s74, s48, 6
	s_add_i32 s75, s74, -2
	s_add_u32 s48, s46, 0x40080
	s_addc_u32 s49, s47, 0
	s_add_u32 s76, s14, 0x100
	s_addc_u32 s77, s15, 0
	s_mov_b32 s14, 0
.Lpeel_1463:
	ds_read_b128 v[128:131], v169
	ds_read_b128 v[132:135], v169 offset:1024
	ds_read_b128 v[136:139], v169 offset:2048
	ds_read_b128 v[140:143], v169 offset:3072
	ds_read_b128 v[158:161], v170
	ds_read_b128 v[162:165], v170 offset:1024
	ds_read_b128 v[172:175], v170 offset:2048
	ds_read_b128 v[176:179], v170 offset:3072
	s_add_i32 s78, s14, 2
	s_add_u32 s15, s48, 0xfffc0080
	s_addc_u32 s46, s49, -1
	s_cmp_eq_u32 s75, s14
	s_cselect_b32 s14, s73, s76
	s_cselect_b32 s47, s3, s46
	s_cselect_b32 s46, s37, s15
	s_cselect_b32 s15, s39, s77
	v_lshl_add_u64 v[144:145], s[48:49], 0, v[154:155]
	s_add_i32 m0, s45, 0xc000
	ds_read_b128 v[180:183], v171
	ds_read_b128 v[184:187], v171 offset:1024
	ds_read_b128 v[188:191], v171 offset:2048
	ds_read_b128 v[192:195], v171 offset:3072
	ds_read_b128 v[196:199], v171 offset:4096
	ds_read_b128 v[200:203], v171 offset:5120
	ds_read_b128 v[204:207], v171 offset:6144
	ds_read_b128 v[208:211], v171 offset:7168
	global_load_lds_dwordx4 v[144:145], off
	v_lshl_add_u64 v[144:145], s[48:49], 0, v[156:157]
	s_add_i32 m0, s45, 0xe000
	s_nop 0
	global_load_lds_dwordx4 v[144:145], off
	s_waitcnt vmcnt(8)
	s_waitcnt lgkmcnt(0)
	s_barrier
	s_setprio 1
	s_waitcnt lgkmcnt(0)
	v_mfma_f32_16x16x32_bf16 v[124:127], v[128:131], v[180:183], 0
	v_mfma_f32_16x16x32_bf16 v[120:123], v[136:139], v[180:183], 0
	v_mfma_f32_16x16x32_bf16 v[116:119], v[128:131], v[188:191], 0
	v_mfma_f32_16x16x32_bf16 v[112:115], v[136:139], v[188:191], 0
	v_mfma_f32_16x16x32_bf16 v[108:111], v[128:131], v[196:199], 0
	v_mfma_f32_16x16x32_bf16 v[104:107], v[136:139], v[196:199], 0
	v_mfma_f32_16x16x32_bf16 v[100:103], v[128:131], v[204:207], 0
	v_mfma_f32_16x16x32_bf16 v[96:99], v[136:139], v[204:207], 0
	v_mfma_f32_16x16x32_bf16 v[124:127], v[132:135], v[184:187], v[124:127]
	v_mfma_f32_16x16x32_bf16 v[120:123], v[140:143], v[184:187], v[120:123]
	v_mfma_f32_16x16x32_bf16 v[116:119], v[132:135], v[192:195], v[116:119]
	v_mfma_f32_16x16x32_bf16 v[112:115], v[140:143], v[192:195], v[112:115]
	v_mfma_f32_16x16x32_bf16 v[108:111], v[132:135], v[200:203], v[108:111]
	v_mfma_f32_16x16x32_bf16 v[104:107], v[140:143], v[200:203], v[104:107]
	v_mfma_f32_16x16x32_bf16 v[100:103], v[132:135], v[208:211], v[100:103]
	v_mfma_f32_16x16x32_bf16 v[96:99], v[140:143], v[208:211], v[96:99]
	s_setprio 0
	s_setprio 1
	v_mfma_f32_16x16x32_bf16 v[60:63], v[158:161], v[180:183], 0
	v_mfma_f32_16x16x32_bf16 v[56:59], v[172:175], v[180:183], 0
	v_mfma_f32_16x16x32_bf16 v[52:55], v[158:161], v[188:191], 0
	v_mfma_f32_16x16x32_bf16 v[48:51], v[172:175], v[188:191], 0
	v_mfma_f32_16x16x32_bf16 v[44:47], v[158:161], v[196:199], 0
	v_mfma_f32_16x16x32_bf16 v[40:43], v[172:175], v[196:199], 0
	v_mfma_f32_16x16x32_bf16 v[36:39], v[158:161], v[204:207], 0
	v_mfma_f32_16x16x32_bf16 v[32:35], v[172:175], v[204:207], 0
	v_mfma_f32_16x16x32_bf16 v[60:63], v[162:165], v[184:187], v[60:63]
	v_mfma_f32_16x16x32_bf16 v[56:59], v[176:179], v[184:187], v[56:59]
	v_mfma_f32_16x16x32_bf16 v[52:55], v[162:165], v[192:195], v[52:55]
	v_mfma_f32_16x16x32_bf16 v[48:51], v[176:179], v[192:195], v[48:51]
	v_mfma_f32_16x16x32_bf16 v[44:47], v[162:165], v[200:203], v[44:47]
	v_mfma_f32_16x16x32_bf16 v[40:43], v[176:179], v[200:203], v[40:43]
	v_mfma_f32_16x16x32_bf16 v[36:39], v[162:165], v[208:211], v[36:39]
	v_mfma_f32_16x16x32_bf16 v[32:35], v[176:179], v[208:211], v[32:35]
	s_setprio 0
	s_barrier
	s_add_i32 s79, s57, s7
	v_lshl_add_u64 v[144:145], s[14:15], 0, v[148:149]
	s_mov_b32 m0, s79
	ds_read_b128 v[180:183], v171 offset:16384
	ds_read_b128 v[184:187], v171 offset:17408
	ds_read_b128 v[188:191], v171 offset:18432
	ds_read_b128 v[192:195], v171 offset:19456
	ds_read_b128 v[196:199], v171 offset:20480
	ds_read_b128 v[200:203], v171 offset:21504
	ds_read_b128 v[204:207], v171 offset:22528
	ds_read_b128 v[208:211], v171 offset:23552
	global_load_lds_dwordx4 v[144:145], off
	s_add_i32 m0, s79, 0x2000
	s_add_u32 s80, s14, 0x40000
	v_lshl_add_u64 v[166:167], s[14:15], 0, v[152:153]
	s_addc_u32 s81, s15, 0
	s_add_i32 s79, s58, s7
	global_load_lds_dwordx4 v[166:167], off
	v_lshl_add_u64 v[212:213], s[80:81], 0, v[148:149]
	s_mov_b32 m0, s79
	v_lshl_add_u64 v[214:215], s[46:47], 0, v[150:151]
	global_load_lds_dwordx4 v[212:213], off
	v_lshl_add_u64 v[212:213], s[80:81], 0, v[152:153]
	s_add_i32 m0, s79, 0x2000
	s_nop 0
	global_load_lds_dwordx4 v[212:213], off
	v_lshl_add_u64 v[212:213], s[46:47], 0, v[146:147]
	s_mov_b32 m0, s45
	s_nop 0
	global_load_lds_dwordx4 v[212:213], off
	s_mov_b32 m0, s50
	s_nop 0
	global_load_lds_dwordx4 v[214:215], off
	s_waitcnt vmcnt(8)
	s_waitcnt lgkmcnt(0)
	s_barrier
; #define G_STAGE(bufoff, gbase, voff) do { _Pragma("unroll") for (int _i = 0; _i < 2; ++_i) \
;         __builtin_amdgcn_global_load_lds((const unsigned*)((const char*)(gbase) + voff[_i]), (LAS unsigned*)(lds + (bufoff) + ldsw + _i * 8192), 16, 0, 0); } while (0)
; #define G_LDA(dst, b, h) do { _Pragma("unroll") for (int m = 0; m < 4; ++m) _Pragma("unroll") for (int k = 0; k < 2; ++k) dst[m][k] = *(const LAS bf16x8*)(lds + G_SA(b, h) + aoff + m * 2048 + k * 1024); } while (0)
; #define G_LDB(dst, b, h) do { _Pragma("unroll") for (int n = 0; n < 2; ++n) _Pragma("unroll") for (int k = 0; k < 2; ++k) dst[n][k] = *(const LAS bf16x8*)(lds + G_SB(b, h) + boff + n * 2048 + k * 1024); } while (0)
; #define G_MMA(ai, bj, At_, Bt_) do { __builtin_amdgcn_s_setprio(1); _Pragma("unroll") for (int m = 0; m < 4; ++m) _Pragma("unroll") for (int n = 0; n < 2; ++n) _Pragma("unroll") for (int k = 0; k < 2; ++k) \
;         acc[ai][bj][m][n] = __builtin_amdgcn_mfma_f32_16x16x32_bf16(Bt_[n][k], At_[m][k], acc[ai][bj][m][n], 0, 0, 0); __builtin_amdgcn_s_setprio(0); } while (0)
; #define WAIT_V(n) asm volatile("s_waitcnt vmcnt(" #n ")" ::: "memory")
; #define WAIT_L(n) asm volatile("s_waitcnt lgkmcnt(" #n ")" ::: "memory")
; #define BAR __builtin_amdgcn_s_barrier()
; #define SCHED __builtin_amdgcn_sched_barrier(0)
; template <class Get, class Epi>
; DI void gemm_loop(int ntiles, int ld, char* shm, const Get& get, const Epi& epi) {
;     ...
;             WAIT_V(8); WAIT_L(0); BAR; G_MMA(1, 0, At, B0); G_MMA(1, 1, At, B1); BAR; SCHED;
;             G_LDB(B0, 1, 0); G_LDB(B1, 1, 1); SCHED; G_LDA(At, 1, 0); G_STAGE(G_SA(0, 1), a2 + hstep, voffA);
;             WAIT_V(8); WAIT_L(0); BAR; G_MMA(0, 0, At, B0); G_MMA(0, 1, At, B1); BAR; SCHED;
	s_setprio 1
	s_waitcnt lgkmcnt(0)
	v_mfma_f32_16x16x32_bf16 v[92:95], v[128:131], v[180:183], 0
	v_mfma_f32_16x16x32_bf16 v[88:91], v[136:139], v[180:183], 0
	v_mfma_f32_16x16x32_bf16 v[84:87], v[128:131], v[188:191], 0
	v_mfma_f32_16x16x32_bf16 v[80:83], v[136:139], v[188:191], 0
	v_mfma_f32_16x16x32_bf16 v[76:79], v[128:131], v[196:199], 0
	v_mfma_f32_16x16x32_bf16 v[72:75], v[136:139], v[196:199], 0
	v_mfma_f32_16x16x32_bf16 v[68:71], v[128:131], v[204:207], 0
	v_mfma_f32_16x16x32_bf16 v[64:67], v[136:139], v[204:207], 0
	v_mfma_f32_16x16x32_bf16 v[92:95], v[132:135], v[184:187], v[92:95]
	v_mfma_f32_16x16x32_bf16 v[88:91], v[140:143], v[184:187], v[88:91]
	v_mfma_f32_16x16x32_bf16 v[84:87], v[132:135], v[192:195], v[84:87]
	v_mfma_f32_16x16x32_bf16 v[80:83], v[140:143], v[192:195], v[80:83]
	v_mfma_f32_16x16x32_bf16 v[76:79], v[132:135], v[200:203], v[76:79]
	v_mfma_f32_16x16x32_bf16 v[72:75], v[140:143], v[200:203], v[72:75]
	v_mfma_f32_16x16x32_bf16 v[68:71], v[132:135], v[208:211], v[68:71]
	v_mfma_f32_16x16x32_bf16 v[64:67], v[140:143], v[208:211], v[64:67]
	s_setprio 0
	s_setprio 1
	v_mfma_f32_16x16x32_bf16 v[28:31], v[158:161], v[180:183], 0
	v_mfma_f32_16x16x32_bf16 v[24:27], v[172:175], v[180:183], 0
	v_mfma_f32_16x16x32_bf16 v[20:23], v[158:161], v[188:191], 0
	v_mfma_f32_16x16x32_bf16 v[16:19], v[172:175], v[188:191], 0
	v_mfma_f32_16x16x32_bf16 v[12:15], v[158:161], v[196:199], 0
	v_mfma_f32_16x16x32_bf16 v[8:11], v[172:175], v[196:199], 0
	v_mfma_f32_16x16x32_bf16 v[4:7], v[158:161], v[204:207], 0
	v_mfma_f32_16x16x32_bf16 v[0:3], v[172:175], v[204:207], 0
	v_mfma_f32_16x16x32_bf16 v[28:31], v[162:165], v[184:187], v[28:31]
	v_mfma_f32_16x16x32_bf16 v[24:27], v[176:179], v[184:187], v[24:27]
	v_mfma_f32_16x16x32_bf16 v[20:23], v[162:165], v[192:195], v[20:23]
	v_mfma_f32_16x16x32_bf16 v[16:19], v[176:179], v[192:195], v[16:19]
	v_mfma_f32_16x16x32_bf16 v[12:15], v[162:165], v[200:203], v[12:15]
	v_mfma_f32_16x16x32_bf16 v[8:11], v[176:179], v[200:203], v[8:11]
	v_mfma_f32_16x16x32_bf16 v[4:7], v[162:165], v[208:211], v[4:7]
	v_mfma_f32_16x16x32_bf16 v[0:3], v[176:179], v[208:211], v[0:3]
	s_setprio 0
	s_barrier
	s_add_i32 s79, 0, 0x18000
	s_add_i32 s80, 0, 0x1c000
	v_add_u32_e32 v140, s79, v168
	v_add_u32_e32 v176, s80, v168
	ds_read_b128 v[128:131], v140
	ds_read_b128 v[132:135], v140 offset:1024
	ds_read_b128 v[136:139], v140 offset:2048
	ds_read_b128 v[140:143], v140 offset:3072
	ds_read_b128 v[158:161], v176
	ds_read_b128 v[162:165], v176 offset:1024
	ds_read_b128 v[172:175], v176 offset:2048
	ds_read_b128 v[176:179], v176 offset:3072
	s_add_u32 s46, s46, 0x40000
	s_addc_u32 s47, s47, 0
	s_mov_b32 m0, s51
	v_lshl_add_u64 v[216:217], s[46:47], 0, v[146:147]
	ds_read_b128 v[180:183], v171 offset:32768
	ds_read_b128 v[184:187], v171 offset:33792
	ds_read_b128 v[188:191], v171 offset:34816
	ds_read_b128 v[192:195], v171 offset:35840
	ds_read_b128 v[196:199], v171 offset:36864
	ds_read_b128 v[200:203], v171 offset:37888
	ds_read_b128 v[204:207], v171 offset:38912
	ds_read_b128 v[208:211], v171 offset:39936
	global_load_lds_dwordx4 v[216:217], off
	v_lshl_add_u64 v[216:217], s[46:47], 0, v[150:151]
	s_mov_b32 m0, s52
	s_nop 0
	global_load_lds_dwordx4 v[216:217], off
	s_waitcnt vmcnt(8)
	s_waitcnt lgkmcnt(0)
	s_barrier
	s_setprio 1
	s_waitcnt lgkmcnt(0)
	v_mfma_f32_16x16x32_bf16 v[124:127], v[128:131], v[180:183], v[124:127]
	v_mfma_f32_16x16x32_bf16 v[120:123], v[136:139], v[180:183], v[120:123]
	v_mfma_f32_16x16x32_bf16 v[116:119], v[128:131], v[188:191], v[116:119]
	v_mfma_f32_16x16x32_bf16 v[112:115], v[136:139], v[188:191], v[112:115]
	v_mfma_f32_16x16x32_bf16 v[108:111], v[128:131], v[196:199], v[108:111]
	v_mfma_f32_16x16x32_bf16 v[104:107], v[136:139], v[196:199], v[104:107]
	v_mfma_f32_16x16x32_bf16 v[100:103], v[128:131], v[204:207], v[100:103]
	v_mfma_f32_16x16x32_bf16 v[96:99], v[136:139], v[204:207], v[96:99]
	v_mfma_f32_16x16x32_bf16 v[124:127], v[132:135], v[184:187], v[124:127]
	v_mfma_f32_16x16x32_bf16 v[120:123], v[140:143], v[184:187], v[120:123]
	v_mfma_f32_16x16x32_bf16 v[116:119], v[132:135], v[192:195], v[116:119]
	v_mfma_f32_16x16x32_bf16 v[112:115], v[140:143], v[192:195], v[112:115]
	v_mfma_f32_16x16x32_bf16 v[108:111], v[132:135], v[200:203], v[108:111]
	v_mfma_f32_16x16x32_bf16 v[104:107], v[140:143], v[200:203], v[104:107]
	v_mfma_f32_16x16x32_bf16 v[100:103], v[132:135], v[208:211], v[100:103]
	v_mfma_f32_16x16x32_bf16 v[96:99], v[140:143], v[208:211], v[96:99]
	s_setprio 0
	s_setprio 1
	v_mfma_f32_16x16x32_bf16 v[60:63], v[158:161], v[180:183], v[60:63]
	v_mfma_f32_16x16x32_bf16 v[56:59], v[172:175], v[180:183], v[56:59]
	v_mfma_f32_16x16x32_bf16 v[52:55], v[158:161], v[188:191], v[52:55]
	v_mfma_f32_16x16x32_bf16 v[48:51], v[172:175], v[188:191], v[48:51]
	v_mfma_f32_16x16x32_bf16 v[44:47], v[158:161], v[196:199], v[44:47]
	v_mfma_f32_16x16x32_bf16 v[40:43], v[172:175], v[196:199], v[40:43]
	v_mfma_f32_16x16x32_bf16 v[36:39], v[158:161], v[204:207], v[36:39]
	v_mfma_f32_16x16x32_bf16 v[32:35], v[172:175], v[204:207], v[32:35]
	v_mfma_f32_16x16x32_bf16 v[60:63], v[162:165], v[184:187], v[60:63]
	v_mfma_f32_16x16x32_bf16 v[56:59], v[176:179], v[184:187], v[56:59]
	v_mfma_f32_16x16x32_bf16 v[52:55], v[162:165], v[192:195], v[52:55]
	v_mfma_f32_16x16x32_bf16 v[48:51], v[176:179], v[192:195], v[48:51]
	v_mfma_f32_16x16x32_bf16 v[44:47], v[162:165], v[200:203], v[44:47]
	v_mfma_f32_16x16x32_bf16 v[40:43], v[176:179], v[200:203], v[40:43]
	v_mfma_f32_16x16x32_bf16 v[36:39], v[162:165], v[208:211], v[36:39]
	v_mfma_f32_16x16x32_bf16 v[32:35], v[176:179], v[208:211], v[32:35]
	s_setprio 0
	s_barrier
; #define G_STAGE(bufoff, gbase, voff) do { _Pragma("unroll") for (int _i = 0; _i < 2; ++_i) \
;         __builtin_amdgcn_global_load_lds((const unsigned*)((const char*)(gbase) + voff[_i]), (LAS unsigned*)(lds + (bufoff) + ldsw + _i * 8192), 16, 0, 0); } while (0)
; #define G_LDA(dst, b, h) do { _Pragma("unroll") for (int m = 0; m < 4; ++m) _Pragma("unroll") for (int k = 0; k < 2; ++k) dst[m][k] = *(const LAS bf16x8*)(lds + G_SA(b, h) + aoff + m * 2048 + k * 1024); } while (0)
; #define G_MMA(ai, bj, At_, Bt_) do { __builtin_amdgcn_s_setprio(1); _Pragma("unroll") for (int m = 0; m < 4; ++m) _Pragma("unroll") for (int n = 0; n < 2; ++n) _Pragma("unroll") for (int k = 0; k < 2; ++k) \
;         acc[ai][bj][m][n] = __builtin_amdgcn_mfma_f32_16x16x32_bf16(Bt_[n][k], At_[m][k], acc[ai][bj][m][n], 0, 0, 0); __builtin_amdgcn_s_setprio(0); } while (0)
; #define WAIT_V(n) asm volatile("s_waitcnt vmcnt(" #n ")" ::: "memory")
; #define WAIT_L(n) asm volatile("s_waitcnt lgkmcnt(" #n ")" ::: "memory")
; #define BAR __builtin_amdgcn_s_barrier()
; #define SCHED __builtin_amdgcn_sched_barrier(0)
; template <class Get, class Epi>
; DI void gemm_loop(int ntiles, int ld, char* shm, const Get& get, const Epi& epi) {
;     ...
;             G_LDA(At, 1, 1); G_STAGE(G_SB(1, 0), b3, voffB); G_STAGE(G_SB(1, 1), b3 + hstep, voffB); G_STAGE(G_SA(1, 0), a3, voffA);
;             WAIT_V(8); WAIT_L(0); BAR; G_MMA(1, 0, At, B0); G_MMA(1, 1, At, B1); BAR; SCHED;
;         }
	s_add_i32 s46, s79, s7
	v_lshl_add_u64 v[144:145], v[144:145], 0, s[10:11]
	s_mov_b32 m0, s46
	ds_read_b128 v[180:183], v171 offset:49152
	ds_read_b128 v[184:187], v171 offset:50176
	ds_read_b128 v[188:191], v171 offset:51200
	ds_read_b128 v[192:195], v171 offset:52224
	ds_read_b128 v[196:199], v171 offset:53248
	ds_read_b128 v[200:203], v171 offset:54272
	ds_read_b128 v[204:207], v171 offset:55296
	ds_read_b128 v[208:211], v171 offset:56320
	global_load_lds_dwordx4 v[144:145], off
	s_add_i32 m0, s46, 0x2000
	s_add_u32 s14, s14, 0x40080
	v_lshl_add_u64 v[144:145], v[166:167], 0, s[10:11]
	s_addc_u32 s15, s15, 0
	s_add_i32 s46, s80, s7
	global_load_lds_dwordx4 v[144:145], off
	v_lshl_add_u64 v[144:145], s[14:15], 0, v[148:149]
	s_mov_b32 m0, s46
	s_nop 0
	global_load_lds_dwordx4 v[144:145], off
	v_lshl_add_u64 v[144:145], s[14:15], 0, v[152:153]
	s_add_i32 m0, s46, 0x2000
	s_nop 0
	global_load_lds_dwordx4 v[144:145], off
	v_lshl_add_u64 v[144:145], v[212:213], 0, s[10:11]
	s_mov_b32 m0, s55
	s_nop 0
	global_load_lds_dwordx4 v[144:145], off
	v_lshl_add_u64 v[144:145], v[214:215], 0, s[10:11]
	s_mov_b32 m0, s56
	s_nop 0
	global_load_lds_dwordx4 v[144:145], off
	s_waitcnt vmcnt(8)
	s_waitcnt lgkmcnt(0)
	s_barrier
	s_setprio 1
	s_waitcnt lgkmcnt(0)
	v_mfma_f32_16x16x32_bf16 v[92:95], v[128:131], v[180:183], v[92:95]
	v_mfma_f32_16x16x32_bf16 v[88:91], v[136:139], v[180:183], v[88:91]
	v_mfma_f32_16x16x32_bf16 v[84:87], v[128:131], v[188:191], v[84:87]
	v_mfma_f32_16x16x32_bf16 v[80:83], v[136:139], v[188:191], v[80:83]
	v_mfma_f32_16x16x32_bf16 v[76:79], v[128:131], v[196:199], v[76:79]
	v_mfma_f32_16x16x32_bf16 v[72:75], v[136:139], v[196:199], v[72:75]
	v_mfma_f32_16x16x32_bf16 v[68:71], v[128:131], v[204:207], v[68:71]
	v_mfma_f32_16x16x32_bf16 v[64:67], v[136:139], v[204:207], v[64:67]
	v_mfma_f32_16x16x32_bf16 v[92:95], v[132:135], v[184:187], v[92:95]
	v_mfma_f32_16x16x32_bf16 v[88:91], v[140:143], v[184:187], v[88:91]
	v_mfma_f32_16x16x32_bf16 v[84:87], v[132:135], v[192:195], v[84:87]
	v_mfma_f32_16x16x32_bf16 v[80:83], v[140:143], v[192:195], v[80:83]
	v_mfma_f32_16x16x32_bf16 v[76:79], v[132:135], v[200:203], v[76:79]
	v_mfma_f32_16x16x32_bf16 v[72:75], v[140:143], v[200:203], v[72:75]
	v_mfma_f32_16x16x32_bf16 v[68:71], v[132:135], v[208:211], v[68:71]
	v_mfma_f32_16x16x32_bf16 v[64:67], v[140:143], v[208:211], v[64:67]
	s_setprio 0
	s_setprio 1
	v_mfma_f32_16x16x32_bf16 v[28:31], v[158:161], v[180:183], v[28:31]
	v_mfma_f32_16x16x32_bf16 v[24:27], v[172:175], v[180:183], v[24:27]
	v_mfma_f32_16x16x32_bf16 v[20:23], v[158:161], v[188:191], v[20:23]
	v_mfma_f32_16x16x32_bf16 v[16:19], v[172:175], v[188:191], v[16:19]
	v_mfma_f32_16x16x32_bf16 v[12:15], v[158:161], v[196:199], v[12:15]
	v_mfma_f32_16x16x32_bf16 v[8:11], v[172:175], v[196:199], v[8:11]
	v_mfma_f32_16x16x32_bf16 v[4:7], v[158:161], v[204:207], v[4:7]
	v_mfma_f32_16x16x32_bf16 v[0:3], v[172:175], v[204:207], v[0:3]
	v_mfma_f32_16x16x32_bf16 v[28:31], v[162:165], v[184:187], v[28:31]
	v_mfma_f32_16x16x32_bf16 v[24:27], v[176:179], v[184:187], v[24:27]
	v_mfma_f32_16x16x32_bf16 v[20:23], v[162:165], v[192:195], v[20:23]
	v_mfma_f32_16x16x32_bf16 v[16:19], v[176:179], v[192:195], v[16:19]
	v_mfma_f32_16x16x32_bf16 v[12:15], v[162:165], v[200:203], v[12:15]
	v_mfma_f32_16x16x32_bf16 v[8:11], v[176:179], v[200:203], v[8:11]
	v_mfma_f32_16x16x32_bf16 v[4:7], v[162:165], v[208:211], v[4:7]
	v_mfma_f32_16x16x32_bf16 v[0:3], v[176:179], v[208:211], v[0:3]
	s_setprio 0
	s_barrier
	s_add_u32 s48, s48, 0x100
	s_addc_u32 s49, s49, 0
	s_add_u32 s76, s76, 0x100
	s_addc_u32 s77, s77, 0
	s_cmp_ge_u32 s78, s74
	s_mov_b32 s14, s78
	s_cbranch_scc0 .LBB0_1463
	s_branch .Lpost_1463

; #define G_STAGE(bufoff, gbase, voff) do { _Pragma("unroll") for (int _i = 0; _i < 2; ++_i) \
;         __builtin_amdgcn_global_load_lds((const unsigned*)((const char*)(gbase) + voff[_i]), (LAS unsigned*)(lds + (bufoff) + ldsw + _i * 8192), 16, 0, 0); } while (0)
; #define G_LDA(dst, b, h) do { _Pragma("unroll") for (int m = 0; m < 4; ++m) _Pragma("unroll") for (int k = 0; k < 2; ++k) dst[m][k] = *(const LAS bf16x8*)(lds + G_SA(b, h) + aoff + m * 2048 + k * 1024); } while (0)
; #define G_LDB(dst, b, h) do { _Pragma("unroll") for (int n = 0; n < 2; ++n) _Pragma("unroll") for (int k = 0; k < 2; ++k) dst[n][k] = *(const LAS bf16x8*)(lds + G_SB(b, h) + boff + n * 2048 + k * 1024); } while (0)
; #define G_MMA(ai, bj, At_, Bt_) do { __builtin_amdgcn_s_setprio(1); _Pragma("unroll") for (int m = 0; m < 4; ++m) _Pragma("unroll") for (int n = 0; n < 2; ++n) _Pragma("unroll") for (int k = 0; k < 2; ++k) \
;         acc[ai][bj][m][n] = __builtin_amdgcn_mfma_f32_16x16x32_bf16(Bt_[n][k], At_[m][k], acc[ai][bj][m][n], 0, 0, 0); __builtin_amdgcn_s_setprio(0); } while (0)
; #define WAIT_V(n) asm volatile("s_waitcnt vmcnt(" #n ")" ::: "memory")
; #define WAIT_L(n) asm volatile("s_waitcnt lgkmcnt(" #n ")" ::: "memory")
; #define BAR __builtin_amdgcn_s_barrier()
; template <class Get, class Epi>
; DI void gemm_loop(int ntiles, int ld, char* shm, const Get& get, const Epi& epi) {
;     ...
;         const int Ln = L + gridDim.x; const bool has_next = Ln < ntiles; if (has_next) nxt = get(Ln);
;         const char* nA = has_next ? (const char*)nxt.A + (size_t)nxt.brow * ld * 2 : cA; const char* nB = has_next ? (const char*)nxt.Bt + (size_t)nxt.bcol * ld * 2 : cB;
;         const int nt = cur.K / BK;
;         for (int t = 0; t < nt; t += 2) {
;             const bool last = (t == nt - 2);
;             const char* a1 = cA + (size_t)(t + 1) * kstep;
;             const char* a2 = last ? nA : cA + (size_t)(t + 2) * kstep; const char* b2 = last ? nB : cB + (size_t)(t + 2) * kstep;
;             const char* a3 = a2 + kstep; const char* b3 = b2 + kstep;
;             G_LDB(B0, 0, 0); G_LDB(B1, 0, 1); SCHED; G_LDA(At, 0, 0); G_STAGE(G_SA(1, 1), a1 + hstep, voffA);
;             WAIT_V(8); WAIT_L(0); BAR; G_MMA(0, 0, At, B0); G_MMA(0, 1, At, B1); BAR; SCHED;
;             G_LDA(At, 0, 1); G_STAGE(G_SB(0, 0), b2, voffB); G_STAGE(G_SB(0, 1), b2 + hstep, voffB); G_STAGE(G_SA(0, 0), a2, voffA);
.LBB0_1693:
	s_ashr_i32 s9, s8, 31
	s_lshl_b64 s[12:13], s[8:9], 11
	s_add_u32 s12, s16, s12
	s_addc_u32 s13, s17, s13
	s_and_b64 s[30:31], s[6:7], exec
	s_cselect_b32 s9, s13, s39
	s_cselect_b32 s53, s12, s38
	s_ashr_i32 s11, s10, 31
	s_lshl_b64 s[30:31], s[10:11], 11
	s_add_u32 s30, s90, s30
	s_addc_u32 s31, s91, s31
	s_and_b64 s[40:41], s[6:7], exec
	s_cselect_b32 s11, s31, s15
	s_cselect_b32 s54, s30, s14
	s_add_u32 s38, s38, 0x40080
	s_addc_u32 s39, s39, 0
	s_add_u32 s55, s14, 0x100
	s_addc_u32 s56, s15, 0
	s_mov_b32 s57, -2
.Lpeel_1694:
	ds_read_b128 v[144:147], v141
	ds_read_b128 v[148:151], v141 offset:1024
	ds_read_b128 v[152:155], v141 offset:2048
	ds_read_b128 v[156:159], v141 offset:3072
	ds_read_b128 v[160:163], v142
	ds_read_b128 v[164:167], v142 offset:1024
	ds_read_b128 v[168:171], v142 offset:2048
	ds_read_b128 v[172:175], v142 offset:3072
	s_add_u32 s14, s38, 0xfffc0080
	s_addc_u32 s15, s39, -1
	s_cmp_eq_u32 s57, 12
	s_cselect_b32 s41, s9, s15
	s_cselect_b32 s40, s53, s14
	s_cselect_b32 s15, s11, s56
	s_cselect_b32 s14, s54, s55
	v_lshl_add_u64 v[208:209], s[38:39], 0, v[136:137]
	s_add_i32 m0, s35, 0xc000
	ds_read_b128 v[176:179], v143
	ds_read_b128 v[180:183], v143 offset:1024
	ds_read_b128 v[184:187], v143 offset:2048
	ds_read_b128 v[188:191], v143 offset:3072
	ds_read_b128 v[192:195], v143 offset:4096
	ds_read_b128 v[196:199], v143 offset:5120
	ds_read_b128 v[200:203], v143 offset:6144
	ds_read_b128 v[204:207], v143 offset:7168
	global_load_lds_dwordx4 v[208:209], off
	v_lshl_add_u64 v[208:209], s[38:39], 0, v[138:139]
	s_add_i32 m0, s35, 0xe000
	s_nop 0
	global_load_lds_dwordx4 v[208:209], off
	s_waitcnt vmcnt(8)
	s_waitcnt lgkmcnt(0)
	s_barrier
	s_setprio 1
	s_waitcnt lgkmcnt(0)
	v_mfma_f32_16x16x32_bf16 v[124:127], v[144:147], v[176:179], 0
	v_mfma_f32_16x16x32_bf16 v[120:123], v[152:155], v[176:179], 0
	v_mfma_f32_16x16x32_bf16 v[108:111], v[144:147], v[184:187], 0
	v_mfma_f32_16x16x32_bf16 v[104:107], v[152:155], v[184:187], 0
	v_mfma_f32_16x16x32_bf16 v[92:95], v[144:147], v[192:195], 0
	v_mfma_f32_16x16x32_bf16 v[88:91], v[152:155], v[192:195], 0
	v_mfma_f32_16x16x32_bf16 v[76:79], v[144:147], v[200:203], 0
	v_mfma_f32_16x16x32_bf16 v[72:75], v[152:155], v[200:203], 0
	v_mfma_f32_16x16x32_bf16 v[124:127], v[148:151], v[180:183], v[124:127]
	v_mfma_f32_16x16x32_bf16 v[120:123], v[156:159], v[180:183], v[120:123]
	v_mfma_f32_16x16x32_bf16 v[108:111], v[148:151], v[188:191], v[108:111]
	v_mfma_f32_16x16x32_bf16 v[104:107], v[156:159], v[188:191], v[104:107]
	v_mfma_f32_16x16x32_bf16 v[92:95], v[148:151], v[196:199], v[92:95]
	v_mfma_f32_16x16x32_bf16 v[88:91], v[156:159], v[196:199], v[88:91]
	v_mfma_f32_16x16x32_bf16 v[76:79], v[148:151], v[204:207], v[76:79]
	v_mfma_f32_16x16x32_bf16 v[72:75], v[156:159], v[204:207], v[72:75]
	s_setprio 0
	s_setprio 1
	v_mfma_f32_16x16x32_bf16 v[116:119], v[160:163], v[176:179], 0
	v_mfma_f32_16x16x32_bf16 v[112:115], v[168:171], v[176:179], 0
	v_mfma_f32_16x16x32_bf16 v[100:103], v[160:163], v[184:187], 0
	v_mfma_f32_16x16x32_bf16 v[96:99], v[168:171], v[184:187], 0
	v_mfma_f32_16x16x32_bf16 v[84:87], v[160:163], v[192:195], 0
	v_mfma_f32_16x16x32_bf16 v[80:83], v[168:171], v[192:195], 0
	v_mfma_f32_16x16x32_bf16 v[68:71], v[160:163], v[200:203], 0
	v_mfma_f32_16x16x32_bf16 v[64:67], v[168:171], v[200:203], 0
	v_mfma_f32_16x16x32_bf16 v[116:119], v[164:167], v[180:183], v[116:119]
	v_mfma_f32_16x16x32_bf16 v[112:115], v[172:175], v[180:183], v[112:115]
	v_mfma_f32_16x16x32_bf16 v[100:103], v[164:167], v[188:191], v[100:103]
	v_mfma_f32_16x16x32_bf16 v[96:99], v[172:175], v[188:191], v[96:99]
	v_mfma_f32_16x16x32_bf16 v[84:87], v[164:167], v[196:199], v[84:87]
	v_mfma_f32_16x16x32_bf16 v[80:83], v[172:175], v[196:199], v[80:83]
	v_mfma_f32_16x16x32_bf16 v[68:71], v[164:167], v[204:207], v[68:71]
	v_mfma_f32_16x16x32_bf16 v[64:67], v[172:175], v[204:207], v[64:67]
	s_setprio 0
	s_barrier
	s_add_i32 s58, s48, s42
	v_lshl_add_u64 v[208:209], s[14:15], 0, v[132:133]
	s_mov_b32 m0, s58
	ds_read_b128 v[176:179], v143 offset:16384
	ds_read_b128 v[180:183], v143 offset:17408
	ds_read_b128 v[184:187], v143 offset:18432
	ds_read_b128 v[188:191], v143 offset:19456
	ds_read_b128 v[192:195], v143 offset:20480
	ds_read_b128 v[196:199], v143 offset:21504
	ds_read_b128 v[200:203], v143 offset:22528
	ds_read_b128 v[204:207], v143 offset:23552
	global_load_lds_dwordx4 v[208:209], off
	s_add_i32 m0, s58, 0x2000
	s_add_u32 s58, s14, 0x40000
	v_lshl_add_u64 v[210:211], s[14:15], 0, v[128:129]
	s_addc_u32 s59, s15, 0
	s_add_i32 s71, s49, s42
	global_load_lds_dwordx4 v[210:211], off
	v_lshl_add_u64 v[212:213], s[58:59], 0, v[132:133]
	s_mov_b32 m0, s71
	v_lshl_add_u64 v[214:215], s[40:41], 0, v[130:131]
	global_load_lds_dwordx4 v[212:213], off
	v_lshl_add_u64 v[212:213], s[58:59], 0, v[128:129]
	s_add_i32 m0, s71, 0x2000
	s_nop 0
	global_load_lds_dwordx4 v[212:213], off
	v_lshl_add_u64 v[212:213], s[40:41], 0, v[134:135]
	s_mov_b32 m0, s35
	s_nop 0
	global_load_lds_dwordx4 v[212:213], off
	s_mov_b32 m0, s37
	s_nop 0
	global_load_lds_dwordx4 v[214:215], off
	s_waitcnt vmcnt(8)
	s_waitcnt lgkmcnt(0)
	s_barrier
; #define G_STAGE(bufoff, gbase, voff) do { _Pragma("unroll") for (int _i = 0; _i < 2; ++_i) \
;         __builtin_amdgcn_global_load_lds((const unsigned*)((const char*)(gbase) + voff[_i]), (LAS unsigned*)(lds + (bufoff) + ldsw + _i * 8192), 16, 0, 0); } while (0)
; #define G_LDA(dst, b, h) do { _Pragma("unroll") for (int m = 0; m < 4; ++m) _Pragma("unroll") for (int k = 0; k < 2; ++k) dst[m][k] = *(const LAS bf16x8*)(lds + G_SA(b, h) + aoff + m * 2048 + k * 1024); } while (0)
; #define G_LDB(dst, b, h) do { _Pragma("unroll") for (int n = 0; n < 2; ++n) _Pragma("unroll") for (int k = 0; k < 2; ++k) dst[n][k] = *(const LAS bf16x8*)(lds + G_SB(b, h) + boff + n * 2048 + k * 1024); } while (0)
; #define G_MMA(ai, bj, At_, Bt_) do { __builtin_amdgcn_s_setprio(1); _Pragma("unroll") for (int m = 0; m < 4; ++m) _Pragma("unroll") for (int n = 0; n < 2; ++n) _Pragma("unroll") for (int k = 0; k < 2; ++k) \
;         acc[ai][bj][m][n] = __builtin_amdgcn_mfma_f32_16x16x32_bf16(Bt_[n][k], At_[m][k], acc[ai][bj][m][n], 0, 0, 0); __builtin_amdgcn_s_setprio(0); } while (0)
; #define WAIT_V(n) asm volatile("s_waitcnt vmcnt(" #n ")" ::: "memory")
; #define WAIT_L(n) asm volatile("s_waitcnt lgkmcnt(" #n ")" ::: "memory")
; #define BAR __builtin_amdgcn_s_barrier()
; #define SCHED __builtin_amdgcn_sched_barrier(0)
; template <class Get, class Epi>
; DI void gemm_loop(int ntiles, int ld, char* shm, const Get& get, const Epi& epi) {
;     ...
;             WAIT_V(8); WAIT_L(0); BAR; G_MMA(1, 0, At, B0); G_MMA(1, 1, At, B1); BAR; SCHED;
;             G_LDB(B0, 1, 0); G_LDB(B1, 1, 1); SCHED; G_LDA(At, 1, 0); G_STAGE(G_SA(0, 1), a2 + hstep, voffA);
;             WAIT_V(8); WAIT_L(0); BAR; G_MMA(0, 0, At, B0); G_MMA(0, 1, At, B1); BAR; SCHED;
	s_setprio 1
	s_waitcnt lgkmcnt(0)
	v_mfma_f32_16x16x32_bf16 v[60:63], v[144:147], v[176:179], 0
	v_mfma_f32_16x16x32_bf16 v[56:59], v[152:155], v[176:179], 0
	v_mfma_f32_16x16x32_bf16 v[44:47], v[144:147], v[184:187], 0
	v_mfma_f32_16x16x32_bf16 v[40:43], v[152:155], v[184:187], 0
	v_mfma_f32_16x16x32_bf16 v[28:31], v[144:147], v[192:195], 0
	v_mfma_f32_16x16x32_bf16 v[24:27], v[152:155], v[192:195], 0
	v_mfma_f32_16x16x32_bf16 v[12:15], v[144:147], v[200:203], 0
	v_mfma_f32_16x16x32_bf16 v[8:11], v[152:155], v[200:203], 0
	v_mfma_f32_16x16x32_bf16 v[60:63], v[148:151], v[180:183], v[60:63]
	v_mfma_f32_16x16x32_bf16 v[56:59], v[156:159], v[180:183], v[56:59]
	v_mfma_f32_16x16x32_bf16 v[44:47], v[148:151], v[188:191], v[44:47]
	v_mfma_f32_16x16x32_bf16 v[40:43], v[156:159], v[188:191], v[40:43]
	v_mfma_f32_16x16x32_bf16 v[28:31], v[148:151], v[196:199], v[28:31]
	v_mfma_f32_16x16x32_bf16 v[24:27], v[156:159], v[196:199], v[24:27]
	v_mfma_f32_16x16x32_bf16 v[12:15], v[148:151], v[204:207], v[12:15]
	v_mfma_f32_16x16x32_bf16 v[8:11], v[156:159], v[204:207], v[8:11]
	s_setprio 0
	s_setprio 1
	v_mfma_f32_16x16x32_bf16 v[52:55], v[160:163], v[176:179], 0
	v_mfma_f32_16x16x32_bf16 v[48:51], v[168:171], v[176:179], 0
	v_mfma_f32_16x16x32_bf16 v[36:39], v[160:163], v[184:187], 0
	v_mfma_f32_16x16x32_bf16 v[32:35], v[168:171], v[184:187], 0
	v_mfma_f32_16x16x32_bf16 v[20:23], v[160:163], v[192:195], 0
	v_mfma_f32_16x16x32_bf16 v[16:19], v[168:171], v[192:195], 0
	v_mfma_f32_16x16x32_bf16 v[4:7], v[160:163], v[200:203], 0
	v_mfma_f32_16x16x32_bf16 v[0:3], v[168:171], v[200:203], 0
	v_mfma_f32_16x16x32_bf16 v[52:55], v[164:167], v[180:183], v[52:55]
	v_mfma_f32_16x16x32_bf16 v[48:51], v[172:175], v[180:183], v[48:51]
	v_mfma_f32_16x16x32_bf16 v[36:39], v[164:167], v[188:191], v[36:39]
	v_mfma_f32_16x16x32_bf16 v[32:35], v[172:175], v[188:191], v[32:35]
	v_mfma_f32_16x16x32_bf16 v[20:23], v[164:167], v[196:199], v[20:23]
	v_mfma_f32_16x16x32_bf16 v[16:19], v[172:175], v[196:199], v[16:19]
	v_mfma_f32_16x16x32_bf16 v[4:7], v[164:167], v[204:207], v[4:7]
	v_mfma_f32_16x16x32_bf16 v[0:3], v[172:175], v[204:207], v[0:3]
	s_setprio 0
	s_barrier
	s_add_i32 s58, 0, 0x18000
	s_add_i32 s59, 0, 0x1c000
	v_add_u32_e32 v156, s58, v140
	v_add_u32_e32 v172, s59, v140
	ds_read_b128 v[144:147], v156
	ds_read_b128 v[148:151], v156 offset:1024
	ds_read_b128 v[152:155], v156 offset:2048
	ds_read_b128 v[156:159], v156 offset:3072
	ds_read_b128 v[160:163], v172
	ds_read_b128 v[164:167], v172 offset:1024
	ds_read_b128 v[168:171], v172 offset:2048
	ds_read_b128 v[172:175], v172 offset:3072
	s_add_u32 s40, s40, 0x40000
	s_addc_u32 s41, s41, 0
	s_mov_b32 m0, s44
	v_lshl_add_u64 v[216:217], s[40:41], 0, v[134:135]
	ds_read_b128 v[176:179], v143 offset:32768
	ds_read_b128 v[180:183], v143 offset:33792
	ds_read_b128 v[184:187], v143 offset:34816
	ds_read_b128 v[188:191], v143 offset:35840
	ds_read_b128 v[192:195], v143 offset:36864
	ds_read_b128 v[196:199], v143 offset:37888
	ds_read_b128 v[200:203], v143 offset:38912
	ds_read_b128 v[204:207], v143 offset:39936
	global_load_lds_dwordx4 v[216:217], off
	v_lshl_add_u64 v[216:217], s[40:41], 0, v[130:131]
	s_mov_b32 m0, s45
	s_nop 0
	global_load_lds_dwordx4 v[216:217], off
	s_waitcnt vmcnt(8)
	s_waitcnt lgkmcnt(0)
	s_barrier
	s_setprio 1
	s_waitcnt lgkmcnt(0)
	v_mfma_f32_16x16x32_bf16 v[124:127], v[144:147], v[176:179], v[124:127]
	v_mfma_f32_16x16x32_bf16 v[120:123], v[152:155], v[176:179], v[120:123]
	v_mfma_f32_16x16x32_bf16 v[108:111], v[144:147], v[184:187], v[108:111]
	v_mfma_f32_16x16x32_bf16 v[104:107], v[152:155], v[184:187], v[104:107]
	v_mfma_f32_16x16x32_bf16 v[92:95], v[144:147], v[192:195], v[92:95]
	v_mfma_f32_16x16x32_bf16 v[88:91], v[152:155], v[192:195], v[88:91]
	v_mfma_f32_16x16x32_bf16 v[76:79], v[144:147], v[200:203], v[76:79]
	v_mfma_f32_16x16x32_bf16 v[72:75], v[152:155], v[200:203], v[72:75]
	v_mfma_f32_16x16x32_bf16 v[124:127], v[148:151], v[180:183], v[124:127]
	v_mfma_f32_16x16x32_bf16 v[120:123], v[156:159], v[180:183], v[120:123]
	v_mfma_f32_16x16x32_bf16 v[108:111], v[148:151], v[188:191], v[108:111]
	v_mfma_f32_16x16x32_bf16 v[104:107], v[156:159], v[188:191], v[104:107]
	v_mfma_f32_16x16x32_bf16 v[92:95], v[148:151], v[196:199], v[92:95]
	v_mfma_f32_16x16x32_bf16 v[88:91], v[156:159], v[196:199], v[88:91]
	v_mfma_f32_16x16x32_bf16 v[76:79], v[148:151], v[204:207], v[76:79]
	v_mfma_f32_16x16x32_bf16 v[72:75], v[156:159], v[204:207], v[72:75]
	s_setprio 0
	s_setprio 1
	v_mfma_f32_16x16x32_bf16 v[116:119], v[160:163], v[176:179], v[116:119]
	v_mfma_f32_16x16x32_bf16 v[112:115], v[168:171], v[176:179], v[112:115]
	v_mfma_f32_16x16x32_bf16 v[100:103], v[160:163], v[184:187], v[100:103]
	v_mfma_f32_16x16x32_bf16 v[96:99], v[168:171], v[184:187], v[96:99]
	v_mfma_f32_16x16x32_bf16 v[84:87], v[160:163], v[192:195], v[84:87]
	v_mfma_f32_16x16x32_bf16 v[80:83], v[168:171], v[192:195], v[80:83]
	v_mfma_f32_16x16x32_bf16 v[68:71], v[160:163], v[200:203], v[68:71]
	v_mfma_f32_16x16x32_bf16 v[64:67], v[168:171], v[200:203], v[64:67]
	v_mfma_f32_16x16x32_bf16 v[116:119], v[164:167], v[180:183], v[116:119]
	v_mfma_f32_16x16x32_bf16 v[112:115], v[172:175], v[180:183], v[112:115]
	v_mfma_f32_16x16x32_bf16 v[100:103], v[164:167], v[188:191], v[100:103]
	v_mfma_f32_16x16x32_bf16 v[96:99], v[172:175], v[188:191], v[96:99]
	v_mfma_f32_16x16x32_bf16 v[84:87], v[164:167], v[196:199], v[84:87]
	v_mfma_f32_16x16x32_bf16 v[80:83], v[172:175], v[196:199], v[80:83]
	v_mfma_f32_16x16x32_bf16 v[68:71], v[164:167], v[204:207], v[68:71]
	v_mfma_f32_16x16x32_bf16 v[64:67], v[172:175], v[204:207], v[64:67]
	s_setprio 0
	s_barrier
; #define G_STAGE(bufoff, gbase, voff) do { _Pragma("unroll") for (int _i = 0; _i < 2; ++_i) \
;         __builtin_amdgcn_global_load_lds((const unsigned*)((const char*)(gbase) + voff[_i]), (LAS unsigned*)(lds + (bufoff) + ldsw + _i * 8192), 16, 0, 0); } while (0)
; #define G_LDA(dst, b, h) do { _Pragma("unroll") for (int m = 0; m < 4; ++m) _Pragma("unroll") for (int k = 0; k < 2; ++k) dst[m][k] = *(const LAS bf16x8*)(lds + G_SA(b, h) + aoff + m * 2048 + k * 1024); } while (0)
; #define G_MMA(ai, bj, At_, Bt_) do { __builtin_amdgcn_s_setprio(1); _Pragma("unroll") for (int m = 0; m < 4; ++m) _Pragma("unroll") for (int n = 0; n < 2; ++n) _Pragma("unroll") for (int k = 0; k < 2; ++k) \
;         acc[ai][bj][m][n] = __builtin_amdgcn_mfma_f32_16x16x32_bf16(Bt_[n][k], At_[m][k], acc[ai][bj][m][n], 0, 0, 0); __builtin_amdgcn_s_setprio(0); } while (0)
; #define WAIT_V(n) asm volatile("s_waitcnt vmcnt(" #n ")" ::: "memory")
; #define WAIT_L(n) asm volatile("s_waitcnt lgkmcnt(" #n ")" ::: "memory")
; #define BAR __builtin_amdgcn_s_barrier()
; #define SCHED __builtin_amdgcn_sched_barrier(0)
; template <class Get, class Epi>
; DI void gemm_loop(int ntiles, int ld, char* shm, const Get& get, const Epi& epi) {
;     ...
;             G_LDA(At, 1, 1); G_STAGE(G_SB(1, 0), b3, voffB); G_STAGE(G_SB(1, 1), b3 + hstep, voffB); G_STAGE(G_SA(1, 0), a3, voffA);
;             WAIT_V(8); WAIT_L(0); BAR; G_MMA(1, 0, At, B0); G_MMA(1, 1, At, B1); BAR; SCHED;
;         }
	s_add_i32 s40, s58, s42
	v_lshl_add_u64 v[208:209], v[208:209], 0, s[2:3]
	s_mov_b32 m0, s40
	ds_read_b128 v[176:179], v143 offset:49152
	ds_read_b128 v[180:183], v143 offset:50176
	ds_read_b128 v[184:187], v143 offset:51200
	ds_read_b128 v[188:191], v143 offset:52224
	ds_read_b128 v[192:195], v143 offset:53248
	ds_read_b128 v[196:199], v143 offset:54272
	ds_read_b128 v[200:203], v143 offset:55296
	ds_read_b128 v[204:207], v143 offset:56320
	global_load_lds_dwordx4 v[208:209], off
	s_add_i32 m0, s40, 0x2000
	s_add_u32 s14, s14, 0x40080
	v_lshl_add_u64 v[208:209], v[210:211], 0, s[2:3]
	s_addc_u32 s15, s15, 0
	s_add_i32 s40, s59, s42
	global_load_lds_dwordx4 v[208:209], off
	v_lshl_add_u64 v[208:209], s[14:15], 0, v[132:133]
	s_mov_b32 m0, s40
	s_nop 0
	global_load_lds_dwordx4 v[208:209], off
	v_lshl_add_u64 v[208:209], s[14:15], 0, v[128:129]
	s_add_i32 m0, s40, 0x2000
	s_nop 0
	global_load_lds_dwordx4 v[208:209], off
	v_lshl_add_u64 v[208:209], v[212:213], 0, s[2:3]
	s_mov_b32 m0, s46
	s_nop 0
	global_load_lds_dwordx4 v[208:209], off
	v_lshl_add_u64 v[208:209], v[214:215], 0, s[2:3]
	s_mov_b32 m0, s47
	s_nop 0
	global_load_lds_dwordx4 v[208:209], off
	s_waitcnt vmcnt(8)
	s_waitcnt lgkmcnt(0)
	s_barrier
	s_setprio 1
	s_waitcnt lgkmcnt(0)
	v_mfma_f32_16x16x32_bf16 v[60:63], v[144:147], v[176:179], v[60:63]
	v_mfma_f32_16x16x32_bf16 v[56:59], v[152:155], v[176:179], v[56:59]
	v_mfma_f32_16x16x32_bf16 v[44:47], v[144:147], v[184:187], v[44:47]
	v_mfma_f32_16x16x32_bf16 v[40:43], v[152:155], v[184:187], v[40:43]
	v_mfma_f32_16x16x32_bf16 v[28:31], v[144:147], v[192:195], v[28:31]
	v_mfma_f32_16x16x32_bf16 v[24:27], v[152:155], v[192:195], v[24:27]
	v_mfma_f32_16x16x32_bf16 v[12:15], v[144:147], v[200:203], v[12:15]
	v_mfma_f32_16x16x32_bf16 v[8:11], v[152:155], v[200:203], v[8:11]
	v_mfma_f32_16x16x32_bf16 v[60:63], v[148:151], v[180:183], v[60:63]
	v_mfma_f32_16x16x32_bf16 v[56:59], v[156:159], v[180:183], v[56:59]
	v_mfma_f32_16x16x32_bf16 v[44:47], v[148:151], v[188:191], v[44:47]
	v_mfma_f32_16x16x32_bf16 v[40:43], v[156:159], v[188:191], v[40:43]
	v_mfma_f32_16x16x32_bf16 v[28:31], v[148:151], v[196:199], v[28:31]
	v_mfma_f32_16x16x32_bf16 v[24:27], v[156:159], v[196:199], v[24:27]
	v_mfma_f32_16x16x32_bf16 v[12:15], v[148:151], v[204:207], v[12:15]
	v_mfma_f32_16x16x32_bf16 v[8:11], v[156:159], v[204:207], v[8:11]
	s_setprio 0
	s_setprio 1
	v_mfma_f32_16x16x32_bf16 v[52:55], v[160:163], v[176:179], v[52:55]
	v_mfma_f32_16x16x32_bf16 v[48:51], v[168:171], v[176:179], v[48:51]
	v_mfma_f32_16x16x32_bf16 v[36:39], v[160:163], v[184:187], v[36:39]
	v_mfma_f32_16x16x32_bf16 v[32:35], v[168:171], v[184:187], v[32:35]
	v_mfma_f32_16x16x32_bf16 v[20:23], v[160:163], v[192:195], v[20:23]
	v_mfma_f32_16x16x32_bf16 v[16:19], v[168:171], v[192:195], v[16:19]
	v_mfma_f32_16x16x32_bf16 v[4:7], v[160:163], v[200:203], v[4:7]
	v_mfma_f32_16x16x32_bf16 v[0:3], v[168:171], v[200:203], v[0:3]
	v_mfma_f32_16x16x32_bf16 v[52:55], v[164:167], v[180:183], v[52:55]
	v_mfma_f32_16x16x32_bf16 v[48:51], v[172:175], v[180:183], v[48:51]
	v_mfma_f32_16x16x32_bf16 v[36:39], v[164:167], v[188:191], v[36:39]
	v_mfma_f32_16x16x32_bf16 v[32:35], v[172:175], v[188:191], v[32:35]
	v_mfma_f32_16x16x32_bf16 v[20:23], v[164:167], v[196:199], v[20:23]
	v_mfma_f32_16x16x32_bf16 v[16:19], v[172:175], v[196:199], v[16:19]
	v_mfma_f32_16x16x32_bf16 v[4:7], v[164:167], v[204:207], v[4:7]
	v_mfma_f32_16x16x32_bf16 v[0:3], v[172:175], v[204:207], v[0:3]
	s_setprio 0
	s_barrier
	s_add_i32 s57, s57, 2
	s_add_u32 s38, s38, 0x100
	s_addc_u32 s39, s39, 0
	s_add_u32 s55, s55, 0x100
	s_addc_u32 s56, s56, 0
	s_cmp_gt_u32 s57, 13
	s_cbranch_scc0 .LBB0_1694
	s_branch .Lpost_1694

; #define G_STAGE(bufoff, gbase, voff) do { _Pragma("unroll") for (int _i = 0; _i < 2; ++_i) \
;         __builtin_amdgcn_global_load_lds((const unsigned*)((const char*)(gbase) + voff[_i]), (LAS unsigned*)(lds + (bufoff) + ldsw + _i * 8192), 16, 0, 0); } while (0)
; #define G_LDA(dst, b, h) do { _Pragma("unroll") for (int m = 0; m < 4; ++m) _Pragma("unroll") for (int k = 0; k < 2; ++k) dst[m][k] = *(const LAS bf16x8*)(lds + G_SA(b, h) + aoff + m * 2048 + k * 1024); } while (0)
; #define G_LDB(dst, b, h) do { _Pragma("unroll") for (int n = 0; n < 2; ++n) _Pragma("unroll") for (int k = 0; k < 2; ++k) dst[n][k] = *(const LAS bf16x8*)(lds + G_SB(b, h) + boff + n * 2048 + k * 1024); } while (0)
; #define G_MMA(ai, bj, At_, Bt_) do { __builtin_amdgcn_s_setprio(1); _Pragma("unroll") for (int m = 0; m < 4; ++m) _Pragma("unroll") for (int n = 0; n < 2; ++n) _Pragma("unroll") for (int k = 0; k < 2; ++k) \
;         acc[ai][bj][m][n] = __builtin_amdgcn_mfma_f32_16x16x32_bf16(Bt_[n][k], At_[m][k], acc[ai][bj][m][n], 0, 0, 0); __builtin_amdgcn_s_setprio(0); } while (0)
; #define WAIT_V(n) asm volatile("s_waitcnt vmcnt(" #n ")" ::: "memory")
; #define WAIT_L(n) asm volatile("s_waitcnt lgkmcnt(" #n ")" ::: "memory")
; #define BAR __builtin_amdgcn_s_barrier()
; template <class Get, class Epi>
; DI void gemm_loop(int ntiles, int ld, char* shm, const Get& get, const Epi& epi) {
;     ...
;         const int Ln = L + gridDim.x; const bool has_next = Ln < ntiles; if (has_next) nxt = get(Ln);
;         const char* nA = has_next ? (const char*)nxt.A + (size_t)nxt.brow * ld * 2 : cA; const char* nB = has_next ? (const char*)nxt.Bt + (size_t)nxt.bcol * ld * 2 : cB;
;         const int nt = cur.K / BK;
;         for (int t = 0; t < nt; t += 2) {
;             const bool last = (t == nt - 2);
;             const char* a1 = cA + (size_t)(t + 1) * kstep;
;             const char* a2 = last ? nA : cA + (size_t)(t + 2) * kstep; const char* b2 = last ? nB : cB + (size_t)(t + 2) * kstep;
;             const char* a3 = a2 + kstep; const char* b3 = b2 + kstep;
;             G_LDB(B0, 0, 0); G_LDB(B1, 0, 1); SCHED; G_LDA(At, 0, 0); G_STAGE(G_SA(1, 1), a1 + hstep, voffA);
;             WAIT_V(8); WAIT_L(0); BAR; G_MMA(0, 0, At, B0); G_MMA(0, 1, At, B1); BAR; SCHED;
;             G_LDA(At, 0, 1); G_STAGE(G_SB(0, 0), b2, voffB); G_STAGE(G_SB(0, 1), b2 + hstep, voffB); G_STAGE(G_SA(0, 0), a2, voffA);
.LBB0_1780:
	s_lshr_b32 s73, s40, 6
	s_add_i32 s74, s73, -2
	s_add_u32 s75, s14, 0x100
	s_addc_u32 s76, s15, 0
	s_mov_b32 s40, 0
.Lpeel_1781:
	ds_read_b128 v[128:131], v169
	ds_read_b128 v[132:135], v169 offset:1024
	ds_read_b128 v[136:139], v169 offset:2048
	ds_read_b128 v[140:143], v169 offset:3072
	ds_read_b128 v[158:161], v170
	ds_read_b128 v[162:165], v170 offset:1024
	ds_read_b128 v[172:175], v170 offset:2048
	ds_read_b128 v[176:179], v170 offset:3072
	s_add_i32 s77, s40, 2
	s_add_u32 s14, s4, 0x100
	s_addc_u32 s15, s5, 0
	s_cmp_eq_u32 s74, s40
	s_cselect_b32 s40, s38, s75
	s_cselect_b32 s43, s37, s15
	s_cselect_b32 s42, s36, s14
	s_cselect_b32 s41, s39, s76
	v_lshl_add_u64 v[144:145], s[4:5], 0, v[154:155]
	s_add_i32 m0, s45, 0xc000
	ds_read_b128 v[180:183], v171
	ds_read_b128 v[184:187], v171 offset:1024
	ds_read_b128 v[188:191], v171 offset:2048
	ds_read_b128 v[192:195], v171 offset:3072
	ds_read_b128 v[196:199], v171 offset:4096
	ds_read_b128 v[200:203], v171 offset:5120
	ds_read_b128 v[204:207], v171 offset:6144
	ds_read_b128 v[208:211], v171 offset:7168
	global_load_lds_dwordx4 v[144:145], off
	v_lshl_add_u64 v[144:145], s[4:5], 0, v[156:157]
	s_add_i32 m0, s45, 0xe000
	s_nop 0
	global_load_lds_dwordx4 v[144:145], off
	s_waitcnt vmcnt(8)
	s_waitcnt lgkmcnt(0)
	s_barrier
	s_setprio 1
	s_waitcnt lgkmcnt(0)
	v_mfma_f32_16x16x32_bf16 v[124:127], v[128:131], v[180:183], 0
	v_mfma_f32_16x16x32_bf16 v[120:123], v[136:139], v[180:183], 0
	v_mfma_f32_16x16x32_bf16 v[116:119], v[128:131], v[188:191], 0
	v_mfma_f32_16x16x32_bf16 v[112:115], v[136:139], v[188:191], 0
	v_mfma_f32_16x16x32_bf16 v[108:111], v[128:131], v[196:199], 0
	v_mfma_f32_16x16x32_bf16 v[104:107], v[136:139], v[196:199], 0
	v_mfma_f32_16x16x32_bf16 v[100:103], v[128:131], v[204:207], 0
	v_mfma_f32_16x16x32_bf16 v[96:99], v[136:139], v[204:207], 0
	v_mfma_f32_16x16x32_bf16 v[124:127], v[132:135], v[184:187], v[124:127]
	v_mfma_f32_16x16x32_bf16 v[120:123], v[140:143], v[184:187], v[120:123]
	v_mfma_f32_16x16x32_bf16 v[116:119], v[132:135], v[192:195], v[116:119]
	v_mfma_f32_16x16x32_bf16 v[112:115], v[140:143], v[192:195], v[112:115]
	v_mfma_f32_16x16x32_bf16 v[108:111], v[132:135], v[200:203], v[108:111]
	v_mfma_f32_16x16x32_bf16 v[104:107], v[140:143], v[200:203], v[104:107]
	v_mfma_f32_16x16x32_bf16 v[100:103], v[132:135], v[208:211], v[100:103]
	v_mfma_f32_16x16x32_bf16 v[96:99], v[140:143], v[208:211], v[96:99]
	s_setprio 0
	s_setprio 1
	v_mfma_f32_16x16x32_bf16 v[60:63], v[158:161], v[180:183], 0
	v_mfma_f32_16x16x32_bf16 v[56:59], v[172:175], v[180:183], 0
	v_mfma_f32_16x16x32_bf16 v[52:55], v[158:161], v[188:191], 0
	v_mfma_f32_16x16x32_bf16 v[48:51], v[172:175], v[188:191], 0
	v_mfma_f32_16x16x32_bf16 v[44:47], v[158:161], v[196:199], 0
	v_mfma_f32_16x16x32_bf16 v[40:43], v[172:175], v[196:199], 0
	v_mfma_f32_16x16x32_bf16 v[36:39], v[158:161], v[204:207], 0
	v_mfma_f32_16x16x32_bf16 v[32:35], v[172:175], v[204:207], 0
	v_mfma_f32_16x16x32_bf16 v[60:63], v[162:165], v[184:187], v[60:63]
	v_mfma_f32_16x16x32_bf16 v[56:59], v[176:179], v[184:187], v[56:59]
	v_mfma_f32_16x16x32_bf16 v[52:55], v[162:165], v[192:195], v[52:55]
	v_mfma_f32_16x16x32_bf16 v[48:51], v[176:179], v[192:195], v[48:51]
	v_mfma_f32_16x16x32_bf16 v[44:47], v[162:165], v[200:203], v[44:47]
	v_mfma_f32_16x16x32_bf16 v[40:43], v[176:179], v[200:203], v[40:43]
	v_mfma_f32_16x16x32_bf16 v[36:39], v[162:165], v[208:211], v[36:39]
	v_mfma_f32_16x16x32_bf16 v[32:35], v[176:179], v[208:211], v[32:35]
	s_setprio 0
	s_barrier
	s_add_i32 s4, s53, s44
	v_lshl_add_u64 v[144:145], s[40:41], 0, v[148:149]
	s_mov_b32 m0, s4
	ds_read_b128 v[180:183], v171 offset:16384
	ds_read_b128 v[184:187], v171 offset:17408
	ds_read_b128 v[188:191], v171 offset:18432
	ds_read_b128 v[192:195], v171 offset:19456
	ds_read_b128 v[196:199], v171 offset:20480
	ds_read_b128 v[200:203], v171 offset:21504
	ds_read_b128 v[204:207], v171 offset:22528
	ds_read_b128 v[208:211], v171 offset:23552
	global_load_lds_dwordx4 v[144:145], off
	s_add_i32 m0, s4, 0x2000
	s_add_u32 s4, s40, 0xb0000
	v_lshl_add_u64 v[166:167], s[40:41], 0, v[152:153]
	s_addc_u32 s5, s41, 0
	s_add_i32 s78, s54, s44
	global_load_lds_dwordx4 v[166:167], off
	v_lshl_add_u64 v[212:213], s[4:5], 0, v[148:149]
	s_mov_b32 m0, s78
	v_lshl_add_u64 v[214:215], s[42:43], 0, v[150:151]
	global_load_lds_dwordx4 v[212:213], off
	v_lshl_add_u64 v[212:213], s[4:5], 0, v[152:153]
	s_add_i32 m0, s78, 0x2000
	s_nop 0
	global_load_lds_dwordx4 v[212:213], off
	v_lshl_add_u64 v[212:213], s[42:43], 0, v[146:147]
	s_mov_b32 m0, s45
	s_nop 0
	global_load_lds_dwordx4 v[212:213], off
	s_mov_b32 m0, s46
	s_nop 0
	global_load_lds_dwordx4 v[214:215], off
	s_waitcnt vmcnt(8)
	s_waitcnt lgkmcnt(0)
	s_barrier
; #define G_STAGE(bufoff, gbase, voff) do { _Pragma("unroll") for (int _i = 0; _i < 2; ++_i) \
;         __builtin_amdgcn_global_load_lds((const unsigned*)((const char*)(gbase) + voff[_i]), (LAS unsigned*)(lds + (bufoff) + ldsw + _i * 8192), 16, 0, 0); } while (0)
; #define G_LDA(dst, b, h) do { _Pragma("unroll") for (int m = 0; m < 4; ++m) _Pragma("unroll") for (int k = 0; k < 2; ++k) dst[m][k] = *(const LAS bf16x8*)(lds + G_SA(b, h) + aoff + m * 2048 + k * 1024); } while (0)
; #define G_LDB(dst, b, h) do { _Pragma("unroll") for (int n = 0; n < 2; ++n) _Pragma("unroll") for (int k = 0; k < 2; ++k) dst[n][k] = *(const LAS bf16x8*)(lds + G_SB(b, h) + boff + n * 2048 + k * 1024); } while (0)
; #define G_MMA(ai, bj, At_, Bt_) do { __builtin_amdgcn_s_setprio(1); _Pragma("unroll") for (int m = 0; m < 4; ++m) _Pragma("unroll") for (int n = 0; n < 2; ++n) _Pragma("unroll") for (int k = 0; k < 2; ++k) \
;         acc[ai][bj][m][n] = __builtin_amdgcn_mfma_f32_16x16x32_bf16(Bt_[n][k], At_[m][k], acc[ai][bj][m][n], 0, 0, 0); __builtin_amdgcn_s_setprio(0); } while (0)
; #define WAIT_V(n) asm volatile("s_waitcnt vmcnt(" #n ")" ::: "memory")
; #define WAIT_L(n) asm volatile("s_waitcnt lgkmcnt(" #n ")" ::: "memory")
; #define BAR __builtin_amdgcn_s_barrier()
; #define SCHED __builtin_amdgcn_sched_barrier(0)
; template <class Get, class Epi>
; DI void gemm_loop(int ntiles, int ld, char* shm, const Get& get, const Epi& epi) {
;     ...
;             WAIT_V(8); WAIT_L(0); BAR; G_MMA(1, 0, At, B0); G_MMA(1, 1, At, B1); BAR; SCHED;
;             G_LDB(B0, 1, 0); G_LDB(B1, 1, 1); SCHED; G_LDA(At, 1, 0); G_STAGE(G_SA(0, 1), a2 + hstep, voffA);
;             WAIT_V(8); WAIT_L(0); BAR; G_MMA(0, 0, At, B0); G_MMA(0, 1, At, B1); BAR; SCHED;
	s_setprio 1
	s_waitcnt lgkmcnt(0)
	v_mfma_f32_16x16x32_bf16 v[92:95], v[128:131], v[180:183], 0
	v_mfma_f32_16x16x32_bf16 v[88:91], v[136:139], v[180:183], 0
	v_mfma_f32_16x16x32_bf16 v[84:87], v[128:131], v[188:191], 0
	v_mfma_f32_16x16x32_bf16 v[80:83], v[136:139], v[188:191], 0
	v_mfma_f32_16x16x32_bf16 v[76:79], v[128:131], v[196:199], 0
	v_mfma_f32_16x16x32_bf16 v[72:75], v[136:139], v[196:199], 0
	v_mfma_f32_16x16x32_bf16 v[68:71], v[128:131], v[204:207], 0
	v_mfma_f32_16x16x32_bf16 v[64:67], v[136:139], v[204:207], 0
	v_mfma_f32_16x16x32_bf16 v[92:95], v[132:135], v[184:187], v[92:95]
	v_mfma_f32_16x16x32_bf16 v[88:91], v[140:143], v[184:187], v[88:91]
	v_mfma_f32_16x16x32_bf16 v[84:87], v[132:135], v[192:195], v[84:87]
	v_mfma_f32_16x16x32_bf16 v[80:83], v[140:143], v[192:195], v[80:83]
	v_mfma_f32_16x16x32_bf16 v[76:79], v[132:135], v[200:203], v[76:79]
	v_mfma_f32_16x16x32_bf16 v[72:75], v[140:143], v[200:203], v[72:75]
	v_mfma_f32_16x16x32_bf16 v[68:71], v[132:135], v[208:211], v[68:71]
	v_mfma_f32_16x16x32_bf16 v[64:67], v[140:143], v[208:211], v[64:67]
	s_setprio 0
	s_setprio 1
	v_mfma_f32_16x16x32_bf16 v[28:31], v[158:161], v[180:183], 0
	v_mfma_f32_16x16x32_bf16 v[24:27], v[172:175], v[180:183], 0
	v_mfma_f32_16x16x32_bf16 v[20:23], v[158:161], v[188:191], 0
	v_mfma_f32_16x16x32_bf16 v[16:19], v[172:175], v[188:191], 0
	v_mfma_f32_16x16x32_bf16 v[12:15], v[158:161], v[196:199], 0
	v_mfma_f32_16x16x32_bf16 v[8:11], v[172:175], v[196:199], 0
	v_mfma_f32_16x16x32_bf16 v[4:7], v[158:161], v[204:207], 0
	v_mfma_f32_16x16x32_bf16 v[0:3], v[172:175], v[204:207], 0
	v_mfma_f32_16x16x32_bf16 v[28:31], v[162:165], v[184:187], v[28:31]
	v_mfma_f32_16x16x32_bf16 v[24:27], v[176:179], v[184:187], v[24:27]
	v_mfma_f32_16x16x32_bf16 v[20:23], v[162:165], v[192:195], v[20:23]
	v_mfma_f32_16x16x32_bf16 v[16:19], v[176:179], v[192:195], v[16:19]
	v_mfma_f32_16x16x32_bf16 v[12:15], v[162:165], v[200:203], v[12:15]
	v_mfma_f32_16x16x32_bf16 v[8:11], v[176:179], v[200:203], v[8:11]
	v_mfma_f32_16x16x32_bf16 v[4:7], v[162:165], v[208:211], v[4:7]
	v_mfma_f32_16x16x32_bf16 v[0:3], v[176:179], v[208:211], v[0:3]
	s_setprio 0
	s_barrier
	s_add_i32 s78, 0, 0x18000
	s_add_i32 s79, 0, 0x1c000
	v_add_u32_e32 v140, s78, v168
	v_add_u32_e32 v176, s79, v168
	ds_read_b128 v[128:131], v140
	ds_read_b128 v[132:135], v140 offset:1024
	ds_read_b128 v[136:139], v140 offset:2048
	ds_read_b128 v[140:143], v140 offset:3072
	ds_read_b128 v[158:161], v176
	ds_read_b128 v[162:165], v176 offset:1024
	ds_read_b128 v[172:175], v176 offset:2048
	ds_read_b128 v[176:179], v176 offset:3072
	s_add_u32 s4, s42, 0xb0000
	s_addc_u32 s5, s43, 0
	s_mov_b32 m0, s47
	v_lshl_add_u64 v[216:217], s[4:5], 0, v[146:147]
	ds_read_b128 v[180:183], v171 offset:32768
	ds_read_b128 v[184:187], v171 offset:33792
	ds_read_b128 v[188:191], v171 offset:34816
	ds_read_b128 v[192:195], v171 offset:35840
	ds_read_b128 v[196:199], v171 offset:36864
	ds_read_b128 v[200:203], v171 offset:37888
	ds_read_b128 v[204:207], v171 offset:38912
	ds_read_b128 v[208:211], v171 offset:39936
	global_load_lds_dwordx4 v[216:217], off
	v_lshl_add_u64 v[216:217], s[4:5], 0, v[150:151]
	s_mov_b32 m0, s48
	s_nop 0
	global_load_lds_dwordx4 v[216:217], off
	s_waitcnt vmcnt(8)
	s_waitcnt lgkmcnt(0)
	s_barrier
	s_setprio 1
	s_waitcnt lgkmcnt(0)
	v_mfma_f32_16x16x32_bf16 v[124:127], v[128:131], v[180:183], v[124:127]
	v_mfma_f32_16x16x32_bf16 v[120:123], v[136:139], v[180:183], v[120:123]
	v_mfma_f32_16x16x32_bf16 v[116:119], v[128:131], v[188:191], v[116:119]
	v_mfma_f32_16x16x32_bf16 v[112:115], v[136:139], v[188:191], v[112:115]
	v_mfma_f32_16x16x32_bf16 v[108:111], v[128:131], v[196:199], v[108:111]
	v_mfma_f32_16x16x32_bf16 v[104:107], v[136:139], v[196:199], v[104:107]
	v_mfma_f32_16x16x32_bf16 v[100:103], v[128:131], v[204:207], v[100:103]
	v_mfma_f32_16x16x32_bf16 v[96:99], v[136:139], v[204:207], v[96:99]
	v_mfma_f32_16x16x32_bf16 v[124:127], v[132:135], v[184:187], v[124:127]
	v_mfma_f32_16x16x32_bf16 v[120:123], v[140:143], v[184:187], v[120:123]
	v_mfma_f32_16x16x32_bf16 v[116:119], v[132:135], v[192:195], v[116:119]
	v_mfma_f32_16x16x32_bf16 v[112:115], v[140:143], v[192:195], v[112:115]
	v_mfma_f32_16x16x32_bf16 v[108:111], v[132:135], v[200:203], v[108:111]
	v_mfma_f32_16x16x32_bf16 v[104:107], v[140:143], v[200:203], v[104:107]
	v_mfma_f32_16x16x32_bf16 v[100:103], v[132:135], v[208:211], v[100:103]
	v_mfma_f32_16x16x32_bf16 v[96:99], v[140:143], v[208:211], v[96:99]
	s_setprio 0
	s_setprio 1
	v_mfma_f32_16x16x32_bf16 v[60:63], v[158:161], v[180:183], v[60:63]
	v_mfma_f32_16x16x32_bf16 v[56:59], v[172:175], v[180:183], v[56:59]
	v_mfma_f32_16x16x32_bf16 v[52:55], v[158:161], v[188:191], v[52:55]
	v_mfma_f32_16x16x32_bf16 v[48:51], v[172:175], v[188:191], v[48:51]
	v_mfma_f32_16x16x32_bf16 v[44:47], v[158:161], v[196:199], v[44:47]
	v_mfma_f32_16x16x32_bf16 v[40:43], v[172:175], v[196:199], v[40:43]
	v_mfma_f32_16x16x32_bf16 v[36:39], v[158:161], v[204:207], v[36:39]
	v_mfma_f32_16x16x32_bf16 v[32:35], v[172:175], v[204:207], v[32:35]
	v_mfma_f32_16x16x32_bf16 v[60:63], v[162:165], v[184:187], v[60:63]
	v_mfma_f32_16x16x32_bf16 v[56:59], v[176:179], v[184:187], v[56:59]
	v_mfma_f32_16x16x32_bf16 v[52:55], v[162:165], v[192:195], v[52:55]
	v_mfma_f32_16x16x32_bf16 v[48:51], v[176:179], v[192:195], v[48:51]
	v_mfma_f32_16x16x32_bf16 v[44:47], v[162:165], v[200:203], v[44:47]
	v_mfma_f32_16x16x32_bf16 v[40:43], v[176:179], v[200:203], v[40:43]
	v_mfma_f32_16x16x32_bf16 v[36:39], v[162:165], v[208:211], v[36:39]
	v_mfma_f32_16x16x32_bf16 v[32:35], v[176:179], v[208:211], v[32:35]
	s_setprio 0
	s_barrier
; #define G_STAGE(bufoff, gbase, voff) do { _Pragma("unroll") for (int _i = 0; _i < 2; ++_i) \
;         __builtin_amdgcn_global_load_lds((const unsigned*)((const char*)(gbase) + voff[_i]), (LAS unsigned*)(lds + (bufoff) + ldsw + _i * 8192), 16, 0, 0); } while (0)
; #define G_LDA(dst, b, h) do { _Pragma("unroll") for (int m = 0; m < 4; ++m) _Pragma("unroll") for (int k = 0; k < 2; ++k) dst[m][k] = *(const LAS bf16x8*)(lds + G_SA(b, h) + aoff + m * 2048 + k * 1024); } while (0)
; #define G_MMA(ai, bj, At_, Bt_) do { __builtin_amdgcn_s_setprio(1); _Pragma("unroll") for (int m = 0; m < 4; ++m) _Pragma("unroll") for (int n = 0; n < 2; ++n) _Pragma("unroll") for (int k = 0; k < 2; ++k) \
;         acc[ai][bj][m][n] = __builtin_amdgcn_mfma_f32_16x16x32_bf16(Bt_[n][k], At_[m][k], acc[ai][bj][m][n], 0, 0, 0); __builtin_amdgcn_s_setprio(0); } while (0)
; #define WAIT_V(n) asm volatile("s_waitcnt vmcnt(" #n ")" ::: "memory")
; #define WAIT_L(n) asm volatile("s_waitcnt lgkmcnt(" #n ")" ::: "memory")
; #define BAR __builtin_amdgcn_s_barrier()
; #define SCHED __builtin_amdgcn_sched_barrier(0)
; template <class Get, class Epi>
; DI void gemm_loop(int ntiles, int ld, char* shm, const Get& get, const Epi& epi) {
;     ...
;             G_LDA(At, 1, 1); G_STAGE(G_SB(1, 0), b3, voffB); G_STAGE(G_SB(1, 1), b3 + hstep, voffB); G_STAGE(G_SA(1, 0), a3, voffA);
;             WAIT_V(8); WAIT_L(0); BAR; G_MMA(1, 0, At, B0); G_MMA(1, 1, At, B1); BAR; SCHED;
;         }
	s_add_i32 s4, s78, s44
	v_lshl_add_u64 v[144:145], v[144:145], 0, s[10:11]
	s_mov_b32 m0, s4
	ds_read_b128 v[180:183], v171 offset:49152
	ds_read_b128 v[184:187], v171 offset:50176
	ds_read_b128 v[188:191], v171 offset:51200
	ds_read_b128 v[192:195], v171 offset:52224
	ds_read_b128 v[196:199], v171 offset:53248
	ds_read_b128 v[200:203], v171 offset:54272
	ds_read_b128 v[204:207], v171 offset:55296
	ds_read_b128 v[208:211], v171 offset:56320
	global_load_lds_dwordx4 v[144:145], off
	s_add_i32 m0, s4, 0x2000
	s_add_u32 s4, s40, 0xb0080
	v_lshl_add_u64 v[144:145], v[166:167], 0, s[10:11]
	s_addc_u32 s5, s41, 0
	s_add_i32 s40, s79, s44
	global_load_lds_dwordx4 v[144:145], off
	v_lshl_add_u64 v[144:145], s[4:5], 0, v[148:149]
	s_mov_b32 m0, s40
	s_nop 0
	global_load_lds_dwordx4 v[144:145], off
	v_lshl_add_u64 v[144:145], s[4:5], 0, v[152:153]
	s_add_i32 m0, s40, 0x2000
	s_nop 0
	global_load_lds_dwordx4 v[144:145], off
	v_lshl_add_u64 v[144:145], v[212:213], 0, s[10:11]
	s_mov_b32 m0, s51
	s_nop 0
	global_load_lds_dwordx4 v[144:145], off
	v_lshl_add_u64 v[144:145], v[214:215], 0, s[10:11]
	s_mov_b32 m0, s52
	s_nop 0
	global_load_lds_dwordx4 v[144:145], off
	s_waitcnt vmcnt(8)
	s_waitcnt lgkmcnt(0)
	s_barrier
	s_setprio 1
	s_waitcnt lgkmcnt(0)
	v_mfma_f32_16x16x32_bf16 v[92:95], v[128:131], v[180:183], v[92:95]
	v_mfma_f32_16x16x32_bf16 v[88:91], v[136:139], v[180:183], v[88:91]
	v_mfma_f32_16x16x32_bf16 v[84:87], v[128:131], v[188:191], v[84:87]
	v_mfma_f32_16x16x32_bf16 v[80:83], v[136:139], v[188:191], v[80:83]
	v_mfma_f32_16x16x32_bf16 v[76:79], v[128:131], v[196:199], v[76:79]
	v_mfma_f32_16x16x32_bf16 v[72:75], v[136:139], v[196:199], v[72:75]
	v_mfma_f32_16x16x32_bf16 v[68:71], v[128:131], v[204:207], v[68:71]
	v_mfma_f32_16x16x32_bf16 v[64:67], v[136:139], v[204:207], v[64:67]
	v_mfma_f32_16x16x32_bf16 v[92:95], v[132:135], v[184:187], v[92:95]
	v_mfma_f32_16x16x32_bf16 v[88:91], v[140:143], v[184:187], v[88:91]
	v_mfma_f32_16x16x32_bf16 v[84:87], v[132:135], v[192:195], v[84:87]
	v_mfma_f32_16x16x32_bf16 v[80:83], v[140:143], v[192:195], v[80:83]
	v_mfma_f32_16x16x32_bf16 v[76:79], v[132:135], v[200:203], v[76:79]
	v_mfma_f32_16x16x32_bf16 v[72:75], v[140:143], v[200:203], v[72:75]
	v_mfma_f32_16x16x32_bf16 v[68:71], v[132:135], v[208:211], v[68:71]
	v_mfma_f32_16x16x32_bf16 v[64:67], v[140:143], v[208:211], v[64:67]
	s_setprio 0
	s_setprio 1
	v_mfma_f32_16x16x32_bf16 v[28:31], v[158:161], v[180:183], v[28:31]
	v_mfma_f32_16x16x32_bf16 v[24:27], v[172:175], v[180:183], v[24:27]
	v_mfma_f32_16x16x32_bf16 v[20:23], v[158:161], v[188:191], v[20:23]
	v_mfma_f32_16x16x32_bf16 v[16:19], v[172:175], v[188:191], v[16:19]
	v_mfma_f32_16x16x32_bf16 v[12:15], v[158:161], v[196:199], v[12:15]
	v_mfma_f32_16x16x32_bf16 v[8:11], v[172:175], v[196:199], v[8:11]
	v_mfma_f32_16x16x32_bf16 v[4:7], v[158:161], v[204:207], v[4:7]
	v_mfma_f32_16x16x32_bf16 v[0:3], v[172:175], v[204:207], v[0:3]
	v_mfma_f32_16x16x32_bf16 v[28:31], v[162:165], v[184:187], v[28:31]
	v_mfma_f32_16x16x32_bf16 v[24:27], v[176:179], v[184:187], v[24:27]
	v_mfma_f32_16x16x32_bf16 v[20:23], v[162:165], v[192:195], v[20:23]
	v_mfma_f32_16x16x32_bf16 v[16:19], v[176:179], v[192:195], v[16:19]
	v_mfma_f32_16x16x32_bf16 v[12:15], v[162:165], v[200:203], v[12:15]
	v_mfma_f32_16x16x32_bf16 v[8:11], v[176:179], v[200:203], v[8:11]
	v_mfma_f32_16x16x32_bf16 v[4:7], v[162:165], v[208:211], v[4:7]
	v_mfma_f32_16x16x32_bf16 v[0:3], v[176:179], v[208:211], v[0:3]
	s_setprio 0
	s_barrier
	s_add_u32 s75, s75, 0x100
	s_addc_u32 s76, s76, 0
	s_cmp_ge_u32 s77, s73
	s_mov_b64 s[4:5], s[14:15]
	s_mov_b32 s40, s77
	s_cbranch_scc0 .LBB0_1781
	s_branch .Lpost_1781

; #define G_STAGE(bufoff, gbase, voff) do { _Pragma("unroll") for (int _i = 0; _i < 2; ++_i) \
;         __builtin_amdgcn_global_load_lds((const unsigned*)((const char*)(gbase) + voff[_i]), (LAS unsigned*)(lds + (bufoff) + ldsw + _i * 8192), 16, 0, 0); } while (0)
; #define G_LDA(dst, b, h) do { _Pragma("unroll") for (int m = 0; m < 4; ++m) _Pragma("unroll") for (int k = 0; k < 2; ++k) dst[m][k] = *(const LAS bf16x8*)(lds + G_SA(b, h) + aoff + m * 2048 + k * 1024); } while (0)
; #define G_LDB(dst, b, h) do { _Pragma("unroll") for (int n = 0; n < 2; ++n) _Pragma("unroll") for (int k = 0; k < 2; ++k) dst[n][k] = *(const LAS bf16x8*)(lds + G_SB(b, h) + boff + n * 2048 + k * 1024); } while (0)
; #define G_MMA(ai, bj, At_, Bt_) do { __builtin_amdgcn_s_setprio(1); _Pragma("unroll") for (int m = 0; m < 4; ++m) _Pragma("unroll") for (int n = 0; n < 2; ++n) _Pragma("unroll") for (int k = 0; k < 2; ++k) \
;         acc[ai][bj][m][n] = __builtin_amdgcn_mfma_f32_16x16x32_bf16(Bt_[n][k], At_[m][k], acc[ai][bj][m][n], 0, 0, 0); __builtin_amdgcn_s_setprio(0); } while (0)
; #define WAIT_V(n) asm volatile("s_waitcnt vmcnt(" #n ")" ::: "memory")
; #define WAIT_L(n) asm volatile("s_waitcnt lgkmcnt(" #n ")" ::: "memory")
; #define BAR __builtin_amdgcn_s_barrier()
; template <class Get, class Epi>
; DI void gemm_loop(int ntiles, int ld, char* shm, const Get& get, const Epi& epi) {
;     ...
;         const int Ln = L + gridDim.x; const bool has_next = Ln < ntiles; if (has_next) nxt = get(Ln);
;         const char* nA = has_next ? (const char*)nxt.A + (size_t)nxt.brow * ld * 2 : cA; const char* nB = has_next ? (const char*)nxt.Bt + (size_t)nxt.bcol * ld * 2 : cB;
;         const int nt = cur.K / BK;
;         for (int t = 0; t < nt; t += 2) {
;             const bool last = (t == nt - 2);
;             const char* a1 = cA + (size_t)(t + 1) * kstep;
;             const char* a2 = last ? nA : cA + (size_t)(t + 2) * kstep; const char* b2 = last ? nB : cB + (size_t)(t + 2) * kstep;
;             const char* a3 = a2 + kstep; const char* b3 = b2 + kstep;
;             G_LDB(B0, 0, 0); G_LDB(B1, 0, 1); SCHED; G_LDA(At, 0, 0); G_STAGE(G_SA(1, 1), a1 + hstep, voffA);
;             WAIT_V(8); WAIT_L(0); BAR; G_MMA(0, 0, At, B0); G_MMA(0, 1, At, B1); BAR; SCHED;
;             G_LDA(At, 0, 1); G_STAGE(G_SB(0, 0), b2, voffB); G_STAGE(G_SB(0, 1), b2 + hstep, voffB); G_STAGE(G_SA(0, 0), a2, voffA);
.LBB0_2021:
	s_ashr_i32 s41, s40, 31
	s_lshl_b64 s[14:15], s[40:41], 11
	s_add_u32 s44, s16, s14
	s_addc_u32 s45, s17, s15
	s_and_b64 s[14:15], s[38:39], exec
	s_cselect_b32 s3, s45, s5
	s_cselect_b32 s41, s44, s4
	s_ashr_i32 s43, s42, 31
	s_lshl_b64 s[14:15], s[42:43], 11
	s_add_u32 s48, s22, s14
	s_addc_u32 s49, s23, s15
	s_and_b64 s[14:15], s[38:39], exec
	s_cselect_b32 s43, s49, s7
	s_cselect_b32 s53, s48, s6
	s_add_u32 s4, s4, 0x40080
	s_addc_u32 s5, s5, 0
	s_add_u32 s54, s6, 0x100
	s_addc_u32 s55, s7, 0
	s_mov_b32 s56, -2
.Lpeel_2022:
	ds_read_b128 v[96:99], v173
	ds_read_b128 v[108:111], v173 offset:1024
	ds_read_b128 v[150:153], v173 offset:2048
	ds_read_b128 v[154:157], v173 offset:3072
	ds_read_b128 v[158:161], v174
	ds_read_b128 v[162:165], v174 offset:1024
	ds_read_b128 v[166:169], v174 offset:2048
	ds_read_b128 v[180:183], v174 offset:3072
	s_add_u32 s6, s4, 0xfffc0080
	s_addc_u32 s7, s5, -1
	s_cmp_eq_u32 s56, 12
	s_cselect_b32 s15, s3, s7
	s_cselect_b32 s14, s41, s6
	s_cselect_b32 s7, s43, s55
	s_cselect_b32 s6, s53, s54
	v_lshl_add_u64 v[170:171], s[4:5], 0, v[146:147]
	s_add_i32 m0, s50, 0xc000
	ds_read_b128 v[184:187], v175
	ds_read_b128 v[188:191], v175 offset:1024
	ds_read_b128 v[192:195], v175 offset:2048
	ds_read_b128 v[196:199], v175 offset:3072
	ds_read_b128 v[200:203], v175 offset:4096
	ds_read_b128 v[204:207], v175 offset:5120
	ds_read_b128 v[208:211], v175 offset:6144
	ds_read_b128 v[212:215], v175 offset:7168
	global_load_lds_dwordx4 v[170:171], off
	v_lshl_add_u64 v[170:171], s[4:5], 0, v[148:149]
	s_add_i32 m0, s50, 0xe000
	s_nop 0
	global_load_lds_dwordx4 v[170:171], off
	s_waitcnt vmcnt(8)
	s_waitcnt lgkmcnt(0)
	s_barrier
	s_setprio 1
	s_waitcnt lgkmcnt(0)
	v_mfma_f32_16x16x32_bf16 v[132:135], v[96:99], v[184:187], 0
	v_mfma_f32_16x16x32_bf16 v[124:127], v[150:153], v[184:187], 0
	v_mfma_f32_16x16x32_bf16 v[128:131], v[96:99], v[192:195], 0
	v_mfma_f32_16x16x32_bf16 v[120:123], v[150:153], v[192:195], 0
	v_mfma_f32_16x16x32_bf16 v[116:119], v[96:99], v[200:203], 0
	v_mfma_f32_16x16x32_bf16 v[104:107], v[150:153], v[200:203], 0
	v_mfma_f32_16x16x32_bf16 v[112:115], v[96:99], v[208:211], 0
	v_mfma_f32_16x16x32_bf16 v[100:103], v[150:153], v[208:211], 0
	v_mfma_f32_16x16x32_bf16 v[132:135], v[108:111], v[188:191], v[132:135]
	v_mfma_f32_16x16x32_bf16 v[124:127], v[154:157], v[188:191], v[124:127]
	v_mfma_f32_16x16x32_bf16 v[128:131], v[108:111], v[196:199], v[128:131]
	v_mfma_f32_16x16x32_bf16 v[120:123], v[154:157], v[196:199], v[120:123]
	v_mfma_f32_16x16x32_bf16 v[116:119], v[108:111], v[204:207], v[116:119]
	v_mfma_f32_16x16x32_bf16 v[104:107], v[154:157], v[204:207], v[104:107]
	v_mfma_f32_16x16x32_bf16 v[112:115], v[108:111], v[212:215], v[112:115]
	v_mfma_f32_16x16x32_bf16 v[100:103], v[154:157], v[212:215], v[100:103]
	s_setprio 0
	s_setprio 1
	v_mfma_f32_16x16x32_bf16 v[60:63], v[158:161], v[184:187], 0
	v_mfma_f32_16x16x32_bf16 v[52:55], v[166:169], v[184:187], 0
	v_mfma_f32_16x16x32_bf16 v[56:59], v[158:161], v[192:195], 0
	v_mfma_f32_16x16x32_bf16 v[48:51], v[166:169], v[192:195], 0
	v_mfma_f32_16x16x32_bf16 v[44:47], v[158:161], v[200:203], 0
	v_mfma_f32_16x16x32_bf16 v[36:39], v[166:169], v[200:203], 0
	v_mfma_f32_16x16x32_bf16 v[40:43], v[158:161], v[208:211], 0
	v_mfma_f32_16x16x32_bf16 v[32:35], v[166:169], v[208:211], 0
	v_mfma_f32_16x16x32_bf16 v[60:63], v[162:165], v[188:191], v[60:63]
	v_mfma_f32_16x16x32_bf16 v[52:55], v[180:183], v[188:191], v[52:55]
	v_mfma_f32_16x16x32_bf16 v[56:59], v[162:165], v[196:199], v[56:59]
	v_mfma_f32_16x16x32_bf16 v[48:51], v[180:183], v[196:199], v[48:51]
	v_mfma_f32_16x16x32_bf16 v[44:47], v[162:165], v[204:207], v[44:47]
	v_mfma_f32_16x16x32_bf16 v[36:39], v[180:183], v[204:207], v[36:39]
	v_mfma_f32_16x16x32_bf16 v[40:43], v[162:165], v[212:215], v[40:43]
	v_mfma_f32_16x16x32_bf16 v[32:35], v[180:183], v[212:215], v[32:35]
	s_setprio 0
	s_barrier
	s_add_i32 s57, s75, s46
	v_lshl_add_u64 v[170:171], s[6:7], 0, v[140:141]
	s_mov_b32 m0, s57
	ds_read_b128 v[184:187], v175 offset:16384
	ds_read_b128 v[188:191], v175 offset:17408
	ds_read_b128 v[192:195], v175 offset:18432
	ds_read_b128 v[196:199], v175 offset:19456
	ds_read_b128 v[200:203], v175 offset:20480
	ds_read_b128 v[204:207], v175 offset:21504
	ds_read_b128 v[208:211], v175 offset:22528
	ds_read_b128 v[212:215], v175 offset:23552
	global_load_lds_dwordx4 v[170:171], off
	s_add_i32 m0, s57, 0x2000
	s_add_u32 s58, s6, 0x40000
	v_lshl_add_u64 v[216:217], s[6:7], 0, v[136:137]
	s_addc_u32 s59, s7, 0
	s_add_i32 s57, s76, s46
	global_load_lds_dwordx4 v[216:217], off
	v_lshl_add_u64 v[218:219], s[58:59], 0, v[140:141]
	s_mov_b32 m0, s57
	v_lshl_add_u64 v[220:221], s[14:15], 0, v[138:139]
	global_load_lds_dwordx4 v[218:219], off
	v_lshl_add_u64 v[218:219], s[58:59], 0, v[136:137]
	s_add_i32 m0, s57, 0x2000
	s_nop 0
	global_load_lds_dwordx4 v[218:219], off
	v_lshl_add_u64 v[218:219], s[14:15], 0, v[142:143]
	s_mov_b32 m0, s50
	s_nop 0
	global_load_lds_dwordx4 v[218:219], off
	s_mov_b32 m0, s51
	s_nop 0
	global_load_lds_dwordx4 v[220:221], off
	s_waitcnt vmcnt(8)
	s_waitcnt lgkmcnt(0)
	s_barrier
; #define G_STAGE(bufoff, gbase, voff) do { _Pragma("unroll") for (int _i = 0; _i < 2; ++_i) \
;         __builtin_amdgcn_global_load_lds((const unsigned*)((const char*)(gbase) + voff[_i]), (LAS unsigned*)(lds + (bufoff) + ldsw + _i * 8192), 16, 0, 0); } while (0)
; #define G_LDA(dst, b, h) do { _Pragma("unroll") for (int m = 0; m < 4; ++m) _Pragma("unroll") for (int k = 0; k < 2; ++k) dst[m][k] = *(const LAS bf16x8*)(lds + G_SA(b, h) + aoff + m * 2048 + k * 1024); } while (0)
; #define G_LDB(dst, b, h) do { _Pragma("unroll") for (int n = 0; n < 2; ++n) _Pragma("unroll") for (int k = 0; k < 2; ++k) dst[n][k] = *(const LAS bf16x8*)(lds + G_SB(b, h) + boff + n * 2048 + k * 1024); } while (0)
; #define G_MMA(ai, bj, At_, Bt_) do { __builtin_amdgcn_s_setprio(1); _Pragma("unroll") for (int m = 0; m < 4; ++m) _Pragma("unroll") for (int n = 0; n < 2; ++n) _Pragma("unroll") for (int k = 0; k < 2; ++k) \
;         acc[ai][bj][m][n] = __builtin_amdgcn_mfma_f32_16x16x32_bf16(Bt_[n][k], At_[m][k], acc[ai][bj][m][n], 0, 0, 0); __builtin_amdgcn_s_setprio(0); } while (0)
; #define WAIT_V(n) asm volatile("s_waitcnt vmcnt(" #n ")" ::: "memory")
; #define WAIT_L(n) asm volatile("s_waitcnt lgkmcnt(" #n ")" ::: "memory")
; #define BAR __builtin_amdgcn_s_barrier()
; #define SCHED __builtin_amdgcn_sched_barrier(0)
; template <class Get, class Epi>
; DI void gemm_loop(int ntiles, int ld, char* shm, const Get& get, const Epi& epi) {
;     ...
;             WAIT_V(8); WAIT_L(0); BAR; G_MMA(1, 0, At, B0); G_MMA(1, 1, At, B1); BAR; SCHED;
;             G_LDB(B0, 1, 0); G_LDB(B1, 1, 1); SCHED; G_LDA(At, 1, 0); G_STAGE(G_SA(0, 1), a2 + hstep, voffA);
;             WAIT_V(8); WAIT_L(0); BAR; G_MMA(0, 0, At, B0); G_MMA(0, 1, At, B1); BAR; SCHED;
	s_setprio 1
	s_waitcnt lgkmcnt(0)
	v_mfma_f32_16x16x32_bf16 v[92:95], v[96:99], v[184:187], 0
	v_mfma_f32_16x16x32_bf16 v[84:87], v[150:153], v[184:187], 0
	v_mfma_f32_16x16x32_bf16 v[88:91], v[96:99], v[192:195], 0
	v_mfma_f32_16x16x32_bf16 v[80:83], v[150:153], v[192:195], 0
	v_mfma_f32_16x16x32_bf16 v[76:79], v[96:99], v[200:203], 0
	v_mfma_f32_16x16x32_bf16 v[68:71], v[150:153], v[200:203], 0
	v_mfma_f32_16x16x32_bf16 v[72:75], v[96:99], v[208:211], 0
	v_mfma_f32_16x16x32_bf16 v[64:67], v[150:153], v[208:211], 0
	v_mfma_f32_16x16x32_bf16 v[92:95], v[108:111], v[188:191], v[92:95]
	v_mfma_f32_16x16x32_bf16 v[84:87], v[154:157], v[188:191], v[84:87]
	v_mfma_f32_16x16x32_bf16 v[88:91], v[108:111], v[196:199], v[88:91]
	v_mfma_f32_16x16x32_bf16 v[80:83], v[154:157], v[196:199], v[80:83]
	v_mfma_f32_16x16x32_bf16 v[76:79], v[108:111], v[204:207], v[76:79]
	v_mfma_f32_16x16x32_bf16 v[68:71], v[154:157], v[204:207], v[68:71]
	v_mfma_f32_16x16x32_bf16 v[72:75], v[108:111], v[212:215], v[72:75]
	v_mfma_f32_16x16x32_bf16 v[64:67], v[154:157], v[212:215], v[64:67]
	s_setprio 0
	s_setprio 1
	v_mfma_f32_16x16x32_bf16 v[28:31], v[158:161], v[184:187], 0
	v_mfma_f32_16x16x32_bf16 v[20:23], v[166:169], v[184:187], 0
	v_mfma_f32_16x16x32_bf16 v[24:27], v[158:161], v[192:195], 0
	v_mfma_f32_16x16x32_bf16 v[16:19], v[166:169], v[192:195], 0
	v_mfma_f32_16x16x32_bf16 v[12:15], v[158:161], v[200:203], 0
	v_mfma_f32_16x16x32_bf16 v[4:7], v[166:169], v[200:203], 0
	v_mfma_f32_16x16x32_bf16 v[8:11], v[158:161], v[208:211], 0
	v_mfma_f32_16x16x32_bf16 v[0:3], v[166:169], v[208:211], 0
	v_mfma_f32_16x16x32_bf16 v[28:31], v[162:165], v[188:191], v[28:31]
	v_mfma_f32_16x16x32_bf16 v[20:23], v[180:183], v[188:191], v[20:23]
	v_mfma_f32_16x16x32_bf16 v[24:27], v[162:165], v[196:199], v[24:27]
	v_mfma_f32_16x16x32_bf16 v[16:19], v[180:183], v[196:199], v[16:19]
	v_mfma_f32_16x16x32_bf16 v[12:15], v[162:165], v[204:207], v[12:15]
	v_mfma_f32_16x16x32_bf16 v[4:7], v[180:183], v[204:207], v[4:7]
	v_mfma_f32_16x16x32_bf16 v[8:11], v[162:165], v[212:215], v[8:11]
	v_mfma_f32_16x16x32_bf16 v[0:3], v[180:183], v[212:215], v[0:3]
	s_setprio 0
	s_barrier
	s_add_i32 s57, 0, 0x18000
	v_add_u32_e32 v144, s57, v172
	s_add_i32 s58, 0, 0x1c000
	ds_read_b128 v[96:99], v144
	ds_read_b128 v[108:111], v144 offset:1024
	ds_read_b128 v[150:153], v144 offset:2048
	ds_read_b128 v[154:157], v144 offset:3072
	v_add_u32_e32 v144, s58, v172
	ds_read_b128 v[158:161], v144
	ds_read_b128 v[162:165], v144 offset:1024
	ds_read_b128 v[166:169], v144 offset:2048
	ds_read_b128 v[180:183], v144 offset:3072
	s_add_u32 s14, s14, 0x40000
	s_addc_u32 s15, s15, 0
	s_mov_b32 m0, s71
	v_lshl_add_u64 v[222:223], s[14:15], 0, v[142:143]
	ds_read_b128 v[184:187], v175 offset:32768
	ds_read_b128 v[188:191], v175 offset:33792
	ds_read_b128 v[192:195], v175 offset:34816
	ds_read_b128 v[196:199], v175 offset:35840
	ds_read_b128 v[200:203], v175 offset:36864
	ds_read_b128 v[204:207], v175 offset:37888
	ds_read_b128 v[208:211], v175 offset:38912
	ds_read_b128 v[212:215], v175 offset:39936
	global_load_lds_dwordx4 v[222:223], off
	v_lshl_add_u64 v[222:223], s[14:15], 0, v[138:139]
	s_mov_b32 m0, s72
	s_nop 0
	global_load_lds_dwordx4 v[222:223], off
	s_waitcnt vmcnt(8)
	s_waitcnt lgkmcnt(0)
	s_barrier
	s_setprio 1
	s_waitcnt lgkmcnt(0)
	v_mfma_f32_16x16x32_bf16 v[132:135], v[96:99], v[184:187], v[132:135]
	v_mfma_f32_16x16x32_bf16 v[124:127], v[150:153], v[184:187], v[124:127]
	v_mfma_f32_16x16x32_bf16 v[128:131], v[96:99], v[192:195], v[128:131]
	v_mfma_f32_16x16x32_bf16 v[120:123], v[150:153], v[192:195], v[120:123]
	v_mfma_f32_16x16x32_bf16 v[116:119], v[96:99], v[200:203], v[116:119]
	v_mfma_f32_16x16x32_bf16 v[104:107], v[150:153], v[200:203], v[104:107]
	v_mfma_f32_16x16x32_bf16 v[112:115], v[96:99], v[208:211], v[112:115]
	v_mfma_f32_16x16x32_bf16 v[100:103], v[150:153], v[208:211], v[100:103]
	v_mfma_f32_16x16x32_bf16 v[132:135], v[108:111], v[188:191], v[132:135]
	v_mfma_f32_16x16x32_bf16 v[124:127], v[154:157], v[188:191], v[124:127]
	v_mfma_f32_16x16x32_bf16 v[128:131], v[108:111], v[196:199], v[128:131]
	v_mfma_f32_16x16x32_bf16 v[120:123], v[154:157], v[196:199], v[120:123]
	v_mfma_f32_16x16x32_bf16 v[116:119], v[108:111], v[204:207], v[116:119]
	v_mfma_f32_16x16x32_bf16 v[104:107], v[154:157], v[204:207], v[104:107]
	v_mfma_f32_16x16x32_bf16 v[112:115], v[108:111], v[212:215], v[112:115]
	v_mfma_f32_16x16x32_bf16 v[100:103], v[154:157], v[212:215], v[100:103]
	s_setprio 0
	s_setprio 1
	v_mfma_f32_16x16x32_bf16 v[60:63], v[158:161], v[184:187], v[60:63]
	v_mfma_f32_16x16x32_bf16 v[52:55], v[166:169], v[184:187], v[52:55]
	v_mfma_f32_16x16x32_bf16 v[56:59], v[158:161], v[192:195], v[56:59]
	v_mfma_f32_16x16x32_bf16 v[48:51], v[166:169], v[192:195], v[48:51]
	v_mfma_f32_16x16x32_bf16 v[44:47], v[158:161], v[200:203], v[44:47]
	v_mfma_f32_16x16x32_bf16 v[36:39], v[166:169], v[200:203], v[36:39]
	v_mfma_f32_16x16x32_bf16 v[40:43], v[158:161], v[208:211], v[40:43]
	v_mfma_f32_16x16x32_bf16 v[32:35], v[166:169], v[208:211], v[32:35]
	v_mfma_f32_16x16x32_bf16 v[60:63], v[162:165], v[188:191], v[60:63]
	v_mfma_f32_16x16x32_bf16 v[52:55], v[180:183], v[188:191], v[52:55]
	v_mfma_f32_16x16x32_bf16 v[56:59], v[162:165], v[196:199], v[56:59]
	v_mfma_f32_16x16x32_bf16 v[48:51], v[180:183], v[196:199], v[48:51]
	v_mfma_f32_16x16x32_bf16 v[44:47], v[162:165], v[204:207], v[44:47]
	v_mfma_f32_16x16x32_bf16 v[36:39], v[180:183], v[204:207], v[36:39]
	v_mfma_f32_16x16x32_bf16 v[40:43], v[162:165], v[212:215], v[40:43]
	v_mfma_f32_16x16x32_bf16 v[32:35], v[180:183], v[212:215], v[32:35]
	s_setprio 0
	s_barrier
; #define G_STAGE(bufoff, gbase, voff) do { _Pragma("unroll") for (int _i = 0; _i < 2; ++_i) \
;         __builtin_amdgcn_global_load_lds((const unsigned*)((const char*)(gbase) + voff[_i]), (LAS unsigned*)(lds + (bufoff) + ldsw + _i * 8192), 16, 0, 0); } while (0)
; #define G_LDA(dst, b, h) do { _Pragma("unroll") for (int m = 0; m < 4; ++m) _Pragma("unroll") for (int k = 0; k < 2; ++k) dst[m][k] = *(const LAS bf16x8*)(lds + G_SA(b, h) + aoff + m * 2048 + k * 1024); } while (0)
; #define G_LDB(dst, b, h) do { _Pragma("unroll") for (int n = 0; n < 2; ++n) _Pragma("unroll") for (int k = 0; k < 2; ++k) dst[n][k] = *(const LAS bf16x8*)(lds + G_SB(b, h) + boff + n * 2048 + k * 1024); } while (0)
; #define G_MMA(ai, bj, At_, Bt_) do { __builtin_amdgcn_s_setprio(1); _Pragma("unroll") for (int m = 0; m < 4; ++m) _Pragma("unroll") for (int n = 0; n < 2; ++n) _Pragma("unroll") for (int k = 0; k < 2; ++k) \
;         acc[ai][bj][m][n] = __builtin_amdgcn_mfma_f32_16x16x32_bf16(Bt_[n][k], At_[m][k], acc[ai][bj][m][n], 0, 0, 0); __builtin_amdgcn_s_setprio(0); } while (0)
; #define WAIT_V(n) asm volatile("s_waitcnt vmcnt(" #n ")" ::: "memory")
; #define WAIT_L(n) asm volatile("s_waitcnt lgkmcnt(" #n ")" ::: "memory")
; #define BAR __builtin_amdgcn_s_barrier()
; #define SCHED __builtin_amdgcn_sched_barrier(0)
; template <class Get, class Epi>
; DI void gemm_loop(int ntiles, int ld, char* shm, const Get& get, const Epi& epi) {
;     ...
;             G_LDB(B0, 1, 0); G_LDB(B1, 1, 1); SCHED; G_LDA(At, 1, 0); G_STAGE(G_SA(0, 1), a2 + hstep, voffA);
;             WAIT_V(8); WAIT_L(0); BAR; G_MMA(0, 0, At, B0); G_MMA(0, 1, At, B1); BAR; SCHED;
;             G_LDA(At, 1, 1); G_STAGE(G_SB(1, 0), b3, voffB); G_STAGE(G_SB(1, 1), b3 + hstep, voffB); G_STAGE(G_SA(1, 0), a3, voffA);
;             WAIT_V(8); WAIT_L(0); BAR; G_MMA(1, 0, At, B0); G_MMA(1, 1, At, B1); BAR; SCHED;
	s_add_i32 s14, s57, s46
	v_lshl_add_u64 v[170:171], v[170:171], 0, s[10:11]
	s_mov_b32 m0, s14
	ds_read_b128 v[184:187], v175 offset:49152
	ds_read_b128 v[188:191], v175 offset:50176
	ds_read_b128 v[192:195], v175 offset:51200
	ds_read_b128 v[196:199], v175 offset:52224
	ds_read_b128 v[200:203], v175 offset:53248
	ds_read_b128 v[204:207], v175 offset:54272
	ds_read_b128 v[208:211], v175 offset:55296
	ds_read_b128 v[212:215], v175 offset:56320
	global_load_lds_dwordx4 v[170:171], off
	s_add_i32 m0, s14, 0x2000
	s_add_u32 s6, s6, 0x40080
	v_lshl_add_u64 v[170:171], v[216:217], 0, s[10:11]
	s_addc_u32 s7, s7, 0
	s_add_i32 s14, s58, s46
	global_load_lds_dwordx4 v[170:171], off
	v_lshl_add_u64 v[170:171], s[6:7], 0, v[140:141]
	s_mov_b32 m0, s14
	s_nop 0
	global_load_lds_dwordx4 v[170:171], off
	v_lshl_add_u64 v[170:171], s[6:7], 0, v[136:137]
	s_add_i32 m0, s14, 0x2000
	s_nop 0
	global_load_lds_dwordx4 v[170:171], off
	v_lshl_add_u64 v[170:171], v[218:219], 0, s[10:11]
	s_mov_b32 m0, s73
	s_nop 0
	global_load_lds_dwordx4 v[170:171], off
	v_lshl_add_u64 v[170:171], v[220:221], 0, s[10:11]
	s_mov_b32 m0, s74
	s_nop 0
	global_load_lds_dwordx4 v[170:171], off
	s_waitcnt vmcnt(8)
	s_waitcnt lgkmcnt(0)
	s_barrier
	s_setprio 1
	s_waitcnt lgkmcnt(0)
	v_mfma_f32_16x16x32_bf16 v[92:95], v[96:99], v[184:187], v[92:95]
	v_mfma_f32_16x16x32_bf16 v[84:87], v[150:153], v[184:187], v[84:87]
	v_mfma_f32_16x16x32_bf16 v[88:91], v[96:99], v[192:195], v[88:91]
	v_mfma_f32_16x16x32_bf16 v[80:83], v[150:153], v[192:195], v[80:83]
	v_mfma_f32_16x16x32_bf16 v[76:79], v[96:99], v[200:203], v[76:79]
	v_mfma_f32_16x16x32_bf16 v[68:71], v[150:153], v[200:203], v[68:71]
	v_mfma_f32_16x16x32_bf16 v[72:75], v[96:99], v[208:211], v[72:75]
	v_mfma_f32_16x16x32_bf16 v[64:67], v[150:153], v[208:211], v[64:67]
	v_mfma_f32_16x16x32_bf16 v[92:95], v[108:111], v[188:191], v[92:95]
	v_mfma_f32_16x16x32_bf16 v[84:87], v[154:157], v[188:191], v[84:87]
	v_mfma_f32_16x16x32_bf16 v[88:91], v[108:111], v[196:199], v[88:91]
	v_mfma_f32_16x16x32_bf16 v[80:83], v[154:157], v[196:199], v[80:83]
	v_mfma_f32_16x16x32_bf16 v[76:79], v[108:111], v[204:207], v[76:79]
	v_mfma_f32_16x16x32_bf16 v[68:71], v[154:157], v[204:207], v[68:71]
	v_mfma_f32_16x16x32_bf16 v[72:75], v[108:111], v[212:215], v[72:75]
	v_mfma_f32_16x16x32_bf16 v[64:67], v[154:157], v[212:215], v[64:67]
	s_setprio 0
	s_setprio 1
	v_mfma_f32_16x16x32_bf16 v[28:31], v[158:161], v[184:187], v[28:31]
	v_mfma_f32_16x16x32_bf16 v[20:23], v[166:169], v[184:187], v[20:23]
	v_mfma_f32_16x16x32_bf16 v[24:27], v[158:161], v[192:195], v[24:27]
	v_mfma_f32_16x16x32_bf16 v[16:19], v[166:169], v[192:195], v[16:19]
	v_mfma_f32_16x16x32_bf16 v[12:15], v[158:161], v[200:203], v[12:15]
	v_mfma_f32_16x16x32_bf16 v[4:7], v[166:169], v[200:203], v[4:7]
	v_mfma_f32_16x16x32_bf16 v[8:11], v[158:161], v[208:211], v[8:11]
	v_mfma_f32_16x16x32_bf16 v[0:3], v[166:169], v[208:211], v[0:3]
	v_mfma_f32_16x16x32_bf16 v[28:31], v[162:165], v[188:191], v[28:31]
	v_mfma_f32_16x16x32_bf16 v[20:23], v[180:183], v[188:191], v[20:23]
	v_mfma_f32_16x16x32_bf16 v[24:27], v[162:165], v[196:199], v[24:27]
	v_mfma_f32_16x16x32_bf16 v[16:19], v[180:183], v[196:199], v[16:19]
	v_mfma_f32_16x16x32_bf16 v[12:15], v[162:165], v[204:207], v[12:15]
	v_mfma_f32_16x16x32_bf16 v[4:7], v[180:183], v[204:207], v[4:7]
	v_mfma_f32_16x16x32_bf16 v[8:11], v[162:165], v[212:215], v[8:11]
	v_mfma_f32_16x16x32_bf16 v[0:3], v[180:183], v[212:215], v[0:3]
	s_setprio 0
	s_barrier
	s_add_i32 s56, s56, 2
	s_add_u32 s4, s4, 0x100
	s_addc_u32 s5, s5, 0
	s_add_u32 s54, s54, 0x100
	s_addc_u32 s55, s55, 0
	s_cmp_gt_u32 s56, 13
	s_cbranch_scc0 .LBB0_2022
	s_branch .Lpost_2022

; #define BAR __builtin_amdgcn_s_barrier()
; template <class Get, class Epi>
; DI void gemm_loop(int ntiles, int ld, char* shm, const Get& get, const Epi& epi) {
;     ...
;         if (wr == 0) BAR;
.Lpost_2022:
	s_and_b64 vcc, exec, s[36:37]
	s_cbranch_vccz .LBB0_2025
	s_barrier

; #define G_STAGE(bufoff, gbase, voff) do { _Pragma("unroll") for (int _i = 0; _i < 2; ++_i) \
;         __builtin_amdgcn_global_load_lds((const unsigned*)((const char*)(gbase) + voff[_i]), (LAS unsigned*)(lds + (bufoff) + ldsw + _i * 8192), 16, 0, 0); } while (0)
; #define G_LDA(dst, b, h) do { _Pragma("unroll") for (int m = 0; m < 4; ++m) _Pragma("unroll") for (int k = 0; k < 2; ++k) dst[m][k] = *(const LAS bf16x8*)(lds + G_SA(b, h) + aoff + m * 2048 + k * 1024); } while (0)
; #define G_LDB(dst, b, h) do { _Pragma("unroll") for (int n = 0; n < 2; ++n) _Pragma("unroll") for (int k = 0; k < 2; ++k) dst[n][k] = *(const LAS bf16x8*)(lds + G_SB(b, h) + boff + n * 2048 + k * 1024); } while (0)
; #define G_MMA(ai, bj, At_, Bt_) do { __builtin_amdgcn_s_setprio(1); _Pragma("unroll") for (int m = 0; m < 4; ++m) _Pragma("unroll") for (int n = 0; n < 2; ++n) _Pragma("unroll") for (int k = 0; k < 2; ++k) \
;         acc[ai][bj][m][n] = __builtin_amdgcn_mfma_f32_16x16x32_bf16(Bt_[n][k], At_[m][k], acc[ai][bj][m][n], 0, 0, 0); __builtin_amdgcn_s_setprio(0); } while (0)
; #define WAIT_V(n) asm volatile("s_waitcnt vmcnt(" #n ")" ::: "memory")
; template <class Get, class Epi>
; DI void gemm_loop(int ntiles, int ld, char* shm, const Get& get, const Epi& epi) {
;     ...
;         const int Ln = L + gridDim.x; const bool has_next = Ln < ntiles; if (has_next) nxt = get(Ln);
;         const char* nA = has_next ? (const char*)nxt.A + (size_t)nxt.brow * ld * 2 : cA; const char* nB = has_next ? (const char*)nxt.Bt + (size_t)nxt.bcol * ld * 2 : cB;
;         const int nt = cur.K / BK;
;         for (int t = 0; t < nt; t += 2) {
;             const bool last = (t == nt - 2);
;             const char* a1 = cA + (size_t)(t + 1) * kstep;
;             const char* a2 = last ? nA : cA + (size_t)(t + 2) * kstep; const char* b2 = last ? nB : cB + (size_t)(t + 2) * kstep;
;             const char* a3 = a2 + kstep; const char* b3 = b2 + kstep;
;             G_LDB(B0, 0, 0); G_LDB(B1, 0, 1); SCHED; G_LDA(At, 0, 0); G_STAGE(G_SA(1, 1), a1 + hstep, voffA);
;             WAIT_V(8); WAIT_L(0); BAR; G_MMA(0, 0, At, B0); G_MMA(0, 1, At, B1); BAR; SCHED;
;             G_LDA(At, 0, 1); G_STAGE(G_SB(0, 0), b2, voffB); G_STAGE(G_SB(0, 1), b2 + hstep, voffB); G_STAGE(G_SA(0, 0), a2, voffA);
;             WAIT_V(8); WAIT_L(0); BAR; G_MMA(1, 0, At, B0); G_MMA(1, 1, At, B1); BAR; SCHED;
.LBB0_2573:
	s_ashr_i32 s41, s40, 31
	s_lshl_b64 s[44:45], s[40:41], 11
	s_add_u32 s44, s0, s44
	s_addc_u32 s45, s1, s45
	s_and_b64 s[48:49], s[38:39], exec
	s_cselect_b32 s3, s45, s47
	s_cselect_b32 s41, s44, s46
	s_ashr_i32 s43, s42, 31
	s_lshl_b64 s[48:49], s[42:43], 11
	s_add_u32 s48, s4, s48
	s_addc_u32 s49, s5, s49
	s_and_b64 s[78:79], s[38:39], exec
	s_cselect_b32 s43, s49, s15
	s_cselect_b32 s77, s48, s14
	s_lshr_b32 s78, s52, 6
	s_add_i32 s79, s78, -2
	s_add_u32 s52, s46, 0x40080
	s_addc_u32 s53, s47, 0
	s_add_u32 s80, s14, 0x100
	s_addc_u32 s81, s15, 0
	s_mov_b32 s14, 0
.Lpeel_2574:
	ds_read_b128 v[128:131], v169
	ds_read_b128 v[132:135], v169 offset:1024
	ds_read_b128 v[136:139], v169 offset:2048
	ds_read_b128 v[140:143], v169 offset:3072
	ds_read_b128 v[158:161], v170
	ds_read_b128 v[162:165], v170 offset:1024
	ds_read_b128 v[172:175], v170 offset:2048
	ds_read_b128 v[176:179], v170 offset:3072
	s_add_i32 s82, s14, 2
	s_add_u32 s15, s52, 0xfffc0080
	s_addc_u32 s46, s53, -1
	s_cmp_eq_u32 s79, s14
	s_cselect_b32 s14, s77, s80
	s_cselect_b32 s47, s3, s46
	s_cselect_b32 s46, s41, s15
	s_cselect_b32 s15, s43, s81
	v_lshl_add_u64 v[144:145], s[52:53], 0, v[154:155]
	s_add_i32 m0, s51, 0xc000
	ds_read_b128 v[180:183], v171
	ds_read_b128 v[184:187], v171 offset:1024
	ds_read_b128 v[188:191], v171 offset:2048
	ds_read_b128 v[192:195], v171 offset:3072
	ds_read_b128 v[196:199], v171 offset:4096
	ds_read_b128 v[200:203], v171 offset:5120
	ds_read_b128 v[204:207], v171 offset:6144
	ds_read_b128 v[208:211], v171 offset:7168
	global_load_lds_dwordx4 v[144:145], off
	v_lshl_add_u64 v[144:145], s[52:53], 0, v[156:157]
	s_add_i32 m0, s51, 0xe000
	s_nop 0
	global_load_lds_dwordx4 v[144:145], off
	s_waitcnt vmcnt(8)
	s_waitcnt lgkmcnt(0)
	s_barrier
	s_setprio 1
	s_waitcnt lgkmcnt(0)
	v_mfma_f32_16x16x32_bf16 v[124:127], v[128:131], v[180:183], 0
	v_mfma_f32_16x16x32_bf16 v[120:123], v[136:139], v[180:183], 0
	v_mfma_f32_16x16x32_bf16 v[116:119], v[128:131], v[188:191], 0
	v_mfma_f32_16x16x32_bf16 v[112:115], v[136:139], v[188:191], 0
	v_mfma_f32_16x16x32_bf16 v[108:111], v[128:131], v[196:199], 0
	v_mfma_f32_16x16x32_bf16 v[104:107], v[136:139], v[196:199], 0
	v_mfma_f32_16x16x32_bf16 v[100:103], v[128:131], v[204:207], 0
	v_mfma_f32_16x16x32_bf16 v[96:99], v[136:139], v[204:207], 0
	v_mfma_f32_16x16x32_bf16 v[124:127], v[132:135], v[184:187], v[124:127]
	v_mfma_f32_16x16x32_bf16 v[120:123], v[140:143], v[184:187], v[120:123]
	v_mfma_f32_16x16x32_bf16 v[116:119], v[132:135], v[192:195], v[116:119]
	v_mfma_f32_16x16x32_bf16 v[112:115], v[140:143], v[192:195], v[112:115]
	v_mfma_f32_16x16x32_bf16 v[108:111], v[132:135], v[200:203], v[108:111]
	v_mfma_f32_16x16x32_bf16 v[104:107], v[140:143], v[200:203], v[104:107]
	v_mfma_f32_16x16x32_bf16 v[100:103], v[132:135], v[208:211], v[100:103]
	v_mfma_f32_16x16x32_bf16 v[96:99], v[140:143], v[208:211], v[96:99]
	s_setprio 0
	s_setprio 1
	v_mfma_f32_16x16x32_bf16 v[60:63], v[158:161], v[180:183], 0
	v_mfma_f32_16x16x32_bf16 v[56:59], v[172:175], v[180:183], 0
	v_mfma_f32_16x16x32_bf16 v[52:55], v[158:161], v[188:191], 0
	v_mfma_f32_16x16x32_bf16 v[48:51], v[172:175], v[188:191], 0
	v_mfma_f32_16x16x32_bf16 v[44:47], v[158:161], v[196:199], 0
	v_mfma_f32_16x16x32_bf16 v[40:43], v[172:175], v[196:199], 0
	v_mfma_f32_16x16x32_bf16 v[36:39], v[158:161], v[204:207], 0
	v_mfma_f32_16x16x32_bf16 v[32:35], v[172:175], v[204:207], 0
	v_mfma_f32_16x16x32_bf16 v[60:63], v[162:165], v[184:187], v[60:63]
	v_mfma_f32_16x16x32_bf16 v[56:59], v[176:179], v[184:187], v[56:59]
	v_mfma_f32_16x16x32_bf16 v[52:55], v[162:165], v[192:195], v[52:55]
	v_mfma_f32_16x16x32_bf16 v[48:51], v[176:179], v[192:195], v[48:51]
	v_mfma_f32_16x16x32_bf16 v[44:47], v[162:165], v[200:203], v[44:47]
	v_mfma_f32_16x16x32_bf16 v[40:43], v[176:179], v[200:203], v[40:43]
	v_mfma_f32_16x16x32_bf16 v[36:39], v[162:165], v[208:211], v[36:39]
	v_mfma_f32_16x16x32_bf16 v[32:35], v[176:179], v[208:211], v[32:35]
	s_setprio 0
	s_barrier
	s_add_i32 s83, s72, s31
	v_lshl_add_u64 v[144:145], s[14:15], 0, v[148:149]
	s_mov_b32 m0, s83
	ds_read_b128 v[180:183], v171 offset:16384
	ds_read_b128 v[184:187], v171 offset:17408
	ds_read_b128 v[188:191], v171 offset:18432
	ds_read_b128 v[192:195], v171 offset:19456
	ds_read_b128 v[196:199], v171 offset:20480
	ds_read_b128 v[200:203], v171 offset:21504
	ds_read_b128 v[204:207], v171 offset:22528
	ds_read_b128 v[208:211], v171 offset:23552
	global_load_lds_dwordx4 v[144:145], off
	s_add_i32 m0, s83, 0x2000
	s_add_u32 s84, s14, 0x40000
	v_lshl_add_u64 v[166:167], s[14:15], 0, v[152:153]
	s_addc_u32 s85, s15, 0
	s_add_i32 s83, s73, s31
	global_load_lds_dwordx4 v[166:167], off
	v_lshl_add_u64 v[212:213], s[84:85], 0, v[148:149]
	s_mov_b32 m0, s83
	v_lshl_add_u64 v[214:215], s[46:47], 0, v[150:151]
	global_load_lds_dwordx4 v[212:213], off
	v_lshl_add_u64 v[212:213], s[84:85], 0, v[152:153]
	s_add_i32 m0, s83, 0x2000
	s_nop 0
	global_load_lds_dwordx4 v[212:213], off
	v_lshl_add_u64 v[212:213], s[46:47], 0, v[146:147]
	s_mov_b32 m0, s51
	s_nop 0
	global_load_lds_dwordx4 v[212:213], off
	s_mov_b32 m0, s54
	s_nop 0
	global_load_lds_dwordx4 v[214:215], off
	s_waitcnt vmcnt(8)
	s_waitcnt lgkmcnt(0)
	s_barrier
; #define G_STAGE(bufoff, gbase, voff) do { _Pragma("unroll") for (int _i = 0; _i < 2; ++_i) \
;         __builtin_amdgcn_global_load_lds((const unsigned*)((const char*)(gbase) + voff[_i]), (LAS unsigned*)(lds + (bufoff) + ldsw + _i * 8192), 16, 0, 0); } while (0)
; #define G_LDA(dst, b, h) do { _Pragma("unroll") for (int m = 0; m < 4; ++m) _Pragma("unroll") for (int k = 0; k < 2; ++k) dst[m][k] = *(const LAS bf16x8*)(lds + G_SA(b, h) + aoff + m * 2048 + k * 1024); } while (0)
; #define G_LDB(dst, b, h) do { _Pragma("unroll") for (int n = 0; n < 2; ++n) _Pragma("unroll") for (int k = 0; k < 2; ++k) dst[n][k] = *(const LAS bf16x8*)(lds + G_SB(b, h) + boff + n * 2048 + k * 1024); } while (0)
; #define G_MMA(ai, bj, At_, Bt_) do { __builtin_amdgcn_s_setprio(1); _Pragma("unroll") for (int m = 0; m < 4; ++m) _Pragma("unroll") for (int n = 0; n < 2; ++n) _Pragma("unroll") for (int k = 0; k < 2; ++k) \
;         acc[ai][bj][m][n] = __builtin_amdgcn_mfma_f32_16x16x32_bf16(Bt_[n][k], At_[m][k], acc[ai][bj][m][n], 0, 0, 0); __builtin_amdgcn_s_setprio(0); } while (0)
; #define WAIT_V(n) asm volatile("s_waitcnt vmcnt(" #n ")" ::: "memory")
; #define WAIT_L(n) asm volatile("s_waitcnt lgkmcnt(" #n ")" ::: "memory")
; #define BAR __builtin_amdgcn_s_barrier()
; #define SCHED __builtin_amdgcn_sched_barrier(0)
; template <class Get, class Epi>
; DI void gemm_loop(int ntiles, int ld, char* shm, const Get& get, const Epi& epi) {
;     ...
;             WAIT_V(8); WAIT_L(0); BAR; G_MMA(1, 0, At, B0); G_MMA(1, 1, At, B1); BAR; SCHED;
;             G_LDB(B0, 1, 0); G_LDB(B1, 1, 1); SCHED; G_LDA(At, 1, 0); G_STAGE(G_SA(0, 1), a2 + hstep, voffA);
;             WAIT_V(8); WAIT_L(0); BAR; G_MMA(0, 0, At, B0); G_MMA(0, 1, At, B1); BAR; SCHED;
;             G_LDA(At, 1, 1); G_STAGE(G_SB(1, 0), b3, voffB); G_STAGE(G_SB(1, 1), b3 + hstep, voffB); G_STAGE(G_SA(1, 0), a3, voffA);
	s_setprio 1
	s_waitcnt lgkmcnt(0)
	v_mfma_f32_16x16x32_bf16 v[92:95], v[128:131], v[180:183], 0
	v_mfma_f32_16x16x32_bf16 v[88:91], v[136:139], v[180:183], 0
	v_mfma_f32_16x16x32_bf16 v[84:87], v[128:131], v[188:191], 0
	v_mfma_f32_16x16x32_bf16 v[80:83], v[136:139], v[188:191], 0
	v_mfma_f32_16x16x32_bf16 v[76:79], v[128:131], v[196:199], 0
	v_mfma_f32_16x16x32_bf16 v[72:75], v[136:139], v[196:199], 0
	v_mfma_f32_16x16x32_bf16 v[68:71], v[128:131], v[204:207], 0
	v_mfma_f32_16x16x32_bf16 v[64:67], v[136:139], v[204:207], 0
	v_mfma_f32_16x16x32_bf16 v[92:95], v[132:135], v[184:187], v[92:95]
	v_mfma_f32_16x16x32_bf16 v[88:91], v[140:143], v[184:187], v[88:91]
	v_mfma_f32_16x16x32_bf16 v[84:87], v[132:135], v[192:195], v[84:87]
	v_mfma_f32_16x16x32_bf16 v[80:83], v[140:143], v[192:195], v[80:83]
	v_mfma_f32_16x16x32_bf16 v[76:79], v[132:135], v[200:203], v[76:79]
	v_mfma_f32_16x16x32_bf16 v[72:75], v[140:143], v[200:203], v[72:75]
	v_mfma_f32_16x16x32_bf16 v[68:71], v[132:135], v[208:211], v[68:71]
	v_mfma_f32_16x16x32_bf16 v[64:67], v[140:143], v[208:211], v[64:67]
	s_setprio 0
	s_setprio 1
	v_mfma_f32_16x16x32_bf16 v[28:31], v[158:161], v[180:183], 0
	v_mfma_f32_16x16x32_bf16 v[24:27], v[172:175], v[180:183], 0
	v_mfma_f32_16x16x32_bf16 v[20:23], v[158:161], v[188:191], 0
	v_mfma_f32_16x16x32_bf16 v[16:19], v[172:175], v[188:191], 0
	v_mfma_f32_16x16x32_bf16 v[12:15], v[158:161], v[196:199], 0
	v_mfma_f32_16x16x32_bf16 v[8:11], v[172:175], v[196:199], 0
	v_mfma_f32_16x16x32_bf16 v[4:7], v[158:161], v[204:207], 0
	v_mfma_f32_16x16x32_bf16 v[0:3], v[172:175], v[204:207], 0
	v_mfma_f32_16x16x32_bf16 v[28:31], v[162:165], v[184:187], v[28:31]
	v_mfma_f32_16x16x32_bf16 v[24:27], v[176:179], v[184:187], v[24:27]
	v_mfma_f32_16x16x32_bf16 v[20:23], v[162:165], v[192:195], v[20:23]
	v_mfma_f32_16x16x32_bf16 v[16:19], v[176:179], v[192:195], v[16:19]
	v_mfma_f32_16x16x32_bf16 v[12:15], v[162:165], v[200:203], v[12:15]
	v_mfma_f32_16x16x32_bf16 v[8:11], v[176:179], v[200:203], v[8:11]
	v_mfma_f32_16x16x32_bf16 v[4:7], v[162:165], v[208:211], v[4:7]
	v_mfma_f32_16x16x32_bf16 v[0:3], v[176:179], v[208:211], v[0:3]
	s_setprio 0
	s_barrier
	s_add_i32 s83, 0, 0x18000
	s_add_i32 s84, 0, 0x1c000
	v_add_u32_e32 v140, s83, v168
	v_add_u32_e32 v176, s84, v168
	ds_read_b128 v[128:131], v140
	ds_read_b128 v[132:135], v140 offset:1024
	ds_read_b128 v[136:139], v140 offset:2048
	ds_read_b128 v[140:143], v140 offset:3072
	ds_read_b128 v[158:161], v176
	ds_read_b128 v[162:165], v176 offset:1024
	ds_read_b128 v[172:175], v176 offset:2048
	ds_read_b128 v[176:179], v176 offset:3072
	s_add_u32 s46, s46, 0x40000
	s_addc_u32 s47, s47, 0
	s_mov_b32 m0, s55
	v_lshl_add_u64 v[216:217], s[46:47], 0, v[146:147]
	ds_read_b128 v[180:183], v171 offset:32768
	ds_read_b128 v[184:187], v171 offset:33792
	ds_read_b128 v[188:191], v171 offset:34816
	ds_read_b128 v[192:195], v171 offset:35840
	ds_read_b128 v[196:199], v171 offset:36864
	ds_read_b128 v[200:203], v171 offset:37888
	ds_read_b128 v[204:207], v171 offset:38912
	ds_read_b128 v[208:211], v171 offset:39936
	global_load_lds_dwordx4 v[216:217], off
	v_lshl_add_u64 v[216:217], s[46:47], 0, v[150:151]
	s_mov_b32 m0, s56
	s_nop 0
	global_load_lds_dwordx4 v[216:217], off
	s_waitcnt vmcnt(8)
	s_waitcnt lgkmcnt(0)
	s_barrier
	s_setprio 1
	s_waitcnt lgkmcnt(0)
	v_mfma_f32_16x16x32_bf16 v[124:127], v[128:131], v[180:183], v[124:127]
	v_mfma_f32_16x16x32_bf16 v[120:123], v[136:139], v[180:183], v[120:123]
	v_mfma_f32_16x16x32_bf16 v[116:119], v[128:131], v[188:191], v[116:119]
	v_mfma_f32_16x16x32_bf16 v[112:115], v[136:139], v[188:191], v[112:115]
	v_mfma_f32_16x16x32_bf16 v[108:111], v[128:131], v[196:199], v[108:111]
	v_mfma_f32_16x16x32_bf16 v[104:107], v[136:139], v[196:199], v[104:107]
	v_mfma_f32_16x16x32_bf16 v[100:103], v[128:131], v[204:207], v[100:103]
	v_mfma_f32_16x16x32_bf16 v[96:99], v[136:139], v[204:207], v[96:99]
	v_mfma_f32_16x16x32_bf16 v[124:127], v[132:135], v[184:187], v[124:127]
	v_mfma_f32_16x16x32_bf16 v[120:123], v[140:143], v[184:187], v[120:123]
	v_mfma_f32_16x16x32_bf16 v[116:119], v[132:135], v[192:195], v[116:119]
	v_mfma_f32_16x16x32_bf16 v[112:115], v[140:143], v[192:195], v[112:115]
	v_mfma_f32_16x16x32_bf16 v[108:111], v[132:135], v[200:203], v[108:111]
	v_mfma_f32_16x16x32_bf16 v[104:107], v[140:143], v[200:203], v[104:107]
	v_mfma_f32_16x16x32_bf16 v[100:103], v[132:135], v[208:211], v[100:103]
	v_mfma_f32_16x16x32_bf16 v[96:99], v[140:143], v[208:211], v[96:99]
	s_setprio 0
	s_setprio 1
	v_mfma_f32_16x16x32_bf16 v[60:63], v[158:161], v[180:183], v[60:63]
	v_mfma_f32_16x16x32_bf16 v[56:59], v[172:175], v[180:183], v[56:59]
	v_mfma_f32_16x16x32_bf16 v[52:55], v[158:161], v[188:191], v[52:55]
	v_mfma_f32_16x16x32_bf16 v[48:51], v[172:175], v[188:191], v[48:51]
	v_mfma_f32_16x16x32_bf16 v[44:47], v[158:161], v[196:199], v[44:47]
	v_mfma_f32_16x16x32_bf16 v[40:43], v[172:175], v[196:199], v[40:43]
	v_mfma_f32_16x16x32_bf16 v[36:39], v[158:161], v[204:207], v[36:39]
	v_mfma_f32_16x16x32_bf16 v[32:35], v[172:175], v[204:207], v[32:35]
	v_mfma_f32_16x16x32_bf16 v[60:63], v[162:165], v[184:187], v[60:63]
	v_mfma_f32_16x16x32_bf16 v[56:59], v[176:179], v[184:187], v[56:59]
	v_mfma_f32_16x16x32_bf16 v[52:55], v[162:165], v[192:195], v[52:55]
	v_mfma_f32_16x16x32_bf16 v[48:51], v[176:179], v[192:195], v[48:51]
	v_mfma_f32_16x16x32_bf16 v[44:47], v[162:165], v[200:203], v[44:47]
	v_mfma_f32_16x16x32_bf16 v[40:43], v[176:179], v[200:203], v[40:43]
	v_mfma_f32_16x16x32_bf16 v[36:39], v[162:165], v[208:211], v[36:39]
	v_mfma_f32_16x16x32_bf16 v[32:35], v[176:179], v[208:211], v[32:35]
	s_setprio 0
	s_barrier
; #define G_STAGE(bufoff, gbase, voff) do { _Pragma("unroll") for (int _i = 0; _i < 2; ++_i) \
;         __builtin_amdgcn_global_load_lds((const unsigned*)((const char*)(gbase) + voff[_i]), (LAS unsigned*)(lds + (bufoff) + ldsw + _i * 8192), 16, 0, 0); } while (0)
; #define G_LDA(dst, b, h) do { _Pragma("unroll") for (int m = 0; m < 4; ++m) _Pragma("unroll") for (int k = 0; k < 2; ++k) dst[m][k] = *(const LAS bf16x8*)(lds + G_SA(b, h) + aoff + m * 2048 + k * 1024); } while (0)
; #define G_MMA(ai, bj, At_, Bt_) do { __builtin_amdgcn_s_setprio(1); _Pragma("unroll") for (int m = 0; m < 4; ++m) _Pragma("unroll") for (int n = 0; n < 2; ++n) _Pragma("unroll") for (int k = 0; k < 2; ++k) \
;         acc[ai][bj][m][n] = __builtin_amdgcn_mfma_f32_16x16x32_bf16(Bt_[n][k], At_[m][k], acc[ai][bj][m][n], 0, 0, 0); __builtin_amdgcn_s_setprio(0); } while (0)
; #define WAIT_V(n) asm volatile("s_waitcnt vmcnt(" #n ")" ::: "memory")
; #define WAIT_L(n) asm volatile("s_waitcnt lgkmcnt(" #n ")" ::: "memory")
; #define BAR __builtin_amdgcn_s_barrier()
; #define SCHED __builtin_amdgcn_sched_barrier(0)
; template <class Get, class Epi>
; DI void gemm_loop(int ntiles, int ld, char* shm, const Get& get, const Epi& epi) {
;     ...
;             G_LDA(At, 1, 1); G_STAGE(G_SB(1, 0), b3, voffB); G_STAGE(G_SB(1, 1), b3 + hstep, voffB); G_STAGE(G_SA(1, 0), a3, voffA);
;             WAIT_V(8); WAIT_L(0); BAR; G_MMA(1, 0, At, B0); G_MMA(1, 1, At, B1); BAR; SCHED;
;         }
	s_add_i32 s46, s83, s31
	v_lshl_add_u64 v[144:145], v[144:145], 0, s[8:9]
	s_mov_b32 m0, s46
	ds_read_b128 v[180:183], v171 offset:49152
	ds_read_b128 v[184:187], v171 offset:50176
	ds_read_b128 v[188:191], v171 offset:51200
	ds_read_b128 v[192:195], v171 offset:52224
	ds_read_b128 v[196:199], v171 offset:53248
	ds_read_b128 v[200:203], v171 offset:54272
	ds_read_b128 v[204:207], v171 offset:55296
	ds_read_b128 v[208:211], v171 offset:56320
	global_load_lds_dwordx4 v[144:145], off
	s_add_i32 m0, s46, 0x2000
	s_add_u32 s14, s14, 0x40080
	v_lshl_add_u64 v[144:145], v[166:167], 0, s[8:9]
	s_addc_u32 s15, s15, 0
	s_add_i32 s46, s84, s31
	global_load_lds_dwordx4 v[144:145], off
	v_lshl_add_u64 v[144:145], s[14:15], 0, v[148:149]
	s_mov_b32 m0, s46
	s_nop 0
	global_load_lds_dwordx4 v[144:145], off
	v_lshl_add_u64 v[144:145], s[14:15], 0, v[152:153]
	s_add_i32 m0, s46, 0x2000
	s_nop 0
	global_load_lds_dwordx4 v[144:145], off
	v_lshl_add_u64 v[144:145], v[212:213], 0, s[8:9]
	s_mov_b32 m0, s59
	s_nop 0
	global_load_lds_dwordx4 v[144:145], off
	v_lshl_add_u64 v[144:145], v[214:215], 0, s[8:9]
	s_mov_b32 m0, s71
	s_nop 0
	global_load_lds_dwordx4 v[144:145], off
	s_waitcnt vmcnt(8)
	s_waitcnt lgkmcnt(0)
	s_barrier
	s_setprio 1
	s_waitcnt lgkmcnt(0)
	v_mfma_f32_16x16x32_bf16 v[92:95], v[128:131], v[180:183], v[92:95]
	v_mfma_f32_16x16x32_bf16 v[88:91], v[136:139], v[180:183], v[88:91]
	v_mfma_f32_16x16x32_bf16 v[84:87], v[128:131], v[188:191], v[84:87]
	v_mfma_f32_16x16x32_bf16 v[80:83], v[136:139], v[188:191], v[80:83]
	v_mfma_f32_16x16x32_bf16 v[76:79], v[128:131], v[196:199], v[76:79]
	v_mfma_f32_16x16x32_bf16 v[72:75], v[136:139], v[196:199], v[72:75]
	v_mfma_f32_16x16x32_bf16 v[68:71], v[128:131], v[204:207], v[68:71]
	v_mfma_f32_16x16x32_bf16 v[64:67], v[136:139], v[204:207], v[64:67]
	v_mfma_f32_16x16x32_bf16 v[92:95], v[132:135], v[184:187], v[92:95]
	v_mfma_f32_16x16x32_bf16 v[88:91], v[140:143], v[184:187], v[88:91]
	v_mfma_f32_16x16x32_bf16 v[84:87], v[132:135], v[192:195], v[84:87]
	v_mfma_f32_16x16x32_bf16 v[80:83], v[140:143], v[192:195], v[80:83]
	v_mfma_f32_16x16x32_bf16 v[76:79], v[132:135], v[200:203], v[76:79]
	v_mfma_f32_16x16x32_bf16 v[72:75], v[140:143], v[200:203], v[72:75]
	v_mfma_f32_16x16x32_bf16 v[68:71], v[132:135], v[208:211], v[68:71]
	v_mfma_f32_16x16x32_bf16 v[64:67], v[140:143], v[208:211], v[64:67]
	s_setprio 0
	s_setprio 1
	v_mfma_f32_16x16x32_bf16 v[28:31], v[158:161], v[180:183], v[28:31]
	v_mfma_f32_16x16x32_bf16 v[24:27], v[172:175], v[180:183], v[24:27]
	v_mfma_f32_16x16x32_bf16 v[20:23], v[158:161], v[188:191], v[20:23]
	v_mfma_f32_16x16x32_bf16 v[16:19], v[172:175], v[188:191], v[16:19]
	v_mfma_f32_16x16x32_bf16 v[12:15], v[158:161], v[196:199], v[12:15]
	v_mfma_f32_16x16x32_bf16 v[8:11], v[172:175], v[196:199], v[8:11]
	v_mfma_f32_16x16x32_bf16 v[4:7], v[158:161], v[204:207], v[4:7]
	v_mfma_f32_16x16x32_bf16 v[0:3], v[172:175], v[204:207], v[0:3]
	v_mfma_f32_16x16x32_bf16 v[28:31], v[162:165], v[184:187], v[28:31]
	v_mfma_f32_16x16x32_bf16 v[24:27], v[176:179], v[184:187], v[24:27]
	v_mfma_f32_16x16x32_bf16 v[20:23], v[162:165], v[192:195], v[20:23]
	v_mfma_f32_16x16x32_bf16 v[16:19], v[176:179], v[192:195], v[16:19]
	v_mfma_f32_16x16x32_bf16 v[12:15], v[162:165], v[200:203], v[12:15]
	v_mfma_f32_16x16x32_bf16 v[8:11], v[176:179], v[200:203], v[8:11]
	v_mfma_f32_16x16x32_bf16 v[4:7], v[162:165], v[208:211], v[4:7]
	v_mfma_f32_16x16x32_bf16 v[0:3], v[176:179], v[208:211], v[0:3]
	s_setprio 0
	s_barrier
	s_add_u32 s52, s52, 0x100
	s_addc_u32 s53, s53, 0
	s_add_u32 s80, s80, 0x100
	s_addc_u32 s81, s81, 0
	s_cmp_ge_u32 s82, s78
	s_mov_b32 s14, s82
	s_cbranch_scc0 .LBB0_2574
	s_branch .Lpost_2574

; #define G_STAGE(bufoff, gbase, voff) do { _Pragma("unroll") for (int _i = 0; _i < 2; ++_i) \
;         __builtin_amdgcn_global_load_lds((const unsigned*)((const char*)(gbase) + voff[_i]), (LAS unsigned*)(lds + (bufoff) + ldsw + _i * 8192), 16, 0, 0); } while (0)
; #define G_LDA(dst, b, h) do { _Pragma("unroll") for (int m = 0; m < 4; ++m) _Pragma("unroll") for (int k = 0; k < 2; ++k) dst[m][k] = *(const LAS bf16x8*)(lds + G_SA(b, h) + aoff + m * 2048 + k * 1024); } while (0)
; #define G_LDB(dst, b, h) do { _Pragma("unroll") for (int n = 0; n < 2; ++n) _Pragma("unroll") for (int k = 0; k < 2; ++k) dst[n][k] = *(const LAS bf16x8*)(lds + G_SB(b, h) + boff + n * 2048 + k * 1024); } while (0)
; #define G_MMA(ai, bj, At_, Bt_) do { __builtin_amdgcn_s_setprio(1); _Pragma("unroll") for (int m = 0; m < 4; ++m) _Pragma("unroll") for (int n = 0; n < 2; ++n) _Pragma("unroll") for (int k = 0; k < 2; ++k) \
;         acc[ai][bj][m][n] = __builtin_amdgcn_mfma_f32_16x16x32_bf16(Bt_[n][k], At_[m][k], acc[ai][bj][m][n], 0, 0, 0); __builtin_amdgcn_s_setprio(0); } while (0)
; #define WAIT_V(n) asm volatile("s_waitcnt vmcnt(" #n ")" ::: "memory")
; #define WAIT_L(n) asm volatile("s_waitcnt lgkmcnt(" #n ")" ::: "memory")
; #define BAR __builtin_amdgcn_s_barrier()
; #define SCHED __builtin_amdgcn_sched_barrier(0)
; template <class Get, class Epi>
; DI void gemm_loop(int ntiles, int ld, char* shm, const Get& get, const Epi& epi) {
;     ...
;         const int nt = cur.K / BK;
;         for (int t = 0; t < nt; t += 2) {
;             const bool last = (t == nt - 2);
;             const char* a1 = cA + (size_t)(t + 1) * kstep;
;             const char* a2 = last ? nA : cA + (size_t)(t + 2) * kstep; const char* b2 = last ? nB : cB + (size_t)(t + 2) * kstep;
;             const char* a3 = a2 + kstep; const char* b3 = b2 + kstep;
;             G_LDB(B0, 0, 0); G_LDB(B1, 0, 1); SCHED; G_LDA(At, 0, 0); G_STAGE(G_SA(1, 1), a1 + hstep, voffA);
;             WAIT_V(8); WAIT_L(0); BAR; G_MMA(0, 0, At, B0); G_MMA(0, 1, At, B1); BAR; SCHED;
;             G_LDA(At, 0, 1); G_STAGE(G_SB(0, 0), b2, voffB); G_STAGE(G_SB(0, 1), b2 + hstep, voffB); G_STAGE(G_SA(0, 0), a2, voffA);
;             WAIT_V(8); WAIT_L(0); BAR; G_MMA(1, 0, At, B0); G_MMA(1, 1, At, B1); BAR; SCHED;
.LBB0_2891:
	s_lshr_b32 s79, s44, 6
	s_add_i32 s80, s79, -2
	s_add_u32 s81, s14, 0x100
	s_addc_u32 s82, s15, 0
	s_mov_b32 s44, 0
.Lpeel_2892:
	ds_read_b128 v[128:131], v169
	ds_read_b128 v[132:135], v169 offset:1024
	ds_read_b128 v[136:139], v169 offset:2048
	ds_read_b128 v[140:143], v169 offset:3072
	ds_read_b128 v[158:161], v170
	ds_read_b128 v[162:165], v170 offset:1024
	ds_read_b128 v[172:175], v170 offset:2048
	ds_read_b128 v[176:179], v170 offset:3072
	s_add_i32 s83, s44, 2
	s_add_u32 s14, s4, 0x100
	s_addc_u32 s15, s5, 0
	s_cmp_eq_u32 s80, s44
	s_cselect_b32 s44, s42, s81
	s_cselect_b32 s47, s41, s15
	s_cselect_b32 s46, s40, s14
	s_cselect_b32 s45, s43, s82
	v_lshl_add_u64 v[144:145], s[4:5], 0, v[154:155]
	s_add_i32 m0, s49, 0xc000
	ds_read_b128 v[180:183], v171
	ds_read_b128 v[184:187], v171 offset:1024
	ds_read_b128 v[188:191], v171 offset:2048
	ds_read_b128 v[192:195], v171 offset:3072
	ds_read_b128 v[196:199], v171 offset:4096
	ds_read_b128 v[200:203], v171 offset:5120
	ds_read_b128 v[204:207], v171 offset:6144
	ds_read_b128 v[208:211], v171 offset:7168
	global_load_lds_dwordx4 v[144:145], off
	v_lshl_add_u64 v[144:145], s[4:5], 0, v[156:157]
	s_add_i32 m0, s49, 0xe000
	s_nop 0
	global_load_lds_dwordx4 v[144:145], off
	s_waitcnt vmcnt(8)
	s_waitcnt lgkmcnt(0)
	s_barrier
	s_setprio 1
	s_waitcnt lgkmcnt(0)
	v_mfma_f32_16x16x32_bf16 v[124:127], v[128:131], v[180:183], 0
	v_mfma_f32_16x16x32_bf16 v[120:123], v[136:139], v[180:183], 0
	v_mfma_f32_16x16x32_bf16 v[116:119], v[128:131], v[188:191], 0
	v_mfma_f32_16x16x32_bf16 v[112:115], v[136:139], v[188:191], 0
	v_mfma_f32_16x16x32_bf16 v[108:111], v[128:131], v[196:199], 0
	v_mfma_f32_16x16x32_bf16 v[104:107], v[136:139], v[196:199], 0
	v_mfma_f32_16x16x32_bf16 v[100:103], v[128:131], v[204:207], 0
	v_mfma_f32_16x16x32_bf16 v[96:99], v[136:139], v[204:207], 0
	v_mfma_f32_16x16x32_bf16 v[124:127], v[132:135], v[184:187], v[124:127]
	v_mfma_f32_16x16x32_bf16 v[120:123], v[140:143], v[184:187], v[120:123]
	v_mfma_f32_16x16x32_bf16 v[116:119], v[132:135], v[192:195], v[116:119]
	v_mfma_f32_16x16x32_bf16 v[112:115], v[140:143], v[192:195], v[112:115]
	v_mfma_f32_16x16x32_bf16 v[108:111], v[132:135], v[200:203], v[108:111]
	v_mfma_f32_16x16x32_bf16 v[104:107], v[140:143], v[200:203], v[104:107]
	v_mfma_f32_16x16x32_bf16 v[100:103], v[132:135], v[208:211], v[100:103]
	v_mfma_f32_16x16x32_bf16 v[96:99], v[140:143], v[208:211], v[96:99]
	s_setprio 0
	s_setprio 1
	v_mfma_f32_16x16x32_bf16 v[60:63], v[158:161], v[180:183], 0
	v_mfma_f32_16x16x32_bf16 v[56:59], v[172:175], v[180:183], 0
	v_mfma_f32_16x16x32_bf16 v[52:55], v[158:161], v[188:191], 0
	v_mfma_f32_16x16x32_bf16 v[48:51], v[172:175], v[188:191], 0
	v_mfma_f32_16x16x32_bf16 v[44:47], v[158:161], v[196:199], 0
	v_mfma_f32_16x16x32_bf16 v[40:43], v[172:175], v[196:199], 0
	v_mfma_f32_16x16x32_bf16 v[36:39], v[158:161], v[204:207], 0
	v_mfma_f32_16x16x32_bf16 v[32:35], v[172:175], v[204:207], 0
	v_mfma_f32_16x16x32_bf16 v[60:63], v[162:165], v[184:187], v[60:63]
	v_mfma_f32_16x16x32_bf16 v[56:59], v[176:179], v[184:187], v[56:59]
	v_mfma_f32_16x16x32_bf16 v[52:55], v[162:165], v[192:195], v[52:55]
	v_mfma_f32_16x16x32_bf16 v[48:51], v[176:179], v[192:195], v[48:51]
	v_mfma_f32_16x16x32_bf16 v[44:47], v[162:165], v[200:203], v[44:47]
	v_mfma_f32_16x16x32_bf16 v[40:43], v[176:179], v[200:203], v[40:43]
	v_mfma_f32_16x16x32_bf16 v[36:39], v[162:165], v[208:211], v[36:39]
	v_mfma_f32_16x16x32_bf16 v[32:35], v[176:179], v[208:211], v[32:35]
	s_setprio 0
	s_barrier
	s_add_i32 s4, s58, s48
	v_lshl_add_u64 v[144:145], s[44:45], 0, v[148:149]
	s_mov_b32 m0, s4
	ds_read_b128 v[180:183], v171 offset:16384
	ds_read_b128 v[184:187], v171 offset:17408
	ds_read_b128 v[188:191], v171 offset:18432
	ds_read_b128 v[192:195], v171 offset:19456
	ds_read_b128 v[196:199], v171 offset:20480
	ds_read_b128 v[200:203], v171 offset:21504
	ds_read_b128 v[204:207], v171 offset:22528
	ds_read_b128 v[208:211], v171 offset:23552
	global_load_lds_dwordx4 v[144:145], off
	s_add_i32 m0, s4, 0x2000
	s_add_u32 s4, s44, 0xb0000
	v_lshl_add_u64 v[166:167], s[44:45], 0, v[152:153]
	s_addc_u32 s5, s45, 0
	s_add_i32 s84, s59, s48
	global_load_lds_dwordx4 v[166:167], off
	v_lshl_add_u64 v[212:213], s[4:5], 0, v[148:149]
	s_mov_b32 m0, s84
	v_lshl_add_u64 v[214:215], s[46:47], 0, v[150:151]
	global_load_lds_dwordx4 v[212:213], off
	v_lshl_add_u64 v[212:213], s[4:5], 0, v[152:153]
	s_add_i32 m0, s84, 0x2000
	s_nop 0
	global_load_lds_dwordx4 v[212:213], off
	v_lshl_add_u64 v[212:213], s[46:47], 0, v[146:147]
	s_mov_b32 m0, s49
	s_nop 0
	global_load_lds_dwordx4 v[212:213], off
	s_mov_b32 m0, s50
	s_nop 0
	global_load_lds_dwordx4 v[214:215], off
	s_waitcnt vmcnt(8)
	s_waitcnt lgkmcnt(0)
	s_barrier
; #define G_STAGE(bufoff, gbase, voff) do { _Pragma("unroll") for (int _i = 0; _i < 2; ++_i) \
;         __builtin_amdgcn_global_load_lds((const unsigned*)((const char*)(gbase) + voff[_i]), (LAS unsigned*)(lds + (bufoff) + ldsw + _i * 8192), 16, 0, 0); } while (0)
; #define G_LDA(dst, b, h) do { _Pragma("unroll") for (int m = 0; m < 4; ++m) _Pragma("unroll") for (int k = 0; k < 2; ++k) dst[m][k] = *(const LAS bf16x8*)(lds + G_SA(b, h) + aoff + m * 2048 + k * 1024); } while (0)
; #define G_LDB(dst, b, h) do { _Pragma("unroll") for (int n = 0; n < 2; ++n) _Pragma("unroll") for (int k = 0; k < 2; ++k) dst[n][k] = *(const LAS bf16x8*)(lds + G_SB(b, h) + boff + n * 2048 + k * 1024); } while (0)
; #define G_MMA(ai, bj, At_, Bt_) do { __builtin_amdgcn_s_setprio(1); _Pragma("unroll") for (int m = 0; m < 4; ++m) _Pragma("unroll") for (int n = 0; n < 2; ++n) _Pragma("unroll") for (int k = 0; k < 2; ++k) \
;         acc[ai][bj][m][n] = __builtin_amdgcn_mfma_f32_16x16x32_bf16(Bt_[n][k], At_[m][k], acc[ai][bj][m][n], 0, 0, 0); __builtin_amdgcn_s_setprio(0); } while (0)
; #define WAIT_V(n) asm volatile("s_waitcnt vmcnt(" #n ")" ::: "memory")
; #define WAIT_L(n) asm volatile("s_waitcnt lgkmcnt(" #n ")" ::: "memory")
; #define BAR __builtin_amdgcn_s_barrier()
; #define SCHED __builtin_amdgcn_sched_barrier(0)
; template <class Get, class Epi>
; DI void gemm_loop(int ntiles, int ld, char* shm, const Get& get, const Epi& epi) {
;     ...
;             WAIT_V(8); WAIT_L(0); BAR; G_MMA(1, 0, At, B0); G_MMA(1, 1, At, B1); BAR; SCHED;
;             G_LDB(B0, 1, 0); G_LDB(B1, 1, 1); SCHED; G_LDA(At, 1, 0); G_STAGE(G_SA(0, 1), a2 + hstep, voffA);
;             WAIT_V(8); WAIT_L(0); BAR; G_MMA(0, 0, At, B0); G_MMA(0, 1, At, B1); BAR; SCHED;
;             G_LDA(At, 1, 1); G_STAGE(G_SB(1, 0), b3, voffB); G_STAGE(G_SB(1, 1), b3 + hstep, voffB); G_STAGE(G_SA(1, 0), a3, voffA);
	s_setprio 1
	s_waitcnt lgkmcnt(0)
	v_mfma_f32_16x16x32_bf16 v[92:95], v[128:131], v[180:183], 0
	v_mfma_f32_16x16x32_bf16 v[88:91], v[136:139], v[180:183], 0
	v_mfma_f32_16x16x32_bf16 v[84:87], v[128:131], v[188:191], 0
	v_mfma_f32_16x16x32_bf16 v[80:83], v[136:139], v[188:191], 0
	v_mfma_f32_16x16x32_bf16 v[76:79], v[128:131], v[196:199], 0
	v_mfma_f32_16x16x32_bf16 v[72:75], v[136:139], v[196:199], 0
	v_mfma_f32_16x16x32_bf16 v[68:71], v[128:131], v[204:207], 0
	v_mfma_f32_16x16x32_bf16 v[64:67], v[136:139], v[204:207], 0
	v_mfma_f32_16x16x32_bf16 v[92:95], v[132:135], v[184:187], v[92:95]
	v_mfma_f32_16x16x32_bf16 v[88:91], v[140:143], v[184:187], v[88:91]
	v_mfma_f32_16x16x32_bf16 v[84:87], v[132:135], v[192:195], v[84:87]
	v_mfma_f32_16x16x32_bf16 v[80:83], v[140:143], v[192:195], v[80:83]
	v_mfma_f32_16x16x32_bf16 v[76:79], v[132:135], v[200:203], v[76:79]
	v_mfma_f32_16x16x32_bf16 v[72:75], v[140:143], v[200:203], v[72:75]
	v_mfma_f32_16x16x32_bf16 v[68:71], v[132:135], v[208:211], v[68:71]
	v_mfma_f32_16x16x32_bf16 v[64:67], v[140:143], v[208:211], v[64:67]
	s_setprio 0
	s_setprio 1
	v_mfma_f32_16x16x32_bf16 v[28:31], v[158:161], v[180:183], 0
	v_mfma_f32_16x16x32_bf16 v[24:27], v[172:175], v[180:183], 0
	v_mfma_f32_16x16x32_bf16 v[20:23], v[158:161], v[188:191], 0
	v_mfma_f32_16x16x32_bf16 v[16:19], v[172:175], v[188:191], 0
	v_mfma_f32_16x16x32_bf16 v[12:15], v[158:161], v[196:199], 0
	v_mfma_f32_16x16x32_bf16 v[8:11], v[172:175], v[196:199], 0
	v_mfma_f32_16x16x32_bf16 v[4:7], v[158:161], v[204:207], 0
	v_mfma_f32_16x16x32_bf16 v[0:3], v[172:175], v[204:207], 0
	v_mfma_f32_16x16x32_bf16 v[28:31], v[162:165], v[184:187], v[28:31]
	v_mfma_f32_16x16x32_bf16 v[24:27], v[176:179], v[184:187], v[24:27]
	v_mfma_f32_16x16x32_bf16 v[20:23], v[162:165], v[192:195], v[20:23]
	v_mfma_f32_16x16x32_bf16 v[16:19], v[176:179], v[192:195], v[16:19]
	v_mfma_f32_16x16x32_bf16 v[12:15], v[162:165], v[200:203], v[12:15]
	v_mfma_f32_16x16x32_bf16 v[8:11], v[176:179], v[200:203], v[8:11]
	v_mfma_f32_16x16x32_bf16 v[4:7], v[162:165], v[208:211], v[4:7]
	v_mfma_f32_16x16x32_bf16 v[0:3], v[176:179], v[208:211], v[0:3]
	s_setprio 0
	s_barrier
	s_add_i32 s84, 0, 0x18000
	s_add_i32 s85, 0, 0x1c000
	v_add_u32_e32 v140, s84, v168
	v_add_u32_e32 v176, s85, v168
	ds_read_b128 v[128:131], v140
	ds_read_b128 v[132:135], v140 offset:1024
	ds_read_b128 v[136:139], v140 offset:2048
	ds_read_b128 v[140:143], v140 offset:3072
	ds_read_b128 v[158:161], v176
	ds_read_b128 v[162:165], v176 offset:1024
	ds_read_b128 v[172:175], v176 offset:2048
	ds_read_b128 v[176:179], v176 offset:3072
	s_add_u32 s4, s46, 0xb0000
	s_addc_u32 s5, s47, 0
	s_mov_b32 m0, s51
	v_lshl_add_u64 v[216:217], s[4:5], 0, v[146:147]
	ds_read_b128 v[180:183], v171 offset:32768
	ds_read_b128 v[184:187], v171 offset:33792
	ds_read_b128 v[188:191], v171 offset:34816
	ds_read_b128 v[192:195], v171 offset:35840
	ds_read_b128 v[196:199], v171 offset:36864
	ds_read_b128 v[200:203], v171 offset:37888
	ds_read_b128 v[204:207], v171 offset:38912
	ds_read_b128 v[208:211], v171 offset:39936
	global_load_lds_dwordx4 v[216:217], off
	v_lshl_add_u64 v[216:217], s[4:5], 0, v[150:151]
	s_mov_b32 m0, s52
	s_nop 0
	global_load_lds_dwordx4 v[216:217], off
	s_waitcnt vmcnt(8)
	s_waitcnt lgkmcnt(0)
	s_barrier
	s_setprio 1
	s_waitcnt lgkmcnt(0)
	v_mfma_f32_16x16x32_bf16 v[124:127], v[128:131], v[180:183], v[124:127]
	v_mfma_f32_16x16x32_bf16 v[120:123], v[136:139], v[180:183], v[120:123]
	v_mfma_f32_16x16x32_bf16 v[116:119], v[128:131], v[188:191], v[116:119]
	v_mfma_f32_16x16x32_bf16 v[112:115], v[136:139], v[188:191], v[112:115]
	v_mfma_f32_16x16x32_bf16 v[108:111], v[128:131], v[196:199], v[108:111]
	v_mfma_f32_16x16x32_bf16 v[104:107], v[136:139], v[196:199], v[104:107]
	v_mfma_f32_16x16x32_bf16 v[100:103], v[128:131], v[204:207], v[100:103]
	v_mfma_f32_16x16x32_bf16 v[96:99], v[136:139], v[204:207], v[96:99]
	v_mfma_f32_16x16x32_bf16 v[124:127], v[132:135], v[184:187], v[124:127]
	v_mfma_f32_16x16x32_bf16 v[120:123], v[140:143], v[184:187], v[120:123]
	v_mfma_f32_16x16x32_bf16 v[116:119], v[132:135], v[192:195], v[116:119]
	v_mfma_f32_16x16x32_bf16 v[112:115], v[140:143], v[192:195], v[112:115]
	v_mfma_f32_16x16x32_bf16 v[108:111], v[132:135], v[200:203], v[108:111]
	v_mfma_f32_16x16x32_bf16 v[104:107], v[140:143], v[200:203], v[104:107]
	v_mfma_f32_16x16x32_bf16 v[100:103], v[132:135], v[208:211], v[100:103]
	v_mfma_f32_16x16x32_bf16 v[96:99], v[140:143], v[208:211], v[96:99]
	s_setprio 0
	s_setprio 1
	v_mfma_f32_16x16x32_bf16 v[60:63], v[158:161], v[180:183], v[60:63]
	v_mfma_f32_16x16x32_bf16 v[56:59], v[172:175], v[180:183], v[56:59]
	v_mfma_f32_16x16x32_bf16 v[52:55], v[158:161], v[188:191], v[52:55]
	v_mfma_f32_16x16x32_bf16 v[48:51], v[172:175], v[188:191], v[48:51]
	v_mfma_f32_16x16x32_bf16 v[44:47], v[158:161], v[196:199], v[44:47]
	v_mfma_f32_16x16x32_bf16 v[40:43], v[172:175], v[196:199], v[40:43]
	v_mfma_f32_16x16x32_bf16 v[36:39], v[158:161], v[204:207], v[36:39]
	v_mfma_f32_16x16x32_bf16 v[32:35], v[172:175], v[204:207], v[32:35]
	v_mfma_f32_16x16x32_bf16 v[60:63], v[162:165], v[184:187], v[60:63]
	v_mfma_f32_16x16x32_bf16 v[56:59], v[176:179], v[184:187], v[56:59]
	v_mfma_f32_16x16x32_bf16 v[52:55], v[162:165], v[192:195], v[52:55]
	v_mfma_f32_16x16x32_bf16 v[48:51], v[176:179], v[192:195], v[48:51]
	v_mfma_f32_16x16x32_bf16 v[44:47], v[162:165], v[200:203], v[44:47]
	v_mfma_f32_16x16x32_bf16 v[40:43], v[176:179], v[200:203], v[40:43]
	v_mfma_f32_16x16x32_bf16 v[36:39], v[162:165], v[208:211], v[36:39]
	v_mfma_f32_16x16x32_bf16 v[32:35], v[176:179], v[208:211], v[32:35]
	s_setprio 0
	s_barrier
; #define G_STAGE(bufoff, gbase, voff) do { _Pragma("unroll") for (int _i = 0; _i < 2; ++_i) \
;         __builtin_amdgcn_global_load_lds((const unsigned*)((const char*)(gbase) + voff[_i]), (LAS unsigned*)(lds + (bufoff) + ldsw + _i * 8192), 16, 0, 0); } while (0)
; #define G_LDA(dst, b, h) do { _Pragma("unroll") for (int m = 0; m < 4; ++m) _Pragma("unroll") for (int k = 0; k < 2; ++k) dst[m][k] = *(const LAS bf16x8*)(lds + G_SA(b, h) + aoff + m * 2048 + k * 1024); } while (0)
; #define G_MMA(ai, bj, At_, Bt_) do { __builtin_amdgcn_s_setprio(1); _Pragma("unroll") for (int m = 0; m < 4; ++m) _Pragma("unroll") for (int n = 0; n < 2; ++n) _Pragma("unroll") for (int k = 0; k < 2; ++k) \
;         acc[ai][bj][m][n] = __builtin_amdgcn_mfma_f32_16x16x32_bf16(Bt_[n][k], At_[m][k], acc[ai][bj][m][n], 0, 0, 0); __builtin_amdgcn_s_setprio(0); } while (0)
; #define WAIT_V(n) asm volatile("s_waitcnt vmcnt(" #n ")" ::: "memory")
; #define WAIT_L(n) asm volatile("s_waitcnt lgkmcnt(" #n ")" ::: "memory")
; #define BAR __builtin_amdgcn_s_barrier()
; #define SCHED __builtin_amdgcn_sched_barrier(0)
; template <class Get, class Epi>
; DI void gemm_loop(int ntiles, int ld, char* shm, const Get& get, const Epi& epi) {
;     ...
;             G_LDA(At, 1, 1); G_STAGE(G_SB(1, 0), b3, voffB); G_STAGE(G_SB(1, 1), b3 + hstep, voffB); G_STAGE(G_SA(1, 0), a3, voffA);
;             WAIT_V(8); WAIT_L(0); BAR; G_MMA(1, 0, At, B0); G_MMA(1, 1, At, B1); BAR; SCHED;
;         }
	s_add_i32 s4, s84, s48
	v_lshl_add_u64 v[144:145], v[144:145], 0, s[10:11]
	s_mov_b32 m0, s4
	ds_read_b128 v[180:183], v171 offset:49152
	ds_read_b128 v[184:187], v171 offset:50176
	ds_read_b128 v[188:191], v171 offset:51200
	ds_read_b128 v[192:195], v171 offset:52224
	ds_read_b128 v[196:199], v171 offset:53248
	ds_read_b128 v[200:203], v171 offset:54272
	ds_read_b128 v[204:207], v171 offset:55296
	ds_read_b128 v[208:211], v171 offset:56320
	global_load_lds_dwordx4 v[144:145], off
	s_add_i32 m0, s4, 0x2000
	s_add_u32 s4, s44, 0xb0080
	v_lshl_add_u64 v[144:145], v[166:167], 0, s[10:11]
	s_addc_u32 s5, s45, 0
	s_add_i32 s44, s85, s48
	global_load_lds_dwordx4 v[144:145], off
	v_lshl_add_u64 v[144:145], s[4:5], 0, v[148:149]
	s_mov_b32 m0, s44
	s_nop 0
	global_load_lds_dwordx4 v[144:145], off
	v_lshl_add_u64 v[144:145], s[4:5], 0, v[152:153]
	s_add_i32 m0, s44, 0x2000
	s_nop 0
	global_load_lds_dwordx4 v[144:145], off
	v_lshl_add_u64 v[144:145], v[212:213], 0, s[10:11]
	s_mov_b32 m0, s55
	s_nop 0
	global_load_lds_dwordx4 v[144:145], off
	v_lshl_add_u64 v[144:145], v[214:215], 0, s[10:11]
	s_mov_b32 m0, s56
	s_nop 0
	global_load_lds_dwordx4 v[144:145], off
	s_waitcnt vmcnt(8)
	s_waitcnt lgkmcnt(0)
	s_barrier
	s_setprio 1
	s_waitcnt lgkmcnt(0)
	v_mfma_f32_16x16x32_bf16 v[92:95], v[128:131], v[180:183], v[92:95]
	v_mfma_f32_16x16x32_bf16 v[88:91], v[136:139], v[180:183], v[88:91]
	v_mfma_f32_16x16x32_bf16 v[84:87], v[128:131], v[188:191], v[84:87]
	v_mfma_f32_16x16x32_bf16 v[80:83], v[136:139], v[188:191], v[80:83]
	v_mfma_f32_16x16x32_bf16 v[76:79], v[128:131], v[196:199], v[76:79]
	v_mfma_f32_16x16x32_bf16 v[72:75], v[136:139], v[196:199], v[72:75]
	v_mfma_f32_16x16x32_bf16 v[68:71], v[128:131], v[204:207], v[68:71]
	v_mfma_f32_16x16x32_bf16 v[64:67], v[136:139], v[204:207], v[64:67]
	v_mfma_f32_16x16x32_bf16 v[92:95], v[132:135], v[184:187], v[92:95]
	v_mfma_f32_16x16x32_bf16 v[88:91], v[140:143], v[184:187], v[88:91]
	v_mfma_f32_16x16x32_bf16 v[84:87], v[132:135], v[192:195], v[84:87]
	v_mfma_f32_16x16x32_bf16 v[80:83], v[140:143], v[192:195], v[80:83]
	v_mfma_f32_16x16x32_bf16 v[76:79], v[132:135], v[200:203], v[76:79]
	v_mfma_f32_16x16x32_bf16 v[72:75], v[140:143], v[200:203], v[72:75]
	v_mfma_f32_16x16x32_bf16 v[68:71], v[132:135], v[208:211], v[68:71]
	v_mfma_f32_16x16x32_bf16 v[64:67], v[140:143], v[208:211], v[64:67]
	s_setprio 0
	s_setprio 1
	v_mfma_f32_16x16x32_bf16 v[28:31], v[158:161], v[180:183], v[28:31]
	v_mfma_f32_16x16x32_bf16 v[24:27], v[172:175], v[180:183], v[24:27]
	v_mfma_f32_16x16x32_bf16 v[20:23], v[158:161], v[188:191], v[20:23]
	v_mfma_f32_16x16x32_bf16 v[16:19], v[172:175], v[188:191], v[16:19]
	v_mfma_f32_16x16x32_bf16 v[12:15], v[158:161], v[196:199], v[12:15]
	v_mfma_f32_16x16x32_bf16 v[8:11], v[172:175], v[196:199], v[8:11]
	v_mfma_f32_16x16x32_bf16 v[4:7], v[158:161], v[204:207], v[4:7]
	v_mfma_f32_16x16x32_bf16 v[0:3], v[172:175], v[204:207], v[0:3]
	v_mfma_f32_16x16x32_bf16 v[28:31], v[162:165], v[184:187], v[28:31]
	v_mfma_f32_16x16x32_bf16 v[24:27], v[176:179], v[184:187], v[24:27]
	v_mfma_f32_16x16x32_bf16 v[20:23], v[162:165], v[192:195], v[20:23]
	v_mfma_f32_16x16x32_bf16 v[16:19], v[176:179], v[192:195], v[16:19]
	v_mfma_f32_16x16x32_bf16 v[12:15], v[162:165], v[200:203], v[12:15]
	v_mfma_f32_16x16x32_bf16 v[8:11], v[176:179], v[200:203], v[8:11]
	v_mfma_f32_16x16x32_bf16 v[4:7], v[162:165], v[208:211], v[4:7]
	v_mfma_f32_16x16x32_bf16 v[0:3], v[176:179], v[208:211], v[0:3]
	s_setprio 0
	s_barrier
	s_add_u32 s81, s81, 0x100
	s_addc_u32 s82, s82, 0
	s_cmp_ge_u32 s83, s79
	s_mov_b64 s[4:5], s[14:15]
	s_mov_b32 s44, s83
	s_cbranch_scc0 .LBB0_2892
	s_branch .Lpost_2892

; #define G_STAGE(bufoff, gbase, voff) do { _Pragma("unroll") for (int _i = 0; _i < 2; ++_i) \
;         __builtin_amdgcn_global_load_lds((const unsigned*)((const char*)(gbase) + voff[_i]), (LAS unsigned*)(lds + (bufoff) + ldsw + _i * 8192), 16, 0, 0); } while (0)
; #define G_LDA(dst, b, h) do { _Pragma("unroll") for (int m = 0; m < 4; ++m) _Pragma("unroll") for (int k = 0; k < 2; ++k) dst[m][k] = *(const LAS bf16x8*)(lds + G_SA(b, h) + aoff + m * 2048 + k * 1024); } while (0)
; #define G_LDB(dst, b, h) do { _Pragma("unroll") for (int n = 0; n < 2; ++n) _Pragma("unroll") for (int k = 0; k < 2; ++k) dst[n][k] = *(const LAS bf16x8*)(lds + G_SB(b, h) + boff + n * 2048 + k * 1024); } while (0)
; #define G_MMA(ai, bj, At_, Bt_) do { __builtin_amdgcn_s_setprio(1); _Pragma("unroll") for (int m = 0; m < 4; ++m) _Pragma("unroll") for (int n = 0; n < 2; ++n) _Pragma("unroll") for (int k = 0; k < 2; ++k) \
;         acc[ai][bj][m][n] = __builtin_amdgcn_mfma_f32_16x16x32_bf16(Bt_[n][k], At_[m][k], acc[ai][bj][m][n], 0, 0, 0); __builtin_amdgcn_s_setprio(0); } while (0)
; #define WAIT_V(n) asm volatile("s_waitcnt vmcnt(" #n ")" ::: "memory")
; template <class Get, class Epi>
; DI void gemm_loop(int ntiles, int ld, char* shm, const Get& get, const Epi& epi) {
;     ...
;         const int Ln = L + gridDim.x; const bool has_next = Ln < ntiles; if (has_next) nxt = get(Ln);
;         const char* nA = has_next ? (const char*)nxt.A + (size_t)nxt.brow * ld * 2 : cA; const char* nB = has_next ? (const char*)nxt.Bt + (size_t)nxt.bcol * ld * 2 : cB;
;         const int nt = cur.K / BK;
;         for (int t = 0; t < nt; t += 2) {
;             const bool last = (t == nt - 2);
;             const char* a1 = cA + (size_t)(t + 1) * kstep;
;             const char* a2 = last ? nA : cA + (size_t)(t + 2) * kstep; const char* b2 = last ? nB : cB + (size_t)(t + 2) * kstep;
;             const char* a3 = a2 + kstep; const char* b3 = b2 + kstep;
;             G_LDB(B0, 0, 0); G_LDB(B1, 0, 1); SCHED; G_LDA(At, 0, 0); G_STAGE(G_SA(1, 1), a1 + hstep, voffA);
;             WAIT_V(8); WAIT_L(0); BAR; G_MMA(0, 0, At, B0); G_MMA(0, 1, At, B1); BAR; SCHED;
;             G_LDA(At, 0, 1); G_STAGE(G_SB(0, 0), b2, voffB); G_STAGE(G_SB(0, 1), b2 + hstep, voffB); G_STAGE(G_SA(0, 0), a2, voffA);
;             WAIT_V(8); WAIT_L(0); BAR; G_MMA(1, 0, At, B0); G_MMA(1, 1, At, B1); BAR; SCHED;
.LBB0_3140:
	s_ashr_i32 s39, s38, 31
	s_lshl_b64 s[42:43], s[38:39], 11
	s_add_u32 s42, s2, s42
	s_addc_u32 s43, s3, s43
	s_and_b64 s[44:45], s[36:37], exec
	s_cselect_b32 s11, s43, s47
	s_cselect_b32 s39, s42, s46
	s_ashr_i32 s41, s40, 31
	s_lshl_b64 s[44:45], s[40:41], 11
	s_add_u32 s44, s0, s44
	s_addc_u32 s45, s1, s45
	s_and_b64 s[48:49], s[36:37], exec
	s_cselect_b32 s41, s45, s15
	s_cselect_b32 s63, s44, s14
	s_add_u32 s48, s46, 0x40080
	s_addc_u32 s49, s47, 0
	s_add_u32 s64, s14, 0x100
	s_addc_u32 s65, s15, 0
	s_mov_b32 s70, -2
.Lpeel_3141:
	ds_read_b128 v[144:147], v141
	ds_read_b128 v[148:151], v141 offset:1024
	ds_read_b128 v[152:155], v141 offset:2048
	ds_read_b128 v[156:159], v141 offset:3072
	ds_read_b128 v[160:163], v142
	ds_read_b128 v[164:167], v142 offset:1024
	ds_read_b128 v[168:171], v142 offset:2048
	ds_read_b128 v[172:175], v142 offset:3072
	s_add_u32 s14, s48, 0xfffc0080
	s_addc_u32 s15, s49, -1
	s_cmp_eq_u32 s70, 12
	s_cselect_b32 s47, s11, s15
	s_cselect_b32 s46, s39, s14
	s_cselect_b32 s15, s41, s65
	s_cselect_b32 s14, s63, s64
	v_lshl_add_u64 v[208:209], s[48:49], 0, v[136:137]
	s_add_i32 m0, s35, 0xc000
	ds_read_b128 v[176:179], v143
	ds_read_b128 v[180:183], v143 offset:1024
	ds_read_b128 v[184:187], v143 offset:2048
	ds_read_b128 v[188:191], v143 offset:3072
	ds_read_b128 v[192:195], v143 offset:4096
	ds_read_b128 v[196:199], v143 offset:5120
	ds_read_b128 v[200:203], v143 offset:6144
	ds_read_b128 v[204:207], v143 offset:7168
	global_load_lds_dwordx4 v[208:209], off
	v_lshl_add_u64 v[208:209], s[48:49], 0, v[138:139]
	s_add_i32 m0, s35, 0xe000
	s_nop 0
	global_load_lds_dwordx4 v[208:209], off
	s_waitcnt vmcnt(8)
	s_waitcnt lgkmcnt(0)
	s_barrier
	s_setprio 1
	s_waitcnt lgkmcnt(0)
	v_mfma_f32_16x16x32_bf16 v[124:127], v[144:147], v[176:179], 0
	v_mfma_f32_16x16x32_bf16 v[120:123], v[152:155], v[176:179], 0
	v_mfma_f32_16x16x32_bf16 v[116:119], v[144:147], v[184:187], 0
	v_mfma_f32_16x16x32_bf16 v[112:115], v[152:155], v[184:187], 0
	v_mfma_f32_16x16x32_bf16 v[100:103], v[144:147], v[192:195], 0
	v_mfma_f32_16x16x32_bf16 v[96:99], v[152:155], v[192:195], 0
	v_mfma_f32_16x16x32_bf16 v[84:87], v[144:147], v[200:203], 0
	v_mfma_f32_16x16x32_bf16 v[80:83], v[152:155], v[200:203], 0
	v_mfma_f32_16x16x32_bf16 v[124:127], v[148:151], v[180:183], v[124:127]
	v_mfma_f32_16x16x32_bf16 v[120:123], v[156:159], v[180:183], v[120:123]
	v_mfma_f32_16x16x32_bf16 v[116:119], v[148:151], v[188:191], v[116:119]
	v_mfma_f32_16x16x32_bf16 v[112:115], v[156:159], v[188:191], v[112:115]
	v_mfma_f32_16x16x32_bf16 v[100:103], v[148:151], v[196:199], v[100:103]
	v_mfma_f32_16x16x32_bf16 v[96:99], v[156:159], v[196:199], v[96:99]
	v_mfma_f32_16x16x32_bf16 v[84:87], v[148:151], v[204:207], v[84:87]
	v_mfma_f32_16x16x32_bf16 v[80:83], v[156:159], v[204:207], v[80:83]
	s_setprio 0
	s_setprio 1
	v_mfma_f32_16x16x32_bf16 v[108:111], v[160:163], v[176:179], 0
	v_mfma_f32_16x16x32_bf16 v[104:107], v[168:171], v[176:179], 0
	v_mfma_f32_16x16x32_bf16 v[92:95], v[160:163], v[184:187], 0
	v_mfma_f32_16x16x32_bf16 v[88:91], v[168:171], v[184:187], 0
	v_mfma_f32_16x16x32_bf16 v[76:79], v[160:163], v[192:195], 0
	v_mfma_f32_16x16x32_bf16 v[72:75], v[168:171], v[192:195], 0
	v_mfma_f32_16x16x32_bf16 v[68:71], v[160:163], v[200:203], 0
	v_mfma_f32_16x16x32_bf16 v[64:67], v[168:171], v[200:203], 0
	v_mfma_f32_16x16x32_bf16 v[108:111], v[164:167], v[180:183], v[108:111]
	v_mfma_f32_16x16x32_bf16 v[104:107], v[172:175], v[180:183], v[104:107]
	v_mfma_f32_16x16x32_bf16 v[92:95], v[164:167], v[188:191], v[92:95]
	v_mfma_f32_16x16x32_bf16 v[88:91], v[172:175], v[188:191], v[88:91]
	v_mfma_f32_16x16x32_bf16 v[76:79], v[164:167], v[196:199], v[76:79]
	v_mfma_f32_16x16x32_bf16 v[72:75], v[172:175], v[196:199], v[72:75]
	v_mfma_f32_16x16x32_bf16 v[68:71], v[164:167], v[204:207], v[68:71]
	v_mfma_f32_16x16x32_bf16 v[64:67], v[172:175], v[204:207], v[64:67]
	s_setprio 0
	s_barrier
	s_add_i32 s71, s57, s50
	v_lshl_add_u64 v[208:209], s[14:15], 0, v[130:131]
	s_mov_b32 m0, s71
	ds_read_b128 v[176:179], v143 offset:16384
	ds_read_b128 v[180:183], v143 offset:17408
	ds_read_b128 v[184:187], v143 offset:18432
	ds_read_b128 v[188:191], v143 offset:19456
	ds_read_b128 v[192:195], v143 offset:20480
	ds_read_b128 v[196:199], v143 offset:21504
	ds_read_b128 v[200:203], v143 offset:22528
	ds_read_b128 v[204:207], v143 offset:23552
	global_load_lds_dwordx4 v[208:209], off
	s_add_i32 m0, s71, 0x2000
	s_add_u32 s72, s14, 0x40000
	v_lshl_add_u64 v[210:211], s[14:15], 0, v[134:135]
	s_addc_u32 s73, s15, 0
	s_add_i32 s71, s58, s50
	global_load_lds_dwordx4 v[210:211], off
	v_lshl_add_u64 v[212:213], s[72:73], 0, v[130:131]
	s_mov_b32 m0, s71
	v_lshl_add_u64 v[214:215], s[46:47], 0, v[132:133]
	global_load_lds_dwordx4 v[212:213], off
	v_lshl_add_u64 v[212:213], s[72:73], 0, v[134:135]
	s_add_i32 m0, s71, 0x2000
	s_nop 0
	global_load_lds_dwordx4 v[212:213], off
	v_lshl_add_u64 v[212:213], s[46:47], 0, v[128:129]
	s_mov_b32 m0, s35
	s_nop 0
	global_load_lds_dwordx4 v[212:213], off
	s_mov_b32 m0, s51
	s_nop 0
	global_load_lds_dwordx4 v[214:215], off
	s_waitcnt vmcnt(8)
	s_waitcnt lgkmcnt(0)
	s_barrier
; #define G_STAGE(bufoff, gbase, voff) do { _Pragma("unroll") for (int _i = 0; _i < 2; ++_i) \
;         __builtin_amdgcn_global_load_lds((const unsigned*)((const char*)(gbase) + voff[_i]), (LAS unsigned*)(lds + (bufoff) + ldsw + _i * 8192), 16, 0, 0); } while (0)
; #define G_LDA(dst, b, h) do { _Pragma("unroll") for (int m = 0; m < 4; ++m) _Pragma("unroll") for (int k = 0; k < 2; ++k) dst[m][k] = *(const LAS bf16x8*)(lds + G_SA(b, h) + aoff + m * 2048 + k * 1024); } while (0)
; #define G_LDB(dst, b, h) do { _Pragma("unroll") for (int n = 0; n < 2; ++n) _Pragma("unroll") for (int k = 0; k < 2; ++k) dst[n][k] = *(const LAS bf16x8*)(lds + G_SB(b, h) + boff + n * 2048 + k * 1024); } while (0)
; #define G_MMA(ai, bj, At_, Bt_) do { __builtin_amdgcn_s_setprio(1); _Pragma("unroll") for (int m = 0; m < 4; ++m) _Pragma("unroll") for (int n = 0; n < 2; ++n) _Pragma("unroll") for (int k = 0; k < 2; ++k) \
;         acc[ai][bj][m][n] = __builtin_amdgcn_mfma_f32_16x16x32_bf16(Bt_[n][k], At_[m][k], acc[ai][bj][m][n], 0, 0, 0); __builtin_amdgcn_s_setprio(0); } while (0)
; #define WAIT_V(n) asm volatile("s_waitcnt vmcnt(" #n ")" ::: "memory")
; #define WAIT_L(n) asm volatile("s_waitcnt lgkmcnt(" #n ")" ::: "memory")
; #define BAR __builtin_amdgcn_s_barrier()
; #define SCHED __builtin_amdgcn_sched_barrier(0)
; template <class Get, class Epi>
; DI void gemm_loop(int ntiles, int ld, char* shm, const Get& get, const Epi& epi) {
;     ...
;             WAIT_V(8); WAIT_L(0); BAR; G_MMA(1, 0, At, B0); G_MMA(1, 1, At, B1); BAR; SCHED;
;             G_LDB(B0, 1, 0); G_LDB(B1, 1, 1); SCHED; G_LDA(At, 1, 0); G_STAGE(G_SA(0, 1), a2 + hstep, voffA);
;             WAIT_V(8); WAIT_L(0); BAR; G_MMA(0, 0, At, B0); G_MMA(0, 1, At, B1); BAR; SCHED;
;             G_LDA(At, 1, 1); G_STAGE(G_SB(1, 0), b3, voffB); G_STAGE(G_SB(1, 1), b3 + hstep, voffB); G_STAGE(G_SA(1, 0), a3, voffA);
	s_setprio 1
	s_waitcnt lgkmcnt(0)
	v_mfma_f32_16x16x32_bf16 v[60:63], v[144:147], v[176:179], 0
	v_mfma_f32_16x16x32_bf16 v[56:59], v[152:155], v[176:179], 0
	v_mfma_f32_16x16x32_bf16 v[52:55], v[144:147], v[184:187], 0
	v_mfma_f32_16x16x32_bf16 v[48:51], v[152:155], v[184:187], 0
	v_mfma_f32_16x16x32_bf16 v[36:39], v[144:147], v[192:195], 0
	v_mfma_f32_16x16x32_bf16 v[32:35], v[152:155], v[192:195], 0
	v_mfma_f32_16x16x32_bf16 v[20:23], v[144:147], v[200:203], 0
	v_mfma_f32_16x16x32_bf16 v[16:19], v[152:155], v[200:203], 0
	v_mfma_f32_16x16x32_bf16 v[60:63], v[148:151], v[180:183], v[60:63]
	v_mfma_f32_16x16x32_bf16 v[56:59], v[156:159], v[180:183], v[56:59]
	v_mfma_f32_16x16x32_bf16 v[52:55], v[148:151], v[188:191], v[52:55]
	v_mfma_f32_16x16x32_bf16 v[48:51], v[156:159], v[188:191], v[48:51]
	v_mfma_f32_16x16x32_bf16 v[36:39], v[148:151], v[196:199], v[36:39]
	v_mfma_f32_16x16x32_bf16 v[32:35], v[156:159], v[196:199], v[32:35]
	v_mfma_f32_16x16x32_bf16 v[20:23], v[148:151], v[204:207], v[20:23]
	v_mfma_f32_16x16x32_bf16 v[16:19], v[156:159], v[204:207], v[16:19]
	s_setprio 0
	s_setprio 1
	v_mfma_f32_16x16x32_bf16 v[44:47], v[160:163], v[176:179], 0
	v_mfma_f32_16x16x32_bf16 v[40:43], v[168:171], v[176:179], 0
	v_mfma_f32_16x16x32_bf16 v[28:31], v[160:163], v[184:187], 0
	v_mfma_f32_16x16x32_bf16 v[24:27], v[168:171], v[184:187], 0
	v_mfma_f32_16x16x32_bf16 v[12:15], v[160:163], v[192:195], 0
	v_mfma_f32_16x16x32_bf16 v[8:11], v[168:171], v[192:195], 0
	v_mfma_f32_16x16x32_bf16 v[4:7], v[160:163], v[200:203], 0
	v_mfma_f32_16x16x32_bf16 v[0:3], v[168:171], v[200:203], 0
	v_mfma_f32_16x16x32_bf16 v[44:47], v[164:167], v[180:183], v[44:47]
	v_mfma_f32_16x16x32_bf16 v[40:43], v[172:175], v[180:183], v[40:43]
	v_mfma_f32_16x16x32_bf16 v[28:31], v[164:167], v[188:191], v[28:31]
	v_mfma_f32_16x16x32_bf16 v[24:27], v[172:175], v[188:191], v[24:27]
	v_mfma_f32_16x16x32_bf16 v[12:15], v[164:167], v[196:199], v[12:15]
	v_mfma_f32_16x16x32_bf16 v[8:11], v[172:175], v[196:199], v[8:11]
	v_mfma_f32_16x16x32_bf16 v[4:7], v[164:167], v[204:207], v[4:7]
	v_mfma_f32_16x16x32_bf16 v[0:3], v[172:175], v[204:207], v[0:3]
	s_setprio 0
	s_barrier
	s_add_i32 s71, 0, 0x18000
	s_add_i32 s72, 0, 0x1c000
	v_add_u32_e32 v156, s71, v140
	v_add_u32_e32 v172, s72, v140
	ds_read_b128 v[144:147], v156
	ds_read_b128 v[148:151], v156 offset:1024
	ds_read_b128 v[152:155], v156 offset:2048
	ds_read_b128 v[156:159], v156 offset:3072
	ds_read_b128 v[160:163], v172
	ds_read_b128 v[164:167], v172 offset:1024
	ds_read_b128 v[168:171], v172 offset:2048
	ds_read_b128 v[172:175], v172 offset:3072
	s_add_u32 s46, s46, 0x40000
	s_addc_u32 s47, s47, 0
	s_mov_b32 m0, s52
	v_lshl_add_u64 v[216:217], s[46:47], 0, v[128:129]
	ds_read_b128 v[176:179], v143 offset:32768
	ds_read_b128 v[180:183], v143 offset:33792
	ds_read_b128 v[184:187], v143 offset:34816
	ds_read_b128 v[188:191], v143 offset:35840
	ds_read_b128 v[192:195], v143 offset:36864
	ds_read_b128 v[196:199], v143 offset:37888
	ds_read_b128 v[200:203], v143 offset:38912
	ds_read_b128 v[204:207], v143 offset:39936
	global_load_lds_dwordx4 v[216:217], off
	v_lshl_add_u64 v[216:217], s[46:47], 0, v[132:133]
	s_mov_b32 m0, s53
	s_nop 0
	global_load_lds_dwordx4 v[216:217], off
	s_waitcnt vmcnt(8)
	s_waitcnt lgkmcnt(0)
	s_barrier
	s_setprio 1
	s_waitcnt lgkmcnt(0)
	v_mfma_f32_16x16x32_bf16 v[124:127], v[144:147], v[176:179], v[124:127]
	v_mfma_f32_16x16x32_bf16 v[120:123], v[152:155], v[176:179], v[120:123]
	v_mfma_f32_16x16x32_bf16 v[116:119], v[144:147], v[184:187], v[116:119]
	v_mfma_f32_16x16x32_bf16 v[112:115], v[152:155], v[184:187], v[112:115]
	v_mfma_f32_16x16x32_bf16 v[100:103], v[144:147], v[192:195], v[100:103]
	v_mfma_f32_16x16x32_bf16 v[96:99], v[152:155], v[192:195], v[96:99]
	v_mfma_f32_16x16x32_bf16 v[84:87], v[144:147], v[200:203], v[84:87]
	v_mfma_f32_16x16x32_bf16 v[80:83], v[152:155], v[200:203], v[80:83]
	v_mfma_f32_16x16x32_bf16 v[124:127], v[148:151], v[180:183], v[124:127]
	v_mfma_f32_16x16x32_bf16 v[120:123], v[156:159], v[180:183], v[120:123]
	v_mfma_f32_16x16x32_bf16 v[116:119], v[148:151], v[188:191], v[116:119]
	v_mfma_f32_16x16x32_bf16 v[112:115], v[156:159], v[188:191], v[112:115]
	v_mfma_f32_16x16x32_bf16 v[100:103], v[148:151], v[196:199], v[100:103]
	v_mfma_f32_16x16x32_bf16 v[96:99], v[156:159], v[196:199], v[96:99]
	v_mfma_f32_16x16x32_bf16 v[84:87], v[148:151], v[204:207], v[84:87]
	v_mfma_f32_16x16x32_bf16 v[80:83], v[156:159], v[204:207], v[80:83]
	s_setprio 0
	s_setprio 1
	v_mfma_f32_16x16x32_bf16 v[108:111], v[160:163], v[176:179], v[108:111]
	v_mfma_f32_16x16x32_bf16 v[104:107], v[168:171], v[176:179], v[104:107]
	v_mfma_f32_16x16x32_bf16 v[92:95], v[160:163], v[184:187], v[92:95]
	v_mfma_f32_16x16x32_bf16 v[88:91], v[168:171], v[184:187], v[88:91]
	v_mfma_f32_16x16x32_bf16 v[76:79], v[160:163], v[192:195], v[76:79]
	v_mfma_f32_16x16x32_bf16 v[72:75], v[168:171], v[192:195], v[72:75]
	v_mfma_f32_16x16x32_bf16 v[68:71], v[160:163], v[200:203], v[68:71]
	v_mfma_f32_16x16x32_bf16 v[64:67], v[168:171], v[200:203], v[64:67]
	v_mfma_f32_16x16x32_bf16 v[108:111], v[164:167], v[180:183], v[108:111]
	v_mfma_f32_16x16x32_bf16 v[104:107], v[172:175], v[180:183], v[104:107]
	v_mfma_f32_16x16x32_bf16 v[92:95], v[164:167], v[188:191], v[92:95]
	v_mfma_f32_16x16x32_bf16 v[88:91], v[172:175], v[188:191], v[88:91]
	v_mfma_f32_16x16x32_bf16 v[76:79], v[164:167], v[196:199], v[76:79]
	v_mfma_f32_16x16x32_bf16 v[72:75], v[172:175], v[196:199], v[72:75]
	v_mfma_f32_16x16x32_bf16 v[68:71], v[164:167], v[204:207], v[68:71]
	v_mfma_f32_16x16x32_bf16 v[64:67], v[172:175], v[204:207], v[64:67]
	s_setprio 0
	s_barrier
; #define G_STAGE(bufoff, gbase, voff) do { _Pragma("unroll") for (int _i = 0; _i < 2; ++_i) \
;         __builtin_amdgcn_global_load_lds((const unsigned*)((const char*)(gbase) + voff[_i]), (LAS unsigned*)(lds + (bufoff) + ldsw + _i * 8192), 16, 0, 0); } while (0)
; #define G_LDA(dst, b, h) do { _Pragma("unroll") for (int m = 0; m < 4; ++m) _Pragma("unroll") for (int k = 0; k < 2; ++k) dst[m][k] = *(const LAS bf16x8*)(lds + G_SA(b, h) + aoff + m * 2048 + k * 1024); } while (0)
; #define G_MMA(ai, bj, At_, Bt_) do { __builtin_amdgcn_s_setprio(1); _Pragma("unroll") for (int m = 0; m < 4; ++m) _Pragma("unroll") for (int n = 0; n < 2; ++n) _Pragma("unroll") for (int k = 0; k < 2; ++k) \
;         acc[ai][bj][m][n] = __builtin_amdgcn_mfma_f32_16x16x32_bf16(Bt_[n][k], At_[m][k], acc[ai][bj][m][n], 0, 0, 0); __builtin_amdgcn_s_setprio(0); } while (0)
; #define WAIT_V(n) asm volatile("s_waitcnt vmcnt(" #n ")" ::: "memory")
; #define WAIT_L(n) asm volatile("s_waitcnt lgkmcnt(" #n ")" ::: "memory")
; #define BAR __builtin_amdgcn_s_barrier()
; #define SCHED __builtin_amdgcn_sched_barrier(0)
; template <class Get, class Epi>
; DI void gemm_loop(int ntiles, int ld, char* shm, const Get& get, const Epi& epi) {
;     ...
;             G_LDA(At, 1, 1); G_STAGE(G_SB(1, 0), b3, voffB); G_STAGE(G_SB(1, 1), b3 + hstep, voffB); G_STAGE(G_SA(1, 0), a3, voffA);
;             WAIT_V(8); WAIT_L(0); BAR; G_MMA(1, 0, At, B0); G_MMA(1, 1, At, B1); BAR; SCHED;
;         }
	s_add_i32 s46, s71, s50
	v_lshl_add_u64 v[208:209], v[208:209], 0, s[8:9]
	s_mov_b32 m0, s46
	ds_read_b128 v[176:179], v143 offset:49152
	ds_read_b128 v[180:183], v143 offset:50176
	ds_read_b128 v[184:187], v143 offset:51200
	ds_read_b128 v[188:191], v143 offset:52224
	ds_read_b128 v[192:195], v143 offset:53248
	ds_read_b128 v[196:199], v143 offset:54272
	ds_read_b128 v[200:203], v143 offset:55296
	ds_read_b128 v[204:207], v143 offset:56320
	global_load_lds_dwordx4 v[208:209], off
	s_add_i32 m0, s46, 0x2000
	s_add_u32 s14, s14, 0x40080
	v_lshl_add_u64 v[208:209], v[210:211], 0, s[8:9]
	s_addc_u32 s15, s15, 0
	s_add_i32 s46, s72, s50
	global_load_lds_dwordx4 v[208:209], off
	v_lshl_add_u64 v[208:209], s[14:15], 0, v[130:131]
	s_mov_b32 m0, s46
	s_nop 0
	global_load_lds_dwordx4 v[208:209], off
	v_lshl_add_u64 v[208:209], s[14:15], 0, v[134:135]
	s_add_i32 m0, s46, 0x2000
	s_nop 0
	global_load_lds_dwordx4 v[208:209], off
	v_lshl_add_u64 v[208:209], v[212:213], 0, s[8:9]
	s_mov_b32 m0, s55
	s_nop 0
	global_load_lds_dwordx4 v[208:209], off
	v_lshl_add_u64 v[208:209], v[214:215], 0, s[8:9]
	s_mov_b32 m0, s56
	s_nop 0
	global_load_lds_dwordx4 v[208:209], off
	s_waitcnt vmcnt(8)
	s_waitcnt lgkmcnt(0)
	s_barrier
	s_setprio 1
	s_waitcnt lgkmcnt(0)
	v_mfma_f32_16x16x32_bf16 v[60:63], v[144:147], v[176:179], v[60:63]
	v_mfma_f32_16x16x32_bf16 v[56:59], v[152:155], v[176:179], v[56:59]
	v_mfma_f32_16x16x32_bf16 v[52:55], v[144:147], v[184:187], v[52:55]
	v_mfma_f32_16x16x32_bf16 v[48:51], v[152:155], v[184:187], v[48:51]
	v_mfma_f32_16x16x32_bf16 v[36:39], v[144:147], v[192:195], v[36:39]
	v_mfma_f32_16x16x32_bf16 v[32:35], v[152:155], v[192:195], v[32:35]
	v_mfma_f32_16x16x32_bf16 v[20:23], v[144:147], v[200:203], v[20:23]
	v_mfma_f32_16x16x32_bf16 v[16:19], v[152:155], v[200:203], v[16:19]
	v_mfma_f32_16x16x32_bf16 v[60:63], v[148:151], v[180:183], v[60:63]
	v_mfma_f32_16x16x32_bf16 v[56:59], v[156:159], v[180:183], v[56:59]
	v_mfma_f32_16x16x32_bf16 v[52:55], v[148:151], v[188:191], v[52:55]
	v_mfma_f32_16x16x32_bf16 v[48:51], v[156:159], v[188:191], v[48:51]
	v_mfma_f32_16x16x32_bf16 v[36:39], v[148:151], v[196:199], v[36:39]
	v_mfma_f32_16x16x32_bf16 v[32:35], v[156:159], v[196:199], v[32:35]
	v_mfma_f32_16x16x32_bf16 v[20:23], v[148:151], v[204:207], v[20:23]
	v_mfma_f32_16x16x32_bf16 v[16:19], v[156:159], v[204:207], v[16:19]
	s_setprio 0
	s_setprio 1
	v_mfma_f32_16x16x32_bf16 v[44:47], v[160:163], v[176:179], v[44:47]
	v_mfma_f32_16x16x32_bf16 v[40:43], v[168:171], v[176:179], v[40:43]
	v_mfma_f32_16x16x32_bf16 v[28:31], v[160:163], v[184:187], v[28:31]
	v_mfma_f32_16x16x32_bf16 v[24:27], v[168:171], v[184:187], v[24:27]
	v_mfma_f32_16x16x32_bf16 v[12:15], v[160:163], v[192:195], v[12:15]
	v_mfma_f32_16x16x32_bf16 v[8:11], v[168:171], v[192:195], v[8:11]
	v_mfma_f32_16x16x32_bf16 v[4:7], v[160:163], v[200:203], v[4:7]
	v_mfma_f32_16x16x32_bf16 v[0:3], v[168:171], v[200:203], v[0:3]
	v_mfma_f32_16x16x32_bf16 v[44:47], v[164:167], v[180:183], v[44:47]
	v_mfma_f32_16x16x32_bf16 v[40:43], v[172:175], v[180:183], v[40:43]
	v_mfma_f32_16x16x32_bf16 v[28:31], v[164:167], v[188:191], v[28:31]
	v_mfma_f32_16x16x32_bf16 v[24:27], v[172:175], v[188:191], v[24:27]
	v_mfma_f32_16x16x32_bf16 v[12:15], v[164:167], v[196:199], v[12:15]
	v_mfma_f32_16x16x32_bf16 v[8:11], v[172:175], v[196:199], v[8:11]
	v_mfma_f32_16x16x32_bf16 v[4:7], v[164:167], v[204:207], v[4:7]
	v_mfma_f32_16x16x32_bf16 v[0:3], v[172:175], v[204:207], v[0:3]
	s_setprio 0
	s_barrier
	s_add_i32 s70, s70, 2
	s_add_u32 s48, s48, 0x100
	s_addc_u32 s49, s49, 0
	s_add_u32 s64, s64, 0x100
	s_addc_u32 s65, s65, 0
	s_cmp_gt_u32 s70, 13
	s_cbranch_scc0 .LBB0_3141
	s_branch .Lpost_3141

; #define G_STAGE(bufoff, gbase, voff) do { _Pragma("unroll") for (int _i = 0; _i < 2; ++_i) \
;         __builtin_amdgcn_global_load_lds((const unsigned*)((const char*)(gbase) + voff[_i]), (LAS unsigned*)(lds + (bufoff) + ldsw + _i * 8192), 16, 0, 0); } while (0)
; #define G_LDA(dst, b, h) do { _Pragma("unroll") for (int m = 0; m < 4; ++m) _Pragma("unroll") for (int k = 0; k < 2; ++k) dst[m][k] = *(const LAS bf16x8*)(lds + G_SA(b, h) + aoff + m * 2048 + k * 1024); } while (0)
; #define G_LDB(dst, b, h) do { _Pragma("unroll") for (int n = 0; n < 2; ++n) _Pragma("unroll") for (int k = 0; k < 2; ++k) dst[n][k] = *(const LAS bf16x8*)(lds + G_SB(b, h) + boff + n * 2048 + k * 1024); } while (0)
; #define G_MMA(ai, bj, At_, Bt_) do { __builtin_amdgcn_s_setprio(1); _Pragma("unroll") for (int m = 0; m < 4; ++m) _Pragma("unroll") for (int n = 0; n < 2; ++n) _Pragma("unroll") for (int k = 0; k < 2; ++k) \
;         acc[ai][bj][m][n] = __builtin_amdgcn_mfma_f32_16x16x32_bf16(Bt_[n][k], At_[m][k], acc[ai][bj][m][n], 0, 0, 0); __builtin_amdgcn_s_setprio(0); } while (0)
; #define WAIT_V(n) asm volatile("s_waitcnt vmcnt(" #n ")" ::: "memory")
; template <class Get, class Epi>
; DI void gemm_loop(int ntiles, int ld, char* shm, const Get& get, const Epi& epi) {
;     ...
;         const int Ln = L + gridDim.x; const bool has_next = Ln < ntiles; if (has_next) nxt = get(Ln);
;         const char* nA = has_next ? (const char*)nxt.A + (size_t)nxt.brow * ld * 2 : cA; const char* nB = has_next ? (const char*)nxt.Bt + (size_t)nxt.bcol * ld * 2 : cB;
;         const int nt = cur.K / BK;
;         for (int t = 0; t < nt; t += 2) {
;             const bool last = (t == nt - 2);
;             const char* a1 = cA + (size_t)(t + 1) * kstep;
;             const char* a2 = last ? nA : cA + (size_t)(t + 2) * kstep; const char* b2 = last ? nB : cB + (size_t)(t + 2) * kstep;
;             const char* a3 = a2 + kstep; const char* b3 = b2 + kstep;
;             G_LDB(B0, 0, 0); G_LDB(B1, 0, 1); SCHED; G_LDA(At, 0, 0); G_STAGE(G_SA(1, 1), a1 + hstep, voffA);
;             WAIT_V(8); WAIT_L(0); BAR; G_MMA(0, 0, At, B0); G_MMA(0, 1, At, B1); BAR; SCHED;
;             G_LDA(At, 0, 1); G_STAGE(G_SB(0, 0), b2, voffB); G_STAGE(G_SB(0, 1), b2 + hstep, voffB); G_STAGE(G_SA(0, 0), a2, voffA);
;             WAIT_V(8); WAIT_L(0); BAR; G_MMA(1, 0, At, B0); G_MMA(1, 1, At, B1); BAR; SCHED;
.LBB0_3465:
	s_ashr_i32 s35, s34, 31
	s_lshl_b64 s[38:39], s[34:35], 11
	s_add_u32 s38, s16, s38
	s_addc_u32 s39, s17, s39
	s_and_b64 s[40:41], s[30:31], exec
	s_cselect_b32 s3, s39, s45
	s_cselect_b32 s35, s38, s44
	s_ashr_i32 s37, s36, 31
	s_lshl_b64 s[40:41], s[36:37], 11
	s_add_u32 s40, s18, s40
	s_addc_u32 s41, s19, s41
	s_and_b64 s[46:47], s[30:31], exec
	s_cselect_b32 s37, s41, s15
	s_cselect_b32 s64, s40, s14
	s_add_u32 s44, s44, 0x40080
	s_addc_u32 s45, s45, 0
	s_add_u32 s65, s14, 0x100
	s_addc_u32 s70, s15, 0
	s_mov_b32 s71, -2
.Lpeel_3466:
	ds_read_b128 v[128:131], v169
	ds_read_b128 v[132:135], v169 offset:1024
	ds_read_b128 v[136:139], v169 offset:2048
	ds_read_b128 v[140:143], v169 offset:3072
	ds_read_b128 v[158:161], v170
	ds_read_b128 v[162:165], v170 offset:1024
	ds_read_b128 v[172:175], v170 offset:2048
	ds_read_b128 v[176:179], v170 offset:3072
	s_add_u32 s14, s44, 0xfffc0080
	s_addc_u32 s15, s45, -1
	s_cmp_eq_u32 s71, 12
	s_cselect_b32 s47, s3, s15
	s_cselect_b32 s46, s35, s14
	s_cselect_b32 s15, s37, s70
	s_cselect_b32 s14, s64, s65
	v_lshl_add_u64 v[144:145], s[44:45], 0, v[154:155]
	s_add_i32 m0, s43, 0xc000
	ds_read_b128 v[180:183], v171
	ds_read_b128 v[184:187], v171 offset:1024
	ds_read_b128 v[188:191], v171 offset:2048
	ds_read_b128 v[192:195], v171 offset:3072
	ds_read_b128 v[196:199], v171 offset:4096
	ds_read_b128 v[200:203], v171 offset:5120
	ds_read_b128 v[204:207], v171 offset:6144
	ds_read_b128 v[208:211], v171 offset:7168
	global_load_lds_dwordx4 v[144:145], off
	v_lshl_add_u64 v[144:145], s[44:45], 0, v[156:157]
	s_add_i32 m0, s43, 0xe000
	s_nop 0
	global_load_lds_dwordx4 v[144:145], off
	s_waitcnt vmcnt(8)
	s_waitcnt lgkmcnt(0)
	s_barrier
	s_setprio 1
	s_waitcnt lgkmcnt(0)
	v_mfma_f32_16x16x32_bf16 v[124:127], v[128:131], v[180:183], 0
	v_mfma_f32_16x16x32_bf16 v[120:123], v[136:139], v[180:183], 0
	v_mfma_f32_16x16x32_bf16 v[116:119], v[128:131], v[188:191], 0
	v_mfma_f32_16x16x32_bf16 v[112:115], v[136:139], v[188:191], 0
	v_mfma_f32_16x16x32_bf16 v[108:111], v[128:131], v[196:199], 0
	v_mfma_f32_16x16x32_bf16 v[104:107], v[136:139], v[196:199], 0
	v_mfma_f32_16x16x32_bf16 v[100:103], v[128:131], v[204:207], 0
	v_mfma_f32_16x16x32_bf16 v[96:99], v[136:139], v[204:207], 0
	v_mfma_f32_16x16x32_bf16 v[124:127], v[132:135], v[184:187], v[124:127]
	v_mfma_f32_16x16x32_bf16 v[120:123], v[140:143], v[184:187], v[120:123]
	v_mfma_f32_16x16x32_bf16 v[116:119], v[132:135], v[192:195], v[116:119]
	v_mfma_f32_16x16x32_bf16 v[112:115], v[140:143], v[192:195], v[112:115]
	v_mfma_f32_16x16x32_bf16 v[108:111], v[132:135], v[200:203], v[108:111]
	v_mfma_f32_16x16x32_bf16 v[104:107], v[140:143], v[200:203], v[104:107]
	v_mfma_f32_16x16x32_bf16 v[100:103], v[132:135], v[208:211], v[100:103]
	v_mfma_f32_16x16x32_bf16 v[96:99], v[140:143], v[208:211], v[96:99]
	s_setprio 0
	s_setprio 1
	v_mfma_f32_16x16x32_bf16 v[60:63], v[158:161], v[180:183], 0
	v_mfma_f32_16x16x32_bf16 v[56:59], v[172:175], v[180:183], 0
	v_mfma_f32_16x16x32_bf16 v[52:55], v[158:161], v[188:191], 0
	v_mfma_f32_16x16x32_bf16 v[48:51], v[172:175], v[188:191], 0
	v_mfma_f32_16x16x32_bf16 v[44:47], v[158:161], v[196:199], 0
	v_mfma_f32_16x16x32_bf16 v[40:43], v[172:175], v[196:199], 0
	v_mfma_f32_16x16x32_bf16 v[36:39], v[158:161], v[204:207], 0
	v_mfma_f32_16x16x32_bf16 v[32:35], v[172:175], v[204:207], 0
	v_mfma_f32_16x16x32_bf16 v[60:63], v[162:165], v[184:187], v[60:63]
	v_mfma_f32_16x16x32_bf16 v[56:59], v[176:179], v[184:187], v[56:59]
	v_mfma_f32_16x16x32_bf16 v[52:55], v[162:165], v[192:195], v[52:55]
	v_mfma_f32_16x16x32_bf16 v[48:51], v[176:179], v[192:195], v[48:51]
	v_mfma_f32_16x16x32_bf16 v[44:47], v[162:165], v[200:203], v[44:47]
	v_mfma_f32_16x16x32_bf16 v[40:43], v[176:179], v[200:203], v[40:43]
	v_mfma_f32_16x16x32_bf16 v[36:39], v[162:165], v[208:211], v[36:39]
	v_mfma_f32_16x16x32_bf16 v[32:35], v[176:179], v[208:211], v[32:35]
	s_setprio 0
	s_barrier
	s_add_i32 s72, s56, s48
	v_lshl_add_u64 v[144:145], s[14:15], 0, v[148:149]
	s_mov_b32 m0, s72
	ds_read_b128 v[180:183], v171 offset:16384
	ds_read_b128 v[184:187], v171 offset:17408
	ds_read_b128 v[188:191], v171 offset:18432
	ds_read_b128 v[192:195], v171 offset:19456
	ds_read_b128 v[196:199], v171 offset:20480
	ds_read_b128 v[200:203], v171 offset:21504
	ds_read_b128 v[204:207], v171 offset:22528
	ds_read_b128 v[208:211], v171 offset:23552
	global_load_lds_dwordx4 v[144:145], off
	s_add_i32 m0, s72, 0x2000
	s_add_u32 s72, s14, 0x40000
	v_lshl_add_u64 v[166:167], s[14:15], 0, v[152:153]
	s_addc_u32 s73, s15, 0
	s_add_i32 s74, s57, s48
	global_load_lds_dwordx4 v[166:167], off
	v_lshl_add_u64 v[212:213], s[72:73], 0, v[148:149]
	s_mov_b32 m0, s74
	v_lshl_add_u64 v[214:215], s[46:47], 0, v[150:151]
	global_load_lds_dwordx4 v[212:213], off
	v_lshl_add_u64 v[212:213], s[72:73], 0, v[152:153]
	s_add_i32 m0, s74, 0x2000
	s_nop 0
	global_load_lds_dwordx4 v[212:213], off
	v_lshl_add_u64 v[212:213], s[46:47], 0, v[146:147]
	s_mov_b32 m0, s43
	s_nop 0
	global_load_lds_dwordx4 v[212:213], off
	s_mov_b32 m0, s49
	s_nop 0
	global_load_lds_dwordx4 v[214:215], off
	s_waitcnt vmcnt(8)
	s_waitcnt lgkmcnt(0)
	s_barrier
; #define G_STAGE(bufoff, gbase, voff) do { _Pragma("unroll") for (int _i = 0; _i < 2; ++_i) \
;         __builtin_amdgcn_global_load_lds((const unsigned*)((const char*)(gbase) + voff[_i]), (LAS unsigned*)(lds + (bufoff) + ldsw + _i * 8192), 16, 0, 0); } while (0)
; #define G_LDA(dst, b, h) do { _Pragma("unroll") for (int m = 0; m < 4; ++m) _Pragma("unroll") for (int k = 0; k < 2; ++k) dst[m][k] = *(const LAS bf16x8*)(lds + G_SA(b, h) + aoff + m * 2048 + k * 1024); } while (0)
; #define G_LDB(dst, b, h) do { _Pragma("unroll") for (int n = 0; n < 2; ++n) _Pragma("unroll") for (int k = 0; k < 2; ++k) dst[n][k] = *(const LAS bf16x8*)(lds + G_SB(b, h) + boff + n * 2048 + k * 1024); } while (0)
; #define G_MMA(ai, bj, At_, Bt_) do { __builtin_amdgcn_s_setprio(1); _Pragma("unroll") for (int m = 0; m < 4; ++m) _Pragma("unroll") for (int n = 0; n < 2; ++n) _Pragma("unroll") for (int k = 0; k < 2; ++k) \
;         acc[ai][bj][m][n] = __builtin_amdgcn_mfma_f32_16x16x32_bf16(Bt_[n][k], At_[m][k], acc[ai][bj][m][n], 0, 0, 0); __builtin_amdgcn_s_setprio(0); } while (0)
; #define WAIT_V(n) asm volatile("s_waitcnt vmcnt(" #n ")" ::: "memory")
; #define WAIT_L(n) asm volatile("s_waitcnt lgkmcnt(" #n ")" ::: "memory")
; #define BAR __builtin_amdgcn_s_barrier()
; #define SCHED __builtin_amdgcn_sched_barrier(0)
; template <class Get, class Epi>
; DI void gemm_loop(int ntiles, int ld, char* shm, const Get& get, const Epi& epi) {
;     ...
;             WAIT_V(8); WAIT_L(0); BAR; G_MMA(1, 0, At, B0); G_MMA(1, 1, At, B1); BAR; SCHED;
;             G_LDB(B0, 1, 0); G_LDB(B1, 1, 1); SCHED; G_LDA(At, 1, 0); G_STAGE(G_SA(0, 1), a2 + hstep, voffA);
;             WAIT_V(8); WAIT_L(0); BAR; G_MMA(0, 0, At, B0); G_MMA(0, 1, At, B1); BAR; SCHED;
;             G_LDA(At, 1, 1); G_STAGE(G_SB(1, 0), b3, voffB); G_STAGE(G_SB(1, 1), b3 + hstep, voffB); G_STAGE(G_SA(1, 0), a3, voffA);
	s_setprio 1
	s_waitcnt lgkmcnt(0)
	v_mfma_f32_16x16x32_bf16 v[92:95], v[128:131], v[180:183], 0
	v_mfma_f32_16x16x32_bf16 v[88:91], v[136:139], v[180:183], 0
	v_mfma_f32_16x16x32_bf16 v[84:87], v[128:131], v[188:191], 0
	v_mfma_f32_16x16x32_bf16 v[80:83], v[136:139], v[188:191], 0
	v_mfma_f32_16x16x32_bf16 v[76:79], v[128:131], v[196:199], 0
	v_mfma_f32_16x16x32_bf16 v[72:75], v[136:139], v[196:199], 0
	v_mfma_f32_16x16x32_bf16 v[68:71], v[128:131], v[204:207], 0
	v_mfma_f32_16x16x32_bf16 v[64:67], v[136:139], v[204:207], 0
	v_mfma_f32_16x16x32_bf16 v[92:95], v[132:135], v[184:187], v[92:95]
	v_mfma_f32_16x16x32_bf16 v[88:91], v[140:143], v[184:187], v[88:91]
	v_mfma_f32_16x16x32_bf16 v[84:87], v[132:135], v[192:195], v[84:87]
	v_mfma_f32_16x16x32_bf16 v[80:83], v[140:143], v[192:195], v[80:83]
	v_mfma_f32_16x16x32_bf16 v[76:79], v[132:135], v[200:203], v[76:79]
	v_mfma_f32_16x16x32_bf16 v[72:75], v[140:143], v[200:203], v[72:75]
	v_mfma_f32_16x16x32_bf16 v[68:71], v[132:135], v[208:211], v[68:71]
	v_mfma_f32_16x16x32_bf16 v[64:67], v[140:143], v[208:211], v[64:67]
	s_setprio 0
	s_setprio 1
	v_mfma_f32_16x16x32_bf16 v[28:31], v[158:161], v[180:183], 0
	v_mfma_f32_16x16x32_bf16 v[24:27], v[172:175], v[180:183], 0
	v_mfma_f32_16x16x32_bf16 v[20:23], v[158:161], v[188:191], 0
	v_mfma_f32_16x16x32_bf16 v[16:19], v[172:175], v[188:191], 0
	v_mfma_f32_16x16x32_bf16 v[12:15], v[158:161], v[196:199], 0
	v_mfma_f32_16x16x32_bf16 v[8:11], v[172:175], v[196:199], 0
	v_mfma_f32_16x16x32_bf16 v[4:7], v[158:161], v[204:207], 0
	v_mfma_f32_16x16x32_bf16 v[0:3], v[172:175], v[204:207], 0
	v_mfma_f32_16x16x32_bf16 v[28:31], v[162:165], v[184:187], v[28:31]
	v_mfma_f32_16x16x32_bf16 v[24:27], v[176:179], v[184:187], v[24:27]
	v_mfma_f32_16x16x32_bf16 v[20:23], v[162:165], v[192:195], v[20:23]
	v_mfma_f32_16x16x32_bf16 v[16:19], v[176:179], v[192:195], v[16:19]
	v_mfma_f32_16x16x32_bf16 v[12:15], v[162:165], v[200:203], v[12:15]
	v_mfma_f32_16x16x32_bf16 v[8:11], v[176:179], v[200:203], v[8:11]
	v_mfma_f32_16x16x32_bf16 v[4:7], v[162:165], v[208:211], v[4:7]
	v_mfma_f32_16x16x32_bf16 v[0:3], v[176:179], v[208:211], v[0:3]
	s_setprio 0
	s_barrier
	s_add_i32 s72, 0, 0x18000
	s_add_i32 s73, 0, 0x1c000
	v_add_u32_e32 v140, s72, v168
	v_add_u32_e32 v176, s73, v168
	ds_read_b128 v[128:131], v140
	ds_read_b128 v[132:135], v140 offset:1024
	ds_read_b128 v[136:139], v140 offset:2048
	ds_read_b128 v[140:143], v140 offset:3072
	ds_read_b128 v[158:161], v176
	ds_read_b128 v[162:165], v176 offset:1024
	ds_read_b128 v[172:175], v176 offset:2048
	ds_read_b128 v[176:179], v176 offset:3072
	s_add_u32 s46, s46, 0x40000
	s_addc_u32 s47, s47, 0
	s_mov_b32 m0, s50
	v_lshl_add_u64 v[216:217], s[46:47], 0, v[146:147]
	ds_read_b128 v[180:183], v171 offset:32768
	ds_read_b128 v[184:187], v171 offset:33792
	ds_read_b128 v[188:191], v171 offset:34816
	ds_read_b128 v[192:195], v171 offset:35840
	ds_read_b128 v[196:199], v171 offset:36864
	ds_read_b128 v[200:203], v171 offset:37888
	ds_read_b128 v[204:207], v171 offset:38912
	ds_read_b128 v[208:211], v171 offset:39936
	global_load_lds_dwordx4 v[216:217], off
	v_lshl_add_u64 v[216:217], s[46:47], 0, v[150:151]
	s_mov_b32 m0, s51
	s_nop 0
	global_load_lds_dwordx4 v[216:217], off
	s_waitcnt vmcnt(8)
	s_waitcnt lgkmcnt(0)
	s_barrier
	s_setprio 1
	s_waitcnt lgkmcnt(0)
	v_mfma_f32_16x16x32_bf16 v[124:127], v[128:131], v[180:183], v[124:127]
	v_mfma_f32_16x16x32_bf16 v[120:123], v[136:139], v[180:183], v[120:123]
	v_mfma_f32_16x16x32_bf16 v[116:119], v[128:131], v[188:191], v[116:119]
	v_mfma_f32_16x16x32_bf16 v[112:115], v[136:139], v[188:191], v[112:115]
	v_mfma_f32_16x16x32_bf16 v[108:111], v[128:131], v[196:199], v[108:111]
	v_mfma_f32_16x16x32_bf16 v[104:107], v[136:139], v[196:199], v[104:107]
	v_mfma_f32_16x16x32_bf16 v[100:103], v[128:131], v[204:207], v[100:103]
	v_mfma_f32_16x16x32_bf16 v[96:99], v[136:139], v[204:207], v[96:99]
	v_mfma_f32_16x16x32_bf16 v[124:127], v[132:135], v[184:187], v[124:127]
	v_mfma_f32_16x16x32_bf16 v[120:123], v[140:143], v[184:187], v[120:123]
	v_mfma_f32_16x16x32_bf16 v[116:119], v[132:135], v[192:195], v[116:119]
	v_mfma_f32_16x16x32_bf16 v[112:115], v[140:143], v[192:195], v[112:115]
	v_mfma_f32_16x16x32_bf16 v[108:111], v[132:135], v[200:203], v[108:111]
	v_mfma_f32_16x16x32_bf16 v[104:107], v[140:143], v[200:203], v[104:107]
	v_mfma_f32_16x16x32_bf16 v[100:103], v[132:135], v[208:211], v[100:103]
	v_mfma_f32_16x16x32_bf16 v[96:99], v[140:143], v[208:211], v[96:99]
	s_setprio 0
	s_setprio 1
	v_mfma_f32_16x16x32_bf16 v[60:63], v[158:161], v[180:183], v[60:63]
	v_mfma_f32_16x16x32_bf16 v[56:59], v[172:175], v[180:183], v[56:59]
	v_mfma_f32_16x16x32_bf16 v[52:55], v[158:161], v[188:191], v[52:55]
	v_mfma_f32_16x16x32_bf16 v[48:51], v[172:175], v[188:191], v[48:51]
	v_mfma_f32_16x16x32_bf16 v[44:47], v[158:161], v[196:199], v[44:47]
	v_mfma_f32_16x16x32_bf16 v[40:43], v[172:175], v[196:199], v[40:43]
	v_mfma_f32_16x16x32_bf16 v[36:39], v[158:161], v[204:207], v[36:39]
	v_mfma_f32_16x16x32_bf16 v[32:35], v[172:175], v[204:207], v[32:35]
	v_mfma_f32_16x16x32_bf16 v[60:63], v[162:165], v[184:187], v[60:63]
	v_mfma_f32_16x16x32_bf16 v[56:59], v[176:179], v[184:187], v[56:59]
	v_mfma_f32_16x16x32_bf16 v[52:55], v[162:165], v[192:195], v[52:55]
	v_mfma_f32_16x16x32_bf16 v[48:51], v[176:179], v[192:195], v[48:51]
	v_mfma_f32_16x16x32_bf16 v[44:47], v[162:165], v[200:203], v[44:47]
	v_mfma_f32_16x16x32_bf16 v[40:43], v[176:179], v[200:203], v[40:43]
	v_mfma_f32_16x16x32_bf16 v[36:39], v[162:165], v[208:211], v[36:39]
	v_mfma_f32_16x16x32_bf16 v[32:35], v[176:179], v[208:211], v[32:35]
	s_setprio 0
	s_barrier
; #define G_STAGE(bufoff, gbase, voff) do { _Pragma("unroll") for (int _i = 0; _i < 2; ++_i) \
;         __builtin_amdgcn_global_load_lds((const unsigned*)((const char*)(gbase) + voff[_i]), (LAS unsigned*)(lds + (bufoff) + ldsw + _i * 8192), 16, 0, 0); } while (0)
; #define G_LDA(dst, b, h) do { _Pragma("unroll") for (int m = 0; m < 4; ++m) _Pragma("unroll") for (int k = 0; k < 2; ++k) dst[m][k] = *(const LAS bf16x8*)(lds + G_SA(b, h) + aoff + m * 2048 + k * 1024); } while (0)
; #define G_MMA(ai, bj, At_, Bt_) do { __builtin_amdgcn_s_setprio(1); _Pragma("unroll") for (int m = 0; m < 4; ++m) _Pragma("unroll") for (int n = 0; n < 2; ++n) _Pragma("unroll") for (int k = 0; k < 2; ++k) \
;         acc[ai][bj][m][n] = __builtin_amdgcn_mfma_f32_16x16x32_bf16(Bt_[n][k], At_[m][k], acc[ai][bj][m][n], 0, 0, 0); __builtin_amdgcn_s_setprio(0); } while (0)
; #define WAIT_V(n) asm volatile("s_waitcnt vmcnt(" #n ")" ::: "memory")
; #define WAIT_L(n) asm volatile("s_waitcnt lgkmcnt(" #n ")" ::: "memory")
; #define BAR __builtin_amdgcn_s_barrier()
; #define SCHED __builtin_amdgcn_sched_barrier(0)
; template <class Get, class Epi>
; DI void gemm_loop(int ntiles, int ld, char* shm, const Get& get, const Epi& epi) {
;     ...
;             G_LDA(At, 1, 1); G_STAGE(G_SB(1, 0), b3, voffB); G_STAGE(G_SB(1, 1), b3 + hstep, voffB); G_STAGE(G_SA(1, 0), a3, voffA);
;             WAIT_V(8); WAIT_L(0); BAR; G_MMA(1, 0, At, B0); G_MMA(1, 1, At, B1); BAR; SCHED;
;         }
	s_add_i32 s46, s72, s48
	v_lshl_add_u64 v[144:145], v[144:145], 0, s[4:5]
	s_mov_b32 m0, s46
	ds_read_b128 v[180:183], v171 offset:49152
	ds_read_b128 v[184:187], v171 offset:50176
	ds_read_b128 v[188:191], v171 offset:51200
	ds_read_b128 v[192:195], v171 offset:52224
	ds_read_b128 v[196:199], v171 offset:53248
	ds_read_b128 v[200:203], v171 offset:54272
	ds_read_b128 v[204:207], v171 offset:55296
	ds_read_b128 v[208:211], v171 offset:56320
	global_load_lds_dwordx4 v[144:145], off
	s_add_i32 m0, s46, 0x2000
	s_add_u32 s14, s14, 0x40080
	v_lshl_add_u64 v[144:145], v[166:167], 0, s[4:5]
	s_addc_u32 s15, s15, 0
	s_add_i32 s46, s73, s48
	global_load_lds_dwordx4 v[144:145], off
	v_lshl_add_u64 v[144:145], s[14:15], 0, v[148:149]
	s_mov_b32 m0, s46
	s_nop 0
	global_load_lds_dwordx4 v[144:145], off
	v_lshl_add_u64 v[144:145], s[14:15], 0, v[152:153]
	s_add_i32 m0, s46, 0x2000
	s_nop 0
	global_load_lds_dwordx4 v[144:145], off
	v_lshl_add_u64 v[144:145], v[212:213], 0, s[4:5]
	s_mov_b32 m0, s54
	s_nop 0
	global_load_lds_dwordx4 v[144:145], off
	v_lshl_add_u64 v[144:145], v[214:215], 0, s[4:5]
	s_mov_b32 m0, s55
	s_nop 0
	global_load_lds_dwordx4 v[144:145], off
	s_waitcnt vmcnt(8)
	s_waitcnt lgkmcnt(0)
	s_barrier
	s_setprio 1
	s_waitcnt lgkmcnt(0)
	v_mfma_f32_16x16x32_bf16 v[92:95], v[128:131], v[180:183], v[92:95]
	v_mfma_f32_16x16x32_bf16 v[88:91], v[136:139], v[180:183], v[88:91]
	v_mfma_f32_16x16x32_bf16 v[84:87], v[128:131], v[188:191], v[84:87]
	v_mfma_f32_16x16x32_bf16 v[80:83], v[136:139], v[188:191], v[80:83]
	v_mfma_f32_16x16x32_bf16 v[76:79], v[128:131], v[196:199], v[76:79]
	v_mfma_f32_16x16x32_bf16 v[72:75], v[136:139], v[196:199], v[72:75]
	v_mfma_f32_16x16x32_bf16 v[68:71], v[128:131], v[204:207], v[68:71]
	v_mfma_f32_16x16x32_bf16 v[64:67], v[136:139], v[204:207], v[64:67]
	v_mfma_f32_16x16x32_bf16 v[92:95], v[132:135], v[184:187], v[92:95]
	v_mfma_f32_16x16x32_bf16 v[88:91], v[140:143], v[184:187], v[88:91]
	v_mfma_f32_16x16x32_bf16 v[84:87], v[132:135], v[192:195], v[84:87]
	v_mfma_f32_16x16x32_bf16 v[80:83], v[140:143], v[192:195], v[80:83]
	v_mfma_f32_16x16x32_bf16 v[76:79], v[132:135], v[200:203], v[76:79]
	v_mfma_f32_16x16x32_bf16 v[72:75], v[140:143], v[200:203], v[72:75]
	v_mfma_f32_16x16x32_bf16 v[68:71], v[132:135], v[208:211], v[68:71]
	v_mfma_f32_16x16x32_bf16 v[64:67], v[140:143], v[208:211], v[64:67]
	s_setprio 0
	s_setprio 1
	v_mfma_f32_16x16x32_bf16 v[28:31], v[158:161], v[180:183], v[28:31]
	v_mfma_f32_16x16x32_bf16 v[24:27], v[172:175], v[180:183], v[24:27]
	v_mfma_f32_16x16x32_bf16 v[20:23], v[158:161], v[188:191], v[20:23]
	v_mfma_f32_16x16x32_bf16 v[16:19], v[172:175], v[188:191], v[16:19]
	v_mfma_f32_16x16x32_bf16 v[12:15], v[158:161], v[196:199], v[12:15]
	v_mfma_f32_16x16x32_bf16 v[8:11], v[172:175], v[196:199], v[8:11]
	v_mfma_f32_16x16x32_bf16 v[4:7], v[158:161], v[204:207], v[4:7]
	v_mfma_f32_16x16x32_bf16 v[0:3], v[172:175], v[204:207], v[0:3]
	v_mfma_f32_16x16x32_bf16 v[28:31], v[162:165], v[184:187], v[28:31]
	v_mfma_f32_16x16x32_bf16 v[24:27], v[176:179], v[184:187], v[24:27]
	v_mfma_f32_16x16x32_bf16 v[20:23], v[162:165], v[192:195], v[20:23]
	v_mfma_f32_16x16x32_bf16 v[16:19], v[176:179], v[192:195], v[16:19]
	v_mfma_f32_16x16x32_bf16 v[12:15], v[162:165], v[200:203], v[12:15]
	v_mfma_f32_16x16x32_bf16 v[8:11], v[176:179], v[200:203], v[8:11]
	v_mfma_f32_16x16x32_bf16 v[4:7], v[162:165], v[208:211], v[4:7]
	v_mfma_f32_16x16x32_bf16 v[0:3], v[176:179], v[208:211], v[0:3]
	s_setprio 0
	s_barrier
	s_add_i32 s71, s71, 2
	s_add_u32 s44, s44, 0x100
	s_addc_u32 s45, s45, 0
	s_add_u32 s65, s65, 0x100
	s_addc_u32 s70, s70, 0
	s_cmp_gt_u32 s71, 13
	s_cbranch_scc0 .LBB0_3466
	s_branch .Lpost_3466

; #define BAR __builtin_amdgcn_s_barrier()
; template <class Get, class Epi>
; DI void gemm_loop(int ntiles, int ld, char* shm, const Get& get, const Epi& epi) {
;     ...
;         if (wr == 0) BAR;
.Lpost_3466:
	s_and_b64 vcc, exec, s[6:7]
	s_cbranch_vccz .LBB0_3469
	s_barrier

; #define G_STAGE(bufoff, gbase, voff) do { _Pragma("unroll") for (int _i = 0; _i < 2; ++_i) \
;         __builtin_amdgcn_global_load_lds((const unsigned*)((const char*)(gbase) + voff[_i]), (LAS unsigned*)(lds + (bufoff) + ldsw + _i * 8192), 16, 0, 0); } while (0)
; #define G_LDA(dst, b, h) do { _Pragma("unroll") for (int m = 0; m < 4; ++m) _Pragma("unroll") for (int k = 0; k < 2; ++k) dst[m][k] = *(const LAS bf16x8*)(lds + G_SA(b, h) + aoff + m * 2048 + k * 1024); } while (0)
; #define G_LDB(dst, b, h) do { _Pragma("unroll") for (int n = 0; n < 2; ++n) _Pragma("unroll") for (int k = 0; k < 2; ++k) dst[n][k] = *(const LAS bf16x8*)(lds + G_SB(b, h) + boff + n * 2048 + k * 1024); } while (0)
; #define G_MMA(ai, bj, At_, Bt_) do { __builtin_amdgcn_s_setprio(1); _Pragma("unroll") for (int m = 0; m < 4; ++m) _Pragma("unroll") for (int n = 0; n < 2; ++n) _Pragma("unroll") for (int k = 0; k < 2; ++k) \
;         acc[ai][bj][m][n] = __builtin_amdgcn_mfma_f32_16x16x32_bf16(Bt_[n][k], At_[m][k], acc[ai][bj][m][n], 0, 0, 0); __builtin_amdgcn_s_setprio(0); } while (0)
; #define WAIT_V(n) asm volatile("s_waitcnt vmcnt(" #n ")" ::: "memory")
; template <class Get, class Epi>
; DI void gemm_loop(int ntiles, int ld, char* shm, const Get& get, const Epi& epi) {
;     ...
;         const int Ln = L + gridDim.x; const bool has_next = Ln < ntiles; if (has_next) nxt = get(Ln);
;         const char* nA = has_next ? (const char*)nxt.A + (size_t)nxt.brow * ld * 2 : cA; const char* nB = has_next ? (const char*)nxt.Bt + (size_t)nxt.bcol * ld * 2 : cB;
;         const int nt = cur.K / BK;
;         for (int t = 0; t < nt; t += 2) {
;             const bool last = (t == nt - 2);
;             const char* a1 = cA + (size_t)(t + 1) * kstep;
;             const char* a2 = last ? nA : cA + (size_t)(t + 2) * kstep; const char* b2 = last ? nB : cB + (size_t)(t + 2) * kstep;
;             const char* a3 = a2 + kstep; const char* b3 = b2 + kstep;
;             G_LDB(B0, 0, 0); G_LDB(B1, 0, 1); SCHED; G_LDA(At, 0, 0); G_STAGE(G_SA(1, 1), a1 + hstep, voffA);
;             WAIT_V(8); WAIT_L(0); BAR; G_MMA(0, 0, At, B0); G_MMA(0, 1, At, B1); BAR; SCHED;
;             G_LDA(At, 0, 1); G_STAGE(G_SB(0, 0), b2, voffB); G_STAGE(G_SB(0, 1), b2 + hstep, voffB); G_STAGE(G_SA(0, 0), a2, voffA);
;             WAIT_V(8); WAIT_L(0); BAR; G_MMA(1, 0, At, B0); G_MMA(1, 1, At, B1); BAR; SCHED;
.LBB0_3678:
	s_ashr_i32 s9, s8, 31
	s_lshl_b64 s[12:13], s[8:9], 11
	s_add_u32 s12, s16, s12
	s_addc_u32 s13, s17, s13
	s_and_b64 s[22:23], s[6:7], exec
	s_cselect_b32 s9, s13, s35
	s_cselect_b32 s49, s12, s34
	s_ashr_i32 s11, s10, 31
	s_lshl_b64 s[22:23], s[10:11], 11
	s_add_u32 s22, s90, s22
	s_addc_u32 s23, s91, s23
	s_and_b64 s[36:37], s[6:7], exec
	s_cselect_b32 s11, s23, s15
	s_cselect_b32 s50, s22, s14
	s_add_u32 s34, s34, 0x40080
	s_addc_u32 s35, s35, 0
	s_add_u32 s51, s14, 0x100
	s_addc_u32 s52, s15, 0
	s_mov_b32 s53, -2
.Lpeel_3679:
	ds_read_b128 v[144:147], v141
	ds_read_b128 v[148:151], v141 offset:1024
	ds_read_b128 v[152:155], v141 offset:2048
	ds_read_b128 v[156:159], v141 offset:3072
	ds_read_b128 v[160:163], v142
	ds_read_b128 v[164:167], v142 offset:1024
	ds_read_b128 v[168:171], v142 offset:2048
	ds_read_b128 v[172:175], v142 offset:3072
	s_add_u32 s14, s34, 0xfffc0080
	s_addc_u32 s15, s35, -1
	s_cmp_eq_u32 s53, 12
	s_cselect_b32 s37, s9, s15
	s_cselect_b32 s36, s49, s14
	s_cselect_b32 s15, s11, s52
	s_cselect_b32 s14, s50, s51
	v_lshl_add_u64 v[208:209], s[34:35], 0, v[136:137]
	s_add_i32 m0, s25, 0xc000
	ds_read_b128 v[176:179], v143
	ds_read_b128 v[180:183], v143 offset:1024
	ds_read_b128 v[184:187], v143 offset:2048
	ds_read_b128 v[188:191], v143 offset:3072
	ds_read_b128 v[192:195], v143 offset:4096
	ds_read_b128 v[196:199], v143 offset:5120
	ds_read_b128 v[200:203], v143 offset:6144
	ds_read_b128 v[204:207], v143 offset:7168
	global_load_lds_dwordx4 v[208:209], off
	v_lshl_add_u64 v[208:209], s[34:35], 0, v[138:139]
	s_add_i32 m0, s25, 0xe000
	s_nop 0
	global_load_lds_dwordx4 v[208:209], off
	s_waitcnt vmcnt(8)
	s_waitcnt lgkmcnt(0)
	s_barrier
	s_setprio 1
	s_waitcnt lgkmcnt(0)
	v_mfma_f32_16x16x32_bf16 v[124:127], v[144:147], v[176:179], 0
	v_mfma_f32_16x16x32_bf16 v[120:123], v[152:155], v[176:179], 0
	v_mfma_f32_16x16x32_bf16 v[108:111], v[144:147], v[184:187], 0
	v_mfma_f32_16x16x32_bf16 v[104:107], v[152:155], v[184:187], 0
	v_mfma_f32_16x16x32_bf16 v[92:95], v[144:147], v[192:195], 0
	v_mfma_f32_16x16x32_bf16 v[88:91], v[152:155], v[192:195], 0
	v_mfma_f32_16x16x32_bf16 v[76:79], v[144:147], v[200:203], 0
	v_mfma_f32_16x16x32_bf16 v[72:75], v[152:155], v[200:203], 0
	v_mfma_f32_16x16x32_bf16 v[124:127], v[148:151], v[180:183], v[124:127]
	v_mfma_f32_16x16x32_bf16 v[120:123], v[156:159], v[180:183], v[120:123]
	v_mfma_f32_16x16x32_bf16 v[108:111], v[148:151], v[188:191], v[108:111]
	v_mfma_f32_16x16x32_bf16 v[104:107], v[156:159], v[188:191], v[104:107]
	v_mfma_f32_16x16x32_bf16 v[92:95], v[148:151], v[196:199], v[92:95]
	v_mfma_f32_16x16x32_bf16 v[88:91], v[156:159], v[196:199], v[88:91]
	v_mfma_f32_16x16x32_bf16 v[76:79], v[148:151], v[204:207], v[76:79]
	v_mfma_f32_16x16x32_bf16 v[72:75], v[156:159], v[204:207], v[72:75]
	s_setprio 0
	s_setprio 1
	v_mfma_f32_16x16x32_bf16 v[116:119], v[160:163], v[176:179], 0
	v_mfma_f32_16x16x32_bf16 v[112:115], v[168:171], v[176:179], 0
	v_mfma_f32_16x16x32_bf16 v[100:103], v[160:163], v[184:187], 0
	v_mfma_f32_16x16x32_bf16 v[96:99], v[168:171], v[184:187], 0
	v_mfma_f32_16x16x32_bf16 v[84:87], v[160:163], v[192:195], 0
	v_mfma_f32_16x16x32_bf16 v[80:83], v[168:171], v[192:195], 0
	v_mfma_f32_16x16x32_bf16 v[68:71], v[160:163], v[200:203], 0
	v_mfma_f32_16x16x32_bf16 v[64:67], v[168:171], v[200:203], 0
	v_mfma_f32_16x16x32_bf16 v[116:119], v[164:167], v[180:183], v[116:119]
	v_mfma_f32_16x16x32_bf16 v[112:115], v[172:175], v[180:183], v[112:115]
	v_mfma_f32_16x16x32_bf16 v[100:103], v[164:167], v[188:191], v[100:103]
	v_mfma_f32_16x16x32_bf16 v[96:99], v[172:175], v[188:191], v[96:99]
	v_mfma_f32_16x16x32_bf16 v[84:87], v[164:167], v[196:199], v[84:87]
	v_mfma_f32_16x16x32_bf16 v[80:83], v[172:175], v[196:199], v[80:83]
	v_mfma_f32_16x16x32_bf16 v[68:71], v[164:167], v[204:207], v[68:71]
	v_mfma_f32_16x16x32_bf16 v[64:67], v[172:175], v[204:207], v[64:67]
	s_setprio 0
	s_barrier
	s_add_i32 s54, s44, s38
	v_lshl_add_u64 v[208:209], s[14:15], 0, v[132:133]
	s_mov_b32 m0, s54
	ds_read_b128 v[176:179], v143 offset:16384
	ds_read_b128 v[180:183], v143 offset:17408
	ds_read_b128 v[184:187], v143 offset:18432
	ds_read_b128 v[188:191], v143 offset:19456
	ds_read_b128 v[192:195], v143 offset:20480
	ds_read_b128 v[196:199], v143 offset:21504
	ds_read_b128 v[200:203], v143 offset:22528
	ds_read_b128 v[204:207], v143 offset:23552
	global_load_lds_dwordx4 v[208:209], off
	s_add_i32 m0, s54, 0x2000
	s_add_u32 s54, s14, 0x40000
	v_lshl_add_u64 v[210:211], s[14:15], 0, v[128:129]
	s_addc_u32 s55, s15, 0
	s_add_i32 s56, s45, s38
	global_load_lds_dwordx4 v[210:211], off
	v_lshl_add_u64 v[212:213], s[54:55], 0, v[132:133]
	s_mov_b32 m0, s56
	v_lshl_add_u64 v[214:215], s[36:37], 0, v[130:131]
	global_load_lds_dwordx4 v[212:213], off
	v_lshl_add_u64 v[212:213], s[54:55], 0, v[128:129]
	s_add_i32 m0, s56, 0x2000
	s_nop 0
	global_load_lds_dwordx4 v[212:213], off
	v_lshl_add_u64 v[212:213], s[36:37], 0, v[134:135]
	s_mov_b32 m0, s25
	s_nop 0
	global_load_lds_dwordx4 v[212:213], off
	s_mov_b32 m0, s31
	s_nop 0
	global_load_lds_dwordx4 v[214:215], off
	s_waitcnt vmcnt(8)
	s_waitcnt lgkmcnt(0)
	s_barrier
; #define G_STAGE(bufoff, gbase, voff) do { _Pragma("unroll") for (int _i = 0; _i < 2; ++_i) \
;         __builtin_amdgcn_global_load_lds((const unsigned*)((const char*)(gbase) + voff[_i]), (LAS unsigned*)(lds + (bufoff) + ldsw + _i * 8192), 16, 0, 0); } while (0)
; #define G_LDA(dst, b, h) do { _Pragma("unroll") for (int m = 0; m < 4; ++m) _Pragma("unroll") for (int k = 0; k < 2; ++k) dst[m][k] = *(const LAS bf16x8*)(lds + G_SA(b, h) + aoff + m * 2048 + k * 1024); } while (0)
; #define G_LDB(dst, b, h) do { _Pragma("unroll") for (int n = 0; n < 2; ++n) _Pragma("unroll") for (int k = 0; k < 2; ++k) dst[n][k] = *(const LAS bf16x8*)(lds + G_SB(b, h) + boff + n * 2048 + k * 1024); } while (0)
; #define G_MMA(ai, bj, At_, Bt_) do { __builtin_amdgcn_s_setprio(1); _Pragma("unroll") for (int m = 0; m < 4; ++m) _Pragma("unroll") for (int n = 0; n < 2; ++n) _Pragma("unroll") for (int k = 0; k < 2; ++k) \
;         acc[ai][bj][m][n] = __builtin_amdgcn_mfma_f32_16x16x32_bf16(Bt_[n][k], At_[m][k], acc[ai][bj][m][n], 0, 0, 0); __builtin_amdgcn_s_setprio(0); } while (0)
; #define WAIT_V(n) asm volatile("s_waitcnt vmcnt(" #n ")" ::: "memory")
; #define WAIT_L(n) asm volatile("s_waitcnt lgkmcnt(" #n ")" ::: "memory")
; #define BAR __builtin_amdgcn_s_barrier()
; #define SCHED __builtin_amdgcn_sched_barrier(0)
; template <class Get, class Epi>
; DI void gemm_loop(int ntiles, int ld, char* shm, const Get& get, const Epi& epi) {
;     ...
;             WAIT_V(8); WAIT_L(0); BAR; G_MMA(1, 0, At, B0); G_MMA(1, 1, At, B1); BAR; SCHED;
;             G_LDB(B0, 1, 0); G_LDB(B1, 1, 1); SCHED; G_LDA(At, 1, 0); G_STAGE(G_SA(0, 1), a2 + hstep, voffA);
;             WAIT_V(8); WAIT_L(0); BAR; G_MMA(0, 0, At, B0); G_MMA(0, 1, At, B1); BAR; SCHED;
;             G_LDA(At, 1, 1); G_STAGE(G_SB(1, 0), b3, voffB); G_STAGE(G_SB(1, 1), b3 + hstep, voffB); G_STAGE(G_SA(1, 0), a3, voffA);
	s_setprio 1
	s_waitcnt lgkmcnt(0)
	v_mfma_f32_16x16x32_bf16 v[60:63], v[144:147], v[176:179], 0
	v_mfma_f32_16x16x32_bf16 v[56:59], v[152:155], v[176:179], 0
	v_mfma_f32_16x16x32_bf16 v[44:47], v[144:147], v[184:187], 0
	v_mfma_f32_16x16x32_bf16 v[40:43], v[152:155], v[184:187], 0
	v_mfma_f32_16x16x32_bf16 v[28:31], v[144:147], v[192:195], 0
	v_mfma_f32_16x16x32_bf16 v[24:27], v[152:155], v[192:195], 0
	v_mfma_f32_16x16x32_bf16 v[12:15], v[144:147], v[200:203], 0
	v_mfma_f32_16x16x32_bf16 v[8:11], v[152:155], v[200:203], 0
	v_mfma_f32_16x16x32_bf16 v[60:63], v[148:151], v[180:183], v[60:63]
	v_mfma_f32_16x16x32_bf16 v[56:59], v[156:159], v[180:183], v[56:59]
	v_mfma_f32_16x16x32_bf16 v[44:47], v[148:151], v[188:191], v[44:47]
	v_mfma_f32_16x16x32_bf16 v[40:43], v[156:159], v[188:191], v[40:43]
	v_mfma_f32_16x16x32_bf16 v[28:31], v[148:151], v[196:199], v[28:31]
	v_mfma_f32_16x16x32_bf16 v[24:27], v[156:159], v[196:199], v[24:27]
	v_mfma_f32_16x16x32_bf16 v[12:15], v[148:151], v[204:207], v[12:15]
	v_mfma_f32_16x16x32_bf16 v[8:11], v[156:159], v[204:207], v[8:11]
	s_setprio 0
	s_setprio 1
	v_mfma_f32_16x16x32_bf16 v[52:55], v[160:163], v[176:179], 0
	v_mfma_f32_16x16x32_bf16 v[48:51], v[168:171], v[176:179], 0
	v_mfma_f32_16x16x32_bf16 v[36:39], v[160:163], v[184:187], 0
	v_mfma_f32_16x16x32_bf16 v[32:35], v[168:171], v[184:187], 0
	v_mfma_f32_16x16x32_bf16 v[20:23], v[160:163], v[192:195], 0
	v_mfma_f32_16x16x32_bf16 v[16:19], v[168:171], v[192:195], 0
	v_mfma_f32_16x16x32_bf16 v[4:7], v[160:163], v[200:203], 0
	v_mfma_f32_16x16x32_bf16 v[0:3], v[168:171], v[200:203], 0
	v_mfma_f32_16x16x32_bf16 v[52:55], v[164:167], v[180:183], v[52:55]
	v_mfma_f32_16x16x32_bf16 v[48:51], v[172:175], v[180:183], v[48:51]
	v_mfma_f32_16x16x32_bf16 v[36:39], v[164:167], v[188:191], v[36:39]
	v_mfma_f32_16x16x32_bf16 v[32:35], v[172:175], v[188:191], v[32:35]
	v_mfma_f32_16x16x32_bf16 v[20:23], v[164:167], v[196:199], v[20:23]
	v_mfma_f32_16x16x32_bf16 v[16:19], v[172:175], v[196:199], v[16:19]
	v_mfma_f32_16x16x32_bf16 v[4:7], v[164:167], v[204:207], v[4:7]
	v_mfma_f32_16x16x32_bf16 v[0:3], v[172:175], v[204:207], v[0:3]
	s_setprio 0
	s_barrier
	s_add_i32 s54, 0, 0x18000
	s_add_i32 s55, 0, 0x1c000
	v_add_u32_e32 v156, s54, v140
	v_add_u32_e32 v172, s55, v140
	ds_read_b128 v[144:147], v156
	ds_read_b128 v[148:151], v156 offset:1024
	ds_read_b128 v[152:155], v156 offset:2048
	ds_read_b128 v[156:159], v156 offset:3072
	ds_read_b128 v[160:163], v172
	ds_read_b128 v[164:167], v172 offset:1024
	ds_read_b128 v[168:171], v172 offset:2048
	ds_read_b128 v[172:175], v172 offset:3072
	s_add_u32 s36, s36, 0x40000
	s_addc_u32 s37, s37, 0
	s_mov_b32 m0, s40
	v_lshl_add_u64 v[216:217], s[36:37], 0, v[134:135]
	ds_read_b128 v[176:179], v143 offset:32768
	ds_read_b128 v[180:183], v143 offset:33792
	ds_read_b128 v[184:187], v143 offset:34816
	ds_read_b128 v[188:191], v143 offset:35840
	ds_read_b128 v[192:195], v143 offset:36864
	ds_read_b128 v[196:199], v143 offset:37888
	ds_read_b128 v[200:203], v143 offset:38912
	ds_read_b128 v[204:207], v143 offset:39936
	global_load_lds_dwordx4 v[216:217], off
	v_lshl_add_u64 v[216:217], s[36:37], 0, v[130:131]
	s_mov_b32 m0, s41
	s_nop 0
	global_load_lds_dwordx4 v[216:217], off
	s_waitcnt vmcnt(8)
	s_waitcnt lgkmcnt(0)
	s_barrier
	s_setprio 1
	s_waitcnt lgkmcnt(0)
	v_mfma_f32_16x16x32_bf16 v[124:127], v[144:147], v[176:179], v[124:127]
	v_mfma_f32_16x16x32_bf16 v[120:123], v[152:155], v[176:179], v[120:123]
	v_mfma_f32_16x16x32_bf16 v[108:111], v[144:147], v[184:187], v[108:111]
	v_mfma_f32_16x16x32_bf16 v[104:107], v[152:155], v[184:187], v[104:107]
	v_mfma_f32_16x16x32_bf16 v[92:95], v[144:147], v[192:195], v[92:95]
	v_mfma_f32_16x16x32_bf16 v[88:91], v[152:155], v[192:195], v[88:91]
	v_mfma_f32_16x16x32_bf16 v[76:79], v[144:147], v[200:203], v[76:79]
	v_mfma_f32_16x16x32_bf16 v[72:75], v[152:155], v[200:203], v[72:75]
	v_mfma_f32_16x16x32_bf16 v[124:127], v[148:151], v[180:183], v[124:127]
	v_mfma_f32_16x16x32_bf16 v[120:123], v[156:159], v[180:183], v[120:123]
	v_mfma_f32_16x16x32_bf16 v[108:111], v[148:151], v[188:191], v[108:111]
	v_mfma_f32_16x16x32_bf16 v[104:107], v[156:159], v[188:191], v[104:107]
	v_mfma_f32_16x16x32_bf16 v[92:95], v[148:151], v[196:199], v[92:95]
	v_mfma_f32_16x16x32_bf16 v[88:91], v[156:159], v[196:199], v[88:91]
	v_mfma_f32_16x16x32_bf16 v[76:79], v[148:151], v[204:207], v[76:79]
	v_mfma_f32_16x16x32_bf16 v[72:75], v[156:159], v[204:207], v[72:75]
	s_setprio 0
	s_setprio 1
	v_mfma_f32_16x16x32_bf16 v[116:119], v[160:163], v[176:179], v[116:119]
	v_mfma_f32_16x16x32_bf16 v[112:115], v[168:171], v[176:179], v[112:115]
	v_mfma_f32_16x16x32_bf16 v[100:103], v[160:163], v[184:187], v[100:103]
	v_mfma_f32_16x16x32_bf16 v[96:99], v[168:171], v[184:187], v[96:99]
	v_mfma_f32_16x16x32_bf16 v[84:87], v[160:163], v[192:195], v[84:87]
	v_mfma_f32_16x16x32_bf16 v[80:83], v[168:171], v[192:195], v[80:83]
	v_mfma_f32_16x16x32_bf16 v[68:71], v[160:163], v[200:203], v[68:71]
	v_mfma_f32_16x16x32_bf16 v[64:67], v[168:171], v[200:203], v[64:67]
	v_mfma_f32_16x16x32_bf16 v[116:119], v[164:167], v[180:183], v[116:119]
	v_mfma_f32_16x16x32_bf16 v[112:115], v[172:175], v[180:183], v[112:115]
	v_mfma_f32_16x16x32_bf16 v[100:103], v[164:167], v[188:191], v[100:103]
	v_mfma_f32_16x16x32_bf16 v[96:99], v[172:175], v[188:191], v[96:99]
	v_mfma_f32_16x16x32_bf16 v[84:87], v[164:167], v[196:199], v[84:87]
	v_mfma_f32_16x16x32_bf16 v[80:83], v[172:175], v[196:199], v[80:83]
	v_mfma_f32_16x16x32_bf16 v[68:71], v[164:167], v[204:207], v[68:71]
	v_mfma_f32_16x16x32_bf16 v[64:67], v[172:175], v[204:207], v[64:67]
	s_setprio 0
	s_barrier
; #define G_STAGE(bufoff, gbase, voff) do { _Pragma("unroll") for (int _i = 0; _i < 2; ++_i) \
;         __builtin_amdgcn_global_load_lds((const unsigned*)((const char*)(gbase) + voff[_i]), (LAS unsigned*)(lds + (bufoff) + ldsw + _i * 8192), 16, 0, 0); } while (0)
; #define G_LDA(dst, b, h) do { _Pragma("unroll") for (int m = 0; m < 4; ++m) _Pragma("unroll") for (int k = 0; k < 2; ++k) dst[m][k] = *(const LAS bf16x8*)(lds + G_SA(b, h) + aoff + m * 2048 + k * 1024); } while (0)
; #define G_MMA(ai, bj, At_, Bt_) do { __builtin_amdgcn_s_setprio(1); _Pragma("unroll") for (int m = 0; m < 4; ++m) _Pragma("unroll") for (int n = 0; n < 2; ++n) _Pragma("unroll") for (int k = 0; k < 2; ++k) \
;         acc[ai][bj][m][n] = __builtin_amdgcn_mfma_f32_16x16x32_bf16(Bt_[n][k], At_[m][k], acc[ai][bj][m][n], 0, 0, 0); __builtin_amdgcn_s_setprio(0); } while (0)
; #define WAIT_V(n) asm volatile("s_waitcnt vmcnt(" #n ")" ::: "memory")
; #define WAIT_L(n) asm volatile("s_waitcnt lgkmcnt(" #n ")" ::: "memory")
; #define BAR __builtin_amdgcn_s_barrier()
; #define SCHED __builtin_amdgcn_sched_barrier(0)
; template <class Get, class Epi>
; DI void gemm_loop(int ntiles, int ld, char* shm, const Get& get, const Epi& epi) {
;     ...
;             G_LDA(At, 1, 1); G_STAGE(G_SB(1, 0), b3, voffB); G_STAGE(G_SB(1, 1), b3 + hstep, voffB); G_STAGE(G_SA(1, 0), a3, voffA);
;             WAIT_V(8); WAIT_L(0); BAR; G_MMA(1, 0, At, B0); G_MMA(1, 1, At, B1); BAR; SCHED;
;         }
	s_add_i32 s36, s54, s38
	v_lshl_add_u64 v[208:209], v[208:209], 0, s[2:3]
	s_mov_b32 m0, s36
	ds_read_b128 v[176:179], v143 offset:49152
	ds_read_b128 v[180:183], v143 offset:50176
	ds_read_b128 v[184:187], v143 offset:51200
	ds_read_b128 v[188:191], v143 offset:52224
	ds_read_b128 v[192:195], v143 offset:53248
	ds_read_b128 v[196:199], v143 offset:54272
	ds_read_b128 v[200:203], v143 offset:55296
	ds_read_b128 v[204:207], v143 offset:56320
	global_load_lds_dwordx4 v[208:209], off
	s_add_i32 m0, s36, 0x2000
	s_add_u32 s14, s14, 0x40080
	v_lshl_add_u64 v[208:209], v[210:211], 0, s[2:3]
	s_addc_u32 s15, s15, 0
	s_add_i32 s36, s55, s38
	global_load_lds_dwordx4 v[208:209], off
	v_lshl_add_u64 v[208:209], s[14:15], 0, v[132:133]
	s_mov_b32 m0, s36
	s_nop 0
	global_load_lds_dwordx4 v[208:209], off
	v_lshl_add_u64 v[208:209], s[14:15], 0, v[128:129]
	s_add_i32 m0, s36, 0x2000
	s_nop 0
	global_load_lds_dwordx4 v[208:209], off
	v_lshl_add_u64 v[208:209], v[212:213], 0, s[2:3]
	s_mov_b32 m0, s42
	s_nop 0
	global_load_lds_dwordx4 v[208:209], off
	v_lshl_add_u64 v[208:209], v[214:215], 0, s[2:3]
	s_mov_b32 m0, s43
	s_nop 0
	global_load_lds_dwordx4 v[208:209], off
	s_waitcnt vmcnt(8)
	s_waitcnt lgkmcnt(0)
	s_barrier
	s_setprio 1
	s_waitcnt lgkmcnt(0)
	v_mfma_f32_16x16x32_bf16 v[60:63], v[144:147], v[176:179], v[60:63]
	v_mfma_f32_16x16x32_bf16 v[56:59], v[152:155], v[176:179], v[56:59]
	v_mfma_f32_16x16x32_bf16 v[44:47], v[144:147], v[184:187], v[44:47]
	v_mfma_f32_16x16x32_bf16 v[40:43], v[152:155], v[184:187], v[40:43]
	v_mfma_f32_16x16x32_bf16 v[28:31], v[144:147], v[192:195], v[28:31]
	v_mfma_f32_16x16x32_bf16 v[24:27], v[152:155], v[192:195], v[24:27]
	v_mfma_f32_16x16x32_bf16 v[12:15], v[144:147], v[200:203], v[12:15]
	v_mfma_f32_16x16x32_bf16 v[8:11], v[152:155], v[200:203], v[8:11]
	v_mfma_f32_16x16x32_bf16 v[60:63], v[148:151], v[180:183], v[60:63]
	v_mfma_f32_16x16x32_bf16 v[56:59], v[156:159], v[180:183], v[56:59]
	v_mfma_f32_16x16x32_bf16 v[44:47], v[148:151], v[188:191], v[44:47]
	v_mfma_f32_16x16x32_bf16 v[40:43], v[156:159], v[188:191], v[40:43]
	v_mfma_f32_16x16x32_bf16 v[28:31], v[148:151], v[196:199], v[28:31]
	v_mfma_f32_16x16x32_bf16 v[24:27], v[156:159], v[196:199], v[24:27]
	v_mfma_f32_16x16x32_bf16 v[12:15], v[148:151], v[204:207], v[12:15]
	v_mfma_f32_16x16x32_bf16 v[8:11], v[156:159], v[204:207], v[8:11]
	s_setprio 0
	s_setprio 1
	v_mfma_f32_16x16x32_bf16 v[52:55], v[160:163], v[176:179], v[52:55]
	v_mfma_f32_16x16x32_bf16 v[48:51], v[168:171], v[176:179], v[48:51]
	v_mfma_f32_16x16x32_bf16 v[36:39], v[160:163], v[184:187], v[36:39]
	v_mfma_f32_16x16x32_bf16 v[32:35], v[168:171], v[184:187], v[32:35]
	v_mfma_f32_16x16x32_bf16 v[20:23], v[160:163], v[192:195], v[20:23]
	v_mfma_f32_16x16x32_bf16 v[16:19], v[168:171], v[192:195], v[16:19]
	v_mfma_f32_16x16x32_bf16 v[4:7], v[160:163], v[200:203], v[4:7]
	v_mfma_f32_16x16x32_bf16 v[0:3], v[168:171], v[200:203], v[0:3]
	v_mfma_f32_16x16x32_bf16 v[52:55], v[164:167], v[180:183], v[52:55]
	v_mfma_f32_16x16x32_bf16 v[48:51], v[172:175], v[180:183], v[48:51]
	v_mfma_f32_16x16x32_bf16 v[36:39], v[164:167], v[188:191], v[36:39]
	v_mfma_f32_16x16x32_bf16 v[32:35], v[172:175], v[188:191], v[32:35]
	v_mfma_f32_16x16x32_bf16 v[20:23], v[164:167], v[196:199], v[20:23]
	v_mfma_f32_16x16x32_bf16 v[16:19], v[172:175], v[196:199], v[16:19]
	v_mfma_f32_16x16x32_bf16 v[4:7], v[164:167], v[204:207], v[4:7]
	v_mfma_f32_16x16x32_bf16 v[0:3], v[172:175], v[204:207], v[0:3]
	s_setprio 0
	s_barrier
	s_add_i32 s53, s53, 2
	s_add_u32 s34, s34, 0x100
	s_addc_u32 s35, s35, 0
	s_add_u32 s51, s51, 0x100
	s_addc_u32 s52, s52, 0
	s_cmp_gt_u32 s53, 13
	s_cbranch_scc0 .LBB0_3679
	s_branch .Lpost_3679

; #define G_STAGE(bufoff, gbase, voff) do { _Pragma("unroll") for (int _i = 0; _i < 2; ++_i) \
;         __builtin_amdgcn_global_load_lds((const unsigned*)((const char*)(gbase) + voff[_i]), (LAS unsigned*)(lds + (bufoff) + ldsw + _i * 8192), 16, 0, 0); } while (0)
; #define G_LDA(dst, b, h) do { _Pragma("unroll") for (int m = 0; m < 4; ++m) _Pragma("unroll") for (int k = 0; k < 2; ++k) dst[m][k] = *(const LAS bf16x8*)(lds + G_SA(b, h) + aoff + m * 2048 + k * 1024); } while (0)
; #define G_LDB(dst, b, h) do { _Pragma("unroll") for (int n = 0; n < 2; ++n) _Pragma("unroll") for (int k = 0; k < 2; ++k) dst[n][k] = *(const LAS bf16x8*)(lds + G_SB(b, h) + boff + n * 2048 + k * 1024); } while (0)
; #define G_MMA(ai, bj, At_, Bt_) do { __builtin_amdgcn_s_setprio(1); _Pragma("unroll") for (int m = 0; m < 4; ++m) _Pragma("unroll") for (int n = 0; n < 2; ++n) _Pragma("unroll") for (int k = 0; k < 2; ++k) \
;         acc[ai][bj][m][n] = __builtin_amdgcn_mfma_f32_16x16x32_bf16(Bt_[n][k], At_[m][k], acc[ai][bj][m][n], 0, 0, 0); __builtin_amdgcn_s_setprio(0); } while (0)
; #define WAIT_V(n) asm volatile("s_waitcnt vmcnt(" #n ")" ::: "memory")
; #define WAIT_L(n) asm volatile("s_waitcnt lgkmcnt(" #n ")" ::: "memory")
; #define BAR __builtin_amdgcn_s_barrier()
; #define SCHED __builtin_amdgcn_sched_barrier(0)
; template <class Get, class Epi>
; DI void gemm_loop(int ntiles, int ld, char* shm, const Get& get, const Epi& epi) {
;     ...
;         const int nt = cur.K / BK;
;         for (int t = 0; t < nt; t += 2) {
;             const bool last = (t == nt - 2);
;             const char* a1 = cA + (size_t)(t + 1) * kstep;
;             const char* a2 = last ? nA : cA + (size_t)(t + 2) * kstep; const char* b2 = last ? nB : cB + (size_t)(t + 2) * kstep;
;             const char* a3 = a2 + kstep; const char* b3 = b2 + kstep;
;             G_LDB(B0, 0, 0); G_LDB(B1, 0, 1); SCHED; G_LDA(At, 0, 0); G_STAGE(G_SA(1, 1), a1 + hstep, voffA);
;             WAIT_V(8); WAIT_L(0); BAR; G_MMA(0, 0, At, B0); G_MMA(0, 1, At, B1); BAR; SCHED;
;             G_LDA(At, 0, 1); G_STAGE(G_SB(0, 0), b2, voffB); G_STAGE(G_SB(0, 1), b2 + hstep, voffB); G_STAGE(G_SA(0, 0), a2, voffA);
;             WAIT_V(8); WAIT_L(0); BAR; G_MMA(1, 0, At, B0); G_MMA(1, 1, At, B1); BAR; SCHED;
.LBB0_3758:
	s_add_u32 s52, s24, 0x100
	s_addc_u32 s53, s25, 0
	s_mov_b32 s54, -2
.Lpeel_3759:
	ds_read_b128 v[128:131], v169
	ds_read_b128 v[132:135], v169 offset:1024
	ds_read_b128 v[136:139], v169 offset:2048
	ds_read_b128 v[140:143], v169 offset:3072
	ds_read_b128 v[158:161], v170
	ds_read_b128 v[162:165], v170 offset:1024
	ds_read_b128 v[172:175], v170 offset:2048
	ds_read_b128 v[176:179], v170 offset:3072
	s_add_u32 s24, s2, 0x100
	s_addc_u32 s25, s3, 0
	s_cmp_eq_u32 s54, 40
	s_cselect_b32 s35, s21, s25
	s_cselect_b32 s34, s20, s24
	s_cselect_b32 s31, s23, s53
	s_cselect_b32 s30, s22, s52
	v_lshl_add_u64 v[144:145], s[2:3], 0, v[154:155]
	s_add_i32 m0, s36, 0xc000
	ds_read_b128 v[180:183], v171
	ds_read_b128 v[184:187], v171 offset:1024
	ds_read_b128 v[188:191], v171 offset:2048
	ds_read_b128 v[192:195], v171 offset:3072
	ds_read_b128 v[196:199], v171 offset:4096
	ds_read_b128 v[200:203], v171 offset:5120
	ds_read_b128 v[204:207], v171 offset:6144
	ds_read_b128 v[208:211], v171 offset:7168
	global_load_lds_dwordx4 v[144:145], off
	v_lshl_add_u64 v[144:145], s[2:3], 0, v[156:157]
	s_add_i32 m0, s36, 0xe000
	s_nop 0
	global_load_lds_dwordx4 v[144:145], off
	s_waitcnt vmcnt(8)
	s_waitcnt lgkmcnt(0)
	s_barrier
	s_setprio 1
	s_waitcnt lgkmcnt(0)
	v_mfma_f32_16x16x32_bf16 v[124:127], v[128:131], v[180:183], 0
	v_mfma_f32_16x16x32_bf16 v[120:123], v[136:139], v[180:183], 0
	v_mfma_f32_16x16x32_bf16 v[116:119], v[128:131], v[188:191], 0
	v_mfma_f32_16x16x32_bf16 v[112:115], v[136:139], v[188:191], 0
	v_mfma_f32_16x16x32_bf16 v[108:111], v[128:131], v[196:199], 0
	v_mfma_f32_16x16x32_bf16 v[104:107], v[136:139], v[196:199], 0
	v_mfma_f32_16x16x32_bf16 v[100:103], v[128:131], v[204:207], 0
	v_mfma_f32_16x16x32_bf16 v[96:99], v[136:139], v[204:207], 0
	v_mfma_f32_16x16x32_bf16 v[124:127], v[132:135], v[184:187], v[124:127]
	v_mfma_f32_16x16x32_bf16 v[120:123], v[140:143], v[184:187], v[120:123]
	v_mfma_f32_16x16x32_bf16 v[116:119], v[132:135], v[192:195], v[116:119]
	v_mfma_f32_16x16x32_bf16 v[112:115], v[140:143], v[192:195], v[112:115]
	v_mfma_f32_16x16x32_bf16 v[108:111], v[132:135], v[200:203], v[108:111]
	v_mfma_f32_16x16x32_bf16 v[104:107], v[140:143], v[200:203], v[104:107]
	v_mfma_f32_16x16x32_bf16 v[100:103], v[132:135], v[208:211], v[100:103]
	v_mfma_f32_16x16x32_bf16 v[96:99], v[140:143], v[208:211], v[96:99]
	s_setprio 0
	s_setprio 1
	v_mfma_f32_16x16x32_bf16 v[60:63], v[158:161], v[180:183], 0
	v_mfma_f32_16x16x32_bf16 v[56:59], v[172:175], v[180:183], 0
	v_mfma_f32_16x16x32_bf16 v[52:55], v[158:161], v[188:191], 0
	v_mfma_f32_16x16x32_bf16 v[48:51], v[172:175], v[188:191], 0
	v_mfma_f32_16x16x32_bf16 v[44:47], v[158:161], v[196:199], 0
	v_mfma_f32_16x16x32_bf16 v[40:43], v[172:175], v[196:199], 0
	v_mfma_f32_16x16x32_bf16 v[36:39], v[158:161], v[204:207], 0
	v_mfma_f32_16x16x32_bf16 v[32:35], v[172:175], v[204:207], 0
	v_mfma_f32_16x16x32_bf16 v[60:63], v[162:165], v[184:187], v[60:63]
	v_mfma_f32_16x16x32_bf16 v[56:59], v[176:179], v[184:187], v[56:59]
	v_mfma_f32_16x16x32_bf16 v[52:55], v[162:165], v[192:195], v[52:55]
	v_mfma_f32_16x16x32_bf16 v[48:51], v[176:179], v[192:195], v[48:51]
	v_mfma_f32_16x16x32_bf16 v[44:47], v[162:165], v[200:203], v[44:47]
	v_mfma_f32_16x16x32_bf16 v[40:43], v[176:179], v[200:203], v[40:43]
	v_mfma_f32_16x16x32_bf16 v[36:39], v[162:165], v[208:211], v[36:39]
	v_mfma_f32_16x16x32_bf16 v[32:35], v[176:179], v[208:211], v[32:35]
	s_setprio 0
	s_barrier
	s_add_i32 s2, s44, s33
	v_lshl_add_u64 v[144:145], s[30:31], 0, v[148:149]
	s_mov_b32 m0, s2
	ds_read_b128 v[180:183], v171 offset:16384
	ds_read_b128 v[184:187], v171 offset:17408
	ds_read_b128 v[188:191], v171 offset:18432
	ds_read_b128 v[192:195], v171 offset:19456
	ds_read_b128 v[196:199], v171 offset:20480
	ds_read_b128 v[200:203], v171 offset:21504
	ds_read_b128 v[204:207], v171 offset:22528
	ds_read_b128 v[208:211], v171 offset:23552
	global_load_lds_dwordx4 v[144:145], off
	s_add_i32 m0, s2, 0x2000
	s_add_u32 s2, s30, 0xb0000
	v_lshl_add_u64 v[166:167], s[30:31], 0, v[152:153]
	s_addc_u32 s3, s31, 0
	s_add_i32 s55, s45, s33
	global_load_lds_dwordx4 v[166:167], off
	v_lshl_add_u64 v[212:213], s[2:3], 0, v[148:149]
	s_mov_b32 m0, s55
	v_lshl_add_u64 v[214:215], s[34:35], 0, v[150:151]
	global_load_lds_dwordx4 v[212:213], off
	v_lshl_add_u64 v[212:213], s[2:3], 0, v[152:153]
	s_add_i32 m0, s55, 0x2000
	s_nop 0
	global_load_lds_dwordx4 v[212:213], off
	v_lshl_add_u64 v[212:213], s[34:35], 0, v[146:147]
	s_mov_b32 m0, s36
	s_nop 0
	global_load_lds_dwordx4 v[212:213], off
	s_mov_b32 m0, s37
	s_nop 0
	global_load_lds_dwordx4 v[214:215], off
	s_waitcnt vmcnt(8)
	s_waitcnt lgkmcnt(0)
	s_barrier
; #define G_STAGE(bufoff, gbase, voff) do { _Pragma("unroll") for (int _i = 0; _i < 2; ++_i) \
;         __builtin_amdgcn_global_load_lds((const unsigned*)((const char*)(gbase) + voff[_i]), (LAS unsigned*)(lds + (bufoff) + ldsw + _i * 8192), 16, 0, 0); } while (0)
; #define G_LDA(dst, b, h) do { _Pragma("unroll") for (int m = 0; m < 4; ++m) _Pragma("unroll") for (int k = 0; k < 2; ++k) dst[m][k] = *(const LAS bf16x8*)(lds + G_SA(b, h) + aoff + m * 2048 + k * 1024); } while (0)
; #define G_LDB(dst, b, h) do { _Pragma("unroll") for (int n = 0; n < 2; ++n) _Pragma("unroll") for (int k = 0; k < 2; ++k) dst[n][k] = *(const LAS bf16x8*)(lds + G_SB(b, h) + boff + n * 2048 + k * 1024); } while (0)
; #define G_MMA(ai, bj, At_, Bt_) do { __builtin_amdgcn_s_setprio(1); _Pragma("unroll") for (int m = 0; m < 4; ++m) _Pragma("unroll") for (int n = 0; n < 2; ++n) _Pragma("unroll") for (int k = 0; k < 2; ++k) \
;         acc[ai][bj][m][n] = __builtin_amdgcn_mfma_f32_16x16x32_bf16(Bt_[n][k], At_[m][k], acc[ai][bj][m][n], 0, 0, 0); __builtin_amdgcn_s_setprio(0); } while (0)
; #define WAIT_V(n) asm volatile("s_waitcnt vmcnt(" #n ")" ::: "memory")
; #define WAIT_L(n) asm volatile("s_waitcnt lgkmcnt(" #n ")" ::: "memory")
; #define BAR __builtin_amdgcn_s_barrier()
; #define SCHED __builtin_amdgcn_sched_barrier(0)
; template <class Get, class Epi>
; DI void gemm_loop(int ntiles, int ld, char* shm, const Get& get, const Epi& epi) {
;     ...
;             WAIT_V(8); WAIT_L(0); BAR; G_MMA(1, 0, At, B0); G_MMA(1, 1, At, B1); BAR; SCHED;
;             G_LDB(B0, 1, 0); G_LDB(B1, 1, 1); SCHED; G_LDA(At, 1, 0); G_STAGE(G_SA(0, 1), a2 + hstep, voffA);
;             WAIT_V(8); WAIT_L(0); BAR; G_MMA(0, 0, At, B0); G_MMA(0, 1, At, B1); BAR; SCHED;
;             G_LDA(At, 1, 1); G_STAGE(G_SB(1, 0), b3, voffB); G_STAGE(G_SB(1, 1), b3 + hstep, voffB); G_STAGE(G_SA(1, 0), a3, voffA);
	s_setprio 1
	s_waitcnt lgkmcnt(0)
	v_mfma_f32_16x16x32_bf16 v[92:95], v[128:131], v[180:183], 0
	v_mfma_f32_16x16x32_bf16 v[88:91], v[136:139], v[180:183], 0
	v_mfma_f32_16x16x32_bf16 v[84:87], v[128:131], v[188:191], 0
	v_mfma_f32_16x16x32_bf16 v[80:83], v[136:139], v[188:191], 0
	v_mfma_f32_16x16x32_bf16 v[76:79], v[128:131], v[196:199], 0
	v_mfma_f32_16x16x32_bf16 v[72:75], v[136:139], v[196:199], 0
	v_mfma_f32_16x16x32_bf16 v[68:71], v[128:131], v[204:207], 0
	v_mfma_f32_16x16x32_bf16 v[64:67], v[136:139], v[204:207], 0
	v_mfma_f32_16x16x32_bf16 v[92:95], v[132:135], v[184:187], v[92:95]
	v_mfma_f32_16x16x32_bf16 v[88:91], v[140:143], v[184:187], v[88:91]
	v_mfma_f32_16x16x32_bf16 v[84:87], v[132:135], v[192:195], v[84:87]
	v_mfma_f32_16x16x32_bf16 v[80:83], v[140:143], v[192:195], v[80:83]
	v_mfma_f32_16x16x32_bf16 v[76:79], v[132:135], v[200:203], v[76:79]
	v_mfma_f32_16x16x32_bf16 v[72:75], v[140:143], v[200:203], v[72:75]
	v_mfma_f32_16x16x32_bf16 v[68:71], v[132:135], v[208:211], v[68:71]
	v_mfma_f32_16x16x32_bf16 v[64:67], v[140:143], v[208:211], v[64:67]
	s_setprio 0
	s_setprio 1
	v_mfma_f32_16x16x32_bf16 v[28:31], v[158:161], v[180:183], 0
	v_mfma_f32_16x16x32_bf16 v[24:27], v[172:175], v[180:183], 0
	v_mfma_f32_16x16x32_bf16 v[20:23], v[158:161], v[188:191], 0
	v_mfma_f32_16x16x32_bf16 v[16:19], v[172:175], v[188:191], 0
	v_mfma_f32_16x16x32_bf16 v[12:15], v[158:161], v[196:199], 0
	v_mfma_f32_16x16x32_bf16 v[8:11], v[172:175], v[196:199], 0
	v_mfma_f32_16x16x32_bf16 v[4:7], v[158:161], v[204:207], 0
	v_mfma_f32_16x16x32_bf16 v[0:3], v[172:175], v[204:207], 0
	v_mfma_f32_16x16x32_bf16 v[28:31], v[162:165], v[184:187], v[28:31]
	v_mfma_f32_16x16x32_bf16 v[24:27], v[176:179], v[184:187], v[24:27]
	v_mfma_f32_16x16x32_bf16 v[20:23], v[162:165], v[192:195], v[20:23]
	v_mfma_f32_16x16x32_bf16 v[16:19], v[176:179], v[192:195], v[16:19]
	v_mfma_f32_16x16x32_bf16 v[12:15], v[162:165], v[200:203], v[12:15]
	v_mfma_f32_16x16x32_bf16 v[8:11], v[176:179], v[200:203], v[8:11]
	v_mfma_f32_16x16x32_bf16 v[4:7], v[162:165], v[208:211], v[4:7]
	v_mfma_f32_16x16x32_bf16 v[0:3], v[176:179], v[208:211], v[0:3]
	s_setprio 0
	s_barrier
	s_add_i32 s55, 0, 0x18000
	s_add_i32 s56, 0, 0x1c000
	v_add_u32_e32 v140, s55, v168
	v_add_u32_e32 v176, s56, v168
	ds_read_b128 v[128:131], v140
	ds_read_b128 v[132:135], v140 offset:1024
	ds_read_b128 v[136:139], v140 offset:2048
	ds_read_b128 v[140:143], v140 offset:3072
	ds_read_b128 v[158:161], v176
	ds_read_b128 v[162:165], v176 offset:1024
	ds_read_b128 v[172:175], v176 offset:2048
	ds_read_b128 v[176:179], v176 offset:3072
	s_add_u32 s2, s34, 0xb0000
	s_addc_u32 s3, s35, 0
	s_mov_b32 m0, s38
	v_lshl_add_u64 v[216:217], s[2:3], 0, v[146:147]
	ds_read_b128 v[180:183], v171 offset:32768
	ds_read_b128 v[184:187], v171 offset:33792
	ds_read_b128 v[188:191], v171 offset:34816
	ds_read_b128 v[192:195], v171 offset:35840
	ds_read_b128 v[196:199], v171 offset:36864
	ds_read_b128 v[200:203], v171 offset:37888
	ds_read_b128 v[204:207], v171 offset:38912
	ds_read_b128 v[208:211], v171 offset:39936
	global_load_lds_dwordx4 v[216:217], off
	v_lshl_add_u64 v[216:217], s[2:3], 0, v[150:151]
	s_mov_b32 m0, s39
	s_nop 0
	global_load_lds_dwordx4 v[216:217], off
	s_waitcnt vmcnt(8)
	s_waitcnt lgkmcnt(0)
	s_barrier
	s_setprio 1
	s_waitcnt lgkmcnt(0)
	v_mfma_f32_16x16x32_bf16 v[124:127], v[128:131], v[180:183], v[124:127]
	v_mfma_f32_16x16x32_bf16 v[120:123], v[136:139], v[180:183], v[120:123]
	v_mfma_f32_16x16x32_bf16 v[116:119], v[128:131], v[188:191], v[116:119]
	v_mfma_f32_16x16x32_bf16 v[112:115], v[136:139], v[188:191], v[112:115]
	v_mfma_f32_16x16x32_bf16 v[108:111], v[128:131], v[196:199], v[108:111]
	v_mfma_f32_16x16x32_bf16 v[104:107], v[136:139], v[196:199], v[104:107]
	v_mfma_f32_16x16x32_bf16 v[100:103], v[128:131], v[204:207], v[100:103]
	v_mfma_f32_16x16x32_bf16 v[96:99], v[136:139], v[204:207], v[96:99]
	v_mfma_f32_16x16x32_bf16 v[124:127], v[132:135], v[184:187], v[124:127]
	v_mfma_f32_16x16x32_bf16 v[120:123], v[140:143], v[184:187], v[120:123]
	v_mfma_f32_16x16x32_bf16 v[116:119], v[132:135], v[192:195], v[116:119]
	v_mfma_f32_16x16x32_bf16 v[112:115], v[140:143], v[192:195], v[112:115]
	v_mfma_f32_16x16x32_bf16 v[108:111], v[132:135], v[200:203], v[108:111]
	v_mfma_f32_16x16x32_bf16 v[104:107], v[140:143], v[200:203], v[104:107]
	v_mfma_f32_16x16x32_bf16 v[100:103], v[132:135], v[208:211], v[100:103]
	v_mfma_f32_16x16x32_bf16 v[96:99], v[140:143], v[208:211], v[96:99]
	s_setprio 0
	s_setprio 1
	v_mfma_f32_16x16x32_bf16 v[60:63], v[158:161], v[180:183], v[60:63]
	v_mfma_f32_16x16x32_bf16 v[56:59], v[172:175], v[180:183], v[56:59]
	v_mfma_f32_16x16x32_bf16 v[52:55], v[158:161], v[188:191], v[52:55]
	v_mfma_f32_16x16x32_bf16 v[48:51], v[172:175], v[188:191], v[48:51]
	v_mfma_f32_16x16x32_bf16 v[44:47], v[158:161], v[196:199], v[44:47]
	v_mfma_f32_16x16x32_bf16 v[40:43], v[172:175], v[196:199], v[40:43]
	v_mfma_f32_16x16x32_bf16 v[36:39], v[158:161], v[204:207], v[36:39]
	v_mfma_f32_16x16x32_bf16 v[32:35], v[172:175], v[204:207], v[32:35]
	v_mfma_f32_16x16x32_bf16 v[60:63], v[162:165], v[184:187], v[60:63]
	v_mfma_f32_16x16x32_bf16 v[56:59], v[176:179], v[184:187], v[56:59]
	v_mfma_f32_16x16x32_bf16 v[52:55], v[162:165], v[192:195], v[52:55]
	v_mfma_f32_16x16x32_bf16 v[48:51], v[176:179], v[192:195], v[48:51]
	v_mfma_f32_16x16x32_bf16 v[44:47], v[162:165], v[200:203], v[44:47]
	v_mfma_f32_16x16x32_bf16 v[40:43], v[176:179], v[200:203], v[40:43]
	v_mfma_f32_16x16x32_bf16 v[36:39], v[162:165], v[208:211], v[36:39]
	v_mfma_f32_16x16x32_bf16 v[32:35], v[176:179], v[208:211], v[32:35]
	s_setprio 0
	s_barrier
; #define G_STAGE(bufoff, gbase, voff) do { _Pragma("unroll") for (int _i = 0; _i < 2; ++_i) \
;         __builtin_amdgcn_global_load_lds((const unsigned*)((const char*)(gbase) + voff[_i]), (LAS unsigned*)(lds + (bufoff) + ldsw + _i * 8192), 16, 0, 0); } while (0)
; #define G_LDA(dst, b, h) do { _Pragma("unroll") for (int m = 0; m < 4; ++m) _Pragma("unroll") for (int k = 0; k < 2; ++k) dst[m][k] = *(const LAS bf16x8*)(lds + G_SA(b, h) + aoff + m * 2048 + k * 1024); } while (0)
; #define G_MMA(ai, bj, At_, Bt_) do { __builtin_amdgcn_s_setprio(1); _Pragma("unroll") for (int m = 0; m < 4; ++m) _Pragma("unroll") for (int n = 0; n < 2; ++n) _Pragma("unroll") for (int k = 0; k < 2; ++k) \
;         acc[ai][bj][m][n] = __builtin_amdgcn_mfma_f32_16x16x32_bf16(Bt_[n][k], At_[m][k], acc[ai][bj][m][n], 0, 0, 0); __builtin_amdgcn_s_setprio(0); } while (0)
; #define WAIT_V(n) asm volatile("s_waitcnt vmcnt(" #n ")" ::: "memory")
; #define WAIT_L(n) asm volatile("s_waitcnt lgkmcnt(" #n ")" ::: "memory")
; #define BAR __builtin_amdgcn_s_barrier()
; #define SCHED __builtin_amdgcn_sched_barrier(0)
; template <class Get, class Epi>
; DI void gemm_loop(int ntiles, int ld, char* shm, const Get& get, const Epi& epi) {
;     ...
;             G_LDA(At, 1, 1); G_STAGE(G_SB(1, 0), b3, voffB); G_STAGE(G_SB(1, 1), b3 + hstep, voffB); G_STAGE(G_SA(1, 0), a3, voffA);
;             WAIT_V(8); WAIT_L(0); BAR; G_MMA(1, 0, At, B0); G_MMA(1, 1, At, B1); BAR; SCHED;
;         }
	s_add_i32 s2, s55, s33
	v_lshl_add_u64 v[144:145], v[144:145], 0, s[6:7]
	s_mov_b32 m0, s2
	ds_read_b128 v[180:183], v171 offset:49152
	ds_read_b128 v[184:187], v171 offset:50176
	ds_read_b128 v[188:191], v171 offset:51200
	ds_read_b128 v[192:195], v171 offset:52224
	ds_read_b128 v[196:199], v171 offset:53248
	ds_read_b128 v[200:203], v171 offset:54272
	ds_read_b128 v[204:207], v171 offset:55296
	ds_read_b128 v[208:211], v171 offset:56320
	global_load_lds_dwordx4 v[144:145], off
	s_add_i32 m0, s2, 0x2000
	s_add_u32 s2, s30, 0xb0080
	v_lshl_add_u64 v[144:145], v[166:167], 0, s[6:7]
	s_addc_u32 s3, s31, 0
	s_add_i32 s30, s56, s33
	global_load_lds_dwordx4 v[144:145], off
	v_lshl_add_u64 v[144:145], s[2:3], 0, v[148:149]
	s_mov_b32 m0, s30
	s_nop 0
	global_load_lds_dwordx4 v[144:145], off
	v_lshl_add_u64 v[144:145], s[2:3], 0, v[152:153]
	s_add_i32 m0, s30, 0x2000
	s_nop 0
	global_load_lds_dwordx4 v[144:145], off
	v_lshl_add_u64 v[144:145], v[212:213], 0, s[6:7]
	s_mov_b32 m0, s42
	s_nop 0
	global_load_lds_dwordx4 v[144:145], off
	v_lshl_add_u64 v[144:145], v[214:215], 0, s[6:7]
	s_mov_b32 m0, s43
	s_nop 0
	global_load_lds_dwordx4 v[144:145], off
	s_waitcnt vmcnt(8)
	s_waitcnt lgkmcnt(0)
	s_barrier
	s_setprio 1
	s_waitcnt lgkmcnt(0)
	v_mfma_f32_16x16x32_bf16 v[92:95], v[128:131], v[180:183], v[92:95]
	v_mfma_f32_16x16x32_bf16 v[88:91], v[136:139], v[180:183], v[88:91]
	v_mfma_f32_16x16x32_bf16 v[84:87], v[128:131], v[188:191], v[84:87]
	v_mfma_f32_16x16x32_bf16 v[80:83], v[136:139], v[188:191], v[80:83]
	v_mfma_f32_16x16x32_bf16 v[76:79], v[128:131], v[196:199], v[76:79]
	v_mfma_f32_16x16x32_bf16 v[72:75], v[136:139], v[196:199], v[72:75]
	v_mfma_f32_16x16x32_bf16 v[68:71], v[128:131], v[204:207], v[68:71]
	v_mfma_f32_16x16x32_bf16 v[64:67], v[136:139], v[204:207], v[64:67]
	v_mfma_f32_16x16x32_bf16 v[92:95], v[132:135], v[184:187], v[92:95]
	v_mfma_f32_16x16x32_bf16 v[88:91], v[140:143], v[184:187], v[88:91]
	v_mfma_f32_16x16x32_bf16 v[84:87], v[132:135], v[192:195], v[84:87]
	v_mfma_f32_16x16x32_bf16 v[80:83], v[140:143], v[192:195], v[80:83]
	v_mfma_f32_16x16x32_bf16 v[76:79], v[132:135], v[200:203], v[76:79]
	v_mfma_f32_16x16x32_bf16 v[72:75], v[140:143], v[200:203], v[72:75]
	v_mfma_f32_16x16x32_bf16 v[68:71], v[132:135], v[208:211], v[68:71]
	v_mfma_f32_16x16x32_bf16 v[64:67], v[140:143], v[208:211], v[64:67]
	s_setprio 0
	s_setprio 1
	v_mfma_f32_16x16x32_bf16 v[28:31], v[158:161], v[180:183], v[28:31]
	v_mfma_f32_16x16x32_bf16 v[24:27], v[172:175], v[180:183], v[24:27]
	v_mfma_f32_16x16x32_bf16 v[20:23], v[158:161], v[188:191], v[20:23]
	v_mfma_f32_16x16x32_bf16 v[16:19], v[172:175], v[188:191], v[16:19]
	v_mfma_f32_16x16x32_bf16 v[12:15], v[158:161], v[196:199], v[12:15]
	v_mfma_f32_16x16x32_bf16 v[8:11], v[172:175], v[196:199], v[8:11]
	v_mfma_f32_16x16x32_bf16 v[4:7], v[158:161], v[204:207], v[4:7]
	v_mfma_f32_16x16x32_bf16 v[0:3], v[172:175], v[204:207], v[0:3]
	v_mfma_f32_16x16x32_bf16 v[28:31], v[162:165], v[184:187], v[28:31]
	v_mfma_f32_16x16x32_bf16 v[24:27], v[176:179], v[184:187], v[24:27]
	v_mfma_f32_16x16x32_bf16 v[20:23], v[162:165], v[192:195], v[20:23]
	v_mfma_f32_16x16x32_bf16 v[16:19], v[176:179], v[192:195], v[16:19]
	v_mfma_f32_16x16x32_bf16 v[12:15], v[162:165], v[200:203], v[12:15]
	v_mfma_f32_16x16x32_bf16 v[8:11], v[176:179], v[200:203], v[8:11]
	v_mfma_f32_16x16x32_bf16 v[4:7], v[162:165], v[208:211], v[4:7]
	v_mfma_f32_16x16x32_bf16 v[0:3], v[176:179], v[208:211], v[0:3]
	s_setprio 0
	s_barrier
	s_add_i32 s54, s54, 2
	s_add_u32 s52, s52, 0x100
	s_addc_u32 s53, s53, 0
	s_cmp_gt_u32 s54, 41
	s_mov_b64 s[2:3], s[24:25]
	s_cbranch_scc0 .LBB0_3759
	s_branch .Lpost_3759

; #define BAR __builtin_amdgcn_s_barrier()
; template <class Get, class Epi>
; DI void gemm_loop(int ntiles, int ld, char* shm, const Get& get, const Epi& epi) {
;     ...
;         if (wr == 0) BAR;
.Lpost_3759:
	s_and_b64 vcc, exec, s[8:9]
	s_cbranch_vccz .LBB0_3762
	s_barrier
